# v050 + MFMA order inside each 32-MFMA block: A-fragment stationary, B snake (one operand register changes per step)
# baseline (speedup 1.0000x reference)
.Lmy_nb_0:
	s_nop 0
	v_readfirstlane_b32 s86, v152
	v_readfirstlane_b32 s87, v153
	v_readfirstlane_b32 s88, v150
	v_readfirstlane_b32 s89, v151
	v_readfirstlane_b32 s90, v146
	v_readfirstlane_b32 s91, v147
	v_readfirstlane_b32 s92, v148
	v_readfirstlane_b32 s93, v149
	v_readfirstlane_b32 s100, v154
	v_readfirstlane_b32 s101, v138
	v_add_u32_e32 v230, s76, v141
	v_add_u32_e32 v231, s77, v141
	v_add_u32_e32 v232, 0x18000, v141
	v_add_u32_e32 v233, 0x1c000, v141
	s_add_u32 s98, s86, 0xfffc0080
	s_addc_u32 s99, s87, -1
	s_cmp_eq_u32 s7, s100
	s_cselect_b64 s[94:95], s[90:91], s[98:99]
	s_cselect_b64 s[96:97], s[92:93], s[88:89]
	s_add_i32 s51, s7, 2
	s_mov_b32 m0, s78
	ds_read_b128 v[164:167], v230
	global_load_lds_dwordx4 v144, s[86:87]
	s_mov_b32 m0, s79
	ds_read_b128 v[168:171], v230 offset:1024
	global_load_lds_dwordx4 v142, s[86:87]
	ds_read_b128 v[172:175], v230 offset:2048
	ds_read_b128 v[176:179], v230 offset:3072
	ds_read_b128 v[180:183], v231
	ds_read_b128 v[184:187], v231 offset:1024
	ds_read_b128 v[188:191], v231 offset:2048
	ds_read_b128 v[192:195], v231 offset:3072
	ds_read_b128 v[196:199], v160
	ds_read_b128 v[200:203], v160 offset:1024
	ds_read_b128 v[204:207], v160 offset:2048
	ds_read_b128 v[208:211], v160 offset:3072
	ds_read_b128 v[212:215], v160 offset:4096
	ds_read_b128 v[216:219], v160 offset:5120
	ds_read_b128 v[220:223], v160 offset:6144
	ds_read_b128 v[224:227], v160 offset:7168
	s_waitcnt vmcnt(8)
	s_waitcnt lgkmcnt(0)
	s_setprio 1
	s_barrier
	v_mfma_f32_16x16x32_bf16 v[122:125], v[164:167], v[196:199], 0
	v_mfma_f32_16x16x32_bf16 v[118:121], v[172:175], v[196:199], 0
	v_mfma_f32_16x16x32_bf16 v[126:129], v[180:183], v[196:199], 0
	v_mfma_f32_16x16x32_bf16 v[114:117], v[188:191], v[196:199], 0
	v_mfma_f32_16x16x32_bf16 v[98:101], v[188:191], v[204:207], 0
	v_mfma_f32_16x16x32_bf16 v[106:109], v[180:183], v[204:207], 0
	v_mfma_f32_16x16x32_bf16 v[102:105], v[172:175], v[204:207], 0
	v_mfma_f32_16x16x32_bf16 v[110:113], v[164:167], v[204:207], 0
	v_mfma_f32_16x16x32_bf16 v[94:97], v[164:167], v[212:215], 0
	v_mfma_f32_16x16x32_bf16 v[86:89], v[172:175], v[212:215], 0
	v_mfma_f32_16x16x32_bf16 v[90:93], v[180:183], v[212:215], 0
	v_mfma_f32_16x16x32_bf16 v[82:85], v[188:191], v[212:215], 0
	v_mfma_f32_16x16x32_bf16 v[66:69], v[188:191], v[220:223], 0
	v_mfma_f32_16x16x32_bf16 v[74:77], v[180:183], v[220:223], 0
	v_mfma_f32_16x16x32_bf16 v[70:73], v[172:175], v[220:223], 0
	v_mfma_f32_16x16x32_bf16 v[78:81], v[164:167], v[220:223], 0
	v_mfma_f32_16x16x32_bf16 v[122:125], v[168:171], v[200:203], v[122:125]
	v_mfma_f32_16x16x32_bf16 v[118:121], v[176:179], v[200:203], v[118:121]
	v_mfma_f32_16x16x32_bf16 v[126:129], v[184:187], v[200:203], v[126:129]
	v_mfma_f32_16x16x32_bf16 v[114:117], v[192:195], v[200:203], v[114:117]
	v_mfma_f32_16x16x32_bf16 v[98:101], v[192:195], v[208:211], v[98:101]
	v_mfma_f32_16x16x32_bf16 v[106:109], v[184:187], v[208:211], v[106:109]
	v_mfma_f32_16x16x32_bf16 v[102:105], v[176:179], v[208:211], v[102:105]
	v_mfma_f32_16x16x32_bf16 v[110:113], v[168:171], v[208:211], v[110:113]
	v_mfma_f32_16x16x32_bf16 v[94:97], v[168:171], v[216:219], v[94:97]
	v_mfma_f32_16x16x32_bf16 v[86:89], v[176:179], v[216:219], v[86:89]
	v_mfma_f32_16x16x32_bf16 v[90:93], v[184:187], v[216:219], v[90:93]
	v_mfma_f32_16x16x32_bf16 v[82:85], v[192:195], v[216:219], v[82:85]
	v_mfma_f32_16x16x32_bf16 v[66:69], v[192:195], v[224:227], v[66:69]
	v_mfma_f32_16x16x32_bf16 v[74:77], v[184:187], v[224:227], v[74:77]
	v_mfma_f32_16x16x32_bf16 v[70:73], v[176:179], v[224:227], v[70:73]
	v_mfma_f32_16x16x32_bf16 v[78:81], v[168:171], v[224:227], v[78:81]
	s_barrier
	s_setprio 0
	s_add_u32 s98, s96, 0x40000
	s_addc_u32 s99, s97, 0
	s_mov_b32 m0, s80
	ds_read_b128 v[196:199], v160 offset:16384
	global_load_lds_dwordx4 v132, s[96:97]
	s_mov_b32 m0, s81
	s_add_i32 s7, s77, s47
	global_load_lds_dwordx4 v136, s[96:97]
	s_mov_b32 m0, s7
	ds_read_b128 v[200:203], v160 offset:17408
	global_load_lds_dwordx4 v132, s[98:99]
	s_add_i32 m0, s7, 0x2000
	ds_read_b128 v[204:207], v160 offset:18432
	global_load_lds_dwordx4 v136, s[98:99]
	s_mov_b32 m0, s57
	ds_read_b128 v[208:211], v160 offset:19456
	global_load_lds_dwordx4 v130, s[94:95]
	s_mov_b32 m0, s62
	ds_read_b128 v[212:215], v160 offset:20480
	global_load_lds_dwordx4 v134, s[94:95]
	ds_read_b128 v[216:219], v160 offset:21504
	ds_read_b128 v[220:223], v160 offset:22528
	ds_read_b128 v[224:227], v160 offset:23552
	s_waitcnt vmcnt(8)
	s_waitcnt lgkmcnt(0)
	s_setprio 1
	s_barrier
	v_mfma_f32_16x16x32_bf16 v[62:65], v[164:167], v[196:199], 0
	v_mfma_f32_16x16x32_bf16 v[54:57], v[172:175], v[196:199], 0
	v_mfma_f32_16x16x32_bf16 v[58:61], v[180:183], v[196:199], 0
	v_mfma_f32_16x16x32_bf16 v[50:53], v[188:191], v[196:199], 0
	v_mfma_f32_16x16x32_bf16 v[34:37], v[188:191], v[204:207], 0
	v_mfma_f32_16x16x32_bf16 v[42:45], v[180:183], v[204:207], 0
	v_mfma_f32_16x16x32_bf16 v[38:41], v[172:175], v[204:207], 0
	v_mfma_f32_16x16x32_bf16 v[46:49], v[164:167], v[204:207], 0
	v_mfma_f32_16x16x32_bf16 v[30:33], v[164:167], v[212:215], 0
	v_mfma_f32_16x16x32_bf16 v[22:25], v[172:175], v[212:215], 0
	v_mfma_f32_16x16x32_bf16 v[26:29], v[180:183], v[212:215], 0
	v_mfma_f32_16x16x32_bf16 v[18:21], v[188:191], v[212:215], 0
	v_mfma_f32_16x16x32_bf16 v[2:5], v[188:191], v[220:223], 0
	v_mfma_f32_16x16x32_bf16 v[10:13], v[180:183], v[220:223], 0
	v_mfma_f32_16x16x32_bf16 v[6:9], v[172:175], v[220:223], 0
	v_mfma_f32_16x16x32_bf16 v[14:17], v[164:167], v[220:223], 0
	v_mfma_f32_16x16x32_bf16 v[62:65], v[168:171], v[200:203], v[62:65]
	v_mfma_f32_16x16x32_bf16 v[54:57], v[176:179], v[200:203], v[54:57]
	v_mfma_f32_16x16x32_bf16 v[58:61], v[184:187], v[200:203], v[58:61]
	v_mfma_f32_16x16x32_bf16 v[50:53], v[192:195], v[200:203], v[50:53]
	v_mfma_f32_16x16x32_bf16 v[34:37], v[192:195], v[208:211], v[34:37]
	v_mfma_f32_16x16x32_bf16 v[42:45], v[184:187], v[208:211], v[42:45]
	v_mfma_f32_16x16x32_bf16 v[38:41], v[176:179], v[208:211], v[38:41]
	v_mfma_f32_16x16x32_bf16 v[46:49], v[168:171], v[208:211], v[46:49]
	v_mfma_f32_16x16x32_bf16 v[30:33], v[168:171], v[216:219], v[30:33]
	v_mfma_f32_16x16x32_bf16 v[22:25], v[176:179], v[216:219], v[22:25]
	v_mfma_f32_16x16x32_bf16 v[26:29], v[184:187], v[216:219], v[26:29]
	v_mfma_f32_16x16x32_bf16 v[18:21], v[192:195], v[216:219], v[18:21]
	v_mfma_f32_16x16x32_bf16 v[2:5], v[192:195], v[224:227], v[2:5]
	v_mfma_f32_16x16x32_bf16 v[10:13], v[184:187], v[224:227], v[10:13]
	v_mfma_f32_16x16x32_bf16 v[6:9], v[176:179], v[224:227], v[6:9]
	v_mfma_f32_16x16x32_bf16 v[14:17], v[168:171], v[224:227], v[14:17]
	s_barrier
	s_setprio 0
	s_add_u32 s98, s94, 0x40000
	s_addc_u32 s99, s95, 0
	s_add_i32 s7, 0, 0x18000
	s_add_i32 s55, 0, 0x1c000
	s_mov_b32 m0, s63
	ds_read_b128 v[164:167], v232
	global_load_lds_dwordx4 v130, s[98:99]
	s_mov_b32 m0, s64
	ds_read_b128 v[168:171], v232 offset:1024
	global_load_lds_dwordx4 v134, s[98:99]
	ds_read_b128 v[172:175], v232 offset:2048
	ds_read_b128 v[176:179], v232 offset:3072
	ds_read_b128 v[180:183], v233
	ds_read_b128 v[184:187], v233 offset:1024
	ds_read_b128 v[188:191], v233 offset:2048
	ds_read_b128 v[192:195], v233 offset:3072
	ds_read_b128 v[196:199], v160 offset:32768
	ds_read_b128 v[200:203], v160 offset:33792
	ds_read_b128 v[204:207], v160 offset:34816
	ds_read_b128 v[208:211], v160 offset:35840
	ds_read_b128 v[212:215], v160 offset:36864
	ds_read_b128 v[216:219], v160 offset:37888
	ds_read_b128 v[220:223], v160 offset:38912
	ds_read_b128 v[224:227], v160 offset:39936
	s_waitcnt vmcnt(8)
	s_waitcnt lgkmcnt(0)
	s_setprio 1
	s_barrier
	v_mfma_f32_16x16x32_bf16 v[122:125], v[164:167], v[196:199], v[122:125]
	v_mfma_f32_16x16x32_bf16 v[118:121], v[172:175], v[196:199], v[118:121]
	v_mfma_f32_16x16x32_bf16 v[126:129], v[180:183], v[196:199], v[126:129]
	v_mfma_f32_16x16x32_bf16 v[114:117], v[188:191], v[196:199], v[114:117]
	v_mfma_f32_16x16x32_bf16 v[98:101], v[188:191], v[204:207], v[98:101]
	v_mfma_f32_16x16x32_bf16 v[106:109], v[180:183], v[204:207], v[106:109]
	v_mfma_f32_16x16x32_bf16 v[102:105], v[172:175], v[204:207], v[102:105]
	v_mfma_f32_16x16x32_bf16 v[110:113], v[164:167], v[204:207], v[110:113]
	v_mfma_f32_16x16x32_bf16 v[94:97], v[164:167], v[212:215], v[94:97]
	v_mfma_f32_16x16x32_bf16 v[86:89], v[172:175], v[212:215], v[86:89]
	v_mfma_f32_16x16x32_bf16 v[90:93], v[180:183], v[212:215], v[90:93]
	v_mfma_f32_16x16x32_bf16 v[82:85], v[188:191], v[212:215], v[82:85]
	v_mfma_f32_16x16x32_bf16 v[66:69], v[188:191], v[220:223], v[66:69]
	v_mfma_f32_16x16x32_bf16 v[74:77], v[180:183], v[220:223], v[74:77]
	v_mfma_f32_16x16x32_bf16 v[70:73], v[172:175], v[220:223], v[70:73]
	v_mfma_f32_16x16x32_bf16 v[78:81], v[164:167], v[220:223], v[78:81]
	v_mfma_f32_16x16x32_bf16 v[122:125], v[168:171], v[200:203], v[122:125]
	v_mfma_f32_16x16x32_bf16 v[118:121], v[176:179], v[200:203], v[118:121]
	v_mfma_f32_16x16x32_bf16 v[126:129], v[184:187], v[200:203], v[126:129]
	v_mfma_f32_16x16x32_bf16 v[114:117], v[192:195], v[200:203], v[114:117]
	v_mfma_f32_16x16x32_bf16 v[98:101], v[192:195], v[208:211], v[98:101]
	v_mfma_f32_16x16x32_bf16 v[106:109], v[184:187], v[208:211], v[106:109]
	v_mfma_f32_16x16x32_bf16 v[102:105], v[176:179], v[208:211], v[102:105]
	v_mfma_f32_16x16x32_bf16 v[110:113], v[168:171], v[208:211], v[110:113]
	v_mfma_f32_16x16x32_bf16 v[94:97], v[168:171], v[216:219], v[94:97]
	v_mfma_f32_16x16x32_bf16 v[86:89], v[176:179], v[216:219], v[86:89]
	v_mfma_f32_16x16x32_bf16 v[90:93], v[184:187], v[216:219], v[90:93]
	v_mfma_f32_16x16x32_bf16 v[82:85], v[192:195], v[216:219], v[82:85]
	v_mfma_f32_16x16x32_bf16 v[66:69], v[192:195], v[224:227], v[66:69]
	v_mfma_f32_16x16x32_bf16 v[74:77], v[184:187], v[224:227], v[74:77]
	v_mfma_f32_16x16x32_bf16 v[70:73], v[176:179], v[224:227], v[70:73]
	v_mfma_f32_16x16x32_bf16 v[78:81], v[168:171], v[224:227], v[78:81]
	s_barrier
	s_setprio 0
	s_add_u32 s96, s96, 0x80
	s_addc_u32 s97, s97, 0
	s_add_u32 s98, s96, 0x40000
	s_addc_u32 s99, s97, 0
	s_add_u32 s94, s94, 0x80
	s_addc_u32 s95, s95, 0
	s_add_i32 s7, s7, s47
	s_mov_b32 m0, s7
	ds_read_b128 v[196:199], v160 offset:49152
	global_load_lds_dwordx4 v132, s[96:97]
	s_add_i32 m0, s7, 0x2000
	s_add_i32 s7, s55, s47
	global_load_lds_dwordx4 v136, s[96:97]
	s_mov_b32 m0, s7
	ds_read_b128 v[200:203], v160 offset:50176
	global_load_lds_dwordx4 v132, s[98:99]
	s_add_i32 m0, s7, 0x2000
	ds_read_b128 v[204:207], v160 offset:51200
	global_load_lds_dwordx4 v136, s[98:99]
	s_mov_b32 m0, s65
	ds_read_b128 v[208:211], v160 offset:52224
	global_load_lds_dwordx4 v130, s[94:95]
	s_mov_b32 m0, s66
	ds_read_b128 v[212:215], v160 offset:53248
	global_load_lds_dwordx4 v134, s[94:95]
	ds_read_b128 v[216:219], v160 offset:54272
	ds_read_b128 v[220:223], v160 offset:55296
	ds_read_b128 v[224:227], v160 offset:56320
	s_waitcnt vmcnt(8)
	s_waitcnt lgkmcnt(0)
	s_setprio 1
	s_barrier
	v_mfma_f32_16x16x32_bf16 v[62:65], v[164:167], v[196:199], v[62:65]
	v_mfma_f32_16x16x32_bf16 v[54:57], v[172:175], v[196:199], v[54:57]
	v_mfma_f32_16x16x32_bf16 v[58:61], v[180:183], v[196:199], v[58:61]
	v_mfma_f32_16x16x32_bf16 v[50:53], v[188:191], v[196:199], v[50:53]
	v_mfma_f32_16x16x32_bf16 v[34:37], v[188:191], v[204:207], v[34:37]
	v_mfma_f32_16x16x32_bf16 v[42:45], v[180:183], v[204:207], v[42:45]
	v_mfma_f32_16x16x32_bf16 v[38:41], v[172:175], v[204:207], v[38:41]
	v_mfma_f32_16x16x32_bf16 v[46:49], v[164:167], v[204:207], v[46:49]
	v_mfma_f32_16x16x32_bf16 v[30:33], v[164:167], v[212:215], v[30:33]
	v_mfma_f32_16x16x32_bf16 v[22:25], v[172:175], v[212:215], v[22:25]
	v_mfma_f32_16x16x32_bf16 v[26:29], v[180:183], v[212:215], v[26:29]
	v_mfma_f32_16x16x32_bf16 v[18:21], v[188:191], v[212:215], v[18:21]
	v_mfma_f32_16x16x32_bf16 v[2:5], v[188:191], v[220:223], v[2:5]
	v_mfma_f32_16x16x32_bf16 v[10:13], v[180:183], v[220:223], v[10:13]
	v_mfma_f32_16x16x32_bf16 v[6:9], v[172:175], v[220:223], v[6:9]
	v_mfma_f32_16x16x32_bf16 v[14:17], v[164:167], v[220:223], v[14:17]
	v_mfma_f32_16x16x32_bf16 v[62:65], v[168:171], v[200:203], v[62:65]
	v_mfma_f32_16x16x32_bf16 v[54:57], v[176:179], v[200:203], v[54:57]
	v_mfma_f32_16x16x32_bf16 v[58:61], v[184:187], v[200:203], v[58:61]
	v_mfma_f32_16x16x32_bf16 v[50:53], v[192:195], v[200:203], v[50:53]
	v_mfma_f32_16x16x32_bf16 v[34:37], v[192:195], v[208:211], v[34:37]
	v_mfma_f32_16x16x32_bf16 v[42:45], v[184:187], v[208:211], v[42:45]
	v_mfma_f32_16x16x32_bf16 v[38:41], v[176:179], v[208:211], v[38:41]
	v_mfma_f32_16x16x32_bf16 v[46:49], v[168:171], v[208:211], v[46:49]
	v_mfma_f32_16x16x32_bf16 v[30:33], v[168:171], v[216:219], v[30:33]
	v_mfma_f32_16x16x32_bf16 v[22:25], v[176:179], v[216:219], v[22:25]
	v_mfma_f32_16x16x32_bf16 v[26:29], v[184:187], v[216:219], v[26:29]
	v_mfma_f32_16x16x32_bf16 v[18:21], v[192:195], v[216:219], v[18:21]
	v_mfma_f32_16x16x32_bf16 v[2:5], v[192:195], v[224:227], v[2:5]
	v_mfma_f32_16x16x32_bf16 v[10:13], v[184:187], v[224:227], v[10:13]
	v_mfma_f32_16x16x32_bf16 v[6:9], v[176:179], v[224:227], v[6:9]
	v_mfma_f32_16x16x32_bf16 v[14:17], v[168:171], v[224:227], v[14:17]
	s_barrier
	s_setprio 0
	s_mov_b32 s7, s51
	s_add_u32 s88, s88, 0x100
	s_addc_u32 s89, s89, 0
	s_add_u32 s86, s86, 0x100
	s_addc_u32 s87, s87, 0
	s_cmp_ge_i32 s51, s101
	s_cbranch_scc1 .Lmy_kexit_0
.LBB0_171:
	s_add_u32 s98, s86, 0xfffc0080
	s_addc_u32 s99, s87, -1
	s_cmp_eq_u32 s7, s100
	s_cselect_b64 s[94:95], s[90:91], s[98:99]
	s_cselect_b64 s[96:97], s[92:93], s[88:89]
	s_add_i32 s51, s7, 2
	s_mov_b32 m0, s78
	ds_read_b128 v[164:167], v230
	global_load_lds_dwordx4 v144, s[86:87]
	s_mov_b32 m0, s79
	ds_read_b128 v[168:171], v230 offset:1024
	global_load_lds_dwordx4 v142, s[86:87]
	ds_read_b128 v[172:175], v230 offset:2048
	ds_read_b128 v[176:179], v230 offset:3072
	ds_read_b128 v[180:183], v231
	ds_read_b128 v[184:187], v231 offset:1024
	ds_read_b128 v[188:191], v231 offset:2048
	ds_read_b128 v[192:195], v231 offset:3072
	ds_read_b128 v[196:199], v160
	ds_read_b128 v[200:203], v160 offset:1024
	ds_read_b128 v[204:207], v160 offset:2048
	ds_read_b128 v[208:211], v160 offset:3072
	ds_read_b128 v[212:215], v160 offset:4096
	ds_read_b128 v[216:219], v160 offset:5120
	ds_read_b128 v[220:223], v160 offset:6144
	ds_read_b128 v[224:227], v160 offset:7168
	s_waitcnt vmcnt(8)
	s_waitcnt lgkmcnt(0)
	s_setprio 1
	s_barrier
	v_mfma_f32_16x16x32_bf16 v[122:125], v[164:167], v[196:199], v[122:125]
	v_mfma_f32_16x16x32_bf16 v[118:121], v[172:175], v[196:199], v[118:121]
	v_mfma_f32_16x16x32_bf16 v[126:129], v[180:183], v[196:199], v[126:129]
	v_mfma_f32_16x16x32_bf16 v[114:117], v[188:191], v[196:199], v[114:117]
	v_mfma_f32_16x16x32_bf16 v[98:101], v[188:191], v[204:207], v[98:101]
	v_mfma_f32_16x16x32_bf16 v[106:109], v[180:183], v[204:207], v[106:109]
	v_mfma_f32_16x16x32_bf16 v[102:105], v[172:175], v[204:207], v[102:105]
	v_mfma_f32_16x16x32_bf16 v[110:113], v[164:167], v[204:207], v[110:113]
	v_mfma_f32_16x16x32_bf16 v[94:97], v[164:167], v[212:215], v[94:97]
	v_mfma_f32_16x16x32_bf16 v[86:89], v[172:175], v[212:215], v[86:89]
	v_mfma_f32_16x16x32_bf16 v[90:93], v[180:183], v[212:215], v[90:93]
	v_mfma_f32_16x16x32_bf16 v[82:85], v[188:191], v[212:215], v[82:85]
	v_mfma_f32_16x16x32_bf16 v[66:69], v[188:191], v[220:223], v[66:69]
	v_mfma_f32_16x16x32_bf16 v[74:77], v[180:183], v[220:223], v[74:77]
	v_mfma_f32_16x16x32_bf16 v[70:73], v[172:175], v[220:223], v[70:73]
	v_mfma_f32_16x16x32_bf16 v[78:81], v[164:167], v[220:223], v[78:81]
	v_mfma_f32_16x16x32_bf16 v[122:125], v[168:171], v[200:203], v[122:125]
	v_mfma_f32_16x16x32_bf16 v[118:121], v[176:179], v[200:203], v[118:121]
	v_mfma_f32_16x16x32_bf16 v[126:129], v[184:187], v[200:203], v[126:129]
	v_mfma_f32_16x16x32_bf16 v[114:117], v[192:195], v[200:203], v[114:117]
	v_mfma_f32_16x16x32_bf16 v[98:101], v[192:195], v[208:211], v[98:101]
	v_mfma_f32_16x16x32_bf16 v[106:109], v[184:187], v[208:211], v[106:109]
	v_mfma_f32_16x16x32_bf16 v[102:105], v[176:179], v[208:211], v[102:105]
	v_mfma_f32_16x16x32_bf16 v[110:113], v[168:171], v[208:211], v[110:113]
	v_mfma_f32_16x16x32_bf16 v[94:97], v[168:171], v[216:219], v[94:97]
	v_mfma_f32_16x16x32_bf16 v[86:89], v[176:179], v[216:219], v[86:89]
	v_mfma_f32_16x16x32_bf16 v[90:93], v[184:187], v[216:219], v[90:93]
	v_mfma_f32_16x16x32_bf16 v[82:85], v[192:195], v[216:219], v[82:85]
	v_mfma_f32_16x16x32_bf16 v[66:69], v[192:195], v[224:227], v[66:69]
	v_mfma_f32_16x16x32_bf16 v[74:77], v[184:187], v[224:227], v[74:77]
	v_mfma_f32_16x16x32_bf16 v[70:73], v[176:179], v[224:227], v[70:73]
	v_mfma_f32_16x16x32_bf16 v[78:81], v[168:171], v[224:227], v[78:81]
	s_barrier
	s_setprio 0
	s_add_u32 s98, s96, 0x40000
	s_addc_u32 s99, s97, 0
	s_mov_b32 m0, s80
	ds_read_b128 v[196:199], v160 offset:16384
	global_load_lds_dwordx4 v132, s[96:97]
	s_mov_b32 m0, s81
	s_add_i32 s7, s77, s47
	global_load_lds_dwordx4 v136, s[96:97]
	s_mov_b32 m0, s7
	ds_read_b128 v[200:203], v160 offset:17408
	global_load_lds_dwordx4 v132, s[98:99]
	s_add_i32 m0, s7, 0x2000
	ds_read_b128 v[204:207], v160 offset:18432
	global_load_lds_dwordx4 v136, s[98:99]
	s_mov_b32 m0, s57
	ds_read_b128 v[208:211], v160 offset:19456
	global_load_lds_dwordx4 v130, s[94:95]
	s_mov_b32 m0, s62
	ds_read_b128 v[212:215], v160 offset:20480
	global_load_lds_dwordx4 v134, s[94:95]
	ds_read_b128 v[216:219], v160 offset:21504
	ds_read_b128 v[220:223], v160 offset:22528
	ds_read_b128 v[224:227], v160 offset:23552
	s_waitcnt vmcnt(8)
	s_waitcnt lgkmcnt(0)
	s_setprio 1
	s_barrier
	v_mfma_f32_16x16x32_bf16 v[62:65], v[164:167], v[196:199], v[62:65]
	v_mfma_f32_16x16x32_bf16 v[54:57], v[172:175], v[196:199], v[54:57]
	v_mfma_f32_16x16x32_bf16 v[58:61], v[180:183], v[196:199], v[58:61]
	v_mfma_f32_16x16x32_bf16 v[50:53], v[188:191], v[196:199], v[50:53]
	v_mfma_f32_16x16x32_bf16 v[34:37], v[188:191], v[204:207], v[34:37]
	v_mfma_f32_16x16x32_bf16 v[42:45], v[180:183], v[204:207], v[42:45]
	v_mfma_f32_16x16x32_bf16 v[38:41], v[172:175], v[204:207], v[38:41]
	v_mfma_f32_16x16x32_bf16 v[46:49], v[164:167], v[204:207], v[46:49]
	v_mfma_f32_16x16x32_bf16 v[30:33], v[164:167], v[212:215], v[30:33]
	v_mfma_f32_16x16x32_bf16 v[22:25], v[172:175], v[212:215], v[22:25]
	v_mfma_f32_16x16x32_bf16 v[26:29], v[180:183], v[212:215], v[26:29]
	v_mfma_f32_16x16x32_bf16 v[18:21], v[188:191], v[212:215], v[18:21]
	v_mfma_f32_16x16x32_bf16 v[2:5], v[188:191], v[220:223], v[2:5]
	v_mfma_f32_16x16x32_bf16 v[10:13], v[180:183], v[220:223], v[10:13]
	v_mfma_f32_16x16x32_bf16 v[6:9], v[172:175], v[220:223], v[6:9]
	v_mfma_f32_16x16x32_bf16 v[14:17], v[164:167], v[220:223], v[14:17]
	v_mfma_f32_16x16x32_bf16 v[62:65], v[168:171], v[200:203], v[62:65]
	v_mfma_f32_16x16x32_bf16 v[54:57], v[176:179], v[200:203], v[54:57]
	v_mfma_f32_16x16x32_bf16 v[58:61], v[184:187], v[200:203], v[58:61]
	v_mfma_f32_16x16x32_bf16 v[50:53], v[192:195], v[200:203], v[50:53]
	v_mfma_f32_16x16x32_bf16 v[34:37], v[192:195], v[208:211], v[34:37]
	v_mfma_f32_16x16x32_bf16 v[42:45], v[184:187], v[208:211], v[42:45]
	v_mfma_f32_16x16x32_bf16 v[38:41], v[176:179], v[208:211], v[38:41]
	v_mfma_f32_16x16x32_bf16 v[46:49], v[168:171], v[208:211], v[46:49]
	v_mfma_f32_16x16x32_bf16 v[30:33], v[168:171], v[216:219], v[30:33]
	v_mfma_f32_16x16x32_bf16 v[22:25], v[176:179], v[216:219], v[22:25]
	v_mfma_f32_16x16x32_bf16 v[26:29], v[184:187], v[216:219], v[26:29]
	v_mfma_f32_16x16x32_bf16 v[18:21], v[192:195], v[216:219], v[18:21]
	v_mfma_f32_16x16x32_bf16 v[2:5], v[192:195], v[224:227], v[2:5]
	v_mfma_f32_16x16x32_bf16 v[10:13], v[184:187], v[224:227], v[10:13]
	v_mfma_f32_16x16x32_bf16 v[6:9], v[176:179], v[224:227], v[6:9]
	v_mfma_f32_16x16x32_bf16 v[14:17], v[168:171], v[224:227], v[14:17]
	s_barrier
	s_setprio 0
	s_add_u32 s98, s94, 0x40000
	s_addc_u32 s99, s95, 0
	s_add_i32 s7, 0, 0x18000
	s_add_i32 s55, 0, 0x1c000
	s_mov_b32 m0, s63
	ds_read_b128 v[164:167], v232
	global_load_lds_dwordx4 v130, s[98:99]
	s_mov_b32 m0, s64
	ds_read_b128 v[168:171], v232 offset:1024
	global_load_lds_dwordx4 v134, s[98:99]
	ds_read_b128 v[172:175], v232 offset:2048
	ds_read_b128 v[176:179], v232 offset:3072
	ds_read_b128 v[180:183], v233
	ds_read_b128 v[184:187], v233 offset:1024
	ds_read_b128 v[188:191], v233 offset:2048
	ds_read_b128 v[192:195], v233 offset:3072
	ds_read_b128 v[196:199], v160 offset:32768
	ds_read_b128 v[200:203], v160 offset:33792
	ds_read_b128 v[204:207], v160 offset:34816
	ds_read_b128 v[208:211], v160 offset:35840
	ds_read_b128 v[212:215], v160 offset:36864
	ds_read_b128 v[216:219], v160 offset:37888
	ds_read_b128 v[220:223], v160 offset:38912
	ds_read_b128 v[224:227], v160 offset:39936
	s_waitcnt vmcnt(8)
	s_waitcnt lgkmcnt(0)
	s_setprio 1
	s_barrier
	v_mfma_f32_16x16x32_bf16 v[122:125], v[164:167], v[196:199], v[122:125]
	v_mfma_f32_16x16x32_bf16 v[118:121], v[172:175], v[196:199], v[118:121]
	v_mfma_f32_16x16x32_bf16 v[126:129], v[180:183], v[196:199], v[126:129]
	v_mfma_f32_16x16x32_bf16 v[114:117], v[188:191], v[196:199], v[114:117]
	v_mfma_f32_16x16x32_bf16 v[98:101], v[188:191], v[204:207], v[98:101]
	v_mfma_f32_16x16x32_bf16 v[106:109], v[180:183], v[204:207], v[106:109]
	v_mfma_f32_16x16x32_bf16 v[102:105], v[172:175], v[204:207], v[102:105]
	v_mfma_f32_16x16x32_bf16 v[110:113], v[164:167], v[204:207], v[110:113]
	v_mfma_f32_16x16x32_bf16 v[94:97], v[164:167], v[212:215], v[94:97]
	v_mfma_f32_16x16x32_bf16 v[86:89], v[172:175], v[212:215], v[86:89]
	v_mfma_f32_16x16x32_bf16 v[90:93], v[180:183], v[212:215], v[90:93]
	v_mfma_f32_16x16x32_bf16 v[82:85], v[188:191], v[212:215], v[82:85]
	v_mfma_f32_16x16x32_bf16 v[66:69], v[188:191], v[220:223], v[66:69]
	v_mfma_f32_16x16x32_bf16 v[74:77], v[180:183], v[220:223], v[74:77]
	v_mfma_f32_16x16x32_bf16 v[70:73], v[172:175], v[220:223], v[70:73]
	v_mfma_f32_16x16x32_bf16 v[78:81], v[164:167], v[220:223], v[78:81]
	v_mfma_f32_16x16x32_bf16 v[122:125], v[168:171], v[200:203], v[122:125]
	v_mfma_f32_16x16x32_bf16 v[118:121], v[176:179], v[200:203], v[118:121]
	v_mfma_f32_16x16x32_bf16 v[126:129], v[184:187], v[200:203], v[126:129]
	v_mfma_f32_16x16x32_bf16 v[114:117], v[192:195], v[200:203], v[114:117]
	v_mfma_f32_16x16x32_bf16 v[98:101], v[192:195], v[208:211], v[98:101]
	v_mfma_f32_16x16x32_bf16 v[106:109], v[184:187], v[208:211], v[106:109]
	v_mfma_f32_16x16x32_bf16 v[102:105], v[176:179], v[208:211], v[102:105]
	v_mfma_f32_16x16x32_bf16 v[110:113], v[168:171], v[208:211], v[110:113]
	v_mfma_f32_16x16x32_bf16 v[94:97], v[168:171], v[216:219], v[94:97]
	v_mfma_f32_16x16x32_bf16 v[86:89], v[176:179], v[216:219], v[86:89]
	v_mfma_f32_16x16x32_bf16 v[90:93], v[184:187], v[216:219], v[90:93]
	v_mfma_f32_16x16x32_bf16 v[82:85], v[192:195], v[216:219], v[82:85]
	v_mfma_f32_16x16x32_bf16 v[66:69], v[192:195], v[224:227], v[66:69]
	v_mfma_f32_16x16x32_bf16 v[74:77], v[184:187], v[224:227], v[74:77]
	v_mfma_f32_16x16x32_bf16 v[70:73], v[176:179], v[224:227], v[70:73]
	v_mfma_f32_16x16x32_bf16 v[78:81], v[168:171], v[224:227], v[78:81]
	s_barrier
	s_setprio 0
	s_add_u32 s96, s96, 0x80
	s_addc_u32 s97, s97, 0
	s_add_u32 s98, s96, 0x40000
	s_addc_u32 s99, s97, 0
	s_add_u32 s94, s94, 0x80
	s_addc_u32 s95, s95, 0
	s_add_i32 s7, s7, s47
	s_mov_b32 m0, s7
	ds_read_b128 v[196:199], v160 offset:49152
	global_load_lds_dwordx4 v132, s[96:97]
	s_add_i32 m0, s7, 0x2000
	s_add_i32 s7, s55, s47
	global_load_lds_dwordx4 v136, s[96:97]
	s_mov_b32 m0, s7
	ds_read_b128 v[200:203], v160 offset:50176
	global_load_lds_dwordx4 v132, s[98:99]
	s_add_i32 m0, s7, 0x2000
	ds_read_b128 v[204:207], v160 offset:51200
	global_load_lds_dwordx4 v136, s[98:99]
	s_mov_b32 m0, s65
	ds_read_b128 v[208:211], v160 offset:52224
	global_load_lds_dwordx4 v130, s[94:95]
	s_mov_b32 m0, s66
	ds_read_b128 v[212:215], v160 offset:53248
	global_load_lds_dwordx4 v134, s[94:95]
	ds_read_b128 v[216:219], v160 offset:54272
	ds_read_b128 v[220:223], v160 offset:55296
	ds_read_b128 v[224:227], v160 offset:56320
	s_waitcnt vmcnt(8)
	s_waitcnt lgkmcnt(0)
	s_setprio 1
	s_barrier
	v_mfma_f32_16x16x32_bf16 v[62:65], v[164:167], v[196:199], v[62:65]
	v_mfma_f32_16x16x32_bf16 v[54:57], v[172:175], v[196:199], v[54:57]
	v_mfma_f32_16x16x32_bf16 v[58:61], v[180:183], v[196:199], v[58:61]
	v_mfma_f32_16x16x32_bf16 v[50:53], v[188:191], v[196:199], v[50:53]
	v_mfma_f32_16x16x32_bf16 v[34:37], v[188:191], v[204:207], v[34:37]
	v_mfma_f32_16x16x32_bf16 v[42:45], v[180:183], v[204:207], v[42:45]
	v_mfma_f32_16x16x32_bf16 v[38:41], v[172:175], v[204:207], v[38:41]
	v_mfma_f32_16x16x32_bf16 v[46:49], v[164:167], v[204:207], v[46:49]
	v_mfma_f32_16x16x32_bf16 v[30:33], v[164:167], v[212:215], v[30:33]
	v_mfma_f32_16x16x32_bf16 v[22:25], v[172:175], v[212:215], v[22:25]
	v_mfma_f32_16x16x32_bf16 v[26:29], v[180:183], v[212:215], v[26:29]
	v_mfma_f32_16x16x32_bf16 v[18:21], v[188:191], v[212:215], v[18:21]
	v_mfma_f32_16x16x32_bf16 v[2:5], v[188:191], v[220:223], v[2:5]
	v_mfma_f32_16x16x32_bf16 v[10:13], v[180:183], v[220:223], v[10:13]
	v_mfma_f32_16x16x32_bf16 v[6:9], v[172:175], v[220:223], v[6:9]
	v_mfma_f32_16x16x32_bf16 v[14:17], v[164:167], v[220:223], v[14:17]
	v_mfma_f32_16x16x32_bf16 v[62:65], v[168:171], v[200:203], v[62:65]
	v_mfma_f32_16x16x32_bf16 v[54:57], v[176:179], v[200:203], v[54:57]
	v_mfma_f32_16x16x32_bf16 v[58:61], v[184:187], v[200:203], v[58:61]
	v_mfma_f32_16x16x32_bf16 v[50:53], v[192:195], v[200:203], v[50:53]
	v_mfma_f32_16x16x32_bf16 v[34:37], v[192:195], v[208:211], v[34:37]
	v_mfma_f32_16x16x32_bf16 v[42:45], v[184:187], v[208:211], v[42:45]
	v_mfma_f32_16x16x32_bf16 v[38:41], v[176:179], v[208:211], v[38:41]
	v_mfma_f32_16x16x32_bf16 v[46:49], v[168:171], v[208:211], v[46:49]
	v_mfma_f32_16x16x32_bf16 v[30:33], v[168:171], v[216:219], v[30:33]
	v_mfma_f32_16x16x32_bf16 v[22:25], v[176:179], v[216:219], v[22:25]
	v_mfma_f32_16x16x32_bf16 v[26:29], v[184:187], v[216:219], v[26:29]
	v_mfma_f32_16x16x32_bf16 v[18:21], v[192:195], v[216:219], v[18:21]
	v_mfma_f32_16x16x32_bf16 v[2:5], v[192:195], v[224:227], v[2:5]
	v_mfma_f32_16x16x32_bf16 v[10:13], v[184:187], v[224:227], v[10:13]
	v_mfma_f32_16x16x32_bf16 v[6:9], v[176:179], v[224:227], v[6:9]
	v_mfma_f32_16x16x32_bf16 v[14:17], v[168:171], v[224:227], v[14:17]
	s_barrier
	s_setprio 0
	s_mov_b32 s7, s51
	s_add_u32 s88, s88, 0x100
	s_addc_u32 s89, s89, 0
	s_add_u32 s86, s86, 0x100
	s_addc_u32 s87, s87, 0
	s_cmp_ge_i32 s51, s101
	s_cbranch_scc0 .LBB0_171

.Lmy_nb_1:
	s_nop 0
	v_readfirstlane_b32 s86, v152
	v_readfirstlane_b32 s87, v153
	v_readfirstlane_b32 s88, v154
	v_readfirstlane_b32 s89, v155
	v_readfirstlane_b32 s90, v148
	v_readfirstlane_b32 s91, v149
	v_readfirstlane_b32 s92, v150
	v_readfirstlane_b32 s93, v151
	v_readfirstlane_b32 s100, v138
	v_readfirstlane_b32 s101, v141
	v_add_u32_e32 v230, s69, v160
	v_add_u32_e32 v231, s72, v160
	v_add_u32_e32 v232, 0x18000, v160
	v_add_u32_e32 v233, 0x1c000, v160
	s_add_u32 s98, s86, 0x100
	s_addc_u32 s99, s87, 0
	s_cmp_eq_u32 s8, s100
	s_cselect_b64 s[94:95], s[90:91], s[98:99]
	s_cselect_b64 s[96:97], s[92:93], s[88:89]
	s_add_i32 s9, s8, 2
	s_add_i32 m0, s55, 0xc000
	ds_read_b128 v[166:169], v230
	global_load_lds_dwordx4 v144, s[86:87]
	s_add_i32 m0, s55, 0xe000
	ds_read_b128 v[170:173], v230 offset:1024
	global_load_lds_dwordx4 v142, s[86:87]
	ds_read_b128 v[174:177], v230 offset:2048
	ds_read_b128 v[178:181], v230 offset:3072
	ds_read_b128 v[182:185], v231
	ds_read_b128 v[186:189], v231 offset:1024
	ds_read_b128 v[190:193], v231 offset:2048
	ds_read_b128 v[194:197], v231 offset:3072
	ds_read_b128 v[198:201], v163
	ds_read_b128 v[202:205], v163 offset:1024
	ds_read_b128 v[206:209], v163 offset:2048
	ds_read_b128 v[210:213], v163 offset:3072
	ds_read_b128 v[214:217], v163 offset:4096
	ds_read_b128 v[218:221], v163 offset:5120
	ds_read_b128 v[222:225], v163 offset:6144
	ds_read_b128 v[226:229], v163 offset:7168
	s_waitcnt vmcnt(8)
	s_waitcnt lgkmcnt(0)
	s_setprio 1
	s_barrier
	v_mfma_f32_16x16x32_bf16 v[122:125], v[166:169], v[198:201], 0
	v_mfma_f32_16x16x32_bf16 v[118:121], v[174:177], v[198:201], 0
	v_mfma_f32_16x16x32_bf16 v[126:129], v[182:185], v[198:201], 0
	v_mfma_f32_16x16x32_bf16 v[114:117], v[190:193], v[198:201], 0
	v_mfma_f32_16x16x32_bf16 v[98:101], v[190:193], v[206:209], 0
	v_mfma_f32_16x16x32_bf16 v[106:109], v[182:185], v[206:209], 0
	v_mfma_f32_16x16x32_bf16 v[102:105], v[174:177], v[206:209], 0
	v_mfma_f32_16x16x32_bf16 v[110:113], v[166:169], v[206:209], 0
	v_mfma_f32_16x16x32_bf16 v[94:97], v[166:169], v[214:217], 0
	v_mfma_f32_16x16x32_bf16 v[86:89], v[174:177], v[214:217], 0
	v_mfma_f32_16x16x32_bf16 v[90:93], v[182:185], v[214:217], 0
	v_mfma_f32_16x16x32_bf16 v[82:85], v[190:193], v[214:217], 0
	v_mfma_f32_16x16x32_bf16 v[66:69], v[190:193], v[222:225], 0
	v_mfma_f32_16x16x32_bf16 v[74:77], v[182:185], v[222:225], 0
	v_mfma_f32_16x16x32_bf16 v[70:73], v[174:177], v[222:225], 0
	v_mfma_f32_16x16x32_bf16 v[78:81], v[166:169], v[222:225], 0
	v_mfma_f32_16x16x32_bf16 v[122:125], v[170:173], v[202:205], v[122:125]
	v_mfma_f32_16x16x32_bf16 v[118:121], v[178:181], v[202:205], v[118:121]
	v_mfma_f32_16x16x32_bf16 v[126:129], v[186:189], v[202:205], v[126:129]
	v_mfma_f32_16x16x32_bf16 v[114:117], v[194:197], v[202:205], v[114:117]
	v_mfma_f32_16x16x32_bf16 v[98:101], v[194:197], v[210:213], v[98:101]
	v_mfma_f32_16x16x32_bf16 v[106:109], v[186:189], v[210:213], v[106:109]
	v_mfma_f32_16x16x32_bf16 v[102:105], v[178:181], v[210:213], v[102:105]
	v_mfma_f32_16x16x32_bf16 v[110:113], v[170:173], v[210:213], v[110:113]
	v_mfma_f32_16x16x32_bf16 v[94:97], v[170:173], v[218:221], v[94:97]
	v_mfma_f32_16x16x32_bf16 v[86:89], v[178:181], v[218:221], v[86:89]
	v_mfma_f32_16x16x32_bf16 v[90:93], v[186:189], v[218:221], v[90:93]
	v_mfma_f32_16x16x32_bf16 v[82:85], v[194:197], v[218:221], v[82:85]
	v_mfma_f32_16x16x32_bf16 v[66:69], v[194:197], v[226:229], v[66:69]
	v_mfma_f32_16x16x32_bf16 v[74:77], v[186:189], v[226:229], v[74:77]
	v_mfma_f32_16x16x32_bf16 v[70:73], v[178:181], v[226:229], v[70:73]
	v_mfma_f32_16x16x32_bf16 v[78:81], v[170:173], v[226:229], v[78:81]
	s_barrier
	s_setprio 0
	s_add_u32 s98, s96, 0xb0000
	s_addc_u32 s99, s97, 0
	s_add_i32 s8, s69, s54
	s_mov_b32 m0, s8
	ds_read_b128 v[198:201], v163 offset:16384
	global_load_lds_dwordx4 v132, s[96:97]
	s_add_i32 m0, s8, 0x2000
	s_add_i32 s8, s72, s54
	global_load_lds_dwordx4 v136, s[96:97]
	s_mov_b32 m0, s8
	ds_read_b128 v[202:205], v163 offset:17408
	global_load_lds_dwordx4 v132, s[98:99]
	s_add_i32 m0, s8, 0x2000
	ds_read_b128 v[206:209], v163 offset:18432
	global_load_lds_dwordx4 v136, s[98:99]
	s_mov_b32 m0, s55
	ds_read_b128 v[210:213], v163 offset:19456
	global_load_lds_dwordx4 v130, s[94:95]
	s_mov_b32 m0, s56
	ds_read_b128 v[214:217], v163 offset:20480
	global_load_lds_dwordx4 v134, s[94:95]
	ds_read_b128 v[218:221], v163 offset:21504
	ds_read_b128 v[222:225], v163 offset:22528
	ds_read_b128 v[226:229], v163 offset:23552
	s_waitcnt vmcnt(8)
	s_waitcnt lgkmcnt(0)
	s_setprio 1
	s_barrier
	v_mfma_f32_16x16x32_bf16 v[62:65], v[166:169], v[198:201], 0
	v_mfma_f32_16x16x32_bf16 v[54:57], v[174:177], v[198:201], 0
	v_mfma_f32_16x16x32_bf16 v[58:61], v[182:185], v[198:201], 0
	v_mfma_f32_16x16x32_bf16 v[50:53], v[190:193], v[198:201], 0
	v_mfma_f32_16x16x32_bf16 v[34:37], v[190:193], v[206:209], 0
	v_mfma_f32_16x16x32_bf16 v[42:45], v[182:185], v[206:209], 0
	v_mfma_f32_16x16x32_bf16 v[38:41], v[174:177], v[206:209], 0
	v_mfma_f32_16x16x32_bf16 v[46:49], v[166:169], v[206:209], 0
	v_mfma_f32_16x16x32_bf16 v[30:33], v[166:169], v[214:217], 0
	v_mfma_f32_16x16x32_bf16 v[22:25], v[174:177], v[214:217], 0
	v_mfma_f32_16x16x32_bf16 v[26:29], v[182:185], v[214:217], 0
	v_mfma_f32_16x16x32_bf16 v[18:21], v[190:193], v[214:217], 0
	v_mfma_f32_16x16x32_bf16 v[2:5], v[190:193], v[222:225], 0
	v_mfma_f32_16x16x32_bf16 v[10:13], v[182:185], v[222:225], 0
	v_mfma_f32_16x16x32_bf16 v[6:9], v[174:177], v[222:225], 0
	v_mfma_f32_16x16x32_bf16 v[14:17], v[166:169], v[222:225], 0
	v_mfma_f32_16x16x32_bf16 v[62:65], v[170:173], v[202:205], v[62:65]
	v_mfma_f32_16x16x32_bf16 v[54:57], v[178:181], v[202:205], v[54:57]
	v_mfma_f32_16x16x32_bf16 v[58:61], v[186:189], v[202:205], v[58:61]
	v_mfma_f32_16x16x32_bf16 v[50:53], v[194:197], v[202:205], v[50:53]
	v_mfma_f32_16x16x32_bf16 v[34:37], v[194:197], v[210:213], v[34:37]
	v_mfma_f32_16x16x32_bf16 v[42:45], v[186:189], v[210:213], v[42:45]
	v_mfma_f32_16x16x32_bf16 v[38:41], v[178:181], v[210:213], v[38:41]
	v_mfma_f32_16x16x32_bf16 v[46:49], v[170:173], v[210:213], v[46:49]
	v_mfma_f32_16x16x32_bf16 v[30:33], v[170:173], v[218:221], v[30:33]
	v_mfma_f32_16x16x32_bf16 v[22:25], v[178:181], v[218:221], v[22:25]
	v_mfma_f32_16x16x32_bf16 v[26:29], v[186:189], v[218:221], v[26:29]
	v_mfma_f32_16x16x32_bf16 v[18:21], v[194:197], v[218:221], v[18:21]
	v_mfma_f32_16x16x32_bf16 v[2:5], v[194:197], v[226:229], v[2:5]
	v_mfma_f32_16x16x32_bf16 v[10:13], v[186:189], v[226:229], v[10:13]
	v_mfma_f32_16x16x32_bf16 v[6:9], v[178:181], v[226:229], v[6:9]
	v_mfma_f32_16x16x32_bf16 v[14:17], v[170:173], v[226:229], v[14:17]
	s_barrier
	s_setprio 0
	s_add_u32 s98, s94, 0xb0000
	s_addc_u32 s99, s95, 0
	s_add_i32 s8, 0, 0x18000
	s_add_i32 s50, 0, 0x1c000
	s_mov_b32 m0, s57
	ds_read_b128 v[166:169], v232
	global_load_lds_dwordx4 v130, s[98:99]
	s_mov_b32 m0, s58
	ds_read_b128 v[170:173], v232 offset:1024
	global_load_lds_dwordx4 v134, s[98:99]
	ds_read_b128 v[174:177], v232 offset:2048
	ds_read_b128 v[178:181], v232 offset:3072
	ds_read_b128 v[182:185], v233
	ds_read_b128 v[186:189], v233 offset:1024
	ds_read_b128 v[190:193], v233 offset:2048
	ds_read_b128 v[194:197], v233 offset:3072
	ds_read_b128 v[198:201], v163 offset:32768
	ds_read_b128 v[202:205], v163 offset:33792
	ds_read_b128 v[206:209], v163 offset:34816
	ds_read_b128 v[210:213], v163 offset:35840
	ds_read_b128 v[214:217], v163 offset:36864
	ds_read_b128 v[218:221], v163 offset:37888
	ds_read_b128 v[222:225], v163 offset:38912
	ds_read_b128 v[226:229], v163 offset:39936
	s_waitcnt vmcnt(8)
	s_waitcnt lgkmcnt(0)
	s_setprio 1
	s_barrier
	v_mfma_f32_16x16x32_bf16 v[122:125], v[166:169], v[198:201], v[122:125]
	v_mfma_f32_16x16x32_bf16 v[118:121], v[174:177], v[198:201], v[118:121]
	v_mfma_f32_16x16x32_bf16 v[126:129], v[182:185], v[198:201], v[126:129]
	v_mfma_f32_16x16x32_bf16 v[114:117], v[190:193], v[198:201], v[114:117]
	v_mfma_f32_16x16x32_bf16 v[98:101], v[190:193], v[206:209], v[98:101]
	v_mfma_f32_16x16x32_bf16 v[106:109], v[182:185], v[206:209], v[106:109]
	v_mfma_f32_16x16x32_bf16 v[102:105], v[174:177], v[206:209], v[102:105]
	v_mfma_f32_16x16x32_bf16 v[110:113], v[166:169], v[206:209], v[110:113]
	v_mfma_f32_16x16x32_bf16 v[94:97], v[166:169], v[214:217], v[94:97]
	v_mfma_f32_16x16x32_bf16 v[86:89], v[174:177], v[214:217], v[86:89]
	v_mfma_f32_16x16x32_bf16 v[90:93], v[182:185], v[214:217], v[90:93]
	v_mfma_f32_16x16x32_bf16 v[82:85], v[190:193], v[214:217], v[82:85]
	v_mfma_f32_16x16x32_bf16 v[66:69], v[190:193], v[222:225], v[66:69]
	v_mfma_f32_16x16x32_bf16 v[74:77], v[182:185], v[222:225], v[74:77]
	v_mfma_f32_16x16x32_bf16 v[70:73], v[174:177], v[222:225], v[70:73]
	v_mfma_f32_16x16x32_bf16 v[78:81], v[166:169], v[222:225], v[78:81]
	v_mfma_f32_16x16x32_bf16 v[122:125], v[170:173], v[202:205], v[122:125]
	v_mfma_f32_16x16x32_bf16 v[118:121], v[178:181], v[202:205], v[118:121]
	v_mfma_f32_16x16x32_bf16 v[126:129], v[186:189], v[202:205], v[126:129]
	v_mfma_f32_16x16x32_bf16 v[114:117], v[194:197], v[202:205], v[114:117]
	v_mfma_f32_16x16x32_bf16 v[98:101], v[194:197], v[210:213], v[98:101]
	v_mfma_f32_16x16x32_bf16 v[106:109], v[186:189], v[210:213], v[106:109]
	v_mfma_f32_16x16x32_bf16 v[102:105], v[178:181], v[210:213], v[102:105]
	v_mfma_f32_16x16x32_bf16 v[110:113], v[170:173], v[210:213], v[110:113]
	v_mfma_f32_16x16x32_bf16 v[94:97], v[170:173], v[218:221], v[94:97]
	v_mfma_f32_16x16x32_bf16 v[86:89], v[178:181], v[218:221], v[86:89]
	v_mfma_f32_16x16x32_bf16 v[90:93], v[186:189], v[218:221], v[90:93]
	v_mfma_f32_16x16x32_bf16 v[82:85], v[194:197], v[218:221], v[82:85]
	v_mfma_f32_16x16x32_bf16 v[66:69], v[194:197], v[226:229], v[66:69]
	v_mfma_f32_16x16x32_bf16 v[74:77], v[186:189], v[226:229], v[74:77]
	v_mfma_f32_16x16x32_bf16 v[70:73], v[178:181], v[226:229], v[70:73]
	v_mfma_f32_16x16x32_bf16 v[78:81], v[170:173], v[226:229], v[78:81]
	s_barrier
	s_setprio 0
	s_add_u32 s96, s96, 0x80
	s_addc_u32 s97, s97, 0
	s_add_u32 s98, s96, 0xb0000
	s_addc_u32 s99, s97, 0
	s_add_u32 s94, s94, 0x80
	s_addc_u32 s95, s95, 0
	s_add_i32 s8, s8, s54
	s_mov_b32 m0, s8
	ds_read_b128 v[198:201], v163 offset:49152
	global_load_lds_dwordx4 v132, s[96:97]
	s_add_i32 m0, s8, 0x2000
	s_add_i32 s8, s50, s54
	global_load_lds_dwordx4 v136, s[96:97]
	s_mov_b32 m0, s8
	ds_read_b128 v[202:205], v163 offset:50176
	global_load_lds_dwordx4 v132, s[98:99]
	s_add_i32 m0, s8, 0x2000
	ds_read_b128 v[206:209], v163 offset:51200
	global_load_lds_dwordx4 v136, s[98:99]
	s_mov_b32 m0, s64
	ds_read_b128 v[210:213], v163 offset:52224
	global_load_lds_dwordx4 v130, s[94:95]
	s_mov_b32 m0, s65
	ds_read_b128 v[214:217], v163 offset:53248
	global_load_lds_dwordx4 v134, s[94:95]
	ds_read_b128 v[218:221], v163 offset:54272
	ds_read_b128 v[222:225], v163 offset:55296
	ds_read_b128 v[226:229], v163 offset:56320
	s_waitcnt vmcnt(8)
	s_waitcnt lgkmcnt(0)
	s_setprio 1
	s_barrier
	v_mfma_f32_16x16x32_bf16 v[62:65], v[166:169], v[198:201], v[62:65]
	v_mfma_f32_16x16x32_bf16 v[54:57], v[174:177], v[198:201], v[54:57]
	v_mfma_f32_16x16x32_bf16 v[58:61], v[182:185], v[198:201], v[58:61]
	v_mfma_f32_16x16x32_bf16 v[50:53], v[190:193], v[198:201], v[50:53]
	v_mfma_f32_16x16x32_bf16 v[34:37], v[190:193], v[206:209], v[34:37]
	v_mfma_f32_16x16x32_bf16 v[42:45], v[182:185], v[206:209], v[42:45]
	v_mfma_f32_16x16x32_bf16 v[38:41], v[174:177], v[206:209], v[38:41]
	v_mfma_f32_16x16x32_bf16 v[46:49], v[166:169], v[206:209], v[46:49]
	v_mfma_f32_16x16x32_bf16 v[30:33], v[166:169], v[214:217], v[30:33]
	v_mfma_f32_16x16x32_bf16 v[22:25], v[174:177], v[214:217], v[22:25]
	v_mfma_f32_16x16x32_bf16 v[26:29], v[182:185], v[214:217], v[26:29]
	v_mfma_f32_16x16x32_bf16 v[18:21], v[190:193], v[214:217], v[18:21]
	v_mfma_f32_16x16x32_bf16 v[2:5], v[190:193], v[222:225], v[2:5]
	v_mfma_f32_16x16x32_bf16 v[10:13], v[182:185], v[222:225], v[10:13]
	v_mfma_f32_16x16x32_bf16 v[6:9], v[174:177], v[222:225], v[6:9]
	v_mfma_f32_16x16x32_bf16 v[14:17], v[166:169], v[222:225], v[14:17]
	v_mfma_f32_16x16x32_bf16 v[62:65], v[170:173], v[202:205], v[62:65]
	v_mfma_f32_16x16x32_bf16 v[54:57], v[178:181], v[202:205], v[54:57]
	v_mfma_f32_16x16x32_bf16 v[58:61], v[186:189], v[202:205], v[58:61]
	v_mfma_f32_16x16x32_bf16 v[50:53], v[194:197], v[202:205], v[50:53]
	v_mfma_f32_16x16x32_bf16 v[34:37], v[194:197], v[210:213], v[34:37]
	v_mfma_f32_16x16x32_bf16 v[42:45], v[186:189], v[210:213], v[42:45]
	v_mfma_f32_16x16x32_bf16 v[38:41], v[178:181], v[210:213], v[38:41]
	v_mfma_f32_16x16x32_bf16 v[46:49], v[170:173], v[210:213], v[46:49]
	v_mfma_f32_16x16x32_bf16 v[30:33], v[170:173], v[218:221], v[30:33]
	v_mfma_f32_16x16x32_bf16 v[22:25], v[178:181], v[218:221], v[22:25]
	v_mfma_f32_16x16x32_bf16 v[26:29], v[186:189], v[218:221], v[26:29]
	v_mfma_f32_16x16x32_bf16 v[18:21], v[194:197], v[218:221], v[18:21]
	v_mfma_f32_16x16x32_bf16 v[2:5], v[194:197], v[226:229], v[2:5]
	v_mfma_f32_16x16x32_bf16 v[10:13], v[186:189], v[226:229], v[10:13]
	v_mfma_f32_16x16x32_bf16 v[6:9], v[178:181], v[226:229], v[6:9]
	v_mfma_f32_16x16x32_bf16 v[14:17], v[170:173], v[226:229], v[14:17]
	s_barrier
	s_setprio 0
	s_mov_b32 s8, s9
	s_add_u32 s88, s88, 0x100
	s_addc_u32 s89, s89, 0
	s_add_u32 s86, s86, 0x100
	s_addc_u32 s87, s87, 0
	s_cmp_ge_i32 s9, s101
	s_cbranch_scc1 .Lmy_kexit_1
.LBB0_310:
	s_add_u32 s98, s86, 0x100
	s_addc_u32 s99, s87, 0
	s_cmp_eq_u32 s8, s100
	s_cselect_b64 s[94:95], s[90:91], s[98:99]
	s_cselect_b64 s[96:97], s[92:93], s[88:89]
	s_add_i32 s9, s8, 2
	s_add_i32 m0, s55, 0xc000
	ds_read_b128 v[166:169], v230
	global_load_lds_dwordx4 v144, s[86:87]
	s_add_i32 m0, s55, 0xe000
	ds_read_b128 v[170:173], v230 offset:1024
	global_load_lds_dwordx4 v142, s[86:87]
	ds_read_b128 v[174:177], v230 offset:2048
	ds_read_b128 v[178:181], v230 offset:3072
	ds_read_b128 v[182:185], v231
	ds_read_b128 v[186:189], v231 offset:1024
	ds_read_b128 v[190:193], v231 offset:2048
	ds_read_b128 v[194:197], v231 offset:3072
	ds_read_b128 v[198:201], v163
	ds_read_b128 v[202:205], v163 offset:1024
	ds_read_b128 v[206:209], v163 offset:2048
	ds_read_b128 v[210:213], v163 offset:3072
	ds_read_b128 v[214:217], v163 offset:4096
	ds_read_b128 v[218:221], v163 offset:5120
	ds_read_b128 v[222:225], v163 offset:6144
	ds_read_b128 v[226:229], v163 offset:7168
	s_waitcnt vmcnt(8)
	s_waitcnt lgkmcnt(0)
	s_setprio 1
	s_barrier
	v_mfma_f32_16x16x32_bf16 v[122:125], v[166:169], v[198:201], v[122:125]
	v_mfma_f32_16x16x32_bf16 v[118:121], v[174:177], v[198:201], v[118:121]
	v_mfma_f32_16x16x32_bf16 v[126:129], v[182:185], v[198:201], v[126:129]
	v_mfma_f32_16x16x32_bf16 v[114:117], v[190:193], v[198:201], v[114:117]
	v_mfma_f32_16x16x32_bf16 v[98:101], v[190:193], v[206:209], v[98:101]
	v_mfma_f32_16x16x32_bf16 v[106:109], v[182:185], v[206:209], v[106:109]
	v_mfma_f32_16x16x32_bf16 v[102:105], v[174:177], v[206:209], v[102:105]
	v_mfma_f32_16x16x32_bf16 v[110:113], v[166:169], v[206:209], v[110:113]
	v_mfma_f32_16x16x32_bf16 v[94:97], v[166:169], v[214:217], v[94:97]
	v_mfma_f32_16x16x32_bf16 v[86:89], v[174:177], v[214:217], v[86:89]
	v_mfma_f32_16x16x32_bf16 v[90:93], v[182:185], v[214:217], v[90:93]
	v_mfma_f32_16x16x32_bf16 v[82:85], v[190:193], v[214:217], v[82:85]
	v_mfma_f32_16x16x32_bf16 v[66:69], v[190:193], v[222:225], v[66:69]
	v_mfma_f32_16x16x32_bf16 v[74:77], v[182:185], v[222:225], v[74:77]
	v_mfma_f32_16x16x32_bf16 v[70:73], v[174:177], v[222:225], v[70:73]
	v_mfma_f32_16x16x32_bf16 v[78:81], v[166:169], v[222:225], v[78:81]
	v_mfma_f32_16x16x32_bf16 v[122:125], v[170:173], v[202:205], v[122:125]
	v_mfma_f32_16x16x32_bf16 v[118:121], v[178:181], v[202:205], v[118:121]
	v_mfma_f32_16x16x32_bf16 v[126:129], v[186:189], v[202:205], v[126:129]
	v_mfma_f32_16x16x32_bf16 v[114:117], v[194:197], v[202:205], v[114:117]
	v_mfma_f32_16x16x32_bf16 v[98:101], v[194:197], v[210:213], v[98:101]
	v_mfma_f32_16x16x32_bf16 v[106:109], v[186:189], v[210:213], v[106:109]
	v_mfma_f32_16x16x32_bf16 v[102:105], v[178:181], v[210:213], v[102:105]
	v_mfma_f32_16x16x32_bf16 v[110:113], v[170:173], v[210:213], v[110:113]
	v_mfma_f32_16x16x32_bf16 v[94:97], v[170:173], v[218:221], v[94:97]
	v_mfma_f32_16x16x32_bf16 v[86:89], v[178:181], v[218:221], v[86:89]
	v_mfma_f32_16x16x32_bf16 v[90:93], v[186:189], v[218:221], v[90:93]
	v_mfma_f32_16x16x32_bf16 v[82:85], v[194:197], v[218:221], v[82:85]
	v_mfma_f32_16x16x32_bf16 v[66:69], v[194:197], v[226:229], v[66:69]
	v_mfma_f32_16x16x32_bf16 v[74:77], v[186:189], v[226:229], v[74:77]
	v_mfma_f32_16x16x32_bf16 v[70:73], v[178:181], v[226:229], v[70:73]
	v_mfma_f32_16x16x32_bf16 v[78:81], v[170:173], v[226:229], v[78:81]
	s_barrier
	s_setprio 0
	s_add_u32 s98, s96, 0xb0000
	s_addc_u32 s99, s97, 0
	s_add_i32 s8, s69, s54
	s_mov_b32 m0, s8
	ds_read_b128 v[198:201], v163 offset:16384
	global_load_lds_dwordx4 v132, s[96:97]
	s_add_i32 m0, s8, 0x2000
	s_add_i32 s8, s72, s54
	global_load_lds_dwordx4 v136, s[96:97]
	s_mov_b32 m0, s8
	ds_read_b128 v[202:205], v163 offset:17408
	global_load_lds_dwordx4 v132, s[98:99]
	s_add_i32 m0, s8, 0x2000
	ds_read_b128 v[206:209], v163 offset:18432
	global_load_lds_dwordx4 v136, s[98:99]
	s_mov_b32 m0, s55
	ds_read_b128 v[210:213], v163 offset:19456
	global_load_lds_dwordx4 v130, s[94:95]
	s_mov_b32 m0, s56
	ds_read_b128 v[214:217], v163 offset:20480
	global_load_lds_dwordx4 v134, s[94:95]
	ds_read_b128 v[218:221], v163 offset:21504
	ds_read_b128 v[222:225], v163 offset:22528
	ds_read_b128 v[226:229], v163 offset:23552
	s_waitcnt vmcnt(8)
	s_waitcnt lgkmcnt(0)
	s_setprio 1
	s_barrier
	v_mfma_f32_16x16x32_bf16 v[62:65], v[166:169], v[198:201], v[62:65]
	v_mfma_f32_16x16x32_bf16 v[54:57], v[174:177], v[198:201], v[54:57]
	v_mfma_f32_16x16x32_bf16 v[58:61], v[182:185], v[198:201], v[58:61]
	v_mfma_f32_16x16x32_bf16 v[50:53], v[190:193], v[198:201], v[50:53]
	v_mfma_f32_16x16x32_bf16 v[34:37], v[190:193], v[206:209], v[34:37]
	v_mfma_f32_16x16x32_bf16 v[42:45], v[182:185], v[206:209], v[42:45]
	v_mfma_f32_16x16x32_bf16 v[38:41], v[174:177], v[206:209], v[38:41]
	v_mfma_f32_16x16x32_bf16 v[46:49], v[166:169], v[206:209], v[46:49]
	v_mfma_f32_16x16x32_bf16 v[30:33], v[166:169], v[214:217], v[30:33]
	v_mfma_f32_16x16x32_bf16 v[22:25], v[174:177], v[214:217], v[22:25]
	v_mfma_f32_16x16x32_bf16 v[26:29], v[182:185], v[214:217], v[26:29]
	v_mfma_f32_16x16x32_bf16 v[18:21], v[190:193], v[214:217], v[18:21]
	v_mfma_f32_16x16x32_bf16 v[2:5], v[190:193], v[222:225], v[2:5]
	v_mfma_f32_16x16x32_bf16 v[10:13], v[182:185], v[222:225], v[10:13]
	v_mfma_f32_16x16x32_bf16 v[6:9], v[174:177], v[222:225], v[6:9]
	v_mfma_f32_16x16x32_bf16 v[14:17], v[166:169], v[222:225], v[14:17]
	v_mfma_f32_16x16x32_bf16 v[62:65], v[170:173], v[202:205], v[62:65]
	v_mfma_f32_16x16x32_bf16 v[54:57], v[178:181], v[202:205], v[54:57]
	v_mfma_f32_16x16x32_bf16 v[58:61], v[186:189], v[202:205], v[58:61]
	v_mfma_f32_16x16x32_bf16 v[50:53], v[194:197], v[202:205], v[50:53]
	v_mfma_f32_16x16x32_bf16 v[34:37], v[194:197], v[210:213], v[34:37]
	v_mfma_f32_16x16x32_bf16 v[42:45], v[186:189], v[210:213], v[42:45]
	v_mfma_f32_16x16x32_bf16 v[38:41], v[178:181], v[210:213], v[38:41]
	v_mfma_f32_16x16x32_bf16 v[46:49], v[170:173], v[210:213], v[46:49]
	v_mfma_f32_16x16x32_bf16 v[30:33], v[170:173], v[218:221], v[30:33]
	v_mfma_f32_16x16x32_bf16 v[22:25], v[178:181], v[218:221], v[22:25]
	v_mfma_f32_16x16x32_bf16 v[26:29], v[186:189], v[218:221], v[26:29]
	v_mfma_f32_16x16x32_bf16 v[18:21], v[194:197], v[218:221], v[18:21]
	v_mfma_f32_16x16x32_bf16 v[2:5], v[194:197], v[226:229], v[2:5]
	v_mfma_f32_16x16x32_bf16 v[10:13], v[186:189], v[226:229], v[10:13]
	v_mfma_f32_16x16x32_bf16 v[6:9], v[178:181], v[226:229], v[6:9]
	v_mfma_f32_16x16x32_bf16 v[14:17], v[170:173], v[226:229], v[14:17]
	s_barrier
	s_setprio 0
	s_add_u32 s98, s94, 0xb0000
	s_addc_u32 s99, s95, 0
	s_add_i32 s8, 0, 0x18000
	s_add_i32 s50, 0, 0x1c000
	s_mov_b32 m0, s57
	ds_read_b128 v[166:169], v232
	global_load_lds_dwordx4 v130, s[98:99]
	s_mov_b32 m0, s58
	ds_read_b128 v[170:173], v232 offset:1024
	global_load_lds_dwordx4 v134, s[98:99]
	ds_read_b128 v[174:177], v232 offset:2048
	ds_read_b128 v[178:181], v232 offset:3072
	ds_read_b128 v[182:185], v233
	ds_read_b128 v[186:189], v233 offset:1024
	ds_read_b128 v[190:193], v233 offset:2048
	ds_read_b128 v[194:197], v233 offset:3072
	ds_read_b128 v[198:201], v163 offset:32768
	ds_read_b128 v[202:205], v163 offset:33792
	ds_read_b128 v[206:209], v163 offset:34816
	ds_read_b128 v[210:213], v163 offset:35840
	ds_read_b128 v[214:217], v163 offset:36864
	ds_read_b128 v[218:221], v163 offset:37888
	ds_read_b128 v[222:225], v163 offset:38912
	ds_read_b128 v[226:229], v163 offset:39936
	s_waitcnt vmcnt(8)
	s_waitcnt lgkmcnt(0)
	s_setprio 1
	s_barrier
	v_mfma_f32_16x16x32_bf16 v[122:125], v[166:169], v[198:201], v[122:125]
	v_mfma_f32_16x16x32_bf16 v[118:121], v[174:177], v[198:201], v[118:121]
	v_mfma_f32_16x16x32_bf16 v[126:129], v[182:185], v[198:201], v[126:129]
	v_mfma_f32_16x16x32_bf16 v[114:117], v[190:193], v[198:201], v[114:117]
	v_mfma_f32_16x16x32_bf16 v[98:101], v[190:193], v[206:209], v[98:101]
	v_mfma_f32_16x16x32_bf16 v[106:109], v[182:185], v[206:209], v[106:109]
	v_mfma_f32_16x16x32_bf16 v[102:105], v[174:177], v[206:209], v[102:105]
	v_mfma_f32_16x16x32_bf16 v[110:113], v[166:169], v[206:209], v[110:113]
	v_mfma_f32_16x16x32_bf16 v[94:97], v[166:169], v[214:217], v[94:97]
	v_mfma_f32_16x16x32_bf16 v[86:89], v[174:177], v[214:217], v[86:89]
	v_mfma_f32_16x16x32_bf16 v[90:93], v[182:185], v[214:217], v[90:93]
	v_mfma_f32_16x16x32_bf16 v[82:85], v[190:193], v[214:217], v[82:85]
	v_mfma_f32_16x16x32_bf16 v[66:69], v[190:193], v[222:225], v[66:69]
	v_mfma_f32_16x16x32_bf16 v[74:77], v[182:185], v[222:225], v[74:77]
	v_mfma_f32_16x16x32_bf16 v[70:73], v[174:177], v[222:225], v[70:73]
	v_mfma_f32_16x16x32_bf16 v[78:81], v[166:169], v[222:225], v[78:81]
	v_mfma_f32_16x16x32_bf16 v[122:125], v[170:173], v[202:205], v[122:125]
	v_mfma_f32_16x16x32_bf16 v[118:121], v[178:181], v[202:205], v[118:121]
	v_mfma_f32_16x16x32_bf16 v[126:129], v[186:189], v[202:205], v[126:129]
	v_mfma_f32_16x16x32_bf16 v[114:117], v[194:197], v[202:205], v[114:117]
	v_mfma_f32_16x16x32_bf16 v[98:101], v[194:197], v[210:213], v[98:101]
	v_mfma_f32_16x16x32_bf16 v[106:109], v[186:189], v[210:213], v[106:109]
	v_mfma_f32_16x16x32_bf16 v[102:105], v[178:181], v[210:213], v[102:105]
	v_mfma_f32_16x16x32_bf16 v[110:113], v[170:173], v[210:213], v[110:113]
	v_mfma_f32_16x16x32_bf16 v[94:97], v[170:173], v[218:221], v[94:97]
	v_mfma_f32_16x16x32_bf16 v[86:89], v[178:181], v[218:221], v[86:89]
	v_mfma_f32_16x16x32_bf16 v[90:93], v[186:189], v[218:221], v[90:93]
	v_mfma_f32_16x16x32_bf16 v[82:85], v[194:197], v[218:221], v[82:85]
	v_mfma_f32_16x16x32_bf16 v[66:69], v[194:197], v[226:229], v[66:69]
	v_mfma_f32_16x16x32_bf16 v[74:77], v[186:189], v[226:229], v[74:77]
	v_mfma_f32_16x16x32_bf16 v[70:73], v[178:181], v[226:229], v[70:73]
	v_mfma_f32_16x16x32_bf16 v[78:81], v[170:173], v[226:229], v[78:81]
	s_barrier
	s_setprio 0
	s_add_u32 s96, s96, 0x80
	s_addc_u32 s97, s97, 0
	s_add_u32 s98, s96, 0xb0000
	s_addc_u32 s99, s97, 0
	s_add_u32 s94, s94, 0x80
	s_addc_u32 s95, s95, 0
	s_add_i32 s8, s8, s54
	s_mov_b32 m0, s8
	ds_read_b128 v[198:201], v163 offset:49152
	global_load_lds_dwordx4 v132, s[96:97]
	s_add_i32 m0, s8, 0x2000
	s_add_i32 s8, s50, s54
	global_load_lds_dwordx4 v136, s[96:97]
	s_mov_b32 m0, s8
	ds_read_b128 v[202:205], v163 offset:50176
	global_load_lds_dwordx4 v132, s[98:99]
	s_add_i32 m0, s8, 0x2000
	ds_read_b128 v[206:209], v163 offset:51200
	global_load_lds_dwordx4 v136, s[98:99]
	s_mov_b32 m0, s64
	ds_read_b128 v[210:213], v163 offset:52224
	global_load_lds_dwordx4 v130, s[94:95]
	s_mov_b32 m0, s65
	ds_read_b128 v[214:217], v163 offset:53248
	global_load_lds_dwordx4 v134, s[94:95]
	ds_read_b128 v[218:221], v163 offset:54272
	ds_read_b128 v[222:225], v163 offset:55296
	ds_read_b128 v[226:229], v163 offset:56320
	s_waitcnt vmcnt(8)
	s_waitcnt lgkmcnt(0)
	s_setprio 1
	s_barrier
	v_mfma_f32_16x16x32_bf16 v[62:65], v[166:169], v[198:201], v[62:65]
	v_mfma_f32_16x16x32_bf16 v[54:57], v[174:177], v[198:201], v[54:57]
	v_mfma_f32_16x16x32_bf16 v[58:61], v[182:185], v[198:201], v[58:61]
	v_mfma_f32_16x16x32_bf16 v[50:53], v[190:193], v[198:201], v[50:53]
	v_mfma_f32_16x16x32_bf16 v[34:37], v[190:193], v[206:209], v[34:37]
	v_mfma_f32_16x16x32_bf16 v[42:45], v[182:185], v[206:209], v[42:45]
	v_mfma_f32_16x16x32_bf16 v[38:41], v[174:177], v[206:209], v[38:41]
	v_mfma_f32_16x16x32_bf16 v[46:49], v[166:169], v[206:209], v[46:49]
	v_mfma_f32_16x16x32_bf16 v[30:33], v[166:169], v[214:217], v[30:33]
	v_mfma_f32_16x16x32_bf16 v[22:25], v[174:177], v[214:217], v[22:25]
	v_mfma_f32_16x16x32_bf16 v[26:29], v[182:185], v[214:217], v[26:29]
	v_mfma_f32_16x16x32_bf16 v[18:21], v[190:193], v[214:217], v[18:21]
	v_mfma_f32_16x16x32_bf16 v[2:5], v[190:193], v[222:225], v[2:5]
	v_mfma_f32_16x16x32_bf16 v[10:13], v[182:185], v[222:225], v[10:13]
	v_mfma_f32_16x16x32_bf16 v[6:9], v[174:177], v[222:225], v[6:9]
	v_mfma_f32_16x16x32_bf16 v[14:17], v[166:169], v[222:225], v[14:17]
	v_mfma_f32_16x16x32_bf16 v[62:65], v[170:173], v[202:205], v[62:65]
	v_mfma_f32_16x16x32_bf16 v[54:57], v[178:181], v[202:205], v[54:57]
	v_mfma_f32_16x16x32_bf16 v[58:61], v[186:189], v[202:205], v[58:61]
	v_mfma_f32_16x16x32_bf16 v[50:53], v[194:197], v[202:205], v[50:53]
	v_mfma_f32_16x16x32_bf16 v[34:37], v[194:197], v[210:213], v[34:37]
	v_mfma_f32_16x16x32_bf16 v[42:45], v[186:189], v[210:213], v[42:45]
	v_mfma_f32_16x16x32_bf16 v[38:41], v[178:181], v[210:213], v[38:41]
	v_mfma_f32_16x16x32_bf16 v[46:49], v[170:173], v[210:213], v[46:49]
	v_mfma_f32_16x16x32_bf16 v[30:33], v[170:173], v[218:221], v[30:33]
	v_mfma_f32_16x16x32_bf16 v[22:25], v[178:181], v[218:221], v[22:25]
	v_mfma_f32_16x16x32_bf16 v[26:29], v[186:189], v[218:221], v[26:29]
	v_mfma_f32_16x16x32_bf16 v[18:21], v[194:197], v[218:221], v[18:21]
	v_mfma_f32_16x16x32_bf16 v[2:5], v[194:197], v[226:229], v[2:5]
	v_mfma_f32_16x16x32_bf16 v[10:13], v[186:189], v[226:229], v[10:13]
	v_mfma_f32_16x16x32_bf16 v[6:9], v[178:181], v[226:229], v[6:9]
	v_mfma_f32_16x16x32_bf16 v[14:17], v[170:173], v[226:229], v[14:17]
	s_barrier
	s_setprio 0
	s_mov_b32 s8, s9
	s_add_u32 s88, s88, 0x100
	s_addc_u32 s89, s89, 0
	s_add_u32 s86, s86, 0x100
	s_addc_u32 s87, s87, 0
	s_cmp_ge_i32 s9, s101
	s_cbranch_scc0 .LBB0_310

.Lmy_nb_2:
	s_nop 0
	v_readfirstlane_b32 s86, v154
	v_readfirstlane_b32 s87, v155
	v_readfirstlane_b32 s88, v152
	v_readfirstlane_b32 s89, v153
	v_readfirstlane_b32 s90, v148
	v_readfirstlane_b32 s91, v149
	v_readfirstlane_b32 s92, v150
	v_readfirstlane_b32 s93, v151
	v_readfirstlane_b32 s100, v138
	v_readfirstlane_b32 s101, v141
	v_add_u32_e32 v230, s77, v160
	v_add_u32_e32 v231, s78, v160
	v_add_u32_e32 v232, 0x18000, v160
	v_add_u32_e32 v233, 0x1c000, v160
	s_add_u32 s98, s86, 0xfffc0080
	s_addc_u32 s99, s87, -1
	s_cmp_eq_u32 s7, s100
	s_cselect_b64 s[94:95], s[90:91], s[98:99]
	s_cselect_b64 s[96:97], s[92:93], s[88:89]
	s_add_i32 s45, s7, 2
	s_add_i32 m0, s49, 0xc000
	ds_read_b128 v[156:159], v230
	global_load_lds_dwordx4 v144, s[86:87]
	s_add_i32 m0, s49, 0xe000
	ds_read_b128 v[166:169], v230 offset:1024
	global_load_lds_dwordx4 v142, s[86:87]
	ds_read_b128 v[170:173], v230 offset:2048
	ds_read_b128 v[174:177], v230 offset:3072
	ds_read_b128 v[178:181], v231
	ds_read_b128 v[182:185], v231 offset:1024
	ds_read_b128 v[186:189], v231 offset:2048
	ds_read_b128 v[190:193], v231 offset:3072
	ds_read_b128 v[194:197], v163
	ds_read_b128 v[198:201], v163 offset:1024
	ds_read_b128 v[202:205], v163 offset:2048
	ds_read_b128 v[206:209], v163 offset:3072
	ds_read_b128 v[210:213], v163 offset:4096
	ds_read_b128 v[214:217], v163 offset:5120
	ds_read_b128 v[218:221], v163 offset:6144
	ds_read_b128 v[222:225], v163 offset:7168
	s_waitcnt vmcnt(8)
	s_waitcnt lgkmcnt(0)
	s_setprio 1
	s_barrier
	v_mfma_f32_16x16x32_bf16 v[122:125], v[156:159], v[194:197], 0
	v_mfma_f32_16x16x32_bf16 v[118:121], v[170:173], v[194:197], 0
	v_mfma_f32_16x16x32_bf16 v[126:129], v[178:181], v[194:197], 0
	v_mfma_f32_16x16x32_bf16 v[114:117], v[186:189], v[194:197], 0
	v_mfma_f32_16x16x32_bf16 v[98:101], v[186:189], v[202:205], 0
	v_mfma_f32_16x16x32_bf16 v[106:109], v[178:181], v[202:205], 0
	v_mfma_f32_16x16x32_bf16 v[102:105], v[170:173], v[202:205], 0
	v_mfma_f32_16x16x32_bf16 v[110:113], v[156:159], v[202:205], 0
	v_mfma_f32_16x16x32_bf16 v[94:97], v[156:159], v[210:213], 0
	v_mfma_f32_16x16x32_bf16 v[86:89], v[170:173], v[210:213], 0
	v_mfma_f32_16x16x32_bf16 v[90:93], v[178:181], v[210:213], 0
	v_mfma_f32_16x16x32_bf16 v[82:85], v[186:189], v[210:213], 0
	v_mfma_f32_16x16x32_bf16 v[66:69], v[186:189], v[218:221], 0
	v_mfma_f32_16x16x32_bf16 v[74:77], v[178:181], v[218:221], 0
	v_mfma_f32_16x16x32_bf16 v[70:73], v[170:173], v[218:221], 0
	v_mfma_f32_16x16x32_bf16 v[78:81], v[156:159], v[218:221], 0
	v_mfma_f32_16x16x32_bf16 v[122:125], v[166:169], v[198:201], v[122:125]
	v_mfma_f32_16x16x32_bf16 v[118:121], v[174:177], v[198:201], v[118:121]
	v_mfma_f32_16x16x32_bf16 v[126:129], v[182:185], v[198:201], v[126:129]
	v_mfma_f32_16x16x32_bf16 v[114:117], v[190:193], v[198:201], v[114:117]
	v_mfma_f32_16x16x32_bf16 v[98:101], v[190:193], v[206:209], v[98:101]
	v_mfma_f32_16x16x32_bf16 v[106:109], v[182:185], v[206:209], v[106:109]
	v_mfma_f32_16x16x32_bf16 v[102:105], v[174:177], v[206:209], v[102:105]
	v_mfma_f32_16x16x32_bf16 v[110:113], v[166:169], v[206:209], v[110:113]
	v_mfma_f32_16x16x32_bf16 v[94:97], v[166:169], v[214:217], v[94:97]
	v_mfma_f32_16x16x32_bf16 v[86:89], v[174:177], v[214:217], v[86:89]
	v_mfma_f32_16x16x32_bf16 v[90:93], v[182:185], v[214:217], v[90:93]
	v_mfma_f32_16x16x32_bf16 v[82:85], v[190:193], v[214:217], v[82:85]
	v_mfma_f32_16x16x32_bf16 v[66:69], v[190:193], v[222:225], v[66:69]
	v_mfma_f32_16x16x32_bf16 v[74:77], v[182:185], v[222:225], v[74:77]
	v_mfma_f32_16x16x32_bf16 v[70:73], v[174:177], v[222:225], v[70:73]
	v_mfma_f32_16x16x32_bf16 v[78:81], v[166:169], v[222:225], v[78:81]
	s_barrier
	s_setprio 0
	s_add_u32 s98, s96, 0x40000
	s_addc_u32 s99, s97, 0
	s_add_i32 s7, s77, s25
	s_mov_b32 m0, s7
	ds_read_b128 v[194:197], v163 offset:16384
	global_load_lds_dwordx4 v132, s[96:97]
	s_add_i32 m0, s7, 0x2000
	s_add_i32 s7, s78, s25
	global_load_lds_dwordx4 v136, s[96:97]
	s_mov_b32 m0, s7
	ds_read_b128 v[198:201], v163 offset:17408
	global_load_lds_dwordx4 v132, s[98:99]
	s_add_i32 m0, s7, 0x2000
	ds_read_b128 v[202:205], v163 offset:18432
	global_load_lds_dwordx4 v136, s[98:99]
	s_mov_b32 m0, s49
	ds_read_b128 v[206:209], v163 offset:19456
	global_load_lds_dwordx4 v130, s[94:95]
	s_mov_b32 m0, s58
	ds_read_b128 v[210:213], v163 offset:20480
	global_load_lds_dwordx4 v134, s[94:95]
	ds_read_b128 v[214:217], v163 offset:21504
	ds_read_b128 v[218:221], v163 offset:22528
	ds_read_b128 v[222:225], v163 offset:23552
	s_waitcnt vmcnt(8)
	s_waitcnt lgkmcnt(0)
	s_setprio 1
	s_barrier
	v_mfma_f32_16x16x32_bf16 v[62:65], v[156:159], v[194:197], 0
	v_mfma_f32_16x16x32_bf16 v[54:57], v[170:173], v[194:197], 0
	v_mfma_f32_16x16x32_bf16 v[58:61], v[178:181], v[194:197], 0
	v_mfma_f32_16x16x32_bf16 v[50:53], v[186:189], v[194:197], 0
	v_mfma_f32_16x16x32_bf16 v[34:37], v[186:189], v[202:205], 0
	v_mfma_f32_16x16x32_bf16 v[42:45], v[178:181], v[202:205], 0
	v_mfma_f32_16x16x32_bf16 v[38:41], v[170:173], v[202:205], 0
	v_mfma_f32_16x16x32_bf16 v[46:49], v[156:159], v[202:205], 0
	v_mfma_f32_16x16x32_bf16 v[30:33], v[156:159], v[210:213], 0
	v_mfma_f32_16x16x32_bf16 v[22:25], v[170:173], v[210:213], 0
	v_mfma_f32_16x16x32_bf16 v[26:29], v[178:181], v[210:213], 0
	v_mfma_f32_16x16x32_bf16 v[18:21], v[186:189], v[210:213], 0
	v_mfma_f32_16x16x32_bf16 v[2:5], v[186:189], v[218:221], 0
	v_mfma_f32_16x16x32_bf16 v[10:13], v[178:181], v[218:221], 0
	v_mfma_f32_16x16x32_bf16 v[6:9], v[170:173], v[218:221], 0
	v_mfma_f32_16x16x32_bf16 v[14:17], v[156:159], v[218:221], 0
	v_mfma_f32_16x16x32_bf16 v[62:65], v[166:169], v[198:201], v[62:65]
	v_mfma_f32_16x16x32_bf16 v[54:57], v[174:177], v[198:201], v[54:57]
	v_mfma_f32_16x16x32_bf16 v[58:61], v[182:185], v[198:201], v[58:61]
	v_mfma_f32_16x16x32_bf16 v[50:53], v[190:193], v[198:201], v[50:53]
	v_mfma_f32_16x16x32_bf16 v[34:37], v[190:193], v[206:209], v[34:37]
	v_mfma_f32_16x16x32_bf16 v[42:45], v[182:185], v[206:209], v[42:45]
	v_mfma_f32_16x16x32_bf16 v[38:41], v[174:177], v[206:209], v[38:41]
	v_mfma_f32_16x16x32_bf16 v[46:49], v[166:169], v[206:209], v[46:49]
	v_mfma_f32_16x16x32_bf16 v[30:33], v[166:169], v[214:217], v[30:33]
	v_mfma_f32_16x16x32_bf16 v[22:25], v[174:177], v[214:217], v[22:25]
	v_mfma_f32_16x16x32_bf16 v[26:29], v[182:185], v[214:217], v[26:29]
	v_mfma_f32_16x16x32_bf16 v[18:21], v[190:193], v[214:217], v[18:21]
	v_mfma_f32_16x16x32_bf16 v[2:5], v[190:193], v[222:225], v[2:5]
	v_mfma_f32_16x16x32_bf16 v[10:13], v[182:185], v[222:225], v[10:13]
	v_mfma_f32_16x16x32_bf16 v[6:9], v[174:177], v[222:225], v[6:9]
	v_mfma_f32_16x16x32_bf16 v[14:17], v[166:169], v[222:225], v[14:17]
	s_barrier
	s_setprio 0
	s_add_u32 s98, s94, 0x40000
	s_addc_u32 s99, s95, 0
	s_add_i32 s7, 0, 0x18000
	s_add_i32 s47, 0, 0x1c000
	s_mov_b32 m0, s59
	ds_read_b128 v[156:159], v232
	global_load_lds_dwordx4 v130, s[98:99]
	s_mov_b32 m0, s60
	ds_read_b128 v[166:169], v232 offset:1024
	global_load_lds_dwordx4 v134, s[98:99]
	ds_read_b128 v[170:173], v232 offset:2048
	ds_read_b128 v[174:177], v232 offset:3072
	ds_read_b128 v[178:181], v233
	ds_read_b128 v[182:185], v233 offset:1024
	ds_read_b128 v[186:189], v233 offset:2048
	ds_read_b128 v[190:193], v233 offset:3072
	ds_read_b128 v[194:197], v163 offset:32768
	ds_read_b128 v[198:201], v163 offset:33792
	ds_read_b128 v[202:205], v163 offset:34816
	ds_read_b128 v[206:209], v163 offset:35840
	ds_read_b128 v[210:213], v163 offset:36864
	ds_read_b128 v[214:217], v163 offset:37888
	ds_read_b128 v[218:221], v163 offset:38912
	ds_read_b128 v[222:225], v163 offset:39936
	s_waitcnt vmcnt(8)
	s_waitcnt lgkmcnt(0)
	s_setprio 1
	s_barrier
	v_mfma_f32_16x16x32_bf16 v[122:125], v[156:159], v[194:197], v[122:125]
	v_mfma_f32_16x16x32_bf16 v[118:121], v[170:173], v[194:197], v[118:121]
	v_mfma_f32_16x16x32_bf16 v[126:129], v[178:181], v[194:197], v[126:129]
	v_mfma_f32_16x16x32_bf16 v[114:117], v[186:189], v[194:197], v[114:117]
	v_mfma_f32_16x16x32_bf16 v[98:101], v[186:189], v[202:205], v[98:101]
	v_mfma_f32_16x16x32_bf16 v[106:109], v[178:181], v[202:205], v[106:109]
	v_mfma_f32_16x16x32_bf16 v[102:105], v[170:173], v[202:205], v[102:105]
	v_mfma_f32_16x16x32_bf16 v[110:113], v[156:159], v[202:205], v[110:113]
	v_mfma_f32_16x16x32_bf16 v[94:97], v[156:159], v[210:213], v[94:97]
	v_mfma_f32_16x16x32_bf16 v[86:89], v[170:173], v[210:213], v[86:89]
	v_mfma_f32_16x16x32_bf16 v[90:93], v[178:181], v[210:213], v[90:93]
	v_mfma_f32_16x16x32_bf16 v[82:85], v[186:189], v[210:213], v[82:85]
	v_mfma_f32_16x16x32_bf16 v[66:69], v[186:189], v[218:221], v[66:69]
	v_mfma_f32_16x16x32_bf16 v[74:77], v[178:181], v[218:221], v[74:77]
	v_mfma_f32_16x16x32_bf16 v[70:73], v[170:173], v[218:221], v[70:73]
	v_mfma_f32_16x16x32_bf16 v[78:81], v[156:159], v[218:221], v[78:81]
	v_mfma_f32_16x16x32_bf16 v[122:125], v[166:169], v[198:201], v[122:125]
	v_mfma_f32_16x16x32_bf16 v[118:121], v[174:177], v[198:201], v[118:121]
	v_mfma_f32_16x16x32_bf16 v[126:129], v[182:185], v[198:201], v[126:129]
	v_mfma_f32_16x16x32_bf16 v[114:117], v[190:193], v[198:201], v[114:117]
	v_mfma_f32_16x16x32_bf16 v[98:101], v[190:193], v[206:209], v[98:101]
	v_mfma_f32_16x16x32_bf16 v[106:109], v[182:185], v[206:209], v[106:109]
	v_mfma_f32_16x16x32_bf16 v[102:105], v[174:177], v[206:209], v[102:105]
	v_mfma_f32_16x16x32_bf16 v[110:113], v[166:169], v[206:209], v[110:113]
	v_mfma_f32_16x16x32_bf16 v[94:97], v[166:169], v[214:217], v[94:97]
	v_mfma_f32_16x16x32_bf16 v[86:89], v[174:177], v[214:217], v[86:89]
	v_mfma_f32_16x16x32_bf16 v[90:93], v[182:185], v[214:217], v[90:93]
	v_mfma_f32_16x16x32_bf16 v[82:85], v[190:193], v[214:217], v[82:85]
	v_mfma_f32_16x16x32_bf16 v[66:69], v[190:193], v[222:225], v[66:69]
	v_mfma_f32_16x16x32_bf16 v[74:77], v[182:185], v[222:225], v[74:77]
	v_mfma_f32_16x16x32_bf16 v[70:73], v[174:177], v[222:225], v[70:73]
	v_mfma_f32_16x16x32_bf16 v[78:81], v[166:169], v[222:225], v[78:81]
	s_barrier
	s_setprio 0
	s_add_u32 s96, s96, 0x80
	s_addc_u32 s97, s97, 0
	s_add_u32 s98, s96, 0x40000
	s_addc_u32 s99, s97, 0
	s_add_u32 s94, s94, 0x80
	s_addc_u32 s95, s95, 0
	s_add_i32 s7, s7, s25
	s_mov_b32 m0, s7
	ds_read_b128 v[194:197], v163 offset:49152
	global_load_lds_dwordx4 v132, s[96:97]
	s_add_i32 m0, s7, 0x2000
	s_add_i32 s7, s47, s25
	global_load_lds_dwordx4 v136, s[96:97]
	s_mov_b32 m0, s7
	ds_read_b128 v[198:201], v163 offset:50176
	global_load_lds_dwordx4 v132, s[98:99]
	s_add_i32 m0, s7, 0x2000
	ds_read_b128 v[202:205], v163 offset:51200
	global_load_lds_dwordx4 v136, s[98:99]
	s_mov_b32 m0, s66
	ds_read_b128 v[206:209], v163 offset:52224
	global_load_lds_dwordx4 v130, s[94:95]
	s_mov_b32 m0, s67
	ds_read_b128 v[210:213], v163 offset:53248
	global_load_lds_dwordx4 v134, s[94:95]
	ds_read_b128 v[214:217], v163 offset:54272
	ds_read_b128 v[218:221], v163 offset:55296
	ds_read_b128 v[222:225], v163 offset:56320
	s_waitcnt vmcnt(8)
	s_waitcnt lgkmcnt(0)
	s_setprio 1
	s_barrier
	v_mfma_f32_16x16x32_bf16 v[62:65], v[156:159], v[194:197], v[62:65]
	v_mfma_f32_16x16x32_bf16 v[54:57], v[170:173], v[194:197], v[54:57]
	v_mfma_f32_16x16x32_bf16 v[58:61], v[178:181], v[194:197], v[58:61]
	v_mfma_f32_16x16x32_bf16 v[50:53], v[186:189], v[194:197], v[50:53]
	v_mfma_f32_16x16x32_bf16 v[34:37], v[186:189], v[202:205], v[34:37]
	v_mfma_f32_16x16x32_bf16 v[42:45], v[178:181], v[202:205], v[42:45]
	v_mfma_f32_16x16x32_bf16 v[38:41], v[170:173], v[202:205], v[38:41]
	v_mfma_f32_16x16x32_bf16 v[46:49], v[156:159], v[202:205], v[46:49]
	v_mfma_f32_16x16x32_bf16 v[30:33], v[156:159], v[210:213], v[30:33]
	v_mfma_f32_16x16x32_bf16 v[22:25], v[170:173], v[210:213], v[22:25]
	v_mfma_f32_16x16x32_bf16 v[26:29], v[178:181], v[210:213], v[26:29]
	v_mfma_f32_16x16x32_bf16 v[18:21], v[186:189], v[210:213], v[18:21]
	v_mfma_f32_16x16x32_bf16 v[2:5], v[186:189], v[218:221], v[2:5]
	v_mfma_f32_16x16x32_bf16 v[10:13], v[178:181], v[218:221], v[10:13]
	v_mfma_f32_16x16x32_bf16 v[6:9], v[170:173], v[218:221], v[6:9]
	v_mfma_f32_16x16x32_bf16 v[14:17], v[156:159], v[218:221], v[14:17]
	v_mfma_f32_16x16x32_bf16 v[62:65], v[166:169], v[198:201], v[62:65]
	v_mfma_f32_16x16x32_bf16 v[54:57], v[174:177], v[198:201], v[54:57]
	v_mfma_f32_16x16x32_bf16 v[58:61], v[182:185], v[198:201], v[58:61]
	v_mfma_f32_16x16x32_bf16 v[50:53], v[190:193], v[198:201], v[50:53]
	v_mfma_f32_16x16x32_bf16 v[34:37], v[190:193], v[206:209], v[34:37]
	v_mfma_f32_16x16x32_bf16 v[42:45], v[182:185], v[206:209], v[42:45]
	v_mfma_f32_16x16x32_bf16 v[38:41], v[174:177], v[206:209], v[38:41]
	v_mfma_f32_16x16x32_bf16 v[46:49], v[166:169], v[206:209], v[46:49]
	v_mfma_f32_16x16x32_bf16 v[30:33], v[166:169], v[214:217], v[30:33]
	v_mfma_f32_16x16x32_bf16 v[22:25], v[174:177], v[214:217], v[22:25]
	v_mfma_f32_16x16x32_bf16 v[26:29], v[182:185], v[214:217], v[26:29]
	v_mfma_f32_16x16x32_bf16 v[18:21], v[190:193], v[214:217], v[18:21]
	v_mfma_f32_16x16x32_bf16 v[2:5], v[190:193], v[222:225], v[2:5]
	v_mfma_f32_16x16x32_bf16 v[10:13], v[182:185], v[222:225], v[10:13]
	v_mfma_f32_16x16x32_bf16 v[6:9], v[174:177], v[222:225], v[6:9]
	v_mfma_f32_16x16x32_bf16 v[14:17], v[166:169], v[222:225], v[14:17]
	s_barrier
	s_setprio 0
	s_mov_b32 s7, s45
	s_add_u32 s88, s88, 0x100
	s_addc_u32 s89, s89, 0
	s_add_u32 s86, s86, 0x100
	s_addc_u32 s87, s87, 0
	s_cmp_ge_i32 s45, s101
	s_cbranch_scc1 .Lmy_kexit_2
.LBB0_499:
	s_add_u32 s98, s86, 0xfffc0080
	s_addc_u32 s99, s87, -1
	s_cmp_eq_u32 s7, s100
	s_cselect_b64 s[94:95], s[90:91], s[98:99]
	s_cselect_b64 s[96:97], s[92:93], s[88:89]
	s_add_i32 s45, s7, 2
	s_add_i32 m0, s49, 0xc000
	ds_read_b128 v[156:159], v230
	global_load_lds_dwordx4 v144, s[86:87]
	s_add_i32 m0, s49, 0xe000
	ds_read_b128 v[166:169], v230 offset:1024
	global_load_lds_dwordx4 v142, s[86:87]
	ds_read_b128 v[170:173], v230 offset:2048
	ds_read_b128 v[174:177], v230 offset:3072
	ds_read_b128 v[178:181], v231
	ds_read_b128 v[182:185], v231 offset:1024
	ds_read_b128 v[186:189], v231 offset:2048
	ds_read_b128 v[190:193], v231 offset:3072
	ds_read_b128 v[194:197], v163
	ds_read_b128 v[198:201], v163 offset:1024
	ds_read_b128 v[202:205], v163 offset:2048
	ds_read_b128 v[206:209], v163 offset:3072
	ds_read_b128 v[210:213], v163 offset:4096
	ds_read_b128 v[214:217], v163 offset:5120
	ds_read_b128 v[218:221], v163 offset:6144
	ds_read_b128 v[222:225], v163 offset:7168
	s_waitcnt vmcnt(8)
	s_waitcnt lgkmcnt(0)
	s_setprio 1
	s_barrier
	v_mfma_f32_16x16x32_bf16 v[122:125], v[156:159], v[194:197], v[122:125]
	v_mfma_f32_16x16x32_bf16 v[118:121], v[170:173], v[194:197], v[118:121]
	v_mfma_f32_16x16x32_bf16 v[126:129], v[178:181], v[194:197], v[126:129]
	v_mfma_f32_16x16x32_bf16 v[114:117], v[186:189], v[194:197], v[114:117]
	v_mfma_f32_16x16x32_bf16 v[98:101], v[186:189], v[202:205], v[98:101]
	v_mfma_f32_16x16x32_bf16 v[106:109], v[178:181], v[202:205], v[106:109]
	v_mfma_f32_16x16x32_bf16 v[102:105], v[170:173], v[202:205], v[102:105]
	v_mfma_f32_16x16x32_bf16 v[110:113], v[156:159], v[202:205], v[110:113]
	v_mfma_f32_16x16x32_bf16 v[94:97], v[156:159], v[210:213], v[94:97]
	v_mfma_f32_16x16x32_bf16 v[86:89], v[170:173], v[210:213], v[86:89]
	v_mfma_f32_16x16x32_bf16 v[90:93], v[178:181], v[210:213], v[90:93]
	v_mfma_f32_16x16x32_bf16 v[82:85], v[186:189], v[210:213], v[82:85]
	v_mfma_f32_16x16x32_bf16 v[66:69], v[186:189], v[218:221], v[66:69]
	v_mfma_f32_16x16x32_bf16 v[74:77], v[178:181], v[218:221], v[74:77]
	v_mfma_f32_16x16x32_bf16 v[70:73], v[170:173], v[218:221], v[70:73]
	v_mfma_f32_16x16x32_bf16 v[78:81], v[156:159], v[218:221], v[78:81]
	v_mfma_f32_16x16x32_bf16 v[122:125], v[166:169], v[198:201], v[122:125]
	v_mfma_f32_16x16x32_bf16 v[118:121], v[174:177], v[198:201], v[118:121]
	v_mfma_f32_16x16x32_bf16 v[126:129], v[182:185], v[198:201], v[126:129]
	v_mfma_f32_16x16x32_bf16 v[114:117], v[190:193], v[198:201], v[114:117]
	v_mfma_f32_16x16x32_bf16 v[98:101], v[190:193], v[206:209], v[98:101]
	v_mfma_f32_16x16x32_bf16 v[106:109], v[182:185], v[206:209], v[106:109]
	v_mfma_f32_16x16x32_bf16 v[102:105], v[174:177], v[206:209], v[102:105]
	v_mfma_f32_16x16x32_bf16 v[110:113], v[166:169], v[206:209], v[110:113]
	v_mfma_f32_16x16x32_bf16 v[94:97], v[166:169], v[214:217], v[94:97]
	v_mfma_f32_16x16x32_bf16 v[86:89], v[174:177], v[214:217], v[86:89]
	v_mfma_f32_16x16x32_bf16 v[90:93], v[182:185], v[214:217], v[90:93]
	v_mfma_f32_16x16x32_bf16 v[82:85], v[190:193], v[214:217], v[82:85]
	v_mfma_f32_16x16x32_bf16 v[66:69], v[190:193], v[222:225], v[66:69]
	v_mfma_f32_16x16x32_bf16 v[74:77], v[182:185], v[222:225], v[74:77]
	v_mfma_f32_16x16x32_bf16 v[70:73], v[174:177], v[222:225], v[70:73]
	v_mfma_f32_16x16x32_bf16 v[78:81], v[166:169], v[222:225], v[78:81]
	s_barrier
	s_setprio 0
	s_add_u32 s98, s96, 0x40000
	s_addc_u32 s99, s97, 0
	s_add_i32 s7, s77, s25
	s_mov_b32 m0, s7
	ds_read_b128 v[194:197], v163 offset:16384
	global_load_lds_dwordx4 v132, s[96:97]
	s_add_i32 m0, s7, 0x2000
	s_add_i32 s7, s78, s25
	global_load_lds_dwordx4 v136, s[96:97]
	s_mov_b32 m0, s7
	ds_read_b128 v[198:201], v163 offset:17408
	global_load_lds_dwordx4 v132, s[98:99]
	s_add_i32 m0, s7, 0x2000
	ds_read_b128 v[202:205], v163 offset:18432
	global_load_lds_dwordx4 v136, s[98:99]
	s_mov_b32 m0, s49
	ds_read_b128 v[206:209], v163 offset:19456
	global_load_lds_dwordx4 v130, s[94:95]
	s_mov_b32 m0, s58
	ds_read_b128 v[210:213], v163 offset:20480
	global_load_lds_dwordx4 v134, s[94:95]
	ds_read_b128 v[214:217], v163 offset:21504
	ds_read_b128 v[218:221], v163 offset:22528
	ds_read_b128 v[222:225], v163 offset:23552
	s_waitcnt vmcnt(8)
	s_waitcnt lgkmcnt(0)
	s_setprio 1
	s_barrier
	v_mfma_f32_16x16x32_bf16 v[62:65], v[156:159], v[194:197], v[62:65]
	v_mfma_f32_16x16x32_bf16 v[54:57], v[170:173], v[194:197], v[54:57]
	v_mfma_f32_16x16x32_bf16 v[58:61], v[178:181], v[194:197], v[58:61]
	v_mfma_f32_16x16x32_bf16 v[50:53], v[186:189], v[194:197], v[50:53]
	v_mfma_f32_16x16x32_bf16 v[34:37], v[186:189], v[202:205], v[34:37]
	v_mfma_f32_16x16x32_bf16 v[42:45], v[178:181], v[202:205], v[42:45]
	v_mfma_f32_16x16x32_bf16 v[38:41], v[170:173], v[202:205], v[38:41]
	v_mfma_f32_16x16x32_bf16 v[46:49], v[156:159], v[202:205], v[46:49]
	v_mfma_f32_16x16x32_bf16 v[30:33], v[156:159], v[210:213], v[30:33]
	v_mfma_f32_16x16x32_bf16 v[22:25], v[170:173], v[210:213], v[22:25]
	v_mfma_f32_16x16x32_bf16 v[26:29], v[178:181], v[210:213], v[26:29]
	v_mfma_f32_16x16x32_bf16 v[18:21], v[186:189], v[210:213], v[18:21]
	v_mfma_f32_16x16x32_bf16 v[2:5], v[186:189], v[218:221], v[2:5]
	v_mfma_f32_16x16x32_bf16 v[10:13], v[178:181], v[218:221], v[10:13]
	v_mfma_f32_16x16x32_bf16 v[6:9], v[170:173], v[218:221], v[6:9]
	v_mfma_f32_16x16x32_bf16 v[14:17], v[156:159], v[218:221], v[14:17]
	v_mfma_f32_16x16x32_bf16 v[62:65], v[166:169], v[198:201], v[62:65]
	v_mfma_f32_16x16x32_bf16 v[54:57], v[174:177], v[198:201], v[54:57]
	v_mfma_f32_16x16x32_bf16 v[58:61], v[182:185], v[198:201], v[58:61]
	v_mfma_f32_16x16x32_bf16 v[50:53], v[190:193], v[198:201], v[50:53]
	v_mfma_f32_16x16x32_bf16 v[34:37], v[190:193], v[206:209], v[34:37]
	v_mfma_f32_16x16x32_bf16 v[42:45], v[182:185], v[206:209], v[42:45]
	v_mfma_f32_16x16x32_bf16 v[38:41], v[174:177], v[206:209], v[38:41]
	v_mfma_f32_16x16x32_bf16 v[46:49], v[166:169], v[206:209], v[46:49]
	v_mfma_f32_16x16x32_bf16 v[30:33], v[166:169], v[214:217], v[30:33]
	v_mfma_f32_16x16x32_bf16 v[22:25], v[174:177], v[214:217], v[22:25]
	v_mfma_f32_16x16x32_bf16 v[26:29], v[182:185], v[214:217], v[26:29]
	v_mfma_f32_16x16x32_bf16 v[18:21], v[190:193], v[214:217], v[18:21]
	v_mfma_f32_16x16x32_bf16 v[2:5], v[190:193], v[222:225], v[2:5]
	v_mfma_f32_16x16x32_bf16 v[10:13], v[182:185], v[222:225], v[10:13]
	v_mfma_f32_16x16x32_bf16 v[6:9], v[174:177], v[222:225], v[6:9]
	v_mfma_f32_16x16x32_bf16 v[14:17], v[166:169], v[222:225], v[14:17]
	s_barrier
	s_setprio 0
	s_add_u32 s98, s94, 0x40000
	s_addc_u32 s99, s95, 0
	s_add_i32 s7, 0, 0x18000
	s_add_i32 s47, 0, 0x1c000
	s_mov_b32 m0, s59
	ds_read_b128 v[156:159], v232
	global_load_lds_dwordx4 v130, s[98:99]
	s_mov_b32 m0, s60
	ds_read_b128 v[166:169], v232 offset:1024
	global_load_lds_dwordx4 v134, s[98:99]
	ds_read_b128 v[170:173], v232 offset:2048
	ds_read_b128 v[174:177], v232 offset:3072
	ds_read_b128 v[178:181], v233
	ds_read_b128 v[182:185], v233 offset:1024
	ds_read_b128 v[186:189], v233 offset:2048
	ds_read_b128 v[190:193], v233 offset:3072
	ds_read_b128 v[194:197], v163 offset:32768
	ds_read_b128 v[198:201], v163 offset:33792
	ds_read_b128 v[202:205], v163 offset:34816
	ds_read_b128 v[206:209], v163 offset:35840
	ds_read_b128 v[210:213], v163 offset:36864
	ds_read_b128 v[214:217], v163 offset:37888
	ds_read_b128 v[218:221], v163 offset:38912
	ds_read_b128 v[222:225], v163 offset:39936
	s_waitcnt vmcnt(8)
	s_waitcnt lgkmcnt(0)
	s_setprio 1
	s_barrier
	v_mfma_f32_16x16x32_bf16 v[122:125], v[156:159], v[194:197], v[122:125]
	v_mfma_f32_16x16x32_bf16 v[118:121], v[170:173], v[194:197], v[118:121]
	v_mfma_f32_16x16x32_bf16 v[126:129], v[178:181], v[194:197], v[126:129]
	v_mfma_f32_16x16x32_bf16 v[114:117], v[186:189], v[194:197], v[114:117]
	v_mfma_f32_16x16x32_bf16 v[98:101], v[186:189], v[202:205], v[98:101]
	v_mfma_f32_16x16x32_bf16 v[106:109], v[178:181], v[202:205], v[106:109]
	v_mfma_f32_16x16x32_bf16 v[102:105], v[170:173], v[202:205], v[102:105]
	v_mfma_f32_16x16x32_bf16 v[110:113], v[156:159], v[202:205], v[110:113]
	v_mfma_f32_16x16x32_bf16 v[94:97], v[156:159], v[210:213], v[94:97]
	v_mfma_f32_16x16x32_bf16 v[86:89], v[170:173], v[210:213], v[86:89]
	v_mfma_f32_16x16x32_bf16 v[90:93], v[178:181], v[210:213], v[90:93]
	v_mfma_f32_16x16x32_bf16 v[82:85], v[186:189], v[210:213], v[82:85]
	v_mfma_f32_16x16x32_bf16 v[66:69], v[186:189], v[218:221], v[66:69]
	v_mfma_f32_16x16x32_bf16 v[74:77], v[178:181], v[218:221], v[74:77]
	v_mfma_f32_16x16x32_bf16 v[70:73], v[170:173], v[218:221], v[70:73]
	v_mfma_f32_16x16x32_bf16 v[78:81], v[156:159], v[218:221], v[78:81]
	v_mfma_f32_16x16x32_bf16 v[122:125], v[166:169], v[198:201], v[122:125]
	v_mfma_f32_16x16x32_bf16 v[118:121], v[174:177], v[198:201], v[118:121]
	v_mfma_f32_16x16x32_bf16 v[126:129], v[182:185], v[198:201], v[126:129]
	v_mfma_f32_16x16x32_bf16 v[114:117], v[190:193], v[198:201], v[114:117]
	v_mfma_f32_16x16x32_bf16 v[98:101], v[190:193], v[206:209], v[98:101]
	v_mfma_f32_16x16x32_bf16 v[106:109], v[182:185], v[206:209], v[106:109]
	v_mfma_f32_16x16x32_bf16 v[102:105], v[174:177], v[206:209], v[102:105]
	v_mfma_f32_16x16x32_bf16 v[110:113], v[166:169], v[206:209], v[110:113]
	v_mfma_f32_16x16x32_bf16 v[94:97], v[166:169], v[214:217], v[94:97]
	v_mfma_f32_16x16x32_bf16 v[86:89], v[174:177], v[214:217], v[86:89]
	v_mfma_f32_16x16x32_bf16 v[90:93], v[182:185], v[214:217], v[90:93]
	v_mfma_f32_16x16x32_bf16 v[82:85], v[190:193], v[214:217], v[82:85]
	v_mfma_f32_16x16x32_bf16 v[66:69], v[190:193], v[222:225], v[66:69]
	v_mfma_f32_16x16x32_bf16 v[74:77], v[182:185], v[222:225], v[74:77]
	v_mfma_f32_16x16x32_bf16 v[70:73], v[174:177], v[222:225], v[70:73]
	v_mfma_f32_16x16x32_bf16 v[78:81], v[166:169], v[222:225], v[78:81]
	s_barrier
	s_setprio 0
	s_add_u32 s96, s96, 0x80
	s_addc_u32 s97, s97, 0
	s_add_u32 s98, s96, 0x40000
	s_addc_u32 s99, s97, 0
	s_add_u32 s94, s94, 0x80
	s_addc_u32 s95, s95, 0
	s_add_i32 s7, s7, s25
	s_mov_b32 m0, s7
	ds_read_b128 v[194:197], v163 offset:49152
	global_load_lds_dwordx4 v132, s[96:97]
	s_add_i32 m0, s7, 0x2000
	s_add_i32 s7, s47, s25
	global_load_lds_dwordx4 v136, s[96:97]
	s_mov_b32 m0, s7
	ds_read_b128 v[198:201], v163 offset:50176
	global_load_lds_dwordx4 v132, s[98:99]
	s_add_i32 m0, s7, 0x2000
	ds_read_b128 v[202:205], v163 offset:51200
	global_load_lds_dwordx4 v136, s[98:99]
	s_mov_b32 m0, s66
	ds_read_b128 v[206:209], v163 offset:52224
	global_load_lds_dwordx4 v130, s[94:95]
	s_mov_b32 m0, s67
	ds_read_b128 v[210:213], v163 offset:53248
	global_load_lds_dwordx4 v134, s[94:95]
	ds_read_b128 v[214:217], v163 offset:54272
	ds_read_b128 v[218:221], v163 offset:55296
	ds_read_b128 v[222:225], v163 offset:56320
	s_waitcnt vmcnt(8)
	s_waitcnt lgkmcnt(0)
	s_setprio 1
	s_barrier
	v_mfma_f32_16x16x32_bf16 v[62:65], v[156:159], v[194:197], v[62:65]
	v_mfma_f32_16x16x32_bf16 v[54:57], v[170:173], v[194:197], v[54:57]
	v_mfma_f32_16x16x32_bf16 v[58:61], v[178:181], v[194:197], v[58:61]
	v_mfma_f32_16x16x32_bf16 v[50:53], v[186:189], v[194:197], v[50:53]
	v_mfma_f32_16x16x32_bf16 v[34:37], v[186:189], v[202:205], v[34:37]
	v_mfma_f32_16x16x32_bf16 v[42:45], v[178:181], v[202:205], v[42:45]
	v_mfma_f32_16x16x32_bf16 v[38:41], v[170:173], v[202:205], v[38:41]
	v_mfma_f32_16x16x32_bf16 v[46:49], v[156:159], v[202:205], v[46:49]
	v_mfma_f32_16x16x32_bf16 v[30:33], v[156:159], v[210:213], v[30:33]
	v_mfma_f32_16x16x32_bf16 v[22:25], v[170:173], v[210:213], v[22:25]
	v_mfma_f32_16x16x32_bf16 v[26:29], v[178:181], v[210:213], v[26:29]
	v_mfma_f32_16x16x32_bf16 v[18:21], v[186:189], v[210:213], v[18:21]
	v_mfma_f32_16x16x32_bf16 v[2:5], v[186:189], v[218:221], v[2:5]
	v_mfma_f32_16x16x32_bf16 v[10:13], v[178:181], v[218:221], v[10:13]
	v_mfma_f32_16x16x32_bf16 v[6:9], v[170:173], v[218:221], v[6:9]
	v_mfma_f32_16x16x32_bf16 v[14:17], v[156:159], v[218:221], v[14:17]
	v_mfma_f32_16x16x32_bf16 v[62:65], v[166:169], v[198:201], v[62:65]
	v_mfma_f32_16x16x32_bf16 v[54:57], v[174:177], v[198:201], v[54:57]
	v_mfma_f32_16x16x32_bf16 v[58:61], v[182:185], v[198:201], v[58:61]
	v_mfma_f32_16x16x32_bf16 v[50:53], v[190:193], v[198:201], v[50:53]
	v_mfma_f32_16x16x32_bf16 v[34:37], v[190:193], v[206:209], v[34:37]
	v_mfma_f32_16x16x32_bf16 v[42:45], v[182:185], v[206:209], v[42:45]
	v_mfma_f32_16x16x32_bf16 v[38:41], v[174:177], v[206:209], v[38:41]
	v_mfma_f32_16x16x32_bf16 v[46:49], v[166:169], v[206:209], v[46:49]
	v_mfma_f32_16x16x32_bf16 v[30:33], v[166:169], v[214:217], v[30:33]
	v_mfma_f32_16x16x32_bf16 v[22:25], v[174:177], v[214:217], v[22:25]
	v_mfma_f32_16x16x32_bf16 v[26:29], v[182:185], v[214:217], v[26:29]
	v_mfma_f32_16x16x32_bf16 v[18:21], v[190:193], v[214:217], v[18:21]
	v_mfma_f32_16x16x32_bf16 v[2:5], v[190:193], v[222:225], v[2:5]
	v_mfma_f32_16x16x32_bf16 v[10:13], v[182:185], v[222:225], v[10:13]
	v_mfma_f32_16x16x32_bf16 v[6:9], v[174:177], v[222:225], v[6:9]
	v_mfma_f32_16x16x32_bf16 v[14:17], v[166:169], v[222:225], v[14:17]
	s_barrier
	s_setprio 0
	s_mov_b32 s7, s45
	s_add_u32 s88, s88, 0x100
	s_addc_u32 s89, s89, 0
	s_add_u32 s86, s86, 0x100
	s_addc_u32 s87, s87, 0
	s_cmp_ge_i32 s45, s101
	s_cbranch_scc0 .LBB0_499

.Lmy_nb_3:
	s_nop 0
	v_readfirstlane_b32 s86, v152
	v_readfirstlane_b32 s87, v153
	v_readfirstlane_b32 s88, v150
	v_readfirstlane_b32 s89, v151
	v_readfirstlane_b32 s90, v146
	v_readfirstlane_b32 s91, v147
	v_readfirstlane_b32 s92, v148
	v_readfirstlane_b32 s93, v149
	v_readfirstlane_b32 s100, v154
	v_readfirstlane_b32 s101, v138
	v_add_u32_e32 v230, s76, v141
	v_add_u32_e32 v231, s77, v141
	v_add_u32_e32 v232, 0x18000, v141
	v_add_u32_e32 v233, 0x1c000, v141
	s_add_u32 s98, s86, 0xfffc0080
	s_addc_u32 s99, s87, -1
	s_cmp_eq_u32 s7, s100
	s_cselect_b64 s[94:95], s[90:91], s[98:99]
	s_cselect_b64 s[96:97], s[92:93], s[88:89]
	s_add_i32 s45, s7, 2
	s_add_i32 m0, s49, 0xc000
	ds_read_b128 v[164:167], v230
	global_load_lds_dwordx4 v144, s[86:87]
	s_add_i32 m0, s49, 0xe000
	ds_read_b128 v[168:171], v230 offset:1024
	global_load_lds_dwordx4 v142, s[86:87]
	ds_read_b128 v[172:175], v230 offset:2048
	ds_read_b128 v[176:179], v230 offset:3072
	ds_read_b128 v[180:183], v231
	ds_read_b128 v[184:187], v231 offset:1024
	ds_read_b128 v[188:191], v231 offset:2048
	ds_read_b128 v[192:195], v231 offset:3072
	ds_read_b128 v[196:199], v160
	ds_read_b128 v[200:203], v160 offset:1024
	ds_read_b128 v[204:207], v160 offset:2048
	ds_read_b128 v[208:211], v160 offset:3072
	ds_read_b128 v[212:215], v160 offset:4096
	ds_read_b128 v[216:219], v160 offset:5120
	ds_read_b128 v[220:223], v160 offset:6144
	ds_read_b128 v[224:227], v160 offset:7168
	s_waitcnt vmcnt(8)
	s_waitcnt lgkmcnt(0)
	s_setprio 1
	s_barrier
	v_mfma_f32_16x16x32_bf16 v[122:125], v[164:167], v[196:199], 0
	v_mfma_f32_16x16x32_bf16 v[118:121], v[172:175], v[196:199], 0
	v_mfma_f32_16x16x32_bf16 v[126:129], v[180:183], v[196:199], 0
	v_mfma_f32_16x16x32_bf16 v[114:117], v[188:191], v[196:199], 0
	v_mfma_f32_16x16x32_bf16 v[98:101], v[188:191], v[204:207], 0
	v_mfma_f32_16x16x32_bf16 v[106:109], v[180:183], v[204:207], 0
	v_mfma_f32_16x16x32_bf16 v[102:105], v[172:175], v[204:207], 0
	v_mfma_f32_16x16x32_bf16 v[110:113], v[164:167], v[204:207], 0
	v_mfma_f32_16x16x32_bf16 v[94:97], v[164:167], v[212:215], 0
	v_mfma_f32_16x16x32_bf16 v[86:89], v[172:175], v[212:215], 0
	v_mfma_f32_16x16x32_bf16 v[90:93], v[180:183], v[212:215], 0
	v_mfma_f32_16x16x32_bf16 v[82:85], v[188:191], v[212:215], 0
	v_mfma_f32_16x16x32_bf16 v[66:69], v[188:191], v[220:223], 0
	v_mfma_f32_16x16x32_bf16 v[74:77], v[180:183], v[220:223], 0
	v_mfma_f32_16x16x32_bf16 v[70:73], v[172:175], v[220:223], 0
	v_mfma_f32_16x16x32_bf16 v[78:81], v[164:167], v[220:223], 0
	v_mfma_f32_16x16x32_bf16 v[122:125], v[168:171], v[200:203], v[122:125]
	v_mfma_f32_16x16x32_bf16 v[118:121], v[176:179], v[200:203], v[118:121]
	v_mfma_f32_16x16x32_bf16 v[126:129], v[184:187], v[200:203], v[126:129]
	v_mfma_f32_16x16x32_bf16 v[114:117], v[192:195], v[200:203], v[114:117]
	v_mfma_f32_16x16x32_bf16 v[98:101], v[192:195], v[208:211], v[98:101]
	v_mfma_f32_16x16x32_bf16 v[106:109], v[184:187], v[208:211], v[106:109]
	v_mfma_f32_16x16x32_bf16 v[102:105], v[176:179], v[208:211], v[102:105]
	v_mfma_f32_16x16x32_bf16 v[110:113], v[168:171], v[208:211], v[110:113]
	v_mfma_f32_16x16x32_bf16 v[94:97], v[168:171], v[216:219], v[94:97]
	v_mfma_f32_16x16x32_bf16 v[86:89], v[176:179], v[216:219], v[86:89]
	v_mfma_f32_16x16x32_bf16 v[90:93], v[184:187], v[216:219], v[90:93]
	v_mfma_f32_16x16x32_bf16 v[82:85], v[192:195], v[216:219], v[82:85]
	v_mfma_f32_16x16x32_bf16 v[66:69], v[192:195], v[224:227], v[66:69]
	v_mfma_f32_16x16x32_bf16 v[74:77], v[184:187], v[224:227], v[74:77]
	v_mfma_f32_16x16x32_bf16 v[70:73], v[176:179], v[224:227], v[70:73]
	v_mfma_f32_16x16x32_bf16 v[78:81], v[168:171], v[224:227], v[78:81]
	s_barrier
	s_setprio 0
	s_add_u32 s98, s96, 0x40000
	s_addc_u32 s99, s97, 0
	s_add_i32 s7, s76, s25
	s_mov_b32 m0, s7
	ds_read_b128 v[196:199], v160 offset:16384
	global_load_lds_dwordx4 v132, s[96:97]
	s_add_i32 m0, s7, 0x2000
	s_add_i32 s7, s77, s25
	global_load_lds_dwordx4 v136, s[96:97]
	s_mov_b32 m0, s7
	ds_read_b128 v[200:203], v160 offset:17408
	global_load_lds_dwordx4 v132, s[98:99]
	s_add_i32 m0, s7, 0x2000
	ds_read_b128 v[204:207], v160 offset:18432
	global_load_lds_dwordx4 v136, s[98:99]
	s_mov_b32 m0, s49
	ds_read_b128 v[208:211], v160 offset:19456
	global_load_lds_dwordx4 v130, s[94:95]
	s_mov_b32 m0, s58
	ds_read_b128 v[212:215], v160 offset:20480
	global_load_lds_dwordx4 v134, s[94:95]
	ds_read_b128 v[216:219], v160 offset:21504
	ds_read_b128 v[220:223], v160 offset:22528
	ds_read_b128 v[224:227], v160 offset:23552
	s_waitcnt vmcnt(8)
	s_waitcnt lgkmcnt(0)
	s_setprio 1
	s_barrier
	v_mfma_f32_16x16x32_bf16 v[62:65], v[164:167], v[196:199], 0
	v_mfma_f32_16x16x32_bf16 v[54:57], v[172:175], v[196:199], 0
	v_mfma_f32_16x16x32_bf16 v[58:61], v[180:183], v[196:199], 0
	v_mfma_f32_16x16x32_bf16 v[50:53], v[188:191], v[196:199], 0
	v_mfma_f32_16x16x32_bf16 v[34:37], v[188:191], v[204:207], 0
	v_mfma_f32_16x16x32_bf16 v[42:45], v[180:183], v[204:207], 0
	v_mfma_f32_16x16x32_bf16 v[38:41], v[172:175], v[204:207], 0
	v_mfma_f32_16x16x32_bf16 v[46:49], v[164:167], v[204:207], 0
	v_mfma_f32_16x16x32_bf16 v[30:33], v[164:167], v[212:215], 0
	v_mfma_f32_16x16x32_bf16 v[22:25], v[172:175], v[212:215], 0
	v_mfma_f32_16x16x32_bf16 v[26:29], v[180:183], v[212:215], 0
	v_mfma_f32_16x16x32_bf16 v[18:21], v[188:191], v[212:215], 0
	v_mfma_f32_16x16x32_bf16 v[2:5], v[188:191], v[220:223], 0
	v_mfma_f32_16x16x32_bf16 v[10:13], v[180:183], v[220:223], 0
	v_mfma_f32_16x16x32_bf16 v[6:9], v[172:175], v[220:223], 0
	v_mfma_f32_16x16x32_bf16 v[14:17], v[164:167], v[220:223], 0
	v_mfma_f32_16x16x32_bf16 v[62:65], v[168:171], v[200:203], v[62:65]
	v_mfma_f32_16x16x32_bf16 v[54:57], v[176:179], v[200:203], v[54:57]
	v_mfma_f32_16x16x32_bf16 v[58:61], v[184:187], v[200:203], v[58:61]
	v_mfma_f32_16x16x32_bf16 v[50:53], v[192:195], v[200:203], v[50:53]
	v_mfma_f32_16x16x32_bf16 v[34:37], v[192:195], v[208:211], v[34:37]
	v_mfma_f32_16x16x32_bf16 v[42:45], v[184:187], v[208:211], v[42:45]
	v_mfma_f32_16x16x32_bf16 v[38:41], v[176:179], v[208:211], v[38:41]
	v_mfma_f32_16x16x32_bf16 v[46:49], v[168:171], v[208:211], v[46:49]
	v_mfma_f32_16x16x32_bf16 v[30:33], v[168:171], v[216:219], v[30:33]
	v_mfma_f32_16x16x32_bf16 v[22:25], v[176:179], v[216:219], v[22:25]
	v_mfma_f32_16x16x32_bf16 v[26:29], v[184:187], v[216:219], v[26:29]
	v_mfma_f32_16x16x32_bf16 v[18:21], v[192:195], v[216:219], v[18:21]
	v_mfma_f32_16x16x32_bf16 v[2:5], v[192:195], v[224:227], v[2:5]
	v_mfma_f32_16x16x32_bf16 v[10:13], v[184:187], v[224:227], v[10:13]
	v_mfma_f32_16x16x32_bf16 v[6:9], v[176:179], v[224:227], v[6:9]
	v_mfma_f32_16x16x32_bf16 v[14:17], v[168:171], v[224:227], v[14:17]
	s_barrier
	s_setprio 0
	s_add_u32 s98, s94, 0x40000
	s_addc_u32 s99, s95, 0
	s_add_i32 s7, 0, 0x18000
	s_add_i32 s47, 0, 0x1c000
	s_mov_b32 m0, s59
	ds_read_b128 v[164:167], v232
	global_load_lds_dwordx4 v130, s[98:99]
	s_mov_b32 m0, s60
	ds_read_b128 v[168:171], v232 offset:1024
	global_load_lds_dwordx4 v134, s[98:99]
	ds_read_b128 v[172:175], v232 offset:2048
	ds_read_b128 v[176:179], v232 offset:3072
	ds_read_b128 v[180:183], v233
	ds_read_b128 v[184:187], v233 offset:1024
	ds_read_b128 v[188:191], v233 offset:2048
	ds_read_b128 v[192:195], v233 offset:3072
	ds_read_b128 v[196:199], v160 offset:32768
	ds_read_b128 v[200:203], v160 offset:33792
	ds_read_b128 v[204:207], v160 offset:34816
	ds_read_b128 v[208:211], v160 offset:35840
	ds_read_b128 v[212:215], v160 offset:36864
	ds_read_b128 v[216:219], v160 offset:37888
	ds_read_b128 v[220:223], v160 offset:38912
	ds_read_b128 v[224:227], v160 offset:39936
	s_waitcnt vmcnt(8)
	s_waitcnt lgkmcnt(0)
	s_setprio 1
	s_barrier
	v_mfma_f32_16x16x32_bf16 v[122:125], v[164:167], v[196:199], v[122:125]
	v_mfma_f32_16x16x32_bf16 v[118:121], v[172:175], v[196:199], v[118:121]
	v_mfma_f32_16x16x32_bf16 v[126:129], v[180:183], v[196:199], v[126:129]
	v_mfma_f32_16x16x32_bf16 v[114:117], v[188:191], v[196:199], v[114:117]
	v_mfma_f32_16x16x32_bf16 v[98:101], v[188:191], v[204:207], v[98:101]
	v_mfma_f32_16x16x32_bf16 v[106:109], v[180:183], v[204:207], v[106:109]
	v_mfma_f32_16x16x32_bf16 v[102:105], v[172:175], v[204:207], v[102:105]
	v_mfma_f32_16x16x32_bf16 v[110:113], v[164:167], v[204:207], v[110:113]
	v_mfma_f32_16x16x32_bf16 v[94:97], v[164:167], v[212:215], v[94:97]
	v_mfma_f32_16x16x32_bf16 v[86:89], v[172:175], v[212:215], v[86:89]
	v_mfma_f32_16x16x32_bf16 v[90:93], v[180:183], v[212:215], v[90:93]
	v_mfma_f32_16x16x32_bf16 v[82:85], v[188:191], v[212:215], v[82:85]
	v_mfma_f32_16x16x32_bf16 v[66:69], v[188:191], v[220:223], v[66:69]
	v_mfma_f32_16x16x32_bf16 v[74:77], v[180:183], v[220:223], v[74:77]
	v_mfma_f32_16x16x32_bf16 v[70:73], v[172:175], v[220:223], v[70:73]
	v_mfma_f32_16x16x32_bf16 v[78:81], v[164:167], v[220:223], v[78:81]
	v_mfma_f32_16x16x32_bf16 v[122:125], v[168:171], v[200:203], v[122:125]
	v_mfma_f32_16x16x32_bf16 v[118:121], v[176:179], v[200:203], v[118:121]
	v_mfma_f32_16x16x32_bf16 v[126:129], v[184:187], v[200:203], v[126:129]
	v_mfma_f32_16x16x32_bf16 v[114:117], v[192:195], v[200:203], v[114:117]
	v_mfma_f32_16x16x32_bf16 v[98:101], v[192:195], v[208:211], v[98:101]
	v_mfma_f32_16x16x32_bf16 v[106:109], v[184:187], v[208:211], v[106:109]
	v_mfma_f32_16x16x32_bf16 v[102:105], v[176:179], v[208:211], v[102:105]
	v_mfma_f32_16x16x32_bf16 v[110:113], v[168:171], v[208:211], v[110:113]
	v_mfma_f32_16x16x32_bf16 v[94:97], v[168:171], v[216:219], v[94:97]
	v_mfma_f32_16x16x32_bf16 v[86:89], v[176:179], v[216:219], v[86:89]
	v_mfma_f32_16x16x32_bf16 v[90:93], v[184:187], v[216:219], v[90:93]
	v_mfma_f32_16x16x32_bf16 v[82:85], v[192:195], v[216:219], v[82:85]
	v_mfma_f32_16x16x32_bf16 v[66:69], v[192:195], v[224:227], v[66:69]
	v_mfma_f32_16x16x32_bf16 v[74:77], v[184:187], v[224:227], v[74:77]
	v_mfma_f32_16x16x32_bf16 v[70:73], v[176:179], v[224:227], v[70:73]
	v_mfma_f32_16x16x32_bf16 v[78:81], v[168:171], v[224:227], v[78:81]
	s_barrier
	s_setprio 0
	s_add_u32 s96, s96, 0x80
	s_addc_u32 s97, s97, 0
	s_add_u32 s98, s96, 0x40000
	s_addc_u32 s99, s97, 0
	s_add_u32 s94, s94, 0x80
	s_addc_u32 s95, s95, 0
	s_add_i32 s7, s7, s25
	s_mov_b32 m0, s7
	ds_read_b128 v[196:199], v160 offset:49152
	global_load_lds_dwordx4 v132, s[96:97]
	s_add_i32 m0, s7, 0x2000
	s_add_i32 s7, s47, s25
	global_load_lds_dwordx4 v136, s[96:97]
	s_mov_b32 m0, s7
	ds_read_b128 v[200:203], v160 offset:50176
	global_load_lds_dwordx4 v132, s[98:99]
	s_add_i32 m0, s7, 0x2000
	ds_read_b128 v[204:207], v160 offset:51200
	global_load_lds_dwordx4 v136, s[98:99]
	s_mov_b32 m0, s66
	ds_read_b128 v[208:211], v160 offset:52224
	global_load_lds_dwordx4 v130, s[94:95]
	s_mov_b32 m0, s67
	ds_read_b128 v[212:215], v160 offset:53248
	global_load_lds_dwordx4 v134, s[94:95]
	ds_read_b128 v[216:219], v160 offset:54272
	ds_read_b128 v[220:223], v160 offset:55296
	ds_read_b128 v[224:227], v160 offset:56320
	s_waitcnt vmcnt(8)
	s_waitcnt lgkmcnt(0)
	s_setprio 1
	s_barrier
	v_mfma_f32_16x16x32_bf16 v[62:65], v[164:167], v[196:199], v[62:65]
	v_mfma_f32_16x16x32_bf16 v[54:57], v[172:175], v[196:199], v[54:57]
	v_mfma_f32_16x16x32_bf16 v[58:61], v[180:183], v[196:199], v[58:61]
	v_mfma_f32_16x16x32_bf16 v[50:53], v[188:191], v[196:199], v[50:53]
	v_mfma_f32_16x16x32_bf16 v[34:37], v[188:191], v[204:207], v[34:37]
	v_mfma_f32_16x16x32_bf16 v[42:45], v[180:183], v[204:207], v[42:45]
	v_mfma_f32_16x16x32_bf16 v[38:41], v[172:175], v[204:207], v[38:41]
	v_mfma_f32_16x16x32_bf16 v[46:49], v[164:167], v[204:207], v[46:49]
	v_mfma_f32_16x16x32_bf16 v[30:33], v[164:167], v[212:215], v[30:33]
	v_mfma_f32_16x16x32_bf16 v[22:25], v[172:175], v[212:215], v[22:25]
	v_mfma_f32_16x16x32_bf16 v[26:29], v[180:183], v[212:215], v[26:29]
	v_mfma_f32_16x16x32_bf16 v[18:21], v[188:191], v[212:215], v[18:21]
	v_mfma_f32_16x16x32_bf16 v[2:5], v[188:191], v[220:223], v[2:5]
	v_mfma_f32_16x16x32_bf16 v[10:13], v[180:183], v[220:223], v[10:13]
	v_mfma_f32_16x16x32_bf16 v[6:9], v[172:175], v[220:223], v[6:9]
	v_mfma_f32_16x16x32_bf16 v[14:17], v[164:167], v[220:223], v[14:17]
	v_mfma_f32_16x16x32_bf16 v[62:65], v[168:171], v[200:203], v[62:65]
	v_mfma_f32_16x16x32_bf16 v[54:57], v[176:179], v[200:203], v[54:57]
	v_mfma_f32_16x16x32_bf16 v[58:61], v[184:187], v[200:203], v[58:61]
	v_mfma_f32_16x16x32_bf16 v[50:53], v[192:195], v[200:203], v[50:53]
	v_mfma_f32_16x16x32_bf16 v[34:37], v[192:195], v[208:211], v[34:37]
	v_mfma_f32_16x16x32_bf16 v[42:45], v[184:187], v[208:211], v[42:45]
	v_mfma_f32_16x16x32_bf16 v[38:41], v[176:179], v[208:211], v[38:41]
	v_mfma_f32_16x16x32_bf16 v[46:49], v[168:171], v[208:211], v[46:49]
	v_mfma_f32_16x16x32_bf16 v[30:33], v[168:171], v[216:219], v[30:33]
	v_mfma_f32_16x16x32_bf16 v[22:25], v[176:179], v[216:219], v[22:25]
	v_mfma_f32_16x16x32_bf16 v[26:29], v[184:187], v[216:219], v[26:29]
	v_mfma_f32_16x16x32_bf16 v[18:21], v[192:195], v[216:219], v[18:21]
	v_mfma_f32_16x16x32_bf16 v[2:5], v[192:195], v[224:227], v[2:5]
	v_mfma_f32_16x16x32_bf16 v[10:13], v[184:187], v[224:227], v[10:13]
	v_mfma_f32_16x16x32_bf16 v[6:9], v[176:179], v[224:227], v[6:9]
	v_mfma_f32_16x16x32_bf16 v[14:17], v[168:171], v[224:227], v[14:17]
	s_barrier
	s_setprio 0
	s_mov_b32 s7, s45
	s_add_u32 s88, s88, 0x100
	s_addc_u32 s89, s89, 0
	s_add_u32 s86, s86, 0x100
	s_addc_u32 s87, s87, 0
	s_cmp_ge_i32 s45, s101
	s_cbranch_scc1 .Lmy_kexit_3
.LBB0_768:
	s_add_u32 s98, s86, 0xfffc0080
	s_addc_u32 s99, s87, -1
	s_cmp_eq_u32 s7, s100
	s_cselect_b64 s[94:95], s[90:91], s[98:99]
	s_cselect_b64 s[96:97], s[92:93], s[88:89]
	s_add_i32 s45, s7, 2
	s_add_i32 m0, s49, 0xc000
	ds_read_b128 v[164:167], v230
	global_load_lds_dwordx4 v144, s[86:87]
	s_add_i32 m0, s49, 0xe000
	ds_read_b128 v[168:171], v230 offset:1024
	global_load_lds_dwordx4 v142, s[86:87]
	ds_read_b128 v[172:175], v230 offset:2048
	ds_read_b128 v[176:179], v230 offset:3072
	ds_read_b128 v[180:183], v231
	ds_read_b128 v[184:187], v231 offset:1024
	ds_read_b128 v[188:191], v231 offset:2048
	ds_read_b128 v[192:195], v231 offset:3072
	ds_read_b128 v[196:199], v160
	ds_read_b128 v[200:203], v160 offset:1024
	ds_read_b128 v[204:207], v160 offset:2048
	ds_read_b128 v[208:211], v160 offset:3072
	ds_read_b128 v[212:215], v160 offset:4096
	ds_read_b128 v[216:219], v160 offset:5120
	ds_read_b128 v[220:223], v160 offset:6144
	ds_read_b128 v[224:227], v160 offset:7168
	s_waitcnt vmcnt(8)
	s_waitcnt lgkmcnt(0)
	s_setprio 1
	s_barrier
	v_mfma_f32_16x16x32_bf16 v[122:125], v[164:167], v[196:199], v[122:125]
	v_mfma_f32_16x16x32_bf16 v[118:121], v[172:175], v[196:199], v[118:121]
	v_mfma_f32_16x16x32_bf16 v[126:129], v[180:183], v[196:199], v[126:129]
	v_mfma_f32_16x16x32_bf16 v[114:117], v[188:191], v[196:199], v[114:117]
	v_mfma_f32_16x16x32_bf16 v[98:101], v[188:191], v[204:207], v[98:101]
	v_mfma_f32_16x16x32_bf16 v[106:109], v[180:183], v[204:207], v[106:109]
	v_mfma_f32_16x16x32_bf16 v[102:105], v[172:175], v[204:207], v[102:105]
	v_mfma_f32_16x16x32_bf16 v[110:113], v[164:167], v[204:207], v[110:113]
	v_mfma_f32_16x16x32_bf16 v[94:97], v[164:167], v[212:215], v[94:97]
	v_mfma_f32_16x16x32_bf16 v[86:89], v[172:175], v[212:215], v[86:89]
	v_mfma_f32_16x16x32_bf16 v[90:93], v[180:183], v[212:215], v[90:93]
	v_mfma_f32_16x16x32_bf16 v[82:85], v[188:191], v[212:215], v[82:85]
	v_mfma_f32_16x16x32_bf16 v[66:69], v[188:191], v[220:223], v[66:69]
	v_mfma_f32_16x16x32_bf16 v[74:77], v[180:183], v[220:223], v[74:77]
	v_mfma_f32_16x16x32_bf16 v[70:73], v[172:175], v[220:223], v[70:73]
	v_mfma_f32_16x16x32_bf16 v[78:81], v[164:167], v[220:223], v[78:81]
	v_mfma_f32_16x16x32_bf16 v[122:125], v[168:171], v[200:203], v[122:125]
	v_mfma_f32_16x16x32_bf16 v[118:121], v[176:179], v[200:203], v[118:121]
	v_mfma_f32_16x16x32_bf16 v[126:129], v[184:187], v[200:203], v[126:129]
	v_mfma_f32_16x16x32_bf16 v[114:117], v[192:195], v[200:203], v[114:117]
	v_mfma_f32_16x16x32_bf16 v[98:101], v[192:195], v[208:211], v[98:101]
	v_mfma_f32_16x16x32_bf16 v[106:109], v[184:187], v[208:211], v[106:109]
	v_mfma_f32_16x16x32_bf16 v[102:105], v[176:179], v[208:211], v[102:105]
	v_mfma_f32_16x16x32_bf16 v[110:113], v[168:171], v[208:211], v[110:113]
	v_mfma_f32_16x16x32_bf16 v[94:97], v[168:171], v[216:219], v[94:97]
	v_mfma_f32_16x16x32_bf16 v[86:89], v[176:179], v[216:219], v[86:89]
	v_mfma_f32_16x16x32_bf16 v[90:93], v[184:187], v[216:219], v[90:93]
	v_mfma_f32_16x16x32_bf16 v[82:85], v[192:195], v[216:219], v[82:85]
	v_mfma_f32_16x16x32_bf16 v[66:69], v[192:195], v[224:227], v[66:69]
	v_mfma_f32_16x16x32_bf16 v[74:77], v[184:187], v[224:227], v[74:77]
	v_mfma_f32_16x16x32_bf16 v[70:73], v[176:179], v[224:227], v[70:73]
	v_mfma_f32_16x16x32_bf16 v[78:81], v[168:171], v[224:227], v[78:81]
	s_barrier
	s_setprio 0
	s_add_u32 s98, s96, 0x40000
	s_addc_u32 s99, s97, 0
	s_add_i32 s7, s76, s25
	s_mov_b32 m0, s7
	ds_read_b128 v[196:199], v160 offset:16384
	global_load_lds_dwordx4 v132, s[96:97]
	s_add_i32 m0, s7, 0x2000
	s_add_i32 s7, s77, s25
	global_load_lds_dwordx4 v136, s[96:97]
	s_mov_b32 m0, s7
	ds_read_b128 v[200:203], v160 offset:17408
	global_load_lds_dwordx4 v132, s[98:99]
	s_add_i32 m0, s7, 0x2000
	ds_read_b128 v[204:207], v160 offset:18432
	global_load_lds_dwordx4 v136, s[98:99]
	s_mov_b32 m0, s49
	ds_read_b128 v[208:211], v160 offset:19456
	global_load_lds_dwordx4 v130, s[94:95]
	s_mov_b32 m0, s58
	ds_read_b128 v[212:215], v160 offset:20480
	global_load_lds_dwordx4 v134, s[94:95]
	ds_read_b128 v[216:219], v160 offset:21504
	ds_read_b128 v[220:223], v160 offset:22528
	ds_read_b128 v[224:227], v160 offset:23552
	s_waitcnt vmcnt(8)
	s_waitcnt lgkmcnt(0)
	s_setprio 1
	s_barrier
	v_mfma_f32_16x16x32_bf16 v[62:65], v[164:167], v[196:199], v[62:65]
	v_mfma_f32_16x16x32_bf16 v[54:57], v[172:175], v[196:199], v[54:57]
	v_mfma_f32_16x16x32_bf16 v[58:61], v[180:183], v[196:199], v[58:61]
	v_mfma_f32_16x16x32_bf16 v[50:53], v[188:191], v[196:199], v[50:53]
	v_mfma_f32_16x16x32_bf16 v[34:37], v[188:191], v[204:207], v[34:37]
	v_mfma_f32_16x16x32_bf16 v[42:45], v[180:183], v[204:207], v[42:45]
	v_mfma_f32_16x16x32_bf16 v[38:41], v[172:175], v[204:207], v[38:41]
	v_mfma_f32_16x16x32_bf16 v[46:49], v[164:167], v[204:207], v[46:49]
	v_mfma_f32_16x16x32_bf16 v[30:33], v[164:167], v[212:215], v[30:33]
	v_mfma_f32_16x16x32_bf16 v[22:25], v[172:175], v[212:215], v[22:25]
	v_mfma_f32_16x16x32_bf16 v[26:29], v[180:183], v[212:215], v[26:29]
	v_mfma_f32_16x16x32_bf16 v[18:21], v[188:191], v[212:215], v[18:21]
	v_mfma_f32_16x16x32_bf16 v[2:5], v[188:191], v[220:223], v[2:5]
	v_mfma_f32_16x16x32_bf16 v[10:13], v[180:183], v[220:223], v[10:13]
	v_mfma_f32_16x16x32_bf16 v[6:9], v[172:175], v[220:223], v[6:9]
	v_mfma_f32_16x16x32_bf16 v[14:17], v[164:167], v[220:223], v[14:17]
	v_mfma_f32_16x16x32_bf16 v[62:65], v[168:171], v[200:203], v[62:65]
	v_mfma_f32_16x16x32_bf16 v[54:57], v[176:179], v[200:203], v[54:57]
	v_mfma_f32_16x16x32_bf16 v[58:61], v[184:187], v[200:203], v[58:61]
	v_mfma_f32_16x16x32_bf16 v[50:53], v[192:195], v[200:203], v[50:53]
	v_mfma_f32_16x16x32_bf16 v[34:37], v[192:195], v[208:211], v[34:37]
	v_mfma_f32_16x16x32_bf16 v[42:45], v[184:187], v[208:211], v[42:45]
	v_mfma_f32_16x16x32_bf16 v[38:41], v[176:179], v[208:211], v[38:41]
	v_mfma_f32_16x16x32_bf16 v[46:49], v[168:171], v[208:211], v[46:49]
	v_mfma_f32_16x16x32_bf16 v[30:33], v[168:171], v[216:219], v[30:33]
	v_mfma_f32_16x16x32_bf16 v[22:25], v[176:179], v[216:219], v[22:25]
	v_mfma_f32_16x16x32_bf16 v[26:29], v[184:187], v[216:219], v[26:29]
	v_mfma_f32_16x16x32_bf16 v[18:21], v[192:195], v[216:219], v[18:21]
	v_mfma_f32_16x16x32_bf16 v[2:5], v[192:195], v[224:227], v[2:5]
	v_mfma_f32_16x16x32_bf16 v[10:13], v[184:187], v[224:227], v[10:13]
	v_mfma_f32_16x16x32_bf16 v[6:9], v[176:179], v[224:227], v[6:9]
	v_mfma_f32_16x16x32_bf16 v[14:17], v[168:171], v[224:227], v[14:17]
	s_barrier
	s_setprio 0
	s_add_u32 s98, s94, 0x40000
	s_addc_u32 s99, s95, 0
	s_add_i32 s7, 0, 0x18000
	s_add_i32 s47, 0, 0x1c000
	s_mov_b32 m0, s59
	ds_read_b128 v[164:167], v232
	global_load_lds_dwordx4 v130, s[98:99]
	s_mov_b32 m0, s60
	ds_read_b128 v[168:171], v232 offset:1024
	global_load_lds_dwordx4 v134, s[98:99]
	ds_read_b128 v[172:175], v232 offset:2048
	ds_read_b128 v[176:179], v232 offset:3072
	ds_read_b128 v[180:183], v233
	ds_read_b128 v[184:187], v233 offset:1024
	ds_read_b128 v[188:191], v233 offset:2048
	ds_read_b128 v[192:195], v233 offset:3072
	ds_read_b128 v[196:199], v160 offset:32768
	ds_read_b128 v[200:203], v160 offset:33792
	ds_read_b128 v[204:207], v160 offset:34816
	ds_read_b128 v[208:211], v160 offset:35840
	ds_read_b128 v[212:215], v160 offset:36864
	ds_read_b128 v[216:219], v160 offset:37888
	ds_read_b128 v[220:223], v160 offset:38912
	ds_read_b128 v[224:227], v160 offset:39936
	s_waitcnt vmcnt(8)
	s_waitcnt lgkmcnt(0)
	s_setprio 1
	s_barrier
	v_mfma_f32_16x16x32_bf16 v[122:125], v[164:167], v[196:199], v[122:125]
	v_mfma_f32_16x16x32_bf16 v[118:121], v[172:175], v[196:199], v[118:121]
	v_mfma_f32_16x16x32_bf16 v[126:129], v[180:183], v[196:199], v[126:129]
	v_mfma_f32_16x16x32_bf16 v[114:117], v[188:191], v[196:199], v[114:117]
	v_mfma_f32_16x16x32_bf16 v[98:101], v[188:191], v[204:207], v[98:101]
	v_mfma_f32_16x16x32_bf16 v[106:109], v[180:183], v[204:207], v[106:109]
	v_mfma_f32_16x16x32_bf16 v[102:105], v[172:175], v[204:207], v[102:105]
	v_mfma_f32_16x16x32_bf16 v[110:113], v[164:167], v[204:207], v[110:113]
	v_mfma_f32_16x16x32_bf16 v[94:97], v[164:167], v[212:215], v[94:97]
	v_mfma_f32_16x16x32_bf16 v[86:89], v[172:175], v[212:215], v[86:89]
	v_mfma_f32_16x16x32_bf16 v[90:93], v[180:183], v[212:215], v[90:93]
	v_mfma_f32_16x16x32_bf16 v[82:85], v[188:191], v[212:215], v[82:85]
	v_mfma_f32_16x16x32_bf16 v[66:69], v[188:191], v[220:223], v[66:69]
	v_mfma_f32_16x16x32_bf16 v[74:77], v[180:183], v[220:223], v[74:77]
	v_mfma_f32_16x16x32_bf16 v[70:73], v[172:175], v[220:223], v[70:73]
	v_mfma_f32_16x16x32_bf16 v[78:81], v[164:167], v[220:223], v[78:81]
	v_mfma_f32_16x16x32_bf16 v[122:125], v[168:171], v[200:203], v[122:125]
	v_mfma_f32_16x16x32_bf16 v[118:121], v[176:179], v[200:203], v[118:121]
	v_mfma_f32_16x16x32_bf16 v[126:129], v[184:187], v[200:203], v[126:129]
	v_mfma_f32_16x16x32_bf16 v[114:117], v[192:195], v[200:203], v[114:117]
	v_mfma_f32_16x16x32_bf16 v[98:101], v[192:195], v[208:211], v[98:101]
	v_mfma_f32_16x16x32_bf16 v[106:109], v[184:187], v[208:211], v[106:109]
	v_mfma_f32_16x16x32_bf16 v[102:105], v[176:179], v[208:211], v[102:105]
	v_mfma_f32_16x16x32_bf16 v[110:113], v[168:171], v[208:211], v[110:113]
	v_mfma_f32_16x16x32_bf16 v[94:97], v[168:171], v[216:219], v[94:97]
	v_mfma_f32_16x16x32_bf16 v[86:89], v[176:179], v[216:219], v[86:89]
	v_mfma_f32_16x16x32_bf16 v[90:93], v[184:187], v[216:219], v[90:93]
	v_mfma_f32_16x16x32_bf16 v[82:85], v[192:195], v[216:219], v[82:85]
	v_mfma_f32_16x16x32_bf16 v[66:69], v[192:195], v[224:227], v[66:69]
	v_mfma_f32_16x16x32_bf16 v[74:77], v[184:187], v[224:227], v[74:77]
	v_mfma_f32_16x16x32_bf16 v[70:73], v[176:179], v[224:227], v[70:73]
	v_mfma_f32_16x16x32_bf16 v[78:81], v[168:171], v[224:227], v[78:81]
	s_barrier
	s_setprio 0
	s_add_u32 s96, s96, 0x80
	s_addc_u32 s97, s97, 0
	s_add_u32 s98, s96, 0x40000
	s_addc_u32 s99, s97, 0
	s_add_u32 s94, s94, 0x80
	s_addc_u32 s95, s95, 0
	s_add_i32 s7, s7, s25
	s_mov_b32 m0, s7
	ds_read_b128 v[196:199], v160 offset:49152
	global_load_lds_dwordx4 v132, s[96:97]
	s_add_i32 m0, s7, 0x2000
	s_add_i32 s7, s47, s25
	global_load_lds_dwordx4 v136, s[96:97]
	s_mov_b32 m0, s7
	ds_read_b128 v[200:203], v160 offset:50176
	global_load_lds_dwordx4 v132, s[98:99]
	s_add_i32 m0, s7, 0x2000
	ds_read_b128 v[204:207], v160 offset:51200
	global_load_lds_dwordx4 v136, s[98:99]
	s_mov_b32 m0, s66
	ds_read_b128 v[208:211], v160 offset:52224
	global_load_lds_dwordx4 v130, s[94:95]
	s_mov_b32 m0, s67
	ds_read_b128 v[212:215], v160 offset:53248
	global_load_lds_dwordx4 v134, s[94:95]
	ds_read_b128 v[216:219], v160 offset:54272
	ds_read_b128 v[220:223], v160 offset:55296
	ds_read_b128 v[224:227], v160 offset:56320
	s_waitcnt vmcnt(8)
	s_waitcnt lgkmcnt(0)
	s_setprio 1
	s_barrier
	v_mfma_f32_16x16x32_bf16 v[62:65], v[164:167], v[196:199], v[62:65]
	v_mfma_f32_16x16x32_bf16 v[54:57], v[172:175], v[196:199], v[54:57]
	v_mfma_f32_16x16x32_bf16 v[58:61], v[180:183], v[196:199], v[58:61]
	v_mfma_f32_16x16x32_bf16 v[50:53], v[188:191], v[196:199], v[50:53]
	v_mfma_f32_16x16x32_bf16 v[34:37], v[188:191], v[204:207], v[34:37]
	v_mfma_f32_16x16x32_bf16 v[42:45], v[180:183], v[204:207], v[42:45]
	v_mfma_f32_16x16x32_bf16 v[38:41], v[172:175], v[204:207], v[38:41]
	v_mfma_f32_16x16x32_bf16 v[46:49], v[164:167], v[204:207], v[46:49]
	v_mfma_f32_16x16x32_bf16 v[30:33], v[164:167], v[212:215], v[30:33]
	v_mfma_f32_16x16x32_bf16 v[22:25], v[172:175], v[212:215], v[22:25]
	v_mfma_f32_16x16x32_bf16 v[26:29], v[180:183], v[212:215], v[26:29]
	v_mfma_f32_16x16x32_bf16 v[18:21], v[188:191], v[212:215], v[18:21]
	v_mfma_f32_16x16x32_bf16 v[2:5], v[188:191], v[220:223], v[2:5]
	v_mfma_f32_16x16x32_bf16 v[10:13], v[180:183], v[220:223], v[10:13]
	v_mfma_f32_16x16x32_bf16 v[6:9], v[172:175], v[220:223], v[6:9]
	v_mfma_f32_16x16x32_bf16 v[14:17], v[164:167], v[220:223], v[14:17]
	v_mfma_f32_16x16x32_bf16 v[62:65], v[168:171], v[200:203], v[62:65]
	v_mfma_f32_16x16x32_bf16 v[54:57], v[176:179], v[200:203], v[54:57]
	v_mfma_f32_16x16x32_bf16 v[58:61], v[184:187], v[200:203], v[58:61]
	v_mfma_f32_16x16x32_bf16 v[50:53], v[192:195], v[200:203], v[50:53]
	v_mfma_f32_16x16x32_bf16 v[34:37], v[192:195], v[208:211], v[34:37]
	v_mfma_f32_16x16x32_bf16 v[42:45], v[184:187], v[208:211], v[42:45]
	v_mfma_f32_16x16x32_bf16 v[38:41], v[176:179], v[208:211], v[38:41]
	v_mfma_f32_16x16x32_bf16 v[46:49], v[168:171], v[208:211], v[46:49]
	v_mfma_f32_16x16x32_bf16 v[30:33], v[168:171], v[216:219], v[30:33]
	v_mfma_f32_16x16x32_bf16 v[22:25], v[176:179], v[216:219], v[22:25]
	v_mfma_f32_16x16x32_bf16 v[26:29], v[184:187], v[216:219], v[26:29]
	v_mfma_f32_16x16x32_bf16 v[18:21], v[192:195], v[216:219], v[18:21]
	v_mfma_f32_16x16x32_bf16 v[2:5], v[192:195], v[224:227], v[2:5]
	v_mfma_f32_16x16x32_bf16 v[10:13], v[184:187], v[224:227], v[10:13]
	v_mfma_f32_16x16x32_bf16 v[6:9], v[176:179], v[224:227], v[6:9]
	v_mfma_f32_16x16x32_bf16 v[14:17], v[168:171], v[224:227], v[14:17]
	s_barrier
	s_setprio 0
	s_mov_b32 s7, s45
	s_add_u32 s88, s88, 0x100
	s_addc_u32 s89, s89, 0
	s_add_u32 s86, s86, 0x100
	s_addc_u32 s87, s87, 0
	s_cmp_ge_i32 s45, s101
	s_cbranch_scc0 .LBB0_768

.Lmy_nb_4:
	s_nop 0
	v_readfirstlane_b32 s86, v152
	v_readfirstlane_b32 s87, v153
	v_readfirstlane_b32 s88, v150
	v_readfirstlane_b32 s89, v151
	v_readfirstlane_b32 s90, v146
	v_readfirstlane_b32 s91, v147
	v_readfirstlane_b32 s92, v148
	v_readfirstlane_b32 s93, v149
	v_readfirstlane_b32 s100, v154
	v_readfirstlane_b32 s101, v138
	v_add_u32_e32 v230, s74, v141
	v_add_u32_e32 v231, s75, v141
	v_add_u32_e32 v232, 0x18000, v141
	v_add_u32_e32 v233, 0x1c000, v141
	s_add_u32 s98, s86, 0xfffc0080
	s_addc_u32 s99, s87, -1
	s_cmp_eq_u32 s7, s100
	s_cselect_b64 s[94:95], s[90:91], s[98:99]
	s_cselect_b64 s[96:97], s[92:93], s[88:89]
	s_add_i32 s47, s7, 2
	s_mov_b32 m0, s76
	ds_read_b128 v[164:167], v230
	global_load_lds_dwordx4 v144, s[86:87]
	s_mov_b32 m0, s77
	ds_read_b128 v[168:171], v230 offset:1024
	global_load_lds_dwordx4 v142, s[86:87]
	ds_read_b128 v[172:175], v230 offset:2048
	ds_read_b128 v[176:179], v230 offset:3072
	ds_read_b128 v[180:183], v231
	ds_read_b128 v[184:187], v231 offset:1024
	ds_read_b128 v[188:191], v231 offset:2048
	ds_read_b128 v[192:195], v231 offset:3072
	ds_read_b128 v[196:199], v160
	ds_read_b128 v[200:203], v160 offset:1024
	ds_read_b128 v[204:207], v160 offset:2048
	ds_read_b128 v[208:211], v160 offset:3072
	ds_read_b128 v[212:215], v160 offset:4096
	ds_read_b128 v[216:219], v160 offset:5120
	ds_read_b128 v[220:223], v160 offset:6144
	ds_read_b128 v[224:227], v160 offset:7168
	s_waitcnt vmcnt(8)
	s_waitcnt lgkmcnt(0)
	s_setprio 1
	s_barrier
	v_mfma_f32_16x16x32_bf16 v[122:125], v[164:167], v[196:199], 0
	v_mfma_f32_16x16x32_bf16 v[118:121], v[172:175], v[196:199], 0
	v_mfma_f32_16x16x32_bf16 v[126:129], v[180:183], v[196:199], 0
	v_mfma_f32_16x16x32_bf16 v[114:117], v[188:191], v[196:199], 0
	v_mfma_f32_16x16x32_bf16 v[98:101], v[188:191], v[204:207], 0
	v_mfma_f32_16x16x32_bf16 v[106:109], v[180:183], v[204:207], 0
	v_mfma_f32_16x16x32_bf16 v[102:105], v[172:175], v[204:207], 0
	v_mfma_f32_16x16x32_bf16 v[110:113], v[164:167], v[204:207], 0
	v_mfma_f32_16x16x32_bf16 v[94:97], v[164:167], v[212:215], 0
	v_mfma_f32_16x16x32_bf16 v[86:89], v[172:175], v[212:215], 0
	v_mfma_f32_16x16x32_bf16 v[90:93], v[180:183], v[212:215], 0
	v_mfma_f32_16x16x32_bf16 v[82:85], v[188:191], v[212:215], 0
	v_mfma_f32_16x16x32_bf16 v[66:69], v[188:191], v[220:223], 0
	v_mfma_f32_16x16x32_bf16 v[74:77], v[180:183], v[220:223], 0
	v_mfma_f32_16x16x32_bf16 v[70:73], v[172:175], v[220:223], 0
	v_mfma_f32_16x16x32_bf16 v[78:81], v[164:167], v[220:223], 0
	v_mfma_f32_16x16x32_bf16 v[122:125], v[168:171], v[200:203], v[122:125]
	v_mfma_f32_16x16x32_bf16 v[118:121], v[176:179], v[200:203], v[118:121]
	v_mfma_f32_16x16x32_bf16 v[126:129], v[184:187], v[200:203], v[126:129]
	v_mfma_f32_16x16x32_bf16 v[114:117], v[192:195], v[200:203], v[114:117]
	v_mfma_f32_16x16x32_bf16 v[98:101], v[192:195], v[208:211], v[98:101]
	v_mfma_f32_16x16x32_bf16 v[106:109], v[184:187], v[208:211], v[106:109]
	v_mfma_f32_16x16x32_bf16 v[102:105], v[176:179], v[208:211], v[102:105]
	v_mfma_f32_16x16x32_bf16 v[110:113], v[168:171], v[208:211], v[110:113]
	v_mfma_f32_16x16x32_bf16 v[94:97], v[168:171], v[216:219], v[94:97]
	v_mfma_f32_16x16x32_bf16 v[86:89], v[176:179], v[216:219], v[86:89]
	v_mfma_f32_16x16x32_bf16 v[90:93], v[184:187], v[216:219], v[90:93]
	v_mfma_f32_16x16x32_bf16 v[82:85], v[192:195], v[216:219], v[82:85]
	v_mfma_f32_16x16x32_bf16 v[66:69], v[192:195], v[224:227], v[66:69]
	v_mfma_f32_16x16x32_bf16 v[74:77], v[184:187], v[224:227], v[74:77]
	v_mfma_f32_16x16x32_bf16 v[70:73], v[176:179], v[224:227], v[70:73]
	v_mfma_f32_16x16x32_bf16 v[78:81], v[168:171], v[224:227], v[78:81]
	s_barrier
	s_setprio 0
	s_add_u32 s98, s96, 0x40000
	s_addc_u32 s99, s97, 0
	s_mov_b32 m0, s78
	ds_read_b128 v[196:199], v160 offset:16384
	global_load_lds_dwordx4 v132, s[96:97]
	s_mov_b32 m0, s79
	s_add_i32 s7, s75, s29
	global_load_lds_dwordx4 v136, s[96:97]
	s_mov_b32 m0, s7
	ds_read_b128 v[200:203], v160 offset:17408
	global_load_lds_dwordx4 v132, s[98:99]
	s_add_i32 m0, s7, 0x2000
	ds_read_b128 v[204:207], v160 offset:18432
	global_load_lds_dwordx4 v136, s[98:99]
	s_mov_b32 m0, s51
	ds_read_b128 v[208:211], v160 offset:19456
	global_load_lds_dwordx4 v130, s[94:95]
	s_mov_b32 m0, s60
	ds_read_b128 v[212:215], v160 offset:20480
	global_load_lds_dwordx4 v134, s[94:95]
	ds_read_b128 v[216:219], v160 offset:21504
	ds_read_b128 v[220:223], v160 offset:22528
	ds_read_b128 v[224:227], v160 offset:23552
	s_waitcnt vmcnt(8)
	s_waitcnt lgkmcnt(0)
	s_setprio 1
	s_barrier
	v_mfma_f32_16x16x32_bf16 v[62:65], v[164:167], v[196:199], 0
	v_mfma_f32_16x16x32_bf16 v[54:57], v[172:175], v[196:199], 0
	v_mfma_f32_16x16x32_bf16 v[58:61], v[180:183], v[196:199], 0
	v_mfma_f32_16x16x32_bf16 v[50:53], v[188:191], v[196:199], 0
	v_mfma_f32_16x16x32_bf16 v[34:37], v[188:191], v[204:207], 0
	v_mfma_f32_16x16x32_bf16 v[42:45], v[180:183], v[204:207], 0
	v_mfma_f32_16x16x32_bf16 v[38:41], v[172:175], v[204:207], 0
	v_mfma_f32_16x16x32_bf16 v[46:49], v[164:167], v[204:207], 0
	v_mfma_f32_16x16x32_bf16 v[30:33], v[164:167], v[212:215], 0
	v_mfma_f32_16x16x32_bf16 v[22:25], v[172:175], v[212:215], 0
	v_mfma_f32_16x16x32_bf16 v[26:29], v[180:183], v[212:215], 0
	v_mfma_f32_16x16x32_bf16 v[18:21], v[188:191], v[212:215], 0
	v_mfma_f32_16x16x32_bf16 v[2:5], v[188:191], v[220:223], 0
	v_mfma_f32_16x16x32_bf16 v[10:13], v[180:183], v[220:223], 0
	v_mfma_f32_16x16x32_bf16 v[6:9], v[172:175], v[220:223], 0
	v_mfma_f32_16x16x32_bf16 v[14:17], v[164:167], v[220:223], 0
	v_mfma_f32_16x16x32_bf16 v[62:65], v[168:171], v[200:203], v[62:65]
	v_mfma_f32_16x16x32_bf16 v[54:57], v[176:179], v[200:203], v[54:57]
	v_mfma_f32_16x16x32_bf16 v[58:61], v[184:187], v[200:203], v[58:61]
	v_mfma_f32_16x16x32_bf16 v[50:53], v[192:195], v[200:203], v[50:53]
	v_mfma_f32_16x16x32_bf16 v[34:37], v[192:195], v[208:211], v[34:37]
	v_mfma_f32_16x16x32_bf16 v[42:45], v[184:187], v[208:211], v[42:45]
	v_mfma_f32_16x16x32_bf16 v[38:41], v[176:179], v[208:211], v[38:41]
	v_mfma_f32_16x16x32_bf16 v[46:49], v[168:171], v[208:211], v[46:49]
	v_mfma_f32_16x16x32_bf16 v[30:33], v[168:171], v[216:219], v[30:33]
	v_mfma_f32_16x16x32_bf16 v[22:25], v[176:179], v[216:219], v[22:25]
	v_mfma_f32_16x16x32_bf16 v[26:29], v[184:187], v[216:219], v[26:29]
	v_mfma_f32_16x16x32_bf16 v[18:21], v[192:195], v[216:219], v[18:21]
	v_mfma_f32_16x16x32_bf16 v[2:5], v[192:195], v[224:227], v[2:5]
	v_mfma_f32_16x16x32_bf16 v[10:13], v[184:187], v[224:227], v[10:13]
	v_mfma_f32_16x16x32_bf16 v[6:9], v[176:179], v[224:227], v[6:9]
	v_mfma_f32_16x16x32_bf16 v[14:17], v[168:171], v[224:227], v[14:17]
	s_barrier
	s_setprio 0
	s_add_u32 s98, s94, 0x40000
	s_addc_u32 s99, s95, 0
	s_add_i32 s7, 0, 0x18000
	s_add_i32 s49, 0, 0x1c000
	s_mov_b32 m0, s61
	ds_read_b128 v[164:167], v232
	global_load_lds_dwordx4 v130, s[98:99]
	s_mov_b32 m0, s62
	ds_read_b128 v[168:171], v232 offset:1024
	global_load_lds_dwordx4 v134, s[98:99]
	ds_read_b128 v[172:175], v232 offset:2048
	ds_read_b128 v[176:179], v232 offset:3072
	ds_read_b128 v[180:183], v233
	ds_read_b128 v[184:187], v233 offset:1024
	ds_read_b128 v[188:191], v233 offset:2048
	ds_read_b128 v[192:195], v233 offset:3072
	ds_read_b128 v[196:199], v160 offset:32768
	ds_read_b128 v[200:203], v160 offset:33792
	ds_read_b128 v[204:207], v160 offset:34816
	ds_read_b128 v[208:211], v160 offset:35840
	ds_read_b128 v[212:215], v160 offset:36864
	ds_read_b128 v[216:219], v160 offset:37888
	ds_read_b128 v[220:223], v160 offset:38912
	ds_read_b128 v[224:227], v160 offset:39936
	s_waitcnt vmcnt(8)
	s_waitcnt lgkmcnt(0)
	s_setprio 1
	s_barrier
	v_mfma_f32_16x16x32_bf16 v[122:125], v[164:167], v[196:199], v[122:125]
	v_mfma_f32_16x16x32_bf16 v[118:121], v[172:175], v[196:199], v[118:121]
	v_mfma_f32_16x16x32_bf16 v[126:129], v[180:183], v[196:199], v[126:129]
	v_mfma_f32_16x16x32_bf16 v[114:117], v[188:191], v[196:199], v[114:117]
	v_mfma_f32_16x16x32_bf16 v[98:101], v[188:191], v[204:207], v[98:101]
	v_mfma_f32_16x16x32_bf16 v[106:109], v[180:183], v[204:207], v[106:109]
	v_mfma_f32_16x16x32_bf16 v[102:105], v[172:175], v[204:207], v[102:105]
	v_mfma_f32_16x16x32_bf16 v[110:113], v[164:167], v[204:207], v[110:113]
	v_mfma_f32_16x16x32_bf16 v[94:97], v[164:167], v[212:215], v[94:97]
	v_mfma_f32_16x16x32_bf16 v[86:89], v[172:175], v[212:215], v[86:89]
	v_mfma_f32_16x16x32_bf16 v[90:93], v[180:183], v[212:215], v[90:93]
	v_mfma_f32_16x16x32_bf16 v[82:85], v[188:191], v[212:215], v[82:85]
	v_mfma_f32_16x16x32_bf16 v[66:69], v[188:191], v[220:223], v[66:69]
	v_mfma_f32_16x16x32_bf16 v[74:77], v[180:183], v[220:223], v[74:77]
	v_mfma_f32_16x16x32_bf16 v[70:73], v[172:175], v[220:223], v[70:73]
	v_mfma_f32_16x16x32_bf16 v[78:81], v[164:167], v[220:223], v[78:81]
	v_mfma_f32_16x16x32_bf16 v[122:125], v[168:171], v[200:203], v[122:125]
	v_mfma_f32_16x16x32_bf16 v[118:121], v[176:179], v[200:203], v[118:121]
	v_mfma_f32_16x16x32_bf16 v[126:129], v[184:187], v[200:203], v[126:129]
	v_mfma_f32_16x16x32_bf16 v[114:117], v[192:195], v[200:203], v[114:117]
	v_mfma_f32_16x16x32_bf16 v[98:101], v[192:195], v[208:211], v[98:101]
	v_mfma_f32_16x16x32_bf16 v[106:109], v[184:187], v[208:211], v[106:109]
	v_mfma_f32_16x16x32_bf16 v[102:105], v[176:179], v[208:211], v[102:105]
	v_mfma_f32_16x16x32_bf16 v[110:113], v[168:171], v[208:211], v[110:113]
	v_mfma_f32_16x16x32_bf16 v[94:97], v[168:171], v[216:219], v[94:97]
	v_mfma_f32_16x16x32_bf16 v[86:89], v[176:179], v[216:219], v[86:89]
	v_mfma_f32_16x16x32_bf16 v[90:93], v[184:187], v[216:219], v[90:93]
	v_mfma_f32_16x16x32_bf16 v[82:85], v[192:195], v[216:219], v[82:85]
	v_mfma_f32_16x16x32_bf16 v[66:69], v[192:195], v[224:227], v[66:69]
	v_mfma_f32_16x16x32_bf16 v[74:77], v[184:187], v[224:227], v[74:77]
	v_mfma_f32_16x16x32_bf16 v[70:73], v[176:179], v[224:227], v[70:73]
	v_mfma_f32_16x16x32_bf16 v[78:81], v[168:171], v[224:227], v[78:81]
	s_barrier
	s_setprio 0
	s_add_u32 s96, s96, 0x80
	s_addc_u32 s97, s97, 0
	s_add_u32 s98, s96, 0x40000
	s_addc_u32 s99, s97, 0
	s_add_u32 s94, s94, 0x80
	s_addc_u32 s95, s95, 0
	s_add_i32 s7, s7, s29
	s_mov_b32 m0, s7
	ds_read_b128 v[196:199], v160 offset:49152
	global_load_lds_dwordx4 v132, s[96:97]
	s_add_i32 m0, s7, 0x2000
	s_add_i32 s7, s49, s29
	global_load_lds_dwordx4 v136, s[96:97]
	s_mov_b32 m0, s7
	ds_read_b128 v[200:203], v160 offset:50176
	global_load_lds_dwordx4 v132, s[98:99]
	s_add_i32 m0, s7, 0x2000
	ds_read_b128 v[204:207], v160 offset:51200
	global_load_lds_dwordx4 v136, s[98:99]
	s_mov_b32 m0, s63
	ds_read_b128 v[208:211], v160 offset:52224
	global_load_lds_dwordx4 v130, s[94:95]
	s_mov_b32 m0, s64
	ds_read_b128 v[212:215], v160 offset:53248
	global_load_lds_dwordx4 v134, s[94:95]
	ds_read_b128 v[216:219], v160 offset:54272
	ds_read_b128 v[220:223], v160 offset:55296
	ds_read_b128 v[224:227], v160 offset:56320
	s_waitcnt vmcnt(8)
	s_waitcnt lgkmcnt(0)
	s_setprio 1
	s_barrier
	v_mfma_f32_16x16x32_bf16 v[62:65], v[164:167], v[196:199], v[62:65]
	v_mfma_f32_16x16x32_bf16 v[54:57], v[172:175], v[196:199], v[54:57]
	v_mfma_f32_16x16x32_bf16 v[58:61], v[180:183], v[196:199], v[58:61]
	v_mfma_f32_16x16x32_bf16 v[50:53], v[188:191], v[196:199], v[50:53]
	v_mfma_f32_16x16x32_bf16 v[34:37], v[188:191], v[204:207], v[34:37]
	v_mfma_f32_16x16x32_bf16 v[42:45], v[180:183], v[204:207], v[42:45]
	v_mfma_f32_16x16x32_bf16 v[38:41], v[172:175], v[204:207], v[38:41]
	v_mfma_f32_16x16x32_bf16 v[46:49], v[164:167], v[204:207], v[46:49]
	v_mfma_f32_16x16x32_bf16 v[30:33], v[164:167], v[212:215], v[30:33]
	v_mfma_f32_16x16x32_bf16 v[22:25], v[172:175], v[212:215], v[22:25]
	v_mfma_f32_16x16x32_bf16 v[26:29], v[180:183], v[212:215], v[26:29]
	v_mfma_f32_16x16x32_bf16 v[18:21], v[188:191], v[212:215], v[18:21]
	v_mfma_f32_16x16x32_bf16 v[2:5], v[188:191], v[220:223], v[2:5]
	v_mfma_f32_16x16x32_bf16 v[10:13], v[180:183], v[220:223], v[10:13]
	v_mfma_f32_16x16x32_bf16 v[6:9], v[172:175], v[220:223], v[6:9]
	v_mfma_f32_16x16x32_bf16 v[14:17], v[164:167], v[220:223], v[14:17]
	v_mfma_f32_16x16x32_bf16 v[62:65], v[168:171], v[200:203], v[62:65]
	v_mfma_f32_16x16x32_bf16 v[54:57], v[176:179], v[200:203], v[54:57]
	v_mfma_f32_16x16x32_bf16 v[58:61], v[184:187], v[200:203], v[58:61]
	v_mfma_f32_16x16x32_bf16 v[50:53], v[192:195], v[200:203], v[50:53]
	v_mfma_f32_16x16x32_bf16 v[34:37], v[192:195], v[208:211], v[34:37]
	v_mfma_f32_16x16x32_bf16 v[42:45], v[184:187], v[208:211], v[42:45]
	v_mfma_f32_16x16x32_bf16 v[38:41], v[176:179], v[208:211], v[38:41]
	v_mfma_f32_16x16x32_bf16 v[46:49], v[168:171], v[208:211], v[46:49]
	v_mfma_f32_16x16x32_bf16 v[30:33], v[168:171], v[216:219], v[30:33]
	v_mfma_f32_16x16x32_bf16 v[22:25], v[176:179], v[216:219], v[22:25]
	v_mfma_f32_16x16x32_bf16 v[26:29], v[184:187], v[216:219], v[26:29]
	v_mfma_f32_16x16x32_bf16 v[18:21], v[192:195], v[216:219], v[18:21]
	v_mfma_f32_16x16x32_bf16 v[2:5], v[192:195], v[224:227], v[2:5]
	v_mfma_f32_16x16x32_bf16 v[10:13], v[184:187], v[224:227], v[10:13]
	v_mfma_f32_16x16x32_bf16 v[6:9], v[176:179], v[224:227], v[6:9]
	v_mfma_f32_16x16x32_bf16 v[14:17], v[168:171], v[224:227], v[14:17]
	s_barrier
	s_setprio 0
	s_mov_b32 s7, s47
	s_add_u32 s88, s88, 0x100
	s_addc_u32 s89, s89, 0
	s_add_u32 s86, s86, 0x100
	s_addc_u32 s87, s87, 0
	s_cmp_ge_i32 s47, s101
	s_cbranch_scc1 .Lmy_kexit_4
.LBB0_949:
	s_add_u32 s98, s86, 0xfffc0080
	s_addc_u32 s99, s87, -1
	s_cmp_eq_u32 s7, s100
	s_cselect_b64 s[94:95], s[90:91], s[98:99]
	s_cselect_b64 s[96:97], s[92:93], s[88:89]
	s_add_i32 s47, s7, 2
	s_mov_b32 m0, s76
	ds_read_b128 v[164:167], v230
	global_load_lds_dwordx4 v144, s[86:87]
	s_mov_b32 m0, s77
	ds_read_b128 v[168:171], v230 offset:1024
	global_load_lds_dwordx4 v142, s[86:87]
	ds_read_b128 v[172:175], v230 offset:2048
	ds_read_b128 v[176:179], v230 offset:3072
	ds_read_b128 v[180:183], v231
	ds_read_b128 v[184:187], v231 offset:1024
	ds_read_b128 v[188:191], v231 offset:2048
	ds_read_b128 v[192:195], v231 offset:3072
	ds_read_b128 v[196:199], v160
	ds_read_b128 v[200:203], v160 offset:1024
	ds_read_b128 v[204:207], v160 offset:2048
	ds_read_b128 v[208:211], v160 offset:3072
	ds_read_b128 v[212:215], v160 offset:4096
	ds_read_b128 v[216:219], v160 offset:5120
	ds_read_b128 v[220:223], v160 offset:6144
	ds_read_b128 v[224:227], v160 offset:7168
	s_waitcnt vmcnt(8)
	s_waitcnt lgkmcnt(0)
	s_setprio 1
	s_barrier
	v_mfma_f32_16x16x32_bf16 v[122:125], v[164:167], v[196:199], v[122:125]
	v_mfma_f32_16x16x32_bf16 v[118:121], v[172:175], v[196:199], v[118:121]
	v_mfma_f32_16x16x32_bf16 v[126:129], v[180:183], v[196:199], v[126:129]
	v_mfma_f32_16x16x32_bf16 v[114:117], v[188:191], v[196:199], v[114:117]
	v_mfma_f32_16x16x32_bf16 v[98:101], v[188:191], v[204:207], v[98:101]
	v_mfma_f32_16x16x32_bf16 v[106:109], v[180:183], v[204:207], v[106:109]
	v_mfma_f32_16x16x32_bf16 v[102:105], v[172:175], v[204:207], v[102:105]
	v_mfma_f32_16x16x32_bf16 v[110:113], v[164:167], v[204:207], v[110:113]
	v_mfma_f32_16x16x32_bf16 v[94:97], v[164:167], v[212:215], v[94:97]
	v_mfma_f32_16x16x32_bf16 v[86:89], v[172:175], v[212:215], v[86:89]
	v_mfma_f32_16x16x32_bf16 v[90:93], v[180:183], v[212:215], v[90:93]
	v_mfma_f32_16x16x32_bf16 v[82:85], v[188:191], v[212:215], v[82:85]
	v_mfma_f32_16x16x32_bf16 v[66:69], v[188:191], v[220:223], v[66:69]
	v_mfma_f32_16x16x32_bf16 v[74:77], v[180:183], v[220:223], v[74:77]
	v_mfma_f32_16x16x32_bf16 v[70:73], v[172:175], v[220:223], v[70:73]
	v_mfma_f32_16x16x32_bf16 v[78:81], v[164:167], v[220:223], v[78:81]
	v_mfma_f32_16x16x32_bf16 v[122:125], v[168:171], v[200:203], v[122:125]
	v_mfma_f32_16x16x32_bf16 v[118:121], v[176:179], v[200:203], v[118:121]
	v_mfma_f32_16x16x32_bf16 v[126:129], v[184:187], v[200:203], v[126:129]
	v_mfma_f32_16x16x32_bf16 v[114:117], v[192:195], v[200:203], v[114:117]
	v_mfma_f32_16x16x32_bf16 v[98:101], v[192:195], v[208:211], v[98:101]
	v_mfma_f32_16x16x32_bf16 v[106:109], v[184:187], v[208:211], v[106:109]
	v_mfma_f32_16x16x32_bf16 v[102:105], v[176:179], v[208:211], v[102:105]
	v_mfma_f32_16x16x32_bf16 v[110:113], v[168:171], v[208:211], v[110:113]
	v_mfma_f32_16x16x32_bf16 v[94:97], v[168:171], v[216:219], v[94:97]
	v_mfma_f32_16x16x32_bf16 v[86:89], v[176:179], v[216:219], v[86:89]
	v_mfma_f32_16x16x32_bf16 v[90:93], v[184:187], v[216:219], v[90:93]
	v_mfma_f32_16x16x32_bf16 v[82:85], v[192:195], v[216:219], v[82:85]
	v_mfma_f32_16x16x32_bf16 v[66:69], v[192:195], v[224:227], v[66:69]
	v_mfma_f32_16x16x32_bf16 v[74:77], v[184:187], v[224:227], v[74:77]
	v_mfma_f32_16x16x32_bf16 v[70:73], v[176:179], v[224:227], v[70:73]
	v_mfma_f32_16x16x32_bf16 v[78:81], v[168:171], v[224:227], v[78:81]
	s_barrier
	s_setprio 0
	s_add_u32 s98, s96, 0x40000
	s_addc_u32 s99, s97, 0
	s_mov_b32 m0, s78
	ds_read_b128 v[196:199], v160 offset:16384
	global_load_lds_dwordx4 v132, s[96:97]
	s_mov_b32 m0, s79
	s_add_i32 s7, s75, s29
	global_load_lds_dwordx4 v136, s[96:97]
	s_mov_b32 m0, s7
	ds_read_b128 v[200:203], v160 offset:17408
	global_load_lds_dwordx4 v132, s[98:99]
	s_add_i32 m0, s7, 0x2000
	ds_read_b128 v[204:207], v160 offset:18432
	global_load_lds_dwordx4 v136, s[98:99]
	s_mov_b32 m0, s51
	ds_read_b128 v[208:211], v160 offset:19456
	global_load_lds_dwordx4 v130, s[94:95]
	s_mov_b32 m0, s60
	ds_read_b128 v[212:215], v160 offset:20480
	global_load_lds_dwordx4 v134, s[94:95]
	ds_read_b128 v[216:219], v160 offset:21504
	ds_read_b128 v[220:223], v160 offset:22528
	ds_read_b128 v[224:227], v160 offset:23552
	s_waitcnt vmcnt(8)
	s_waitcnt lgkmcnt(0)
	s_setprio 1
	s_barrier
	v_mfma_f32_16x16x32_bf16 v[62:65], v[164:167], v[196:199], v[62:65]
	v_mfma_f32_16x16x32_bf16 v[54:57], v[172:175], v[196:199], v[54:57]
	v_mfma_f32_16x16x32_bf16 v[58:61], v[180:183], v[196:199], v[58:61]
	v_mfma_f32_16x16x32_bf16 v[50:53], v[188:191], v[196:199], v[50:53]
	v_mfma_f32_16x16x32_bf16 v[34:37], v[188:191], v[204:207], v[34:37]
	v_mfma_f32_16x16x32_bf16 v[42:45], v[180:183], v[204:207], v[42:45]
	v_mfma_f32_16x16x32_bf16 v[38:41], v[172:175], v[204:207], v[38:41]
	v_mfma_f32_16x16x32_bf16 v[46:49], v[164:167], v[204:207], v[46:49]
	v_mfma_f32_16x16x32_bf16 v[30:33], v[164:167], v[212:215], v[30:33]
	v_mfma_f32_16x16x32_bf16 v[22:25], v[172:175], v[212:215], v[22:25]
	v_mfma_f32_16x16x32_bf16 v[26:29], v[180:183], v[212:215], v[26:29]
	v_mfma_f32_16x16x32_bf16 v[18:21], v[188:191], v[212:215], v[18:21]
	v_mfma_f32_16x16x32_bf16 v[2:5], v[188:191], v[220:223], v[2:5]
	v_mfma_f32_16x16x32_bf16 v[10:13], v[180:183], v[220:223], v[10:13]
	v_mfma_f32_16x16x32_bf16 v[6:9], v[172:175], v[220:223], v[6:9]
	v_mfma_f32_16x16x32_bf16 v[14:17], v[164:167], v[220:223], v[14:17]
	v_mfma_f32_16x16x32_bf16 v[62:65], v[168:171], v[200:203], v[62:65]
	v_mfma_f32_16x16x32_bf16 v[54:57], v[176:179], v[200:203], v[54:57]
	v_mfma_f32_16x16x32_bf16 v[58:61], v[184:187], v[200:203], v[58:61]
	v_mfma_f32_16x16x32_bf16 v[50:53], v[192:195], v[200:203], v[50:53]
	v_mfma_f32_16x16x32_bf16 v[34:37], v[192:195], v[208:211], v[34:37]
	v_mfma_f32_16x16x32_bf16 v[42:45], v[184:187], v[208:211], v[42:45]
	v_mfma_f32_16x16x32_bf16 v[38:41], v[176:179], v[208:211], v[38:41]
	v_mfma_f32_16x16x32_bf16 v[46:49], v[168:171], v[208:211], v[46:49]
	v_mfma_f32_16x16x32_bf16 v[30:33], v[168:171], v[216:219], v[30:33]
	v_mfma_f32_16x16x32_bf16 v[22:25], v[176:179], v[216:219], v[22:25]
	v_mfma_f32_16x16x32_bf16 v[26:29], v[184:187], v[216:219], v[26:29]
	v_mfma_f32_16x16x32_bf16 v[18:21], v[192:195], v[216:219], v[18:21]
	v_mfma_f32_16x16x32_bf16 v[2:5], v[192:195], v[224:227], v[2:5]
	v_mfma_f32_16x16x32_bf16 v[10:13], v[184:187], v[224:227], v[10:13]
	v_mfma_f32_16x16x32_bf16 v[6:9], v[176:179], v[224:227], v[6:9]
	v_mfma_f32_16x16x32_bf16 v[14:17], v[168:171], v[224:227], v[14:17]
	s_barrier
	s_setprio 0
	s_add_u32 s98, s94, 0x40000
	s_addc_u32 s99, s95, 0
	s_add_i32 s7, 0, 0x18000
	s_add_i32 s49, 0, 0x1c000
	s_mov_b32 m0, s61
	ds_read_b128 v[164:167], v232
	global_load_lds_dwordx4 v130, s[98:99]
	s_mov_b32 m0, s62
	ds_read_b128 v[168:171], v232 offset:1024
	global_load_lds_dwordx4 v134, s[98:99]
	ds_read_b128 v[172:175], v232 offset:2048
	ds_read_b128 v[176:179], v232 offset:3072
	ds_read_b128 v[180:183], v233
	ds_read_b128 v[184:187], v233 offset:1024
	ds_read_b128 v[188:191], v233 offset:2048
	ds_read_b128 v[192:195], v233 offset:3072
	ds_read_b128 v[196:199], v160 offset:32768
	ds_read_b128 v[200:203], v160 offset:33792
	ds_read_b128 v[204:207], v160 offset:34816
	ds_read_b128 v[208:211], v160 offset:35840
	ds_read_b128 v[212:215], v160 offset:36864
	ds_read_b128 v[216:219], v160 offset:37888
	ds_read_b128 v[220:223], v160 offset:38912
	ds_read_b128 v[224:227], v160 offset:39936
	s_waitcnt vmcnt(8)
	s_waitcnt lgkmcnt(0)
	s_setprio 1
	s_barrier
	v_mfma_f32_16x16x32_bf16 v[122:125], v[164:167], v[196:199], v[122:125]
	v_mfma_f32_16x16x32_bf16 v[118:121], v[172:175], v[196:199], v[118:121]
	v_mfma_f32_16x16x32_bf16 v[126:129], v[180:183], v[196:199], v[126:129]
	v_mfma_f32_16x16x32_bf16 v[114:117], v[188:191], v[196:199], v[114:117]
	v_mfma_f32_16x16x32_bf16 v[98:101], v[188:191], v[204:207], v[98:101]
	v_mfma_f32_16x16x32_bf16 v[106:109], v[180:183], v[204:207], v[106:109]
	v_mfma_f32_16x16x32_bf16 v[102:105], v[172:175], v[204:207], v[102:105]
	v_mfma_f32_16x16x32_bf16 v[110:113], v[164:167], v[204:207], v[110:113]
	v_mfma_f32_16x16x32_bf16 v[94:97], v[164:167], v[212:215], v[94:97]
	v_mfma_f32_16x16x32_bf16 v[86:89], v[172:175], v[212:215], v[86:89]
	v_mfma_f32_16x16x32_bf16 v[90:93], v[180:183], v[212:215], v[90:93]
	v_mfma_f32_16x16x32_bf16 v[82:85], v[188:191], v[212:215], v[82:85]
	v_mfma_f32_16x16x32_bf16 v[66:69], v[188:191], v[220:223], v[66:69]
	v_mfma_f32_16x16x32_bf16 v[74:77], v[180:183], v[220:223], v[74:77]
	v_mfma_f32_16x16x32_bf16 v[70:73], v[172:175], v[220:223], v[70:73]
	v_mfma_f32_16x16x32_bf16 v[78:81], v[164:167], v[220:223], v[78:81]
	v_mfma_f32_16x16x32_bf16 v[122:125], v[168:171], v[200:203], v[122:125]
	v_mfma_f32_16x16x32_bf16 v[118:121], v[176:179], v[200:203], v[118:121]
	v_mfma_f32_16x16x32_bf16 v[126:129], v[184:187], v[200:203], v[126:129]
	v_mfma_f32_16x16x32_bf16 v[114:117], v[192:195], v[200:203], v[114:117]
	v_mfma_f32_16x16x32_bf16 v[98:101], v[192:195], v[208:211], v[98:101]
	v_mfma_f32_16x16x32_bf16 v[106:109], v[184:187], v[208:211], v[106:109]
	v_mfma_f32_16x16x32_bf16 v[102:105], v[176:179], v[208:211], v[102:105]
	v_mfma_f32_16x16x32_bf16 v[110:113], v[168:171], v[208:211], v[110:113]
	v_mfma_f32_16x16x32_bf16 v[94:97], v[168:171], v[216:219], v[94:97]
	v_mfma_f32_16x16x32_bf16 v[86:89], v[176:179], v[216:219], v[86:89]
	v_mfma_f32_16x16x32_bf16 v[90:93], v[184:187], v[216:219], v[90:93]
	v_mfma_f32_16x16x32_bf16 v[82:85], v[192:195], v[216:219], v[82:85]
	v_mfma_f32_16x16x32_bf16 v[66:69], v[192:195], v[224:227], v[66:69]
	v_mfma_f32_16x16x32_bf16 v[74:77], v[184:187], v[224:227], v[74:77]
	v_mfma_f32_16x16x32_bf16 v[70:73], v[176:179], v[224:227], v[70:73]
	v_mfma_f32_16x16x32_bf16 v[78:81], v[168:171], v[224:227], v[78:81]
	s_barrier
	s_setprio 0
	s_add_u32 s96, s96, 0x80
	s_addc_u32 s97, s97, 0
	s_add_u32 s98, s96, 0x40000
	s_addc_u32 s99, s97, 0
	s_add_u32 s94, s94, 0x80
	s_addc_u32 s95, s95, 0
	s_add_i32 s7, s7, s29
	s_mov_b32 m0, s7
	ds_read_b128 v[196:199], v160 offset:49152
	global_load_lds_dwordx4 v132, s[96:97]
	s_add_i32 m0, s7, 0x2000
	s_add_i32 s7, s49, s29
	global_load_lds_dwordx4 v136, s[96:97]
	s_mov_b32 m0, s7
	ds_read_b128 v[200:203], v160 offset:50176
	global_load_lds_dwordx4 v132, s[98:99]
	s_add_i32 m0, s7, 0x2000
	ds_read_b128 v[204:207], v160 offset:51200
	global_load_lds_dwordx4 v136, s[98:99]
	s_mov_b32 m0, s63
	ds_read_b128 v[208:211], v160 offset:52224
	global_load_lds_dwordx4 v130, s[94:95]
	s_mov_b32 m0, s64
	ds_read_b128 v[212:215], v160 offset:53248
	global_load_lds_dwordx4 v134, s[94:95]
	ds_read_b128 v[216:219], v160 offset:54272
	ds_read_b128 v[220:223], v160 offset:55296
	ds_read_b128 v[224:227], v160 offset:56320
	s_waitcnt vmcnt(8)
	s_waitcnt lgkmcnt(0)
	s_setprio 1
	s_barrier
	v_mfma_f32_16x16x32_bf16 v[62:65], v[164:167], v[196:199], v[62:65]
	v_mfma_f32_16x16x32_bf16 v[54:57], v[172:175], v[196:199], v[54:57]
	v_mfma_f32_16x16x32_bf16 v[58:61], v[180:183], v[196:199], v[58:61]
	v_mfma_f32_16x16x32_bf16 v[50:53], v[188:191], v[196:199], v[50:53]
	v_mfma_f32_16x16x32_bf16 v[34:37], v[188:191], v[204:207], v[34:37]
	v_mfma_f32_16x16x32_bf16 v[42:45], v[180:183], v[204:207], v[42:45]
	v_mfma_f32_16x16x32_bf16 v[38:41], v[172:175], v[204:207], v[38:41]
	v_mfma_f32_16x16x32_bf16 v[46:49], v[164:167], v[204:207], v[46:49]
	v_mfma_f32_16x16x32_bf16 v[30:33], v[164:167], v[212:215], v[30:33]
	v_mfma_f32_16x16x32_bf16 v[22:25], v[172:175], v[212:215], v[22:25]
	v_mfma_f32_16x16x32_bf16 v[26:29], v[180:183], v[212:215], v[26:29]
	v_mfma_f32_16x16x32_bf16 v[18:21], v[188:191], v[212:215], v[18:21]
	v_mfma_f32_16x16x32_bf16 v[2:5], v[188:191], v[220:223], v[2:5]
	v_mfma_f32_16x16x32_bf16 v[10:13], v[180:183], v[220:223], v[10:13]
	v_mfma_f32_16x16x32_bf16 v[6:9], v[172:175], v[220:223], v[6:9]
	v_mfma_f32_16x16x32_bf16 v[14:17], v[164:167], v[220:223], v[14:17]
	v_mfma_f32_16x16x32_bf16 v[62:65], v[168:171], v[200:203], v[62:65]
	v_mfma_f32_16x16x32_bf16 v[54:57], v[176:179], v[200:203], v[54:57]
	v_mfma_f32_16x16x32_bf16 v[58:61], v[184:187], v[200:203], v[58:61]
	v_mfma_f32_16x16x32_bf16 v[50:53], v[192:195], v[200:203], v[50:53]
	v_mfma_f32_16x16x32_bf16 v[34:37], v[192:195], v[208:211], v[34:37]
	v_mfma_f32_16x16x32_bf16 v[42:45], v[184:187], v[208:211], v[42:45]
	v_mfma_f32_16x16x32_bf16 v[38:41], v[176:179], v[208:211], v[38:41]
	v_mfma_f32_16x16x32_bf16 v[46:49], v[168:171], v[208:211], v[46:49]
	v_mfma_f32_16x16x32_bf16 v[30:33], v[168:171], v[216:219], v[30:33]
	v_mfma_f32_16x16x32_bf16 v[22:25], v[176:179], v[216:219], v[22:25]
	v_mfma_f32_16x16x32_bf16 v[26:29], v[184:187], v[216:219], v[26:29]
	v_mfma_f32_16x16x32_bf16 v[18:21], v[192:195], v[216:219], v[18:21]
	v_mfma_f32_16x16x32_bf16 v[2:5], v[192:195], v[224:227], v[2:5]
	v_mfma_f32_16x16x32_bf16 v[10:13], v[184:187], v[224:227], v[10:13]
	v_mfma_f32_16x16x32_bf16 v[6:9], v[176:179], v[224:227], v[6:9]
	v_mfma_f32_16x16x32_bf16 v[14:17], v[168:171], v[224:227], v[14:17]
	s_barrier
	s_setprio 0
	s_mov_b32 s7, s47
	s_add_u32 s88, s88, 0x100
	s_addc_u32 s89, s89, 0
	s_add_u32 s86, s86, 0x100
	s_addc_u32 s87, s87, 0
	s_cmp_ge_i32 s47, s101
	s_cbranch_scc0 .LBB0_949

.Lmy_nb_5:
	s_nop 0
	v_readfirstlane_b32 s86, v150
	v_readfirstlane_b32 s87, v151
	v_readfirstlane_b32 s88, v152
	v_readfirstlane_b32 s89, v153
	v_readfirstlane_b32 s90, v146
	v_readfirstlane_b32 s91, v147
	v_readfirstlane_b32 s92, v148
	v_readfirstlane_b32 s93, v149
	v_readfirstlane_b32 s100, v138
	v_readfirstlane_b32 s101, v156
	v_add_u32_e32 v230, s67, v141
	v_add_u32_e32 v231, s68, v141
	v_add_u32_e32 v232, 0x18000, v141
	v_add_u32_e32 v233, 0x1c000, v141
	s_add_u32 s98, s86, 0x100
	s_addc_u32 s99, s87, 0
	s_cmp_eq_u32 s6, s100
	s_cselect_b64 s[94:95], s[90:91], s[98:99]
	s_cselect_b64 s[96:97], s[92:93], s[88:89]
	s_add_i32 s7, s6, 2
	s_add_i32 m0, s46, 0xc000
	ds_read_b128 v[164:167], v230
	global_load_lds_dwordx4 v144, s[86:87]
	s_add_i32 m0, s46, 0xe000
	ds_read_b128 v[168:171], v230 offset:1024
	global_load_lds_dwordx4 v142, s[86:87]
	ds_read_b128 v[172:175], v230 offset:2048
	ds_read_b128 v[176:179], v230 offset:3072
	ds_read_b128 v[180:183], v231
	ds_read_b128 v[184:187], v231 offset:1024
	ds_read_b128 v[188:191], v231 offset:2048
	ds_read_b128 v[192:195], v231 offset:3072
	ds_read_b128 v[196:199], v160
	ds_read_b128 v[200:203], v160 offset:1024
	ds_read_b128 v[204:207], v160 offset:2048
	ds_read_b128 v[208:211], v160 offset:3072
	ds_read_b128 v[212:215], v160 offset:4096
	ds_read_b128 v[216:219], v160 offset:5120
	ds_read_b128 v[220:223], v160 offset:6144
	ds_read_b128 v[224:227], v160 offset:7168
	s_waitcnt vmcnt(8)
	s_waitcnt lgkmcnt(0)
	s_setprio 1
	s_barrier
	v_mfma_f32_16x16x32_bf16 v[122:125], v[164:167], v[196:199], 0
	v_mfma_f32_16x16x32_bf16 v[118:121], v[172:175], v[196:199], 0
	v_mfma_f32_16x16x32_bf16 v[126:129], v[180:183], v[196:199], 0
	v_mfma_f32_16x16x32_bf16 v[114:117], v[188:191], v[196:199], 0
	v_mfma_f32_16x16x32_bf16 v[98:101], v[188:191], v[204:207], 0
	v_mfma_f32_16x16x32_bf16 v[106:109], v[180:183], v[204:207], 0
	v_mfma_f32_16x16x32_bf16 v[102:105], v[172:175], v[204:207], 0
	v_mfma_f32_16x16x32_bf16 v[110:113], v[164:167], v[204:207], 0
	v_mfma_f32_16x16x32_bf16 v[94:97], v[164:167], v[212:215], 0
	v_mfma_f32_16x16x32_bf16 v[86:89], v[172:175], v[212:215], 0
	v_mfma_f32_16x16x32_bf16 v[90:93], v[180:183], v[212:215], 0
	v_mfma_f32_16x16x32_bf16 v[82:85], v[188:191], v[212:215], 0
	v_mfma_f32_16x16x32_bf16 v[66:69], v[188:191], v[220:223], 0
	v_mfma_f32_16x16x32_bf16 v[74:77], v[180:183], v[220:223], 0
	v_mfma_f32_16x16x32_bf16 v[70:73], v[172:175], v[220:223], 0
	v_mfma_f32_16x16x32_bf16 v[78:81], v[164:167], v[220:223], 0
	v_mfma_f32_16x16x32_bf16 v[122:125], v[168:171], v[200:203], v[122:125]
	v_mfma_f32_16x16x32_bf16 v[118:121], v[176:179], v[200:203], v[118:121]
	v_mfma_f32_16x16x32_bf16 v[126:129], v[184:187], v[200:203], v[126:129]
	v_mfma_f32_16x16x32_bf16 v[114:117], v[192:195], v[200:203], v[114:117]
	v_mfma_f32_16x16x32_bf16 v[98:101], v[192:195], v[208:211], v[98:101]
	v_mfma_f32_16x16x32_bf16 v[106:109], v[184:187], v[208:211], v[106:109]
	v_mfma_f32_16x16x32_bf16 v[102:105], v[176:179], v[208:211], v[102:105]
	v_mfma_f32_16x16x32_bf16 v[110:113], v[168:171], v[208:211], v[110:113]
	v_mfma_f32_16x16x32_bf16 v[94:97], v[168:171], v[216:219], v[94:97]
	v_mfma_f32_16x16x32_bf16 v[86:89], v[176:179], v[216:219], v[86:89]
	v_mfma_f32_16x16x32_bf16 v[90:93], v[184:187], v[216:219], v[90:93]
	v_mfma_f32_16x16x32_bf16 v[82:85], v[192:195], v[216:219], v[82:85]
	v_mfma_f32_16x16x32_bf16 v[66:69], v[192:195], v[224:227], v[66:69]
	v_mfma_f32_16x16x32_bf16 v[74:77], v[184:187], v[224:227], v[74:77]
	v_mfma_f32_16x16x32_bf16 v[70:73], v[176:179], v[224:227], v[70:73]
	v_mfma_f32_16x16x32_bf16 v[78:81], v[168:171], v[224:227], v[78:81]
	s_barrier
	s_setprio 0
	s_add_u32 s98, s96, 0xb0000
	s_addc_u32 s99, s97, 0
	s_add_i32 s6, s67, s23
	s_mov_b32 m0, s6
	ds_read_b128 v[196:199], v160 offset:16384
	global_load_lds_dwordx4 v132, s[96:97]
	s_add_i32 m0, s6, 0x2000
	s_add_i32 s6, s68, s23
	global_load_lds_dwordx4 v136, s[96:97]
	s_mov_b32 m0, s6
	ds_read_b128 v[200:203], v160 offset:17408
	global_load_lds_dwordx4 v132, s[98:99]
	s_add_i32 m0, s6, 0x2000
	ds_read_b128 v[204:207], v160 offset:18432
	global_load_lds_dwordx4 v136, s[98:99]
	s_mov_b32 m0, s46
	ds_read_b128 v[208:211], v160 offset:19456
	global_load_lds_dwordx4 v130, s[94:95]
	s_mov_b32 m0, s47
	ds_read_b128 v[212:215], v160 offset:20480
	global_load_lds_dwordx4 v134, s[94:95]
	ds_read_b128 v[216:219], v160 offset:21504
	ds_read_b128 v[220:223], v160 offset:22528
	ds_read_b128 v[224:227], v160 offset:23552
	s_waitcnt vmcnt(8)
	s_waitcnt lgkmcnt(0)
	s_setprio 1
	s_barrier
	v_mfma_f32_16x16x32_bf16 v[62:65], v[164:167], v[196:199], 0
	v_mfma_f32_16x16x32_bf16 v[54:57], v[172:175], v[196:199], 0
	v_mfma_f32_16x16x32_bf16 v[58:61], v[180:183], v[196:199], 0
	v_mfma_f32_16x16x32_bf16 v[50:53], v[188:191], v[196:199], 0
	v_mfma_f32_16x16x32_bf16 v[34:37], v[188:191], v[204:207], 0
	v_mfma_f32_16x16x32_bf16 v[42:45], v[180:183], v[204:207], 0
	v_mfma_f32_16x16x32_bf16 v[38:41], v[172:175], v[204:207], 0
	v_mfma_f32_16x16x32_bf16 v[46:49], v[164:167], v[204:207], 0
	v_mfma_f32_16x16x32_bf16 v[30:33], v[164:167], v[212:215], 0
	v_mfma_f32_16x16x32_bf16 v[22:25], v[172:175], v[212:215], 0
	v_mfma_f32_16x16x32_bf16 v[26:29], v[180:183], v[212:215], 0
	v_mfma_f32_16x16x32_bf16 v[18:21], v[188:191], v[212:215], 0
	v_mfma_f32_16x16x32_bf16 v[2:5], v[188:191], v[220:223], 0
	v_mfma_f32_16x16x32_bf16 v[10:13], v[180:183], v[220:223], 0
	v_mfma_f32_16x16x32_bf16 v[6:9], v[172:175], v[220:223], 0
	v_mfma_f32_16x16x32_bf16 v[14:17], v[164:167], v[220:223], 0
	v_mfma_f32_16x16x32_bf16 v[62:65], v[168:171], v[200:203], v[62:65]
	v_mfma_f32_16x16x32_bf16 v[54:57], v[176:179], v[200:203], v[54:57]
	v_mfma_f32_16x16x32_bf16 v[58:61], v[184:187], v[200:203], v[58:61]
	v_mfma_f32_16x16x32_bf16 v[50:53], v[192:195], v[200:203], v[50:53]
	v_mfma_f32_16x16x32_bf16 v[34:37], v[192:195], v[208:211], v[34:37]
	v_mfma_f32_16x16x32_bf16 v[42:45], v[184:187], v[208:211], v[42:45]
	v_mfma_f32_16x16x32_bf16 v[38:41], v[176:179], v[208:211], v[38:41]
	v_mfma_f32_16x16x32_bf16 v[46:49], v[168:171], v[208:211], v[46:49]
	v_mfma_f32_16x16x32_bf16 v[30:33], v[168:171], v[216:219], v[30:33]
	v_mfma_f32_16x16x32_bf16 v[22:25], v[176:179], v[216:219], v[22:25]
	v_mfma_f32_16x16x32_bf16 v[26:29], v[184:187], v[216:219], v[26:29]
	v_mfma_f32_16x16x32_bf16 v[18:21], v[192:195], v[216:219], v[18:21]
	v_mfma_f32_16x16x32_bf16 v[2:5], v[192:195], v[224:227], v[2:5]
	v_mfma_f32_16x16x32_bf16 v[10:13], v[184:187], v[224:227], v[10:13]
	v_mfma_f32_16x16x32_bf16 v[6:9], v[176:179], v[224:227], v[6:9]
	v_mfma_f32_16x16x32_bf16 v[14:17], v[168:171], v[224:227], v[14:17]
	s_barrier
	s_setprio 0
	s_add_u32 s98, s94, 0xb0000
	s_addc_u32 s99, s95, 0
	s_add_i32 s6, 0, 0x18000
	s_add_i32 s29, 0, 0x1c000
	s_mov_b32 m0, s48
	ds_read_b128 v[164:167], v232
	global_load_lds_dwordx4 v130, s[98:99]
	s_mov_b32 m0, s49
	ds_read_b128 v[168:171], v232 offset:1024
	global_load_lds_dwordx4 v134, s[98:99]
	ds_read_b128 v[172:175], v232 offset:2048
	ds_read_b128 v[176:179], v232 offset:3072
	ds_read_b128 v[180:183], v233
	ds_read_b128 v[184:187], v233 offset:1024
	ds_read_b128 v[188:191], v233 offset:2048
	ds_read_b128 v[192:195], v233 offset:3072
	ds_read_b128 v[196:199], v160 offset:32768
	ds_read_b128 v[200:203], v160 offset:33792
	ds_read_b128 v[204:207], v160 offset:34816
	ds_read_b128 v[208:211], v160 offset:35840
	ds_read_b128 v[212:215], v160 offset:36864
	ds_read_b128 v[216:219], v160 offset:37888
	ds_read_b128 v[220:223], v160 offset:38912
	ds_read_b128 v[224:227], v160 offset:39936
	s_waitcnt vmcnt(8)
	s_waitcnt lgkmcnt(0)
	s_setprio 1
	s_barrier
	v_mfma_f32_16x16x32_bf16 v[122:125], v[164:167], v[196:199], v[122:125]
	v_mfma_f32_16x16x32_bf16 v[118:121], v[172:175], v[196:199], v[118:121]
	v_mfma_f32_16x16x32_bf16 v[126:129], v[180:183], v[196:199], v[126:129]
	v_mfma_f32_16x16x32_bf16 v[114:117], v[188:191], v[196:199], v[114:117]
	v_mfma_f32_16x16x32_bf16 v[98:101], v[188:191], v[204:207], v[98:101]
	v_mfma_f32_16x16x32_bf16 v[106:109], v[180:183], v[204:207], v[106:109]
	v_mfma_f32_16x16x32_bf16 v[102:105], v[172:175], v[204:207], v[102:105]
	v_mfma_f32_16x16x32_bf16 v[110:113], v[164:167], v[204:207], v[110:113]
	v_mfma_f32_16x16x32_bf16 v[94:97], v[164:167], v[212:215], v[94:97]
	v_mfma_f32_16x16x32_bf16 v[86:89], v[172:175], v[212:215], v[86:89]
	v_mfma_f32_16x16x32_bf16 v[90:93], v[180:183], v[212:215], v[90:93]
	v_mfma_f32_16x16x32_bf16 v[82:85], v[188:191], v[212:215], v[82:85]
	v_mfma_f32_16x16x32_bf16 v[66:69], v[188:191], v[220:223], v[66:69]
	v_mfma_f32_16x16x32_bf16 v[74:77], v[180:183], v[220:223], v[74:77]
	v_mfma_f32_16x16x32_bf16 v[70:73], v[172:175], v[220:223], v[70:73]
	v_mfma_f32_16x16x32_bf16 v[78:81], v[164:167], v[220:223], v[78:81]
	v_mfma_f32_16x16x32_bf16 v[122:125], v[168:171], v[200:203], v[122:125]
	v_mfma_f32_16x16x32_bf16 v[118:121], v[176:179], v[200:203], v[118:121]
	v_mfma_f32_16x16x32_bf16 v[126:129], v[184:187], v[200:203], v[126:129]
	v_mfma_f32_16x16x32_bf16 v[114:117], v[192:195], v[200:203], v[114:117]
	v_mfma_f32_16x16x32_bf16 v[98:101], v[192:195], v[208:211], v[98:101]
	v_mfma_f32_16x16x32_bf16 v[106:109], v[184:187], v[208:211], v[106:109]
	v_mfma_f32_16x16x32_bf16 v[102:105], v[176:179], v[208:211], v[102:105]
	v_mfma_f32_16x16x32_bf16 v[110:113], v[168:171], v[208:211], v[110:113]
	v_mfma_f32_16x16x32_bf16 v[94:97], v[168:171], v[216:219], v[94:97]
	v_mfma_f32_16x16x32_bf16 v[86:89], v[176:179], v[216:219], v[86:89]
	v_mfma_f32_16x16x32_bf16 v[90:93], v[184:187], v[216:219], v[90:93]
	v_mfma_f32_16x16x32_bf16 v[82:85], v[192:195], v[216:219], v[82:85]
	v_mfma_f32_16x16x32_bf16 v[66:69], v[192:195], v[224:227], v[66:69]
	v_mfma_f32_16x16x32_bf16 v[74:77], v[184:187], v[224:227], v[74:77]
	v_mfma_f32_16x16x32_bf16 v[70:73], v[176:179], v[224:227], v[70:73]
	v_mfma_f32_16x16x32_bf16 v[78:81], v[168:171], v[224:227], v[78:81]
	s_barrier
	s_setprio 0
	s_add_u32 s96, s96, 0x80
	s_addc_u32 s97, s97, 0
	s_add_u32 s98, s96, 0xb0000
	s_addc_u32 s99, s97, 0
	s_add_u32 s94, s94, 0x80
	s_addc_u32 s95, s95, 0
	s_add_i32 s6, s6, s23
	s_mov_b32 m0, s6
	ds_read_b128 v[196:199], v160 offset:49152
	global_load_lds_dwordx4 v132, s[96:97]
	s_add_i32 m0, s6, 0x2000
	s_add_i32 s6, s29, s23
	global_load_lds_dwordx4 v136, s[96:97]
	s_mov_b32 m0, s6
	ds_read_b128 v[200:203], v160 offset:50176
	global_load_lds_dwordx4 v132, s[98:99]
	s_add_i32 m0, s6, 0x2000
	ds_read_b128 v[204:207], v160 offset:51200
	global_load_lds_dwordx4 v136, s[98:99]
	s_mov_b32 m0, s59
	ds_read_b128 v[208:211], v160 offset:52224
	global_load_lds_dwordx4 v130, s[94:95]
	s_mov_b32 m0, s60
	ds_read_b128 v[212:215], v160 offset:53248
	global_load_lds_dwordx4 v134, s[94:95]
	ds_read_b128 v[216:219], v160 offset:54272
	ds_read_b128 v[220:223], v160 offset:55296
	ds_read_b128 v[224:227], v160 offset:56320
	s_waitcnt vmcnt(8)
	s_waitcnt lgkmcnt(0)
	s_setprio 1
	s_barrier
	v_mfma_f32_16x16x32_bf16 v[62:65], v[164:167], v[196:199], v[62:65]
	v_mfma_f32_16x16x32_bf16 v[54:57], v[172:175], v[196:199], v[54:57]
	v_mfma_f32_16x16x32_bf16 v[58:61], v[180:183], v[196:199], v[58:61]
	v_mfma_f32_16x16x32_bf16 v[50:53], v[188:191], v[196:199], v[50:53]
	v_mfma_f32_16x16x32_bf16 v[34:37], v[188:191], v[204:207], v[34:37]
	v_mfma_f32_16x16x32_bf16 v[42:45], v[180:183], v[204:207], v[42:45]
	v_mfma_f32_16x16x32_bf16 v[38:41], v[172:175], v[204:207], v[38:41]
	v_mfma_f32_16x16x32_bf16 v[46:49], v[164:167], v[204:207], v[46:49]
	v_mfma_f32_16x16x32_bf16 v[30:33], v[164:167], v[212:215], v[30:33]
	v_mfma_f32_16x16x32_bf16 v[22:25], v[172:175], v[212:215], v[22:25]
	v_mfma_f32_16x16x32_bf16 v[26:29], v[180:183], v[212:215], v[26:29]
	v_mfma_f32_16x16x32_bf16 v[18:21], v[188:191], v[212:215], v[18:21]
	v_mfma_f32_16x16x32_bf16 v[2:5], v[188:191], v[220:223], v[2:5]
	v_mfma_f32_16x16x32_bf16 v[10:13], v[180:183], v[220:223], v[10:13]
	v_mfma_f32_16x16x32_bf16 v[6:9], v[172:175], v[220:223], v[6:9]
	v_mfma_f32_16x16x32_bf16 v[14:17], v[164:167], v[220:223], v[14:17]
	v_mfma_f32_16x16x32_bf16 v[62:65], v[168:171], v[200:203], v[62:65]
	v_mfma_f32_16x16x32_bf16 v[54:57], v[176:179], v[200:203], v[54:57]
	v_mfma_f32_16x16x32_bf16 v[58:61], v[184:187], v[200:203], v[58:61]
	v_mfma_f32_16x16x32_bf16 v[50:53], v[192:195], v[200:203], v[50:53]
	v_mfma_f32_16x16x32_bf16 v[34:37], v[192:195], v[208:211], v[34:37]
	v_mfma_f32_16x16x32_bf16 v[42:45], v[184:187], v[208:211], v[42:45]
	v_mfma_f32_16x16x32_bf16 v[38:41], v[176:179], v[208:211], v[38:41]
	v_mfma_f32_16x16x32_bf16 v[46:49], v[168:171], v[208:211], v[46:49]
	v_mfma_f32_16x16x32_bf16 v[30:33], v[168:171], v[216:219], v[30:33]
	v_mfma_f32_16x16x32_bf16 v[22:25], v[176:179], v[216:219], v[22:25]
	v_mfma_f32_16x16x32_bf16 v[26:29], v[184:187], v[216:219], v[26:29]
	v_mfma_f32_16x16x32_bf16 v[18:21], v[192:195], v[216:219], v[18:21]
	v_mfma_f32_16x16x32_bf16 v[2:5], v[192:195], v[224:227], v[2:5]
	v_mfma_f32_16x16x32_bf16 v[10:13], v[184:187], v[224:227], v[10:13]
	v_mfma_f32_16x16x32_bf16 v[6:9], v[176:179], v[224:227], v[6:9]
	v_mfma_f32_16x16x32_bf16 v[14:17], v[168:171], v[224:227], v[14:17]
	s_barrier
	s_setprio 0
	s_mov_b32 s6, s7
	s_add_u32 s88, s88, 0x100
	s_addc_u32 s89, s89, 0
	s_add_u32 s86, s86, 0x100
	s_addc_u32 s87, s87, 0
	s_cmp_ge_i32 s7, s101
	s_cbranch_scc1 .Lmy_kexit_5
.LBB0_1080:
	s_add_u32 s98, s86, 0x100
	s_addc_u32 s99, s87, 0
	s_cmp_eq_u32 s6, s100
	s_cselect_b64 s[94:95], s[90:91], s[98:99]
	s_cselect_b64 s[96:97], s[92:93], s[88:89]
	s_add_i32 s7, s6, 2
	s_add_i32 m0, s46, 0xc000
	ds_read_b128 v[164:167], v230
	global_load_lds_dwordx4 v144, s[86:87]
	s_add_i32 m0, s46, 0xe000
	ds_read_b128 v[168:171], v230 offset:1024
	global_load_lds_dwordx4 v142, s[86:87]
	ds_read_b128 v[172:175], v230 offset:2048
	ds_read_b128 v[176:179], v230 offset:3072
	ds_read_b128 v[180:183], v231
	ds_read_b128 v[184:187], v231 offset:1024
	ds_read_b128 v[188:191], v231 offset:2048
	ds_read_b128 v[192:195], v231 offset:3072
	ds_read_b128 v[196:199], v160
	ds_read_b128 v[200:203], v160 offset:1024
	ds_read_b128 v[204:207], v160 offset:2048
	ds_read_b128 v[208:211], v160 offset:3072
	ds_read_b128 v[212:215], v160 offset:4096
	ds_read_b128 v[216:219], v160 offset:5120
	ds_read_b128 v[220:223], v160 offset:6144
	ds_read_b128 v[224:227], v160 offset:7168
	s_waitcnt vmcnt(8)
	s_waitcnt lgkmcnt(0)
	s_setprio 1
	s_barrier
	v_mfma_f32_16x16x32_bf16 v[122:125], v[164:167], v[196:199], v[122:125]
	v_mfma_f32_16x16x32_bf16 v[118:121], v[172:175], v[196:199], v[118:121]
	v_mfma_f32_16x16x32_bf16 v[126:129], v[180:183], v[196:199], v[126:129]
	v_mfma_f32_16x16x32_bf16 v[114:117], v[188:191], v[196:199], v[114:117]
	v_mfma_f32_16x16x32_bf16 v[98:101], v[188:191], v[204:207], v[98:101]
	v_mfma_f32_16x16x32_bf16 v[106:109], v[180:183], v[204:207], v[106:109]
	v_mfma_f32_16x16x32_bf16 v[102:105], v[172:175], v[204:207], v[102:105]
	v_mfma_f32_16x16x32_bf16 v[110:113], v[164:167], v[204:207], v[110:113]
	v_mfma_f32_16x16x32_bf16 v[94:97], v[164:167], v[212:215], v[94:97]
	v_mfma_f32_16x16x32_bf16 v[86:89], v[172:175], v[212:215], v[86:89]
	v_mfma_f32_16x16x32_bf16 v[90:93], v[180:183], v[212:215], v[90:93]
	v_mfma_f32_16x16x32_bf16 v[82:85], v[188:191], v[212:215], v[82:85]
	v_mfma_f32_16x16x32_bf16 v[66:69], v[188:191], v[220:223], v[66:69]
	v_mfma_f32_16x16x32_bf16 v[74:77], v[180:183], v[220:223], v[74:77]
	v_mfma_f32_16x16x32_bf16 v[70:73], v[172:175], v[220:223], v[70:73]
	v_mfma_f32_16x16x32_bf16 v[78:81], v[164:167], v[220:223], v[78:81]
	v_mfma_f32_16x16x32_bf16 v[122:125], v[168:171], v[200:203], v[122:125]
	v_mfma_f32_16x16x32_bf16 v[118:121], v[176:179], v[200:203], v[118:121]
	v_mfma_f32_16x16x32_bf16 v[126:129], v[184:187], v[200:203], v[126:129]
	v_mfma_f32_16x16x32_bf16 v[114:117], v[192:195], v[200:203], v[114:117]
	v_mfma_f32_16x16x32_bf16 v[98:101], v[192:195], v[208:211], v[98:101]
	v_mfma_f32_16x16x32_bf16 v[106:109], v[184:187], v[208:211], v[106:109]
	v_mfma_f32_16x16x32_bf16 v[102:105], v[176:179], v[208:211], v[102:105]
	v_mfma_f32_16x16x32_bf16 v[110:113], v[168:171], v[208:211], v[110:113]
	v_mfma_f32_16x16x32_bf16 v[94:97], v[168:171], v[216:219], v[94:97]
	v_mfma_f32_16x16x32_bf16 v[86:89], v[176:179], v[216:219], v[86:89]
	v_mfma_f32_16x16x32_bf16 v[90:93], v[184:187], v[216:219], v[90:93]
	v_mfma_f32_16x16x32_bf16 v[82:85], v[192:195], v[216:219], v[82:85]
	v_mfma_f32_16x16x32_bf16 v[66:69], v[192:195], v[224:227], v[66:69]
	v_mfma_f32_16x16x32_bf16 v[74:77], v[184:187], v[224:227], v[74:77]
	v_mfma_f32_16x16x32_bf16 v[70:73], v[176:179], v[224:227], v[70:73]
	v_mfma_f32_16x16x32_bf16 v[78:81], v[168:171], v[224:227], v[78:81]
	s_barrier
	s_setprio 0
	s_add_u32 s98, s96, 0xb0000
	s_addc_u32 s99, s97, 0
	s_add_i32 s6, s67, s23
	s_mov_b32 m0, s6
	ds_read_b128 v[196:199], v160 offset:16384
	global_load_lds_dwordx4 v132, s[96:97]
	s_add_i32 m0, s6, 0x2000
	s_add_i32 s6, s68, s23
	global_load_lds_dwordx4 v136, s[96:97]
	s_mov_b32 m0, s6
	ds_read_b128 v[200:203], v160 offset:17408
	global_load_lds_dwordx4 v132, s[98:99]
	s_add_i32 m0, s6, 0x2000
	ds_read_b128 v[204:207], v160 offset:18432
	global_load_lds_dwordx4 v136, s[98:99]
	s_mov_b32 m0, s46
	ds_read_b128 v[208:211], v160 offset:19456
	global_load_lds_dwordx4 v130, s[94:95]
	s_mov_b32 m0, s47
	ds_read_b128 v[212:215], v160 offset:20480
	global_load_lds_dwordx4 v134, s[94:95]
	ds_read_b128 v[216:219], v160 offset:21504
	ds_read_b128 v[220:223], v160 offset:22528
	ds_read_b128 v[224:227], v160 offset:23552
	s_waitcnt vmcnt(8)
	s_waitcnt lgkmcnt(0)
	s_setprio 1
	s_barrier
	v_mfma_f32_16x16x32_bf16 v[62:65], v[164:167], v[196:199], v[62:65]
	v_mfma_f32_16x16x32_bf16 v[54:57], v[172:175], v[196:199], v[54:57]
	v_mfma_f32_16x16x32_bf16 v[58:61], v[180:183], v[196:199], v[58:61]
	v_mfma_f32_16x16x32_bf16 v[50:53], v[188:191], v[196:199], v[50:53]
	v_mfma_f32_16x16x32_bf16 v[34:37], v[188:191], v[204:207], v[34:37]
	v_mfma_f32_16x16x32_bf16 v[42:45], v[180:183], v[204:207], v[42:45]
	v_mfma_f32_16x16x32_bf16 v[38:41], v[172:175], v[204:207], v[38:41]
	v_mfma_f32_16x16x32_bf16 v[46:49], v[164:167], v[204:207], v[46:49]
	v_mfma_f32_16x16x32_bf16 v[30:33], v[164:167], v[212:215], v[30:33]
	v_mfma_f32_16x16x32_bf16 v[22:25], v[172:175], v[212:215], v[22:25]
	v_mfma_f32_16x16x32_bf16 v[26:29], v[180:183], v[212:215], v[26:29]
	v_mfma_f32_16x16x32_bf16 v[18:21], v[188:191], v[212:215], v[18:21]
	v_mfma_f32_16x16x32_bf16 v[2:5], v[188:191], v[220:223], v[2:5]
	v_mfma_f32_16x16x32_bf16 v[10:13], v[180:183], v[220:223], v[10:13]
	v_mfma_f32_16x16x32_bf16 v[6:9], v[172:175], v[220:223], v[6:9]
	v_mfma_f32_16x16x32_bf16 v[14:17], v[164:167], v[220:223], v[14:17]
	v_mfma_f32_16x16x32_bf16 v[62:65], v[168:171], v[200:203], v[62:65]
	v_mfma_f32_16x16x32_bf16 v[54:57], v[176:179], v[200:203], v[54:57]
	v_mfma_f32_16x16x32_bf16 v[58:61], v[184:187], v[200:203], v[58:61]
	v_mfma_f32_16x16x32_bf16 v[50:53], v[192:195], v[200:203], v[50:53]
	v_mfma_f32_16x16x32_bf16 v[34:37], v[192:195], v[208:211], v[34:37]
	v_mfma_f32_16x16x32_bf16 v[42:45], v[184:187], v[208:211], v[42:45]
	v_mfma_f32_16x16x32_bf16 v[38:41], v[176:179], v[208:211], v[38:41]
	v_mfma_f32_16x16x32_bf16 v[46:49], v[168:171], v[208:211], v[46:49]
	v_mfma_f32_16x16x32_bf16 v[30:33], v[168:171], v[216:219], v[30:33]
	v_mfma_f32_16x16x32_bf16 v[22:25], v[176:179], v[216:219], v[22:25]
	v_mfma_f32_16x16x32_bf16 v[26:29], v[184:187], v[216:219], v[26:29]
	v_mfma_f32_16x16x32_bf16 v[18:21], v[192:195], v[216:219], v[18:21]
	v_mfma_f32_16x16x32_bf16 v[2:5], v[192:195], v[224:227], v[2:5]
	v_mfma_f32_16x16x32_bf16 v[10:13], v[184:187], v[224:227], v[10:13]
	v_mfma_f32_16x16x32_bf16 v[6:9], v[176:179], v[224:227], v[6:9]
	v_mfma_f32_16x16x32_bf16 v[14:17], v[168:171], v[224:227], v[14:17]
	s_barrier
	s_setprio 0
	s_add_u32 s98, s94, 0xb0000
	s_addc_u32 s99, s95, 0
	s_add_i32 s6, 0, 0x18000
	s_add_i32 s29, 0, 0x1c000
	s_mov_b32 m0, s48
	ds_read_b128 v[164:167], v232
	global_load_lds_dwordx4 v130, s[98:99]
	s_mov_b32 m0, s49
	ds_read_b128 v[168:171], v232 offset:1024
	global_load_lds_dwordx4 v134, s[98:99]
	ds_read_b128 v[172:175], v232 offset:2048
	ds_read_b128 v[176:179], v232 offset:3072
	ds_read_b128 v[180:183], v233
	ds_read_b128 v[184:187], v233 offset:1024
	ds_read_b128 v[188:191], v233 offset:2048
	ds_read_b128 v[192:195], v233 offset:3072
	ds_read_b128 v[196:199], v160 offset:32768
	ds_read_b128 v[200:203], v160 offset:33792
	ds_read_b128 v[204:207], v160 offset:34816
	ds_read_b128 v[208:211], v160 offset:35840
	ds_read_b128 v[212:215], v160 offset:36864
	ds_read_b128 v[216:219], v160 offset:37888
	ds_read_b128 v[220:223], v160 offset:38912
	ds_read_b128 v[224:227], v160 offset:39936
	s_waitcnt vmcnt(8)
	s_waitcnt lgkmcnt(0)
	s_setprio 1
	s_barrier
	v_mfma_f32_16x16x32_bf16 v[122:125], v[164:167], v[196:199], v[122:125]
	v_mfma_f32_16x16x32_bf16 v[118:121], v[172:175], v[196:199], v[118:121]
	v_mfma_f32_16x16x32_bf16 v[126:129], v[180:183], v[196:199], v[126:129]
	v_mfma_f32_16x16x32_bf16 v[114:117], v[188:191], v[196:199], v[114:117]
	v_mfma_f32_16x16x32_bf16 v[98:101], v[188:191], v[204:207], v[98:101]
	v_mfma_f32_16x16x32_bf16 v[106:109], v[180:183], v[204:207], v[106:109]
	v_mfma_f32_16x16x32_bf16 v[102:105], v[172:175], v[204:207], v[102:105]
	v_mfma_f32_16x16x32_bf16 v[110:113], v[164:167], v[204:207], v[110:113]
	v_mfma_f32_16x16x32_bf16 v[94:97], v[164:167], v[212:215], v[94:97]
	v_mfma_f32_16x16x32_bf16 v[86:89], v[172:175], v[212:215], v[86:89]
	v_mfma_f32_16x16x32_bf16 v[90:93], v[180:183], v[212:215], v[90:93]
	v_mfma_f32_16x16x32_bf16 v[82:85], v[188:191], v[212:215], v[82:85]
	v_mfma_f32_16x16x32_bf16 v[66:69], v[188:191], v[220:223], v[66:69]
	v_mfma_f32_16x16x32_bf16 v[74:77], v[180:183], v[220:223], v[74:77]
	v_mfma_f32_16x16x32_bf16 v[70:73], v[172:175], v[220:223], v[70:73]
	v_mfma_f32_16x16x32_bf16 v[78:81], v[164:167], v[220:223], v[78:81]
	v_mfma_f32_16x16x32_bf16 v[122:125], v[168:171], v[200:203], v[122:125]
	v_mfma_f32_16x16x32_bf16 v[118:121], v[176:179], v[200:203], v[118:121]
	v_mfma_f32_16x16x32_bf16 v[126:129], v[184:187], v[200:203], v[126:129]
	v_mfma_f32_16x16x32_bf16 v[114:117], v[192:195], v[200:203], v[114:117]
	v_mfma_f32_16x16x32_bf16 v[98:101], v[192:195], v[208:211], v[98:101]
	v_mfma_f32_16x16x32_bf16 v[106:109], v[184:187], v[208:211], v[106:109]
	v_mfma_f32_16x16x32_bf16 v[102:105], v[176:179], v[208:211], v[102:105]
	v_mfma_f32_16x16x32_bf16 v[110:113], v[168:171], v[208:211], v[110:113]
	v_mfma_f32_16x16x32_bf16 v[94:97], v[168:171], v[216:219], v[94:97]
	v_mfma_f32_16x16x32_bf16 v[86:89], v[176:179], v[216:219], v[86:89]
	v_mfma_f32_16x16x32_bf16 v[90:93], v[184:187], v[216:219], v[90:93]
	v_mfma_f32_16x16x32_bf16 v[82:85], v[192:195], v[216:219], v[82:85]
	v_mfma_f32_16x16x32_bf16 v[66:69], v[192:195], v[224:227], v[66:69]
	v_mfma_f32_16x16x32_bf16 v[74:77], v[184:187], v[224:227], v[74:77]
	v_mfma_f32_16x16x32_bf16 v[70:73], v[176:179], v[224:227], v[70:73]
	v_mfma_f32_16x16x32_bf16 v[78:81], v[168:171], v[224:227], v[78:81]
	s_barrier
	s_setprio 0
	s_add_u32 s96, s96, 0x80
	s_addc_u32 s97, s97, 0
	s_add_u32 s98, s96, 0xb0000
	s_addc_u32 s99, s97, 0
	s_add_u32 s94, s94, 0x80
	s_addc_u32 s95, s95, 0
	s_add_i32 s6, s6, s23
	s_mov_b32 m0, s6
	ds_read_b128 v[196:199], v160 offset:49152
	global_load_lds_dwordx4 v132, s[96:97]
	s_add_i32 m0, s6, 0x2000
	s_add_i32 s6, s29, s23
	global_load_lds_dwordx4 v136, s[96:97]
	s_mov_b32 m0, s6
	ds_read_b128 v[200:203], v160 offset:50176
	global_load_lds_dwordx4 v132, s[98:99]
	s_add_i32 m0, s6, 0x2000
	ds_read_b128 v[204:207], v160 offset:51200
	global_load_lds_dwordx4 v136, s[98:99]
	s_mov_b32 m0, s59
	ds_read_b128 v[208:211], v160 offset:52224
	global_load_lds_dwordx4 v130, s[94:95]
	s_mov_b32 m0, s60
	ds_read_b128 v[212:215], v160 offset:53248
	global_load_lds_dwordx4 v134, s[94:95]
	ds_read_b128 v[216:219], v160 offset:54272
	ds_read_b128 v[220:223], v160 offset:55296
	ds_read_b128 v[224:227], v160 offset:56320
	s_waitcnt vmcnt(8)
	s_waitcnt lgkmcnt(0)
	s_setprio 1
	s_barrier
	v_mfma_f32_16x16x32_bf16 v[62:65], v[164:167], v[196:199], v[62:65]
	v_mfma_f32_16x16x32_bf16 v[54:57], v[172:175], v[196:199], v[54:57]
	v_mfma_f32_16x16x32_bf16 v[58:61], v[180:183], v[196:199], v[58:61]
	v_mfma_f32_16x16x32_bf16 v[50:53], v[188:191], v[196:199], v[50:53]
	v_mfma_f32_16x16x32_bf16 v[34:37], v[188:191], v[204:207], v[34:37]
	v_mfma_f32_16x16x32_bf16 v[42:45], v[180:183], v[204:207], v[42:45]
	v_mfma_f32_16x16x32_bf16 v[38:41], v[172:175], v[204:207], v[38:41]
	v_mfma_f32_16x16x32_bf16 v[46:49], v[164:167], v[204:207], v[46:49]
	v_mfma_f32_16x16x32_bf16 v[30:33], v[164:167], v[212:215], v[30:33]
	v_mfma_f32_16x16x32_bf16 v[22:25], v[172:175], v[212:215], v[22:25]
	v_mfma_f32_16x16x32_bf16 v[26:29], v[180:183], v[212:215], v[26:29]
	v_mfma_f32_16x16x32_bf16 v[18:21], v[188:191], v[212:215], v[18:21]
	v_mfma_f32_16x16x32_bf16 v[2:5], v[188:191], v[220:223], v[2:5]
	v_mfma_f32_16x16x32_bf16 v[10:13], v[180:183], v[220:223], v[10:13]
	v_mfma_f32_16x16x32_bf16 v[6:9], v[172:175], v[220:223], v[6:9]
	v_mfma_f32_16x16x32_bf16 v[14:17], v[164:167], v[220:223], v[14:17]
	v_mfma_f32_16x16x32_bf16 v[62:65], v[168:171], v[200:203], v[62:65]
	v_mfma_f32_16x16x32_bf16 v[54:57], v[176:179], v[200:203], v[54:57]
	v_mfma_f32_16x16x32_bf16 v[58:61], v[184:187], v[200:203], v[58:61]
	v_mfma_f32_16x16x32_bf16 v[50:53], v[192:195], v[200:203], v[50:53]
	v_mfma_f32_16x16x32_bf16 v[34:37], v[192:195], v[208:211], v[34:37]
	v_mfma_f32_16x16x32_bf16 v[42:45], v[184:187], v[208:211], v[42:45]
	v_mfma_f32_16x16x32_bf16 v[38:41], v[176:179], v[208:211], v[38:41]
	v_mfma_f32_16x16x32_bf16 v[46:49], v[168:171], v[208:211], v[46:49]
	v_mfma_f32_16x16x32_bf16 v[30:33], v[168:171], v[216:219], v[30:33]
	v_mfma_f32_16x16x32_bf16 v[22:25], v[176:179], v[216:219], v[22:25]
	v_mfma_f32_16x16x32_bf16 v[26:29], v[184:187], v[216:219], v[26:29]
	v_mfma_f32_16x16x32_bf16 v[18:21], v[192:195], v[216:219], v[18:21]
	v_mfma_f32_16x16x32_bf16 v[2:5], v[192:195], v[224:227], v[2:5]
	v_mfma_f32_16x16x32_bf16 v[10:13], v[184:187], v[224:227], v[10:13]
	v_mfma_f32_16x16x32_bf16 v[6:9], v[176:179], v[224:227], v[6:9]
	v_mfma_f32_16x16x32_bf16 v[14:17], v[168:171], v[224:227], v[14:17]
	s_barrier
	s_setprio 0
	s_mov_b32 s6, s7
	s_add_u32 s88, s88, 0x100
	s_addc_u32 s89, s89, 0
	s_add_u32 s86, s86, 0x100
	s_addc_u32 s87, s87, 0
	s_cmp_ge_i32 s7, s101
	s_cbranch_scc0 .LBB0_1080

.Lmy_nb_7:
	s_nop 0
	v_readfirstlane_b32 s86, v150
	v_readfirstlane_b32 s87, v151
	v_readfirstlane_b32 s88, v152
	v_readfirstlane_b32 s89, v153
	v_readfirstlane_b32 s90, v146
	v_readfirstlane_b32 s91, v147
	v_readfirstlane_b32 s92, v148
	v_readfirstlane_b32 s93, v149
	v_readfirstlane_b32 s100, v138
	v_readfirstlane_b32 s101, v156
	v_add_u32_e32 v230, s67, v141
	v_add_u32_e32 v231, s70, v141
	v_add_u32_e32 v232, 0x18000, v141
	v_add_u32_e32 v233, 0x1c000, v141
	s_add_u32 s98, s86, 0x100
	s_addc_u32 s99, s87, 0
	s_cmp_eq_u32 s6, s100
	s_cselect_b64 s[94:95], s[90:91], s[98:99]
	s_cselect_b64 s[96:97], s[92:93], s[88:89]
	s_add_i32 s7, s6, 2
	s_add_i32 m0, s46, 0xc000
	ds_read_b128 v[164:167], v230
	global_load_lds_dwordx4 v144, s[86:87]
	s_add_i32 m0, s46, 0xe000
	ds_read_b128 v[168:171], v230 offset:1024
	global_load_lds_dwordx4 v142, s[86:87]
	ds_read_b128 v[172:175], v230 offset:2048
	ds_read_b128 v[176:179], v230 offset:3072
	ds_read_b128 v[180:183], v231
	ds_read_b128 v[184:187], v231 offset:1024
	ds_read_b128 v[188:191], v231 offset:2048
	ds_read_b128 v[192:195], v231 offset:3072
	ds_read_b128 v[196:199], v160
	ds_read_b128 v[200:203], v160 offset:1024
	ds_read_b128 v[204:207], v160 offset:2048
	ds_read_b128 v[208:211], v160 offset:3072
	ds_read_b128 v[212:215], v160 offset:4096
	ds_read_b128 v[216:219], v160 offset:5120
	ds_read_b128 v[220:223], v160 offset:6144
	ds_read_b128 v[224:227], v160 offset:7168
	s_waitcnt vmcnt(8)
	s_waitcnt lgkmcnt(0)
	s_setprio 1
	s_barrier
	v_mfma_f32_16x16x32_bf16 v[122:125], v[164:167], v[196:199], 0
	v_mfma_f32_16x16x32_bf16 v[118:121], v[172:175], v[196:199], 0
	v_mfma_f32_16x16x32_bf16 v[126:129], v[180:183], v[196:199], 0
	v_mfma_f32_16x16x32_bf16 v[114:117], v[188:191], v[196:199], 0
	v_mfma_f32_16x16x32_bf16 v[98:101], v[188:191], v[204:207], 0
	v_mfma_f32_16x16x32_bf16 v[106:109], v[180:183], v[204:207], 0
	v_mfma_f32_16x16x32_bf16 v[102:105], v[172:175], v[204:207], 0
	v_mfma_f32_16x16x32_bf16 v[110:113], v[164:167], v[204:207], 0
	v_mfma_f32_16x16x32_bf16 v[94:97], v[164:167], v[212:215], 0
	v_mfma_f32_16x16x32_bf16 v[86:89], v[172:175], v[212:215], 0
	v_mfma_f32_16x16x32_bf16 v[90:93], v[180:183], v[212:215], 0
	v_mfma_f32_16x16x32_bf16 v[82:85], v[188:191], v[212:215], 0
	v_mfma_f32_16x16x32_bf16 v[66:69], v[188:191], v[220:223], 0
	v_mfma_f32_16x16x32_bf16 v[74:77], v[180:183], v[220:223], 0
	v_mfma_f32_16x16x32_bf16 v[70:73], v[172:175], v[220:223], 0
	v_mfma_f32_16x16x32_bf16 v[78:81], v[164:167], v[220:223], 0
	v_mfma_f32_16x16x32_bf16 v[122:125], v[168:171], v[200:203], v[122:125]
	v_mfma_f32_16x16x32_bf16 v[118:121], v[176:179], v[200:203], v[118:121]
	v_mfma_f32_16x16x32_bf16 v[126:129], v[184:187], v[200:203], v[126:129]
	v_mfma_f32_16x16x32_bf16 v[114:117], v[192:195], v[200:203], v[114:117]
	v_mfma_f32_16x16x32_bf16 v[98:101], v[192:195], v[208:211], v[98:101]
	v_mfma_f32_16x16x32_bf16 v[106:109], v[184:187], v[208:211], v[106:109]
	v_mfma_f32_16x16x32_bf16 v[102:105], v[176:179], v[208:211], v[102:105]
	v_mfma_f32_16x16x32_bf16 v[110:113], v[168:171], v[208:211], v[110:113]
	v_mfma_f32_16x16x32_bf16 v[94:97], v[168:171], v[216:219], v[94:97]
	v_mfma_f32_16x16x32_bf16 v[86:89], v[176:179], v[216:219], v[86:89]
	v_mfma_f32_16x16x32_bf16 v[90:93], v[184:187], v[216:219], v[90:93]
	v_mfma_f32_16x16x32_bf16 v[82:85], v[192:195], v[216:219], v[82:85]
	v_mfma_f32_16x16x32_bf16 v[66:69], v[192:195], v[224:227], v[66:69]
	v_mfma_f32_16x16x32_bf16 v[74:77], v[184:187], v[224:227], v[74:77]
	v_mfma_f32_16x16x32_bf16 v[70:73], v[176:179], v[224:227], v[70:73]
	v_mfma_f32_16x16x32_bf16 v[78:81], v[168:171], v[224:227], v[78:81]
	s_barrier
	s_setprio 0
	s_add_u32 s98, s96, 0xb0000
	s_addc_u32 s99, s97, 0
	s_add_i32 s6, s67, s23
	s_mov_b32 m0, s6
	ds_read_b128 v[196:199], v160 offset:16384
	global_load_lds_dwordx4 v132, s[96:97]
	s_add_i32 m0, s6, 0x2000
	s_add_i32 s6, s70, s23
	global_load_lds_dwordx4 v136, s[96:97]
	s_mov_b32 m0, s6
	ds_read_b128 v[200:203], v160 offset:17408
	global_load_lds_dwordx4 v132, s[98:99]
	s_add_i32 m0, s6, 0x2000
	ds_read_b128 v[204:207], v160 offset:18432
	global_load_lds_dwordx4 v136, s[98:99]
	s_mov_b32 m0, s46
	ds_read_b128 v[208:211], v160 offset:19456
	global_load_lds_dwordx4 v130, s[94:95]
	s_mov_b32 m0, s47
	ds_read_b128 v[212:215], v160 offset:20480
	global_load_lds_dwordx4 v134, s[94:95]
	ds_read_b128 v[216:219], v160 offset:21504
	ds_read_b128 v[220:223], v160 offset:22528
	ds_read_b128 v[224:227], v160 offset:23552
	s_waitcnt vmcnt(8)
	s_waitcnt lgkmcnt(0)
	s_setprio 1
	s_barrier
	v_mfma_f32_16x16x32_bf16 v[62:65], v[164:167], v[196:199], 0
	v_mfma_f32_16x16x32_bf16 v[54:57], v[172:175], v[196:199], 0
	v_mfma_f32_16x16x32_bf16 v[58:61], v[180:183], v[196:199], 0
	v_mfma_f32_16x16x32_bf16 v[50:53], v[188:191], v[196:199], 0
	v_mfma_f32_16x16x32_bf16 v[34:37], v[188:191], v[204:207], 0
	v_mfma_f32_16x16x32_bf16 v[42:45], v[180:183], v[204:207], 0
	v_mfma_f32_16x16x32_bf16 v[38:41], v[172:175], v[204:207], 0
	v_mfma_f32_16x16x32_bf16 v[46:49], v[164:167], v[204:207], 0
	v_mfma_f32_16x16x32_bf16 v[30:33], v[164:167], v[212:215], 0
	v_mfma_f32_16x16x32_bf16 v[22:25], v[172:175], v[212:215], 0
	v_mfma_f32_16x16x32_bf16 v[26:29], v[180:183], v[212:215], 0
	v_mfma_f32_16x16x32_bf16 v[18:21], v[188:191], v[212:215], 0
	v_mfma_f32_16x16x32_bf16 v[2:5], v[188:191], v[220:223], 0
	v_mfma_f32_16x16x32_bf16 v[10:13], v[180:183], v[220:223], 0
	v_mfma_f32_16x16x32_bf16 v[6:9], v[172:175], v[220:223], 0
	v_mfma_f32_16x16x32_bf16 v[14:17], v[164:167], v[220:223], 0
	v_mfma_f32_16x16x32_bf16 v[62:65], v[168:171], v[200:203], v[62:65]
	v_mfma_f32_16x16x32_bf16 v[54:57], v[176:179], v[200:203], v[54:57]
	v_mfma_f32_16x16x32_bf16 v[58:61], v[184:187], v[200:203], v[58:61]
	v_mfma_f32_16x16x32_bf16 v[50:53], v[192:195], v[200:203], v[50:53]
	v_mfma_f32_16x16x32_bf16 v[34:37], v[192:195], v[208:211], v[34:37]
	v_mfma_f32_16x16x32_bf16 v[42:45], v[184:187], v[208:211], v[42:45]
	v_mfma_f32_16x16x32_bf16 v[38:41], v[176:179], v[208:211], v[38:41]
	v_mfma_f32_16x16x32_bf16 v[46:49], v[168:171], v[208:211], v[46:49]
	v_mfma_f32_16x16x32_bf16 v[30:33], v[168:171], v[216:219], v[30:33]
	v_mfma_f32_16x16x32_bf16 v[22:25], v[176:179], v[216:219], v[22:25]
	v_mfma_f32_16x16x32_bf16 v[26:29], v[184:187], v[216:219], v[26:29]
	v_mfma_f32_16x16x32_bf16 v[18:21], v[192:195], v[216:219], v[18:21]
	v_mfma_f32_16x16x32_bf16 v[2:5], v[192:195], v[224:227], v[2:5]
	v_mfma_f32_16x16x32_bf16 v[10:13], v[184:187], v[224:227], v[10:13]
	v_mfma_f32_16x16x32_bf16 v[6:9], v[176:179], v[224:227], v[6:9]
	v_mfma_f32_16x16x32_bf16 v[14:17], v[168:171], v[224:227], v[14:17]
	s_barrier
	s_setprio 0
	s_add_u32 s98, s94, 0xb0000
	s_addc_u32 s99, s95, 0
	s_add_i32 s6, 0, 0x18000
	s_add_i32 s29, 0, 0x1c000
	s_mov_b32 m0, s48
	ds_read_b128 v[164:167], v232
	global_load_lds_dwordx4 v130, s[98:99]
	s_mov_b32 m0, s49
	ds_read_b128 v[168:171], v232 offset:1024
	global_load_lds_dwordx4 v134, s[98:99]
	ds_read_b128 v[172:175], v232 offset:2048
	ds_read_b128 v[176:179], v232 offset:3072
	ds_read_b128 v[180:183], v233
	ds_read_b128 v[184:187], v233 offset:1024
	ds_read_b128 v[188:191], v233 offset:2048
	ds_read_b128 v[192:195], v233 offset:3072
	ds_read_b128 v[196:199], v160 offset:32768
	ds_read_b128 v[200:203], v160 offset:33792
	ds_read_b128 v[204:207], v160 offset:34816
	ds_read_b128 v[208:211], v160 offset:35840
	ds_read_b128 v[212:215], v160 offset:36864
	ds_read_b128 v[216:219], v160 offset:37888
	ds_read_b128 v[220:223], v160 offset:38912
	ds_read_b128 v[224:227], v160 offset:39936
	s_waitcnt vmcnt(8)
	s_waitcnt lgkmcnt(0)
	s_setprio 1
	s_barrier
	v_mfma_f32_16x16x32_bf16 v[122:125], v[164:167], v[196:199], v[122:125]
	v_mfma_f32_16x16x32_bf16 v[118:121], v[172:175], v[196:199], v[118:121]
	v_mfma_f32_16x16x32_bf16 v[126:129], v[180:183], v[196:199], v[126:129]
	v_mfma_f32_16x16x32_bf16 v[114:117], v[188:191], v[196:199], v[114:117]
	v_mfma_f32_16x16x32_bf16 v[98:101], v[188:191], v[204:207], v[98:101]
	v_mfma_f32_16x16x32_bf16 v[106:109], v[180:183], v[204:207], v[106:109]
	v_mfma_f32_16x16x32_bf16 v[102:105], v[172:175], v[204:207], v[102:105]
	v_mfma_f32_16x16x32_bf16 v[110:113], v[164:167], v[204:207], v[110:113]
	v_mfma_f32_16x16x32_bf16 v[94:97], v[164:167], v[212:215], v[94:97]
	v_mfma_f32_16x16x32_bf16 v[86:89], v[172:175], v[212:215], v[86:89]
	v_mfma_f32_16x16x32_bf16 v[90:93], v[180:183], v[212:215], v[90:93]
	v_mfma_f32_16x16x32_bf16 v[82:85], v[188:191], v[212:215], v[82:85]
	v_mfma_f32_16x16x32_bf16 v[66:69], v[188:191], v[220:223], v[66:69]
	v_mfma_f32_16x16x32_bf16 v[74:77], v[180:183], v[220:223], v[74:77]
	v_mfma_f32_16x16x32_bf16 v[70:73], v[172:175], v[220:223], v[70:73]
	v_mfma_f32_16x16x32_bf16 v[78:81], v[164:167], v[220:223], v[78:81]
	v_mfma_f32_16x16x32_bf16 v[122:125], v[168:171], v[200:203], v[122:125]
	v_mfma_f32_16x16x32_bf16 v[118:121], v[176:179], v[200:203], v[118:121]
	v_mfma_f32_16x16x32_bf16 v[126:129], v[184:187], v[200:203], v[126:129]
	v_mfma_f32_16x16x32_bf16 v[114:117], v[192:195], v[200:203], v[114:117]
	v_mfma_f32_16x16x32_bf16 v[98:101], v[192:195], v[208:211], v[98:101]
	v_mfma_f32_16x16x32_bf16 v[106:109], v[184:187], v[208:211], v[106:109]
	v_mfma_f32_16x16x32_bf16 v[102:105], v[176:179], v[208:211], v[102:105]
	v_mfma_f32_16x16x32_bf16 v[110:113], v[168:171], v[208:211], v[110:113]
	v_mfma_f32_16x16x32_bf16 v[94:97], v[168:171], v[216:219], v[94:97]
	v_mfma_f32_16x16x32_bf16 v[86:89], v[176:179], v[216:219], v[86:89]
	v_mfma_f32_16x16x32_bf16 v[90:93], v[184:187], v[216:219], v[90:93]
	v_mfma_f32_16x16x32_bf16 v[82:85], v[192:195], v[216:219], v[82:85]
	v_mfma_f32_16x16x32_bf16 v[66:69], v[192:195], v[224:227], v[66:69]
	v_mfma_f32_16x16x32_bf16 v[74:77], v[184:187], v[224:227], v[74:77]
	v_mfma_f32_16x16x32_bf16 v[70:73], v[176:179], v[224:227], v[70:73]
	v_mfma_f32_16x16x32_bf16 v[78:81], v[168:171], v[224:227], v[78:81]
	s_barrier
	s_setprio 0
	s_add_u32 s96, s96, 0x80
	s_addc_u32 s97, s97, 0
	s_add_u32 s98, s96, 0xb0000
	s_addc_u32 s99, s97, 0
	s_add_u32 s94, s94, 0x80
	s_addc_u32 s95, s95, 0
	s_add_i32 s6, s6, s23
	s_mov_b32 m0, s6
	ds_read_b128 v[196:199], v160 offset:49152
	global_load_lds_dwordx4 v132, s[96:97]
	s_add_i32 m0, s6, 0x2000
	s_add_i32 s6, s29, s23
	global_load_lds_dwordx4 v136, s[96:97]
	s_mov_b32 m0, s6
	ds_read_b128 v[200:203], v160 offset:50176
	global_load_lds_dwordx4 v132, s[98:99]
	s_add_i32 m0, s6, 0x2000
	ds_read_b128 v[204:207], v160 offset:51200
	global_load_lds_dwordx4 v136, s[98:99]
	s_mov_b32 m0, s59
	ds_read_b128 v[208:211], v160 offset:52224
	global_load_lds_dwordx4 v130, s[94:95]
	s_mov_b32 m0, s60
	ds_read_b128 v[212:215], v160 offset:53248
	global_load_lds_dwordx4 v134, s[94:95]
	ds_read_b128 v[216:219], v160 offset:54272
	ds_read_b128 v[220:223], v160 offset:55296
	ds_read_b128 v[224:227], v160 offset:56320
	s_waitcnt vmcnt(8)
	s_waitcnt lgkmcnt(0)
	s_setprio 1
	s_barrier
	v_mfma_f32_16x16x32_bf16 v[62:65], v[164:167], v[196:199], v[62:65]
	v_mfma_f32_16x16x32_bf16 v[54:57], v[172:175], v[196:199], v[54:57]
	v_mfma_f32_16x16x32_bf16 v[58:61], v[180:183], v[196:199], v[58:61]
	v_mfma_f32_16x16x32_bf16 v[50:53], v[188:191], v[196:199], v[50:53]
	v_mfma_f32_16x16x32_bf16 v[34:37], v[188:191], v[204:207], v[34:37]
	v_mfma_f32_16x16x32_bf16 v[42:45], v[180:183], v[204:207], v[42:45]
	v_mfma_f32_16x16x32_bf16 v[38:41], v[172:175], v[204:207], v[38:41]
	v_mfma_f32_16x16x32_bf16 v[46:49], v[164:167], v[204:207], v[46:49]
	v_mfma_f32_16x16x32_bf16 v[30:33], v[164:167], v[212:215], v[30:33]
	v_mfma_f32_16x16x32_bf16 v[22:25], v[172:175], v[212:215], v[22:25]
	v_mfma_f32_16x16x32_bf16 v[26:29], v[180:183], v[212:215], v[26:29]
	v_mfma_f32_16x16x32_bf16 v[18:21], v[188:191], v[212:215], v[18:21]
	v_mfma_f32_16x16x32_bf16 v[2:5], v[188:191], v[220:223], v[2:5]
	v_mfma_f32_16x16x32_bf16 v[10:13], v[180:183], v[220:223], v[10:13]
	v_mfma_f32_16x16x32_bf16 v[6:9], v[172:175], v[220:223], v[6:9]
	v_mfma_f32_16x16x32_bf16 v[14:17], v[164:167], v[220:223], v[14:17]
	v_mfma_f32_16x16x32_bf16 v[62:65], v[168:171], v[200:203], v[62:65]
	v_mfma_f32_16x16x32_bf16 v[54:57], v[176:179], v[200:203], v[54:57]
	v_mfma_f32_16x16x32_bf16 v[58:61], v[184:187], v[200:203], v[58:61]
	v_mfma_f32_16x16x32_bf16 v[50:53], v[192:195], v[200:203], v[50:53]
	v_mfma_f32_16x16x32_bf16 v[34:37], v[192:195], v[208:211], v[34:37]
	v_mfma_f32_16x16x32_bf16 v[42:45], v[184:187], v[208:211], v[42:45]
	v_mfma_f32_16x16x32_bf16 v[38:41], v[176:179], v[208:211], v[38:41]
	v_mfma_f32_16x16x32_bf16 v[46:49], v[168:171], v[208:211], v[46:49]
	v_mfma_f32_16x16x32_bf16 v[30:33], v[168:171], v[216:219], v[30:33]
	v_mfma_f32_16x16x32_bf16 v[22:25], v[176:179], v[216:219], v[22:25]
	v_mfma_f32_16x16x32_bf16 v[26:29], v[184:187], v[216:219], v[26:29]
	v_mfma_f32_16x16x32_bf16 v[18:21], v[192:195], v[216:219], v[18:21]
	v_mfma_f32_16x16x32_bf16 v[2:5], v[192:195], v[224:227], v[2:5]
	v_mfma_f32_16x16x32_bf16 v[10:13], v[184:187], v[224:227], v[10:13]
	v_mfma_f32_16x16x32_bf16 v[6:9], v[176:179], v[224:227], v[6:9]
	v_mfma_f32_16x16x32_bf16 v[14:17], v[168:171], v[224:227], v[14:17]
	s_barrier
	s_setprio 0
	s_mov_b32 s6, s7
	s_add_u32 s88, s88, 0x100
	s_addc_u32 s89, s89, 0
	s_add_u32 s86, s86, 0x100
	s_addc_u32 s87, s87, 0
	s_cmp_ge_i32 s7, s101
	s_cbranch_scc1 .Lmy_kexit_7
.LBB0_1392:
	s_add_u32 s98, s86, 0x100
	s_addc_u32 s99, s87, 0
	s_cmp_eq_u32 s6, s100
	s_cselect_b64 s[94:95], s[90:91], s[98:99]
	s_cselect_b64 s[96:97], s[92:93], s[88:89]
	s_add_i32 s7, s6, 2
	s_add_i32 m0, s46, 0xc000
	ds_read_b128 v[164:167], v230
	global_load_lds_dwordx4 v144, s[86:87]
	s_add_i32 m0, s46, 0xe000
	ds_read_b128 v[168:171], v230 offset:1024
	global_load_lds_dwordx4 v142, s[86:87]
	ds_read_b128 v[172:175], v230 offset:2048
	ds_read_b128 v[176:179], v230 offset:3072
	ds_read_b128 v[180:183], v231
	ds_read_b128 v[184:187], v231 offset:1024
	ds_read_b128 v[188:191], v231 offset:2048
	ds_read_b128 v[192:195], v231 offset:3072
	ds_read_b128 v[196:199], v160
	ds_read_b128 v[200:203], v160 offset:1024
	ds_read_b128 v[204:207], v160 offset:2048
	ds_read_b128 v[208:211], v160 offset:3072
	ds_read_b128 v[212:215], v160 offset:4096
	ds_read_b128 v[216:219], v160 offset:5120
	ds_read_b128 v[220:223], v160 offset:6144
	ds_read_b128 v[224:227], v160 offset:7168
	s_waitcnt vmcnt(8)
	s_waitcnt lgkmcnt(0)
	s_setprio 1
	s_barrier
	v_mfma_f32_16x16x32_bf16 v[122:125], v[164:167], v[196:199], v[122:125]
	v_mfma_f32_16x16x32_bf16 v[118:121], v[172:175], v[196:199], v[118:121]
	v_mfma_f32_16x16x32_bf16 v[126:129], v[180:183], v[196:199], v[126:129]
	v_mfma_f32_16x16x32_bf16 v[114:117], v[188:191], v[196:199], v[114:117]
	v_mfma_f32_16x16x32_bf16 v[98:101], v[188:191], v[204:207], v[98:101]
	v_mfma_f32_16x16x32_bf16 v[106:109], v[180:183], v[204:207], v[106:109]
	v_mfma_f32_16x16x32_bf16 v[102:105], v[172:175], v[204:207], v[102:105]
	v_mfma_f32_16x16x32_bf16 v[110:113], v[164:167], v[204:207], v[110:113]
	v_mfma_f32_16x16x32_bf16 v[94:97], v[164:167], v[212:215], v[94:97]
	v_mfma_f32_16x16x32_bf16 v[86:89], v[172:175], v[212:215], v[86:89]
	v_mfma_f32_16x16x32_bf16 v[90:93], v[180:183], v[212:215], v[90:93]
	v_mfma_f32_16x16x32_bf16 v[82:85], v[188:191], v[212:215], v[82:85]
	v_mfma_f32_16x16x32_bf16 v[66:69], v[188:191], v[220:223], v[66:69]
	v_mfma_f32_16x16x32_bf16 v[74:77], v[180:183], v[220:223], v[74:77]
	v_mfma_f32_16x16x32_bf16 v[70:73], v[172:175], v[220:223], v[70:73]
	v_mfma_f32_16x16x32_bf16 v[78:81], v[164:167], v[220:223], v[78:81]
	v_mfma_f32_16x16x32_bf16 v[122:125], v[168:171], v[200:203], v[122:125]
	v_mfma_f32_16x16x32_bf16 v[118:121], v[176:179], v[200:203], v[118:121]
	v_mfma_f32_16x16x32_bf16 v[126:129], v[184:187], v[200:203], v[126:129]
	v_mfma_f32_16x16x32_bf16 v[114:117], v[192:195], v[200:203], v[114:117]
	v_mfma_f32_16x16x32_bf16 v[98:101], v[192:195], v[208:211], v[98:101]
	v_mfma_f32_16x16x32_bf16 v[106:109], v[184:187], v[208:211], v[106:109]
	v_mfma_f32_16x16x32_bf16 v[102:105], v[176:179], v[208:211], v[102:105]
	v_mfma_f32_16x16x32_bf16 v[110:113], v[168:171], v[208:211], v[110:113]
	v_mfma_f32_16x16x32_bf16 v[94:97], v[168:171], v[216:219], v[94:97]
	v_mfma_f32_16x16x32_bf16 v[86:89], v[176:179], v[216:219], v[86:89]
	v_mfma_f32_16x16x32_bf16 v[90:93], v[184:187], v[216:219], v[90:93]
	v_mfma_f32_16x16x32_bf16 v[82:85], v[192:195], v[216:219], v[82:85]
	v_mfma_f32_16x16x32_bf16 v[66:69], v[192:195], v[224:227], v[66:69]
	v_mfma_f32_16x16x32_bf16 v[74:77], v[184:187], v[224:227], v[74:77]
	v_mfma_f32_16x16x32_bf16 v[70:73], v[176:179], v[224:227], v[70:73]
	v_mfma_f32_16x16x32_bf16 v[78:81], v[168:171], v[224:227], v[78:81]
	s_barrier
	s_setprio 0
	s_add_u32 s98, s96, 0xb0000
	s_addc_u32 s99, s97, 0
	s_add_i32 s6, s67, s23
	s_mov_b32 m0, s6
	ds_read_b128 v[196:199], v160 offset:16384
	global_load_lds_dwordx4 v132, s[96:97]
	s_add_i32 m0, s6, 0x2000
	s_add_i32 s6, s70, s23
	global_load_lds_dwordx4 v136, s[96:97]
	s_mov_b32 m0, s6
	ds_read_b128 v[200:203], v160 offset:17408
	global_load_lds_dwordx4 v132, s[98:99]
	s_add_i32 m0, s6, 0x2000
	ds_read_b128 v[204:207], v160 offset:18432
	global_load_lds_dwordx4 v136, s[98:99]
	s_mov_b32 m0, s46
	ds_read_b128 v[208:211], v160 offset:19456
	global_load_lds_dwordx4 v130, s[94:95]
	s_mov_b32 m0, s47
	ds_read_b128 v[212:215], v160 offset:20480
	global_load_lds_dwordx4 v134, s[94:95]
	ds_read_b128 v[216:219], v160 offset:21504
	ds_read_b128 v[220:223], v160 offset:22528
	ds_read_b128 v[224:227], v160 offset:23552
	s_waitcnt vmcnt(8)
	s_waitcnt lgkmcnt(0)
	s_setprio 1
	s_barrier
	v_mfma_f32_16x16x32_bf16 v[62:65], v[164:167], v[196:199], v[62:65]
	v_mfma_f32_16x16x32_bf16 v[54:57], v[172:175], v[196:199], v[54:57]
	v_mfma_f32_16x16x32_bf16 v[58:61], v[180:183], v[196:199], v[58:61]
	v_mfma_f32_16x16x32_bf16 v[50:53], v[188:191], v[196:199], v[50:53]
	v_mfma_f32_16x16x32_bf16 v[34:37], v[188:191], v[204:207], v[34:37]
	v_mfma_f32_16x16x32_bf16 v[42:45], v[180:183], v[204:207], v[42:45]
	v_mfma_f32_16x16x32_bf16 v[38:41], v[172:175], v[204:207], v[38:41]
	v_mfma_f32_16x16x32_bf16 v[46:49], v[164:167], v[204:207], v[46:49]
	v_mfma_f32_16x16x32_bf16 v[30:33], v[164:167], v[212:215], v[30:33]
	v_mfma_f32_16x16x32_bf16 v[22:25], v[172:175], v[212:215], v[22:25]
	v_mfma_f32_16x16x32_bf16 v[26:29], v[180:183], v[212:215], v[26:29]
	v_mfma_f32_16x16x32_bf16 v[18:21], v[188:191], v[212:215], v[18:21]
	v_mfma_f32_16x16x32_bf16 v[2:5], v[188:191], v[220:223], v[2:5]
	v_mfma_f32_16x16x32_bf16 v[10:13], v[180:183], v[220:223], v[10:13]
	v_mfma_f32_16x16x32_bf16 v[6:9], v[172:175], v[220:223], v[6:9]
	v_mfma_f32_16x16x32_bf16 v[14:17], v[164:167], v[220:223], v[14:17]
	v_mfma_f32_16x16x32_bf16 v[62:65], v[168:171], v[200:203], v[62:65]
	v_mfma_f32_16x16x32_bf16 v[54:57], v[176:179], v[200:203], v[54:57]
	v_mfma_f32_16x16x32_bf16 v[58:61], v[184:187], v[200:203], v[58:61]
	v_mfma_f32_16x16x32_bf16 v[50:53], v[192:195], v[200:203], v[50:53]
	v_mfma_f32_16x16x32_bf16 v[34:37], v[192:195], v[208:211], v[34:37]
	v_mfma_f32_16x16x32_bf16 v[42:45], v[184:187], v[208:211], v[42:45]
	v_mfma_f32_16x16x32_bf16 v[38:41], v[176:179], v[208:211], v[38:41]
	v_mfma_f32_16x16x32_bf16 v[46:49], v[168:171], v[208:211], v[46:49]
	v_mfma_f32_16x16x32_bf16 v[30:33], v[168:171], v[216:219], v[30:33]
	v_mfma_f32_16x16x32_bf16 v[22:25], v[176:179], v[216:219], v[22:25]
	v_mfma_f32_16x16x32_bf16 v[26:29], v[184:187], v[216:219], v[26:29]
	v_mfma_f32_16x16x32_bf16 v[18:21], v[192:195], v[216:219], v[18:21]
	v_mfma_f32_16x16x32_bf16 v[2:5], v[192:195], v[224:227], v[2:5]
	v_mfma_f32_16x16x32_bf16 v[10:13], v[184:187], v[224:227], v[10:13]
	v_mfma_f32_16x16x32_bf16 v[6:9], v[176:179], v[224:227], v[6:9]
	v_mfma_f32_16x16x32_bf16 v[14:17], v[168:171], v[224:227], v[14:17]
	s_barrier
	s_setprio 0
	s_add_u32 s98, s94, 0xb0000
	s_addc_u32 s99, s95, 0
	s_add_i32 s6, 0, 0x18000
	s_add_i32 s29, 0, 0x1c000
	s_mov_b32 m0, s48
	ds_read_b128 v[164:167], v232
	global_load_lds_dwordx4 v130, s[98:99]
	s_mov_b32 m0, s49
	ds_read_b128 v[168:171], v232 offset:1024
	global_load_lds_dwordx4 v134, s[98:99]
	ds_read_b128 v[172:175], v232 offset:2048
	ds_read_b128 v[176:179], v232 offset:3072
	ds_read_b128 v[180:183], v233
	ds_read_b128 v[184:187], v233 offset:1024
	ds_read_b128 v[188:191], v233 offset:2048
	ds_read_b128 v[192:195], v233 offset:3072
	ds_read_b128 v[196:199], v160 offset:32768
	ds_read_b128 v[200:203], v160 offset:33792
	ds_read_b128 v[204:207], v160 offset:34816
	ds_read_b128 v[208:211], v160 offset:35840
	ds_read_b128 v[212:215], v160 offset:36864
	ds_read_b128 v[216:219], v160 offset:37888
	ds_read_b128 v[220:223], v160 offset:38912
	ds_read_b128 v[224:227], v160 offset:39936
	s_waitcnt vmcnt(8)
	s_waitcnt lgkmcnt(0)
	s_setprio 1
	s_barrier
	v_mfma_f32_16x16x32_bf16 v[122:125], v[164:167], v[196:199], v[122:125]
	v_mfma_f32_16x16x32_bf16 v[118:121], v[172:175], v[196:199], v[118:121]
	v_mfma_f32_16x16x32_bf16 v[126:129], v[180:183], v[196:199], v[126:129]
	v_mfma_f32_16x16x32_bf16 v[114:117], v[188:191], v[196:199], v[114:117]
	v_mfma_f32_16x16x32_bf16 v[98:101], v[188:191], v[204:207], v[98:101]
	v_mfma_f32_16x16x32_bf16 v[106:109], v[180:183], v[204:207], v[106:109]
	v_mfma_f32_16x16x32_bf16 v[102:105], v[172:175], v[204:207], v[102:105]
	v_mfma_f32_16x16x32_bf16 v[110:113], v[164:167], v[204:207], v[110:113]
	v_mfma_f32_16x16x32_bf16 v[94:97], v[164:167], v[212:215], v[94:97]
	v_mfma_f32_16x16x32_bf16 v[86:89], v[172:175], v[212:215], v[86:89]
	v_mfma_f32_16x16x32_bf16 v[90:93], v[180:183], v[212:215], v[90:93]
	v_mfma_f32_16x16x32_bf16 v[82:85], v[188:191], v[212:215], v[82:85]
	v_mfma_f32_16x16x32_bf16 v[66:69], v[188:191], v[220:223], v[66:69]
	v_mfma_f32_16x16x32_bf16 v[74:77], v[180:183], v[220:223], v[74:77]
	v_mfma_f32_16x16x32_bf16 v[70:73], v[172:175], v[220:223], v[70:73]
	v_mfma_f32_16x16x32_bf16 v[78:81], v[164:167], v[220:223], v[78:81]
	v_mfma_f32_16x16x32_bf16 v[122:125], v[168:171], v[200:203], v[122:125]
	v_mfma_f32_16x16x32_bf16 v[118:121], v[176:179], v[200:203], v[118:121]
	v_mfma_f32_16x16x32_bf16 v[126:129], v[184:187], v[200:203], v[126:129]
	v_mfma_f32_16x16x32_bf16 v[114:117], v[192:195], v[200:203], v[114:117]
	v_mfma_f32_16x16x32_bf16 v[98:101], v[192:195], v[208:211], v[98:101]
	v_mfma_f32_16x16x32_bf16 v[106:109], v[184:187], v[208:211], v[106:109]
	v_mfma_f32_16x16x32_bf16 v[102:105], v[176:179], v[208:211], v[102:105]
	v_mfma_f32_16x16x32_bf16 v[110:113], v[168:171], v[208:211], v[110:113]
	v_mfma_f32_16x16x32_bf16 v[94:97], v[168:171], v[216:219], v[94:97]
	v_mfma_f32_16x16x32_bf16 v[86:89], v[176:179], v[216:219], v[86:89]
	v_mfma_f32_16x16x32_bf16 v[90:93], v[184:187], v[216:219], v[90:93]
	v_mfma_f32_16x16x32_bf16 v[82:85], v[192:195], v[216:219], v[82:85]
	v_mfma_f32_16x16x32_bf16 v[66:69], v[192:195], v[224:227], v[66:69]
	v_mfma_f32_16x16x32_bf16 v[74:77], v[184:187], v[224:227], v[74:77]
	v_mfma_f32_16x16x32_bf16 v[70:73], v[176:179], v[224:227], v[70:73]
	v_mfma_f32_16x16x32_bf16 v[78:81], v[168:171], v[224:227], v[78:81]
	s_barrier
	s_setprio 0
	s_add_u32 s96, s96, 0x80
	s_addc_u32 s97, s97, 0
	s_add_u32 s98, s96, 0xb0000
	s_addc_u32 s99, s97, 0
	s_add_u32 s94, s94, 0x80
	s_addc_u32 s95, s95, 0
	s_add_i32 s6, s6, s23
	s_mov_b32 m0, s6
	ds_read_b128 v[196:199], v160 offset:49152
	global_load_lds_dwordx4 v132, s[96:97]
	s_add_i32 m0, s6, 0x2000
	s_add_i32 s6, s29, s23
	global_load_lds_dwordx4 v136, s[96:97]
	s_mov_b32 m0, s6
	ds_read_b128 v[200:203], v160 offset:50176
	global_load_lds_dwordx4 v132, s[98:99]
	s_add_i32 m0, s6, 0x2000
	ds_read_b128 v[204:207], v160 offset:51200
	global_load_lds_dwordx4 v136, s[98:99]
	s_mov_b32 m0, s59
	ds_read_b128 v[208:211], v160 offset:52224
	global_load_lds_dwordx4 v130, s[94:95]
	s_mov_b32 m0, s60
	ds_read_b128 v[212:215], v160 offset:53248
	global_load_lds_dwordx4 v134, s[94:95]
	ds_read_b128 v[216:219], v160 offset:54272
	ds_read_b128 v[220:223], v160 offset:55296
	ds_read_b128 v[224:227], v160 offset:56320
	s_waitcnt vmcnt(8)
	s_waitcnt lgkmcnt(0)
	s_setprio 1
	s_barrier
	v_mfma_f32_16x16x32_bf16 v[62:65], v[164:167], v[196:199], v[62:65]
	v_mfma_f32_16x16x32_bf16 v[54:57], v[172:175], v[196:199], v[54:57]
	v_mfma_f32_16x16x32_bf16 v[58:61], v[180:183], v[196:199], v[58:61]
	v_mfma_f32_16x16x32_bf16 v[50:53], v[188:191], v[196:199], v[50:53]
	v_mfma_f32_16x16x32_bf16 v[34:37], v[188:191], v[204:207], v[34:37]
	v_mfma_f32_16x16x32_bf16 v[42:45], v[180:183], v[204:207], v[42:45]
	v_mfma_f32_16x16x32_bf16 v[38:41], v[172:175], v[204:207], v[38:41]
	v_mfma_f32_16x16x32_bf16 v[46:49], v[164:167], v[204:207], v[46:49]
	v_mfma_f32_16x16x32_bf16 v[30:33], v[164:167], v[212:215], v[30:33]
	v_mfma_f32_16x16x32_bf16 v[22:25], v[172:175], v[212:215], v[22:25]
	v_mfma_f32_16x16x32_bf16 v[26:29], v[180:183], v[212:215], v[26:29]
	v_mfma_f32_16x16x32_bf16 v[18:21], v[188:191], v[212:215], v[18:21]
	v_mfma_f32_16x16x32_bf16 v[2:5], v[188:191], v[220:223], v[2:5]
	v_mfma_f32_16x16x32_bf16 v[10:13], v[180:183], v[220:223], v[10:13]
	v_mfma_f32_16x16x32_bf16 v[6:9], v[172:175], v[220:223], v[6:9]
	v_mfma_f32_16x16x32_bf16 v[14:17], v[164:167], v[220:223], v[14:17]
	v_mfma_f32_16x16x32_bf16 v[62:65], v[168:171], v[200:203], v[62:65]
	v_mfma_f32_16x16x32_bf16 v[54:57], v[176:179], v[200:203], v[54:57]
	v_mfma_f32_16x16x32_bf16 v[58:61], v[184:187], v[200:203], v[58:61]
	v_mfma_f32_16x16x32_bf16 v[50:53], v[192:195], v[200:203], v[50:53]
	v_mfma_f32_16x16x32_bf16 v[34:37], v[192:195], v[208:211], v[34:37]
	v_mfma_f32_16x16x32_bf16 v[42:45], v[184:187], v[208:211], v[42:45]
	v_mfma_f32_16x16x32_bf16 v[38:41], v[176:179], v[208:211], v[38:41]
	v_mfma_f32_16x16x32_bf16 v[46:49], v[168:171], v[208:211], v[46:49]
	v_mfma_f32_16x16x32_bf16 v[30:33], v[168:171], v[216:219], v[30:33]
	v_mfma_f32_16x16x32_bf16 v[22:25], v[176:179], v[216:219], v[22:25]
	v_mfma_f32_16x16x32_bf16 v[26:29], v[184:187], v[216:219], v[26:29]
	v_mfma_f32_16x16x32_bf16 v[18:21], v[192:195], v[216:219], v[18:21]
	v_mfma_f32_16x16x32_bf16 v[2:5], v[192:195], v[224:227], v[2:5]
	v_mfma_f32_16x16x32_bf16 v[10:13], v[184:187], v[224:227], v[10:13]
	v_mfma_f32_16x16x32_bf16 v[6:9], v[176:179], v[224:227], v[6:9]
	v_mfma_f32_16x16x32_bf16 v[14:17], v[168:171], v[224:227], v[14:17]
	s_barrier
	s_setprio 0
	s_mov_b32 s6, s7
	s_add_u32 s88, s88, 0x100
	s_addc_u32 s89, s89, 0
	s_add_u32 s86, s86, 0x100
	s_addc_u32 s87, s87, 0
	s_cmp_ge_i32 s7, s101
	s_cbranch_scc0 .LBB0_1392

.Lmy_nb_8:
	s_nop 0
	v_readfirstlane_b32 s86, v154
	v_readfirstlane_b32 s87, v155
	v_readfirstlane_b32 s88, v152
	v_readfirstlane_b32 s89, v153
	v_readfirstlane_b32 s90, v148
	v_readfirstlane_b32 s91, v149
	v_readfirstlane_b32 s92, v150
	v_readfirstlane_b32 s93, v151
	v_readfirstlane_b32 s100, v138
	v_readfirstlane_b32 s101, v141
	v_add_u32_e32 v230, s71, v160
	v_add_u32_e32 v231, s72, v160
	v_add_u32_e32 v232, 0x18000, v160
	v_add_u32_e32 v233, 0x1c000, v160
	s_add_u32 s98, s86, 0xfffc0080
	s_addc_u32 s99, s87, -1
	s_cmp_eq_u32 s7, s100
	s_cselect_b64 s[94:95], s[90:91], s[98:99]
	s_cselect_b64 s[96:97], s[92:93], s[88:89]
	s_add_i32 s47, s7, 2
	s_mov_b32 m0, s74
	ds_read_b128 v[156:159], v230
	global_load_lds_dwordx4 v144, s[86:87]
	s_mov_b32 m0, s75
	ds_read_b128 v[166:169], v230 offset:1024
	global_load_lds_dwordx4 v142, s[86:87]
	ds_read_b128 v[170:173], v230 offset:2048
	ds_read_b128 v[174:177], v230 offset:3072
	ds_read_b128 v[178:181], v231
	ds_read_b128 v[182:185], v231 offset:1024
	ds_read_b128 v[186:189], v231 offset:2048
	ds_read_b128 v[190:193], v231 offset:3072
	ds_read_b128 v[194:197], v163
	ds_read_b128 v[198:201], v163 offset:1024
	ds_read_b128 v[202:205], v163 offset:2048
	ds_read_b128 v[206:209], v163 offset:3072
	ds_read_b128 v[210:213], v163 offset:4096
	ds_read_b128 v[214:217], v163 offset:5120
	ds_read_b128 v[218:221], v163 offset:6144
	ds_read_b128 v[222:225], v163 offset:7168
	s_waitcnt vmcnt(8)
	s_waitcnt lgkmcnt(0)
	s_setprio 1
	s_barrier
	v_mfma_f32_16x16x32_bf16 v[122:125], v[156:159], v[194:197], 0
	v_mfma_f32_16x16x32_bf16 v[118:121], v[170:173], v[194:197], 0
	v_mfma_f32_16x16x32_bf16 v[126:129], v[178:181], v[194:197], 0
	v_mfma_f32_16x16x32_bf16 v[114:117], v[186:189], v[194:197], 0
	v_mfma_f32_16x16x32_bf16 v[98:101], v[186:189], v[202:205], 0
	v_mfma_f32_16x16x32_bf16 v[106:109], v[178:181], v[202:205], 0
	v_mfma_f32_16x16x32_bf16 v[102:105], v[170:173], v[202:205], 0
	v_mfma_f32_16x16x32_bf16 v[110:113], v[156:159], v[202:205], 0
	v_mfma_f32_16x16x32_bf16 v[94:97], v[156:159], v[210:213], 0
	v_mfma_f32_16x16x32_bf16 v[86:89], v[170:173], v[210:213], 0
	v_mfma_f32_16x16x32_bf16 v[90:93], v[178:181], v[210:213], 0
	v_mfma_f32_16x16x32_bf16 v[82:85], v[186:189], v[210:213], 0
	v_mfma_f32_16x16x32_bf16 v[66:69], v[186:189], v[218:221], 0
	v_mfma_f32_16x16x32_bf16 v[74:77], v[178:181], v[218:221], 0
	v_mfma_f32_16x16x32_bf16 v[70:73], v[170:173], v[218:221], 0
	v_mfma_f32_16x16x32_bf16 v[78:81], v[156:159], v[218:221], 0
	v_mfma_f32_16x16x32_bf16 v[122:125], v[166:169], v[198:201], v[122:125]
	v_mfma_f32_16x16x32_bf16 v[118:121], v[174:177], v[198:201], v[118:121]
	v_mfma_f32_16x16x32_bf16 v[126:129], v[182:185], v[198:201], v[126:129]
	v_mfma_f32_16x16x32_bf16 v[114:117], v[190:193], v[198:201], v[114:117]
	v_mfma_f32_16x16x32_bf16 v[98:101], v[190:193], v[206:209], v[98:101]
	v_mfma_f32_16x16x32_bf16 v[106:109], v[182:185], v[206:209], v[106:109]
	v_mfma_f32_16x16x32_bf16 v[102:105], v[174:177], v[206:209], v[102:105]
	v_mfma_f32_16x16x32_bf16 v[110:113], v[166:169], v[206:209], v[110:113]
	v_mfma_f32_16x16x32_bf16 v[94:97], v[166:169], v[214:217], v[94:97]
	v_mfma_f32_16x16x32_bf16 v[86:89], v[174:177], v[214:217], v[86:89]
	v_mfma_f32_16x16x32_bf16 v[90:93], v[182:185], v[214:217], v[90:93]
	v_mfma_f32_16x16x32_bf16 v[82:85], v[190:193], v[214:217], v[82:85]
	v_mfma_f32_16x16x32_bf16 v[66:69], v[190:193], v[222:225], v[66:69]
	v_mfma_f32_16x16x32_bf16 v[74:77], v[182:185], v[222:225], v[74:77]
	v_mfma_f32_16x16x32_bf16 v[70:73], v[174:177], v[222:225], v[70:73]
	v_mfma_f32_16x16x32_bf16 v[78:81], v[166:169], v[222:225], v[78:81]
	s_barrier
	s_setprio 0
	s_add_u32 s98, s96, 0x40000
	s_addc_u32 s99, s97, 0
	s_add_i32 s7, s71, s29
	s_mov_b32 m0, s7
	ds_read_b128 v[194:197], v163 offset:16384
	global_load_lds_dwordx4 v132, s[96:97]
	s_add_i32 m0, s7, 0x2000
	s_add_i32 s7, s72, s29
	global_load_lds_dwordx4 v136, s[96:97]
	s_mov_b32 m0, s7
	ds_read_b128 v[198:201], v163 offset:17408
	global_load_lds_dwordx4 v132, s[98:99]
	s_add_i32 m0, s7, 0x2000
	ds_read_b128 v[202:205], v163 offset:18432
	global_load_lds_dwordx4 v136, s[98:99]
	s_mov_b32 m0, s51
	ds_read_b128 v[206:209], v163 offset:19456
	global_load_lds_dwordx4 v130, s[94:95]
	s_mov_b32 m0, s60
	ds_read_b128 v[210:213], v163 offset:20480
	global_load_lds_dwordx4 v134, s[94:95]
	ds_read_b128 v[214:217], v163 offset:21504
	ds_read_b128 v[218:221], v163 offset:22528
	ds_read_b128 v[222:225], v163 offset:23552
	s_waitcnt vmcnt(8)
	s_waitcnt lgkmcnt(0)
	s_setprio 1
	s_barrier
	v_mfma_f32_16x16x32_bf16 v[62:65], v[156:159], v[194:197], 0
	v_mfma_f32_16x16x32_bf16 v[54:57], v[170:173], v[194:197], 0
	v_mfma_f32_16x16x32_bf16 v[58:61], v[178:181], v[194:197], 0
	v_mfma_f32_16x16x32_bf16 v[50:53], v[186:189], v[194:197], 0
	v_mfma_f32_16x16x32_bf16 v[34:37], v[186:189], v[202:205], 0
	v_mfma_f32_16x16x32_bf16 v[42:45], v[178:181], v[202:205], 0
	v_mfma_f32_16x16x32_bf16 v[38:41], v[170:173], v[202:205], 0
	v_mfma_f32_16x16x32_bf16 v[46:49], v[156:159], v[202:205], 0
	v_mfma_f32_16x16x32_bf16 v[30:33], v[156:159], v[210:213], 0
	v_mfma_f32_16x16x32_bf16 v[22:25], v[170:173], v[210:213], 0
	v_mfma_f32_16x16x32_bf16 v[26:29], v[178:181], v[210:213], 0
	v_mfma_f32_16x16x32_bf16 v[18:21], v[186:189], v[210:213], 0
	v_mfma_f32_16x16x32_bf16 v[2:5], v[186:189], v[218:221], 0
	v_mfma_f32_16x16x32_bf16 v[10:13], v[178:181], v[218:221], 0
	v_mfma_f32_16x16x32_bf16 v[6:9], v[170:173], v[218:221], 0
	v_mfma_f32_16x16x32_bf16 v[14:17], v[156:159], v[218:221], 0
	v_mfma_f32_16x16x32_bf16 v[62:65], v[166:169], v[198:201], v[62:65]
	v_mfma_f32_16x16x32_bf16 v[54:57], v[174:177], v[198:201], v[54:57]
	v_mfma_f32_16x16x32_bf16 v[58:61], v[182:185], v[198:201], v[58:61]
	v_mfma_f32_16x16x32_bf16 v[50:53], v[190:193], v[198:201], v[50:53]
	v_mfma_f32_16x16x32_bf16 v[34:37], v[190:193], v[206:209], v[34:37]
	v_mfma_f32_16x16x32_bf16 v[42:45], v[182:185], v[206:209], v[42:45]
	v_mfma_f32_16x16x32_bf16 v[38:41], v[174:177], v[206:209], v[38:41]
	v_mfma_f32_16x16x32_bf16 v[46:49], v[166:169], v[206:209], v[46:49]
	v_mfma_f32_16x16x32_bf16 v[30:33], v[166:169], v[214:217], v[30:33]
	v_mfma_f32_16x16x32_bf16 v[22:25], v[174:177], v[214:217], v[22:25]
	v_mfma_f32_16x16x32_bf16 v[26:29], v[182:185], v[214:217], v[26:29]
	v_mfma_f32_16x16x32_bf16 v[18:21], v[190:193], v[214:217], v[18:21]
	v_mfma_f32_16x16x32_bf16 v[2:5], v[190:193], v[222:225], v[2:5]
	v_mfma_f32_16x16x32_bf16 v[10:13], v[182:185], v[222:225], v[10:13]
	v_mfma_f32_16x16x32_bf16 v[6:9], v[174:177], v[222:225], v[6:9]
	v_mfma_f32_16x16x32_bf16 v[14:17], v[166:169], v[222:225], v[14:17]
	s_barrier
	s_setprio 0
	s_add_u32 s98, s94, 0x40000
	s_addc_u32 s99, s95, 0
	s_add_i32 s7, 0, 0x18000
	s_add_i32 s49, 0, 0x1c000
	s_mov_b32 m0, s61
	ds_read_b128 v[156:159], v232
	global_load_lds_dwordx4 v130, s[98:99]
	s_mov_b32 m0, s62
	ds_read_b128 v[166:169], v232 offset:1024
	global_load_lds_dwordx4 v134, s[98:99]
	ds_read_b128 v[170:173], v232 offset:2048
	ds_read_b128 v[174:177], v232 offset:3072
	ds_read_b128 v[178:181], v233
	ds_read_b128 v[182:185], v233 offset:1024
	ds_read_b128 v[186:189], v233 offset:2048
	ds_read_b128 v[190:193], v233 offset:3072
	ds_read_b128 v[194:197], v163 offset:32768
	ds_read_b128 v[198:201], v163 offset:33792
	ds_read_b128 v[202:205], v163 offset:34816
	ds_read_b128 v[206:209], v163 offset:35840
	ds_read_b128 v[210:213], v163 offset:36864
	ds_read_b128 v[214:217], v163 offset:37888
	ds_read_b128 v[218:221], v163 offset:38912
	ds_read_b128 v[222:225], v163 offset:39936
	s_waitcnt vmcnt(8)
	s_waitcnt lgkmcnt(0)
	s_setprio 1
	s_barrier
	v_mfma_f32_16x16x32_bf16 v[122:125], v[156:159], v[194:197], v[122:125]
	v_mfma_f32_16x16x32_bf16 v[118:121], v[170:173], v[194:197], v[118:121]
	v_mfma_f32_16x16x32_bf16 v[126:129], v[178:181], v[194:197], v[126:129]
	v_mfma_f32_16x16x32_bf16 v[114:117], v[186:189], v[194:197], v[114:117]
	v_mfma_f32_16x16x32_bf16 v[98:101], v[186:189], v[202:205], v[98:101]
	v_mfma_f32_16x16x32_bf16 v[106:109], v[178:181], v[202:205], v[106:109]
	v_mfma_f32_16x16x32_bf16 v[102:105], v[170:173], v[202:205], v[102:105]
	v_mfma_f32_16x16x32_bf16 v[110:113], v[156:159], v[202:205], v[110:113]
	v_mfma_f32_16x16x32_bf16 v[94:97], v[156:159], v[210:213], v[94:97]
	v_mfma_f32_16x16x32_bf16 v[86:89], v[170:173], v[210:213], v[86:89]
	v_mfma_f32_16x16x32_bf16 v[90:93], v[178:181], v[210:213], v[90:93]
	v_mfma_f32_16x16x32_bf16 v[82:85], v[186:189], v[210:213], v[82:85]
	v_mfma_f32_16x16x32_bf16 v[66:69], v[186:189], v[218:221], v[66:69]
	v_mfma_f32_16x16x32_bf16 v[74:77], v[178:181], v[218:221], v[74:77]
	v_mfma_f32_16x16x32_bf16 v[70:73], v[170:173], v[218:221], v[70:73]
	v_mfma_f32_16x16x32_bf16 v[78:81], v[156:159], v[218:221], v[78:81]
	v_mfma_f32_16x16x32_bf16 v[122:125], v[166:169], v[198:201], v[122:125]
	v_mfma_f32_16x16x32_bf16 v[118:121], v[174:177], v[198:201], v[118:121]
	v_mfma_f32_16x16x32_bf16 v[126:129], v[182:185], v[198:201], v[126:129]
	v_mfma_f32_16x16x32_bf16 v[114:117], v[190:193], v[198:201], v[114:117]
	v_mfma_f32_16x16x32_bf16 v[98:101], v[190:193], v[206:209], v[98:101]
	v_mfma_f32_16x16x32_bf16 v[106:109], v[182:185], v[206:209], v[106:109]
	v_mfma_f32_16x16x32_bf16 v[102:105], v[174:177], v[206:209], v[102:105]
	v_mfma_f32_16x16x32_bf16 v[110:113], v[166:169], v[206:209], v[110:113]
	v_mfma_f32_16x16x32_bf16 v[94:97], v[166:169], v[214:217], v[94:97]
	v_mfma_f32_16x16x32_bf16 v[86:89], v[174:177], v[214:217], v[86:89]
	v_mfma_f32_16x16x32_bf16 v[90:93], v[182:185], v[214:217], v[90:93]
	v_mfma_f32_16x16x32_bf16 v[82:85], v[190:193], v[214:217], v[82:85]
	v_mfma_f32_16x16x32_bf16 v[66:69], v[190:193], v[222:225], v[66:69]
	v_mfma_f32_16x16x32_bf16 v[74:77], v[182:185], v[222:225], v[74:77]
	v_mfma_f32_16x16x32_bf16 v[70:73], v[174:177], v[222:225], v[70:73]
	v_mfma_f32_16x16x32_bf16 v[78:81], v[166:169], v[222:225], v[78:81]
	s_barrier
	s_setprio 0
	s_add_u32 s96, s96, 0x80
	s_addc_u32 s97, s97, 0
	s_add_u32 s98, s96, 0x40000
	s_addc_u32 s99, s97, 0
	s_add_u32 s94, s94, 0x80
	s_addc_u32 s95, s95, 0
	s_add_i32 s7, s7, s29
	s_mov_b32 m0, s7
	ds_read_b128 v[194:197], v163 offset:49152
	global_load_lds_dwordx4 v132, s[96:97]
	s_add_i32 m0, s7, 0x2000
	s_add_i32 s7, s49, s29
	global_load_lds_dwordx4 v136, s[96:97]
	s_mov_b32 m0, s7
	ds_read_b128 v[198:201], v163 offset:50176
	global_load_lds_dwordx4 v132, s[98:99]
	s_add_i32 m0, s7, 0x2000
	ds_read_b128 v[202:205], v163 offset:51200
	global_load_lds_dwordx4 v136, s[98:99]
	s_mov_b32 m0, s63
	ds_read_b128 v[206:209], v163 offset:52224
	global_load_lds_dwordx4 v130, s[94:95]
	s_mov_b32 m0, s64
	ds_read_b128 v[210:213], v163 offset:53248
	global_load_lds_dwordx4 v134, s[94:95]
	ds_read_b128 v[214:217], v163 offset:54272
	ds_read_b128 v[218:221], v163 offset:55296
	ds_read_b128 v[222:225], v163 offset:56320
	s_waitcnt vmcnt(8)
	s_waitcnt lgkmcnt(0)
	s_setprio 1
	s_barrier
	v_mfma_f32_16x16x32_bf16 v[62:65], v[156:159], v[194:197], v[62:65]
	v_mfma_f32_16x16x32_bf16 v[54:57], v[170:173], v[194:197], v[54:57]
	v_mfma_f32_16x16x32_bf16 v[58:61], v[178:181], v[194:197], v[58:61]
	v_mfma_f32_16x16x32_bf16 v[50:53], v[186:189], v[194:197], v[50:53]
	v_mfma_f32_16x16x32_bf16 v[34:37], v[186:189], v[202:205], v[34:37]
	v_mfma_f32_16x16x32_bf16 v[42:45], v[178:181], v[202:205], v[42:45]
	v_mfma_f32_16x16x32_bf16 v[38:41], v[170:173], v[202:205], v[38:41]
	v_mfma_f32_16x16x32_bf16 v[46:49], v[156:159], v[202:205], v[46:49]
	v_mfma_f32_16x16x32_bf16 v[30:33], v[156:159], v[210:213], v[30:33]
	v_mfma_f32_16x16x32_bf16 v[22:25], v[170:173], v[210:213], v[22:25]
	v_mfma_f32_16x16x32_bf16 v[26:29], v[178:181], v[210:213], v[26:29]
	v_mfma_f32_16x16x32_bf16 v[18:21], v[186:189], v[210:213], v[18:21]
	v_mfma_f32_16x16x32_bf16 v[2:5], v[186:189], v[218:221], v[2:5]
	v_mfma_f32_16x16x32_bf16 v[10:13], v[178:181], v[218:221], v[10:13]
	v_mfma_f32_16x16x32_bf16 v[6:9], v[170:173], v[218:221], v[6:9]
	v_mfma_f32_16x16x32_bf16 v[14:17], v[156:159], v[218:221], v[14:17]
	v_mfma_f32_16x16x32_bf16 v[62:65], v[166:169], v[198:201], v[62:65]
	v_mfma_f32_16x16x32_bf16 v[54:57], v[174:177], v[198:201], v[54:57]
	v_mfma_f32_16x16x32_bf16 v[58:61], v[182:185], v[198:201], v[58:61]
	v_mfma_f32_16x16x32_bf16 v[50:53], v[190:193], v[198:201], v[50:53]
	v_mfma_f32_16x16x32_bf16 v[34:37], v[190:193], v[206:209], v[34:37]
	v_mfma_f32_16x16x32_bf16 v[42:45], v[182:185], v[206:209], v[42:45]
	v_mfma_f32_16x16x32_bf16 v[38:41], v[174:177], v[206:209], v[38:41]
	v_mfma_f32_16x16x32_bf16 v[46:49], v[166:169], v[206:209], v[46:49]
	v_mfma_f32_16x16x32_bf16 v[30:33], v[166:169], v[214:217], v[30:33]
	v_mfma_f32_16x16x32_bf16 v[22:25], v[174:177], v[214:217], v[22:25]
	v_mfma_f32_16x16x32_bf16 v[26:29], v[182:185], v[214:217], v[26:29]
	v_mfma_f32_16x16x32_bf16 v[18:21], v[190:193], v[214:217], v[18:21]
	v_mfma_f32_16x16x32_bf16 v[2:5], v[190:193], v[222:225], v[2:5]
	v_mfma_f32_16x16x32_bf16 v[10:13], v[182:185], v[222:225], v[10:13]
	v_mfma_f32_16x16x32_bf16 v[6:9], v[174:177], v[222:225], v[6:9]
	v_mfma_f32_16x16x32_bf16 v[14:17], v[166:169], v[222:225], v[14:17]
	s_barrier
	s_setprio 0
	s_mov_b32 s7, s47
	s_add_u32 s88, s88, 0x100
	s_addc_u32 s89, s89, 0
	s_add_u32 s86, s86, 0x100
	s_addc_u32 s87, s87, 0
	s_cmp_ge_i32 s47, s101
	s_cbranch_scc1 .Lmy_kexit_8
.LBB0_1573:
	s_add_u32 s98, s86, 0xfffc0080
	s_addc_u32 s99, s87, -1
	s_cmp_eq_u32 s7, s100
	s_cselect_b64 s[94:95], s[90:91], s[98:99]
	s_cselect_b64 s[96:97], s[92:93], s[88:89]
	s_add_i32 s47, s7, 2
	s_mov_b32 m0, s74
	ds_read_b128 v[156:159], v230
	global_load_lds_dwordx4 v144, s[86:87]
	s_mov_b32 m0, s75
	ds_read_b128 v[166:169], v230 offset:1024
	global_load_lds_dwordx4 v142, s[86:87]
	ds_read_b128 v[170:173], v230 offset:2048
	ds_read_b128 v[174:177], v230 offset:3072
	ds_read_b128 v[178:181], v231
	ds_read_b128 v[182:185], v231 offset:1024
	ds_read_b128 v[186:189], v231 offset:2048
	ds_read_b128 v[190:193], v231 offset:3072
	ds_read_b128 v[194:197], v163
	ds_read_b128 v[198:201], v163 offset:1024
	ds_read_b128 v[202:205], v163 offset:2048
	ds_read_b128 v[206:209], v163 offset:3072
	ds_read_b128 v[210:213], v163 offset:4096
	ds_read_b128 v[214:217], v163 offset:5120
	ds_read_b128 v[218:221], v163 offset:6144
	ds_read_b128 v[222:225], v163 offset:7168
	s_waitcnt vmcnt(8)
	s_waitcnt lgkmcnt(0)
	s_setprio 1
	s_barrier
	v_mfma_f32_16x16x32_bf16 v[122:125], v[156:159], v[194:197], v[122:125]
	v_mfma_f32_16x16x32_bf16 v[118:121], v[170:173], v[194:197], v[118:121]
	v_mfma_f32_16x16x32_bf16 v[126:129], v[178:181], v[194:197], v[126:129]
	v_mfma_f32_16x16x32_bf16 v[114:117], v[186:189], v[194:197], v[114:117]
	v_mfma_f32_16x16x32_bf16 v[98:101], v[186:189], v[202:205], v[98:101]
	v_mfma_f32_16x16x32_bf16 v[106:109], v[178:181], v[202:205], v[106:109]
	v_mfma_f32_16x16x32_bf16 v[102:105], v[170:173], v[202:205], v[102:105]
	v_mfma_f32_16x16x32_bf16 v[110:113], v[156:159], v[202:205], v[110:113]
	v_mfma_f32_16x16x32_bf16 v[94:97], v[156:159], v[210:213], v[94:97]
	v_mfma_f32_16x16x32_bf16 v[86:89], v[170:173], v[210:213], v[86:89]
	v_mfma_f32_16x16x32_bf16 v[90:93], v[178:181], v[210:213], v[90:93]
	v_mfma_f32_16x16x32_bf16 v[82:85], v[186:189], v[210:213], v[82:85]
	v_mfma_f32_16x16x32_bf16 v[66:69], v[186:189], v[218:221], v[66:69]
	v_mfma_f32_16x16x32_bf16 v[74:77], v[178:181], v[218:221], v[74:77]
	v_mfma_f32_16x16x32_bf16 v[70:73], v[170:173], v[218:221], v[70:73]
	v_mfma_f32_16x16x32_bf16 v[78:81], v[156:159], v[218:221], v[78:81]
	v_mfma_f32_16x16x32_bf16 v[122:125], v[166:169], v[198:201], v[122:125]
	v_mfma_f32_16x16x32_bf16 v[118:121], v[174:177], v[198:201], v[118:121]
	v_mfma_f32_16x16x32_bf16 v[126:129], v[182:185], v[198:201], v[126:129]
	v_mfma_f32_16x16x32_bf16 v[114:117], v[190:193], v[198:201], v[114:117]
	v_mfma_f32_16x16x32_bf16 v[98:101], v[190:193], v[206:209], v[98:101]
	v_mfma_f32_16x16x32_bf16 v[106:109], v[182:185], v[206:209], v[106:109]
	v_mfma_f32_16x16x32_bf16 v[102:105], v[174:177], v[206:209], v[102:105]
	v_mfma_f32_16x16x32_bf16 v[110:113], v[166:169], v[206:209], v[110:113]
	v_mfma_f32_16x16x32_bf16 v[94:97], v[166:169], v[214:217], v[94:97]
	v_mfma_f32_16x16x32_bf16 v[86:89], v[174:177], v[214:217], v[86:89]
	v_mfma_f32_16x16x32_bf16 v[90:93], v[182:185], v[214:217], v[90:93]
	v_mfma_f32_16x16x32_bf16 v[82:85], v[190:193], v[214:217], v[82:85]
	v_mfma_f32_16x16x32_bf16 v[66:69], v[190:193], v[222:225], v[66:69]
	v_mfma_f32_16x16x32_bf16 v[74:77], v[182:185], v[222:225], v[74:77]
	v_mfma_f32_16x16x32_bf16 v[70:73], v[174:177], v[222:225], v[70:73]
	v_mfma_f32_16x16x32_bf16 v[78:81], v[166:169], v[222:225], v[78:81]
	s_barrier
	s_setprio 0
	s_add_u32 s98, s96, 0x40000
	s_addc_u32 s99, s97, 0
	s_add_i32 s7, s71, s29
	s_mov_b32 m0, s7
	ds_read_b128 v[194:197], v163 offset:16384
	global_load_lds_dwordx4 v132, s[96:97]
	s_add_i32 m0, s7, 0x2000
	s_add_i32 s7, s72, s29
	global_load_lds_dwordx4 v136, s[96:97]
	s_mov_b32 m0, s7
	ds_read_b128 v[198:201], v163 offset:17408
	global_load_lds_dwordx4 v132, s[98:99]
	s_add_i32 m0, s7, 0x2000
	ds_read_b128 v[202:205], v163 offset:18432
	global_load_lds_dwordx4 v136, s[98:99]
	s_mov_b32 m0, s51
	ds_read_b128 v[206:209], v163 offset:19456
	global_load_lds_dwordx4 v130, s[94:95]
	s_mov_b32 m0, s60
	ds_read_b128 v[210:213], v163 offset:20480
	global_load_lds_dwordx4 v134, s[94:95]
	ds_read_b128 v[214:217], v163 offset:21504
	ds_read_b128 v[218:221], v163 offset:22528
	ds_read_b128 v[222:225], v163 offset:23552
	s_waitcnt vmcnt(8)
	s_waitcnt lgkmcnt(0)
	s_setprio 1
	s_barrier
	v_mfma_f32_16x16x32_bf16 v[62:65], v[156:159], v[194:197], v[62:65]
	v_mfma_f32_16x16x32_bf16 v[54:57], v[170:173], v[194:197], v[54:57]
	v_mfma_f32_16x16x32_bf16 v[58:61], v[178:181], v[194:197], v[58:61]
	v_mfma_f32_16x16x32_bf16 v[50:53], v[186:189], v[194:197], v[50:53]
	v_mfma_f32_16x16x32_bf16 v[34:37], v[186:189], v[202:205], v[34:37]
	v_mfma_f32_16x16x32_bf16 v[42:45], v[178:181], v[202:205], v[42:45]
	v_mfma_f32_16x16x32_bf16 v[38:41], v[170:173], v[202:205], v[38:41]
	v_mfma_f32_16x16x32_bf16 v[46:49], v[156:159], v[202:205], v[46:49]
	v_mfma_f32_16x16x32_bf16 v[30:33], v[156:159], v[210:213], v[30:33]
	v_mfma_f32_16x16x32_bf16 v[22:25], v[170:173], v[210:213], v[22:25]
	v_mfma_f32_16x16x32_bf16 v[26:29], v[178:181], v[210:213], v[26:29]
	v_mfma_f32_16x16x32_bf16 v[18:21], v[186:189], v[210:213], v[18:21]
	v_mfma_f32_16x16x32_bf16 v[2:5], v[186:189], v[218:221], v[2:5]
	v_mfma_f32_16x16x32_bf16 v[10:13], v[178:181], v[218:221], v[10:13]
	v_mfma_f32_16x16x32_bf16 v[6:9], v[170:173], v[218:221], v[6:9]
	v_mfma_f32_16x16x32_bf16 v[14:17], v[156:159], v[218:221], v[14:17]
	v_mfma_f32_16x16x32_bf16 v[62:65], v[166:169], v[198:201], v[62:65]
	v_mfma_f32_16x16x32_bf16 v[54:57], v[174:177], v[198:201], v[54:57]
	v_mfma_f32_16x16x32_bf16 v[58:61], v[182:185], v[198:201], v[58:61]
	v_mfma_f32_16x16x32_bf16 v[50:53], v[190:193], v[198:201], v[50:53]
	v_mfma_f32_16x16x32_bf16 v[34:37], v[190:193], v[206:209], v[34:37]
	v_mfma_f32_16x16x32_bf16 v[42:45], v[182:185], v[206:209], v[42:45]
	v_mfma_f32_16x16x32_bf16 v[38:41], v[174:177], v[206:209], v[38:41]
	v_mfma_f32_16x16x32_bf16 v[46:49], v[166:169], v[206:209], v[46:49]
	v_mfma_f32_16x16x32_bf16 v[30:33], v[166:169], v[214:217], v[30:33]
	v_mfma_f32_16x16x32_bf16 v[22:25], v[174:177], v[214:217], v[22:25]
	v_mfma_f32_16x16x32_bf16 v[26:29], v[182:185], v[214:217], v[26:29]
	v_mfma_f32_16x16x32_bf16 v[18:21], v[190:193], v[214:217], v[18:21]
	v_mfma_f32_16x16x32_bf16 v[2:5], v[190:193], v[222:225], v[2:5]
	v_mfma_f32_16x16x32_bf16 v[10:13], v[182:185], v[222:225], v[10:13]
	v_mfma_f32_16x16x32_bf16 v[6:9], v[174:177], v[222:225], v[6:9]
	v_mfma_f32_16x16x32_bf16 v[14:17], v[166:169], v[222:225], v[14:17]
	s_barrier
	s_setprio 0
	s_add_u32 s98, s94, 0x40000
	s_addc_u32 s99, s95, 0
	s_add_i32 s7, 0, 0x18000
	s_add_i32 s49, 0, 0x1c000
	s_mov_b32 m0, s61
	ds_read_b128 v[156:159], v232
	global_load_lds_dwordx4 v130, s[98:99]
	s_mov_b32 m0, s62
	ds_read_b128 v[166:169], v232 offset:1024
	global_load_lds_dwordx4 v134, s[98:99]
	ds_read_b128 v[170:173], v232 offset:2048
	ds_read_b128 v[174:177], v232 offset:3072
	ds_read_b128 v[178:181], v233
	ds_read_b128 v[182:185], v233 offset:1024
	ds_read_b128 v[186:189], v233 offset:2048
	ds_read_b128 v[190:193], v233 offset:3072
	ds_read_b128 v[194:197], v163 offset:32768
	ds_read_b128 v[198:201], v163 offset:33792
	ds_read_b128 v[202:205], v163 offset:34816
	ds_read_b128 v[206:209], v163 offset:35840
	ds_read_b128 v[210:213], v163 offset:36864
	ds_read_b128 v[214:217], v163 offset:37888
	ds_read_b128 v[218:221], v163 offset:38912
	ds_read_b128 v[222:225], v163 offset:39936
	s_waitcnt vmcnt(8)
	s_waitcnt lgkmcnt(0)
	s_setprio 1
	s_barrier
	v_mfma_f32_16x16x32_bf16 v[122:125], v[156:159], v[194:197], v[122:125]
	v_mfma_f32_16x16x32_bf16 v[118:121], v[170:173], v[194:197], v[118:121]
	v_mfma_f32_16x16x32_bf16 v[126:129], v[178:181], v[194:197], v[126:129]
	v_mfma_f32_16x16x32_bf16 v[114:117], v[186:189], v[194:197], v[114:117]
	v_mfma_f32_16x16x32_bf16 v[98:101], v[186:189], v[202:205], v[98:101]
	v_mfma_f32_16x16x32_bf16 v[106:109], v[178:181], v[202:205], v[106:109]
	v_mfma_f32_16x16x32_bf16 v[102:105], v[170:173], v[202:205], v[102:105]
	v_mfma_f32_16x16x32_bf16 v[110:113], v[156:159], v[202:205], v[110:113]
	v_mfma_f32_16x16x32_bf16 v[94:97], v[156:159], v[210:213], v[94:97]
	v_mfma_f32_16x16x32_bf16 v[86:89], v[170:173], v[210:213], v[86:89]
	v_mfma_f32_16x16x32_bf16 v[90:93], v[178:181], v[210:213], v[90:93]
	v_mfma_f32_16x16x32_bf16 v[82:85], v[186:189], v[210:213], v[82:85]
	v_mfma_f32_16x16x32_bf16 v[66:69], v[186:189], v[218:221], v[66:69]
	v_mfma_f32_16x16x32_bf16 v[74:77], v[178:181], v[218:221], v[74:77]
	v_mfma_f32_16x16x32_bf16 v[70:73], v[170:173], v[218:221], v[70:73]
	v_mfma_f32_16x16x32_bf16 v[78:81], v[156:159], v[218:221], v[78:81]
	v_mfma_f32_16x16x32_bf16 v[122:125], v[166:169], v[198:201], v[122:125]
	v_mfma_f32_16x16x32_bf16 v[118:121], v[174:177], v[198:201], v[118:121]
	v_mfma_f32_16x16x32_bf16 v[126:129], v[182:185], v[198:201], v[126:129]
	v_mfma_f32_16x16x32_bf16 v[114:117], v[190:193], v[198:201], v[114:117]
	v_mfma_f32_16x16x32_bf16 v[98:101], v[190:193], v[206:209], v[98:101]
	v_mfma_f32_16x16x32_bf16 v[106:109], v[182:185], v[206:209], v[106:109]
	v_mfma_f32_16x16x32_bf16 v[102:105], v[174:177], v[206:209], v[102:105]
	v_mfma_f32_16x16x32_bf16 v[110:113], v[166:169], v[206:209], v[110:113]
	v_mfma_f32_16x16x32_bf16 v[94:97], v[166:169], v[214:217], v[94:97]
	v_mfma_f32_16x16x32_bf16 v[86:89], v[174:177], v[214:217], v[86:89]
	v_mfma_f32_16x16x32_bf16 v[90:93], v[182:185], v[214:217], v[90:93]
	v_mfma_f32_16x16x32_bf16 v[82:85], v[190:193], v[214:217], v[82:85]
	v_mfma_f32_16x16x32_bf16 v[66:69], v[190:193], v[222:225], v[66:69]
	v_mfma_f32_16x16x32_bf16 v[74:77], v[182:185], v[222:225], v[74:77]
	v_mfma_f32_16x16x32_bf16 v[70:73], v[174:177], v[222:225], v[70:73]
	v_mfma_f32_16x16x32_bf16 v[78:81], v[166:169], v[222:225], v[78:81]
	s_barrier
	s_setprio 0
	s_add_u32 s96, s96, 0x80
	s_addc_u32 s97, s97, 0
	s_add_u32 s98, s96, 0x40000
	s_addc_u32 s99, s97, 0
	s_add_u32 s94, s94, 0x80
	s_addc_u32 s95, s95, 0
	s_add_i32 s7, s7, s29
	s_mov_b32 m0, s7
	ds_read_b128 v[194:197], v163 offset:49152
	global_load_lds_dwordx4 v132, s[96:97]
	s_add_i32 m0, s7, 0x2000
	s_add_i32 s7, s49, s29
	global_load_lds_dwordx4 v136, s[96:97]
	s_mov_b32 m0, s7
	ds_read_b128 v[198:201], v163 offset:50176
	global_load_lds_dwordx4 v132, s[98:99]
	s_add_i32 m0, s7, 0x2000
	ds_read_b128 v[202:205], v163 offset:51200
	global_load_lds_dwordx4 v136, s[98:99]
	s_mov_b32 m0, s63
	ds_read_b128 v[206:209], v163 offset:52224
	global_load_lds_dwordx4 v130, s[94:95]
	s_mov_b32 m0, s64
	ds_read_b128 v[210:213], v163 offset:53248
	global_load_lds_dwordx4 v134, s[94:95]
	ds_read_b128 v[214:217], v163 offset:54272
	ds_read_b128 v[218:221], v163 offset:55296
	ds_read_b128 v[222:225], v163 offset:56320
	s_waitcnt vmcnt(8)
	s_waitcnt lgkmcnt(0)
	s_setprio 1
	s_barrier
	v_mfma_f32_16x16x32_bf16 v[62:65], v[156:159], v[194:197], v[62:65]
	v_mfma_f32_16x16x32_bf16 v[54:57], v[170:173], v[194:197], v[54:57]
	v_mfma_f32_16x16x32_bf16 v[58:61], v[178:181], v[194:197], v[58:61]
	v_mfma_f32_16x16x32_bf16 v[50:53], v[186:189], v[194:197], v[50:53]
	v_mfma_f32_16x16x32_bf16 v[34:37], v[186:189], v[202:205], v[34:37]
	v_mfma_f32_16x16x32_bf16 v[42:45], v[178:181], v[202:205], v[42:45]
	v_mfma_f32_16x16x32_bf16 v[38:41], v[170:173], v[202:205], v[38:41]
	v_mfma_f32_16x16x32_bf16 v[46:49], v[156:159], v[202:205], v[46:49]
	v_mfma_f32_16x16x32_bf16 v[30:33], v[156:159], v[210:213], v[30:33]
	v_mfma_f32_16x16x32_bf16 v[22:25], v[170:173], v[210:213], v[22:25]
	v_mfma_f32_16x16x32_bf16 v[26:29], v[178:181], v[210:213], v[26:29]
	v_mfma_f32_16x16x32_bf16 v[18:21], v[186:189], v[210:213], v[18:21]
	v_mfma_f32_16x16x32_bf16 v[2:5], v[186:189], v[218:221], v[2:5]
	v_mfma_f32_16x16x32_bf16 v[10:13], v[178:181], v[218:221], v[10:13]
	v_mfma_f32_16x16x32_bf16 v[6:9], v[170:173], v[218:221], v[6:9]
	v_mfma_f32_16x16x32_bf16 v[14:17], v[156:159], v[218:221], v[14:17]
	v_mfma_f32_16x16x32_bf16 v[62:65], v[166:169], v[198:201], v[62:65]
	v_mfma_f32_16x16x32_bf16 v[54:57], v[174:177], v[198:201], v[54:57]
	v_mfma_f32_16x16x32_bf16 v[58:61], v[182:185], v[198:201], v[58:61]
	v_mfma_f32_16x16x32_bf16 v[50:53], v[190:193], v[198:201], v[50:53]
	v_mfma_f32_16x16x32_bf16 v[34:37], v[190:193], v[206:209], v[34:37]
	v_mfma_f32_16x16x32_bf16 v[42:45], v[182:185], v[206:209], v[42:45]
	v_mfma_f32_16x16x32_bf16 v[38:41], v[174:177], v[206:209], v[38:41]
	v_mfma_f32_16x16x32_bf16 v[46:49], v[166:169], v[206:209], v[46:49]
	v_mfma_f32_16x16x32_bf16 v[30:33], v[166:169], v[214:217], v[30:33]
	v_mfma_f32_16x16x32_bf16 v[22:25], v[174:177], v[214:217], v[22:25]
	v_mfma_f32_16x16x32_bf16 v[26:29], v[182:185], v[214:217], v[26:29]
	v_mfma_f32_16x16x32_bf16 v[18:21], v[190:193], v[214:217], v[18:21]
	v_mfma_f32_16x16x32_bf16 v[2:5], v[190:193], v[222:225], v[2:5]
	v_mfma_f32_16x16x32_bf16 v[10:13], v[182:185], v[222:225], v[10:13]
	v_mfma_f32_16x16x32_bf16 v[6:9], v[174:177], v[222:225], v[6:9]
	v_mfma_f32_16x16x32_bf16 v[14:17], v[166:169], v[222:225], v[14:17]
	s_barrier
	s_setprio 0
	s_mov_b32 s7, s47
	s_add_u32 s88, s88, 0x100
	s_addc_u32 s89, s89, 0
	s_add_u32 s86, s86, 0x100
	s_addc_u32 s87, s87, 0
	s_cmp_ge_i32 s47, s101
	s_cbranch_scc0 .LBB0_1573

.Lmy_nb_9:
	s_nop 0
	v_readfirstlane_b32 s86, v152
	v_readfirstlane_b32 s87, v153
	v_readfirstlane_b32 s88, v150
	v_readfirstlane_b32 s89, v151
	v_readfirstlane_b32 s90, v146
	v_readfirstlane_b32 s91, v147
	v_readfirstlane_b32 s92, v148
	v_readfirstlane_b32 s93, v149
	v_readfirstlane_b32 s100, v154
	v_readfirstlane_b32 s101, v138
	v_add_u32_e32 v230, s74, v141
	v_add_u32_e32 v231, s75, v141
	v_add_u32_e32 v232, 0x18000, v141
	v_add_u32_e32 v233, 0x1c000, v141
	s_add_u32 s98, s86, 0xfffc0080
	s_addc_u32 s99, s87, -1
	s_cmp_eq_u32 s5, s100
	s_cselect_b64 s[94:95], s[90:91], s[98:99]
	s_cselect_b64 s[96:97], s[92:93], s[88:89]
	s_add_i32 s29, s5, 2
	s_add_i32 m0, s47, 0xc000
	ds_read_b128 v[164:167], v230
	global_load_lds_dwordx4 v144, s[86:87]
	s_add_i32 m0, s47, 0xe000
	ds_read_b128 v[168:171], v230 offset:1024
	global_load_lds_dwordx4 v142, s[86:87]
	ds_read_b128 v[172:175], v230 offset:2048
	ds_read_b128 v[176:179], v230 offset:3072
	ds_read_b128 v[180:183], v231
	ds_read_b128 v[184:187], v231 offset:1024
	ds_read_b128 v[188:191], v231 offset:2048
	ds_read_b128 v[192:195], v231 offset:3072
	ds_read_b128 v[196:199], v160
	ds_read_b128 v[200:203], v160 offset:1024
	ds_read_b128 v[204:207], v160 offset:2048
	ds_read_b128 v[208:211], v160 offset:3072
	ds_read_b128 v[212:215], v160 offset:4096
	ds_read_b128 v[216:219], v160 offset:5120
	ds_read_b128 v[220:223], v160 offset:6144
	ds_read_b128 v[224:227], v160 offset:7168
	s_waitcnt vmcnt(8)
	s_waitcnt lgkmcnt(0)
	s_setprio 1
	s_barrier
	v_mfma_f32_16x16x32_bf16 v[122:125], v[164:167], v[196:199], 0
	v_mfma_f32_16x16x32_bf16 v[118:121], v[172:175], v[196:199], 0
	v_mfma_f32_16x16x32_bf16 v[126:129], v[180:183], v[196:199], 0
	v_mfma_f32_16x16x32_bf16 v[114:117], v[188:191], v[196:199], 0
	v_mfma_f32_16x16x32_bf16 v[98:101], v[188:191], v[204:207], 0
	v_mfma_f32_16x16x32_bf16 v[106:109], v[180:183], v[204:207], 0
	v_mfma_f32_16x16x32_bf16 v[102:105], v[172:175], v[204:207], 0
	v_mfma_f32_16x16x32_bf16 v[110:113], v[164:167], v[204:207], 0
	v_mfma_f32_16x16x32_bf16 v[94:97], v[164:167], v[212:215], 0
	v_mfma_f32_16x16x32_bf16 v[86:89], v[172:175], v[212:215], 0
	v_mfma_f32_16x16x32_bf16 v[90:93], v[180:183], v[212:215], 0
	v_mfma_f32_16x16x32_bf16 v[82:85], v[188:191], v[212:215], 0
	v_mfma_f32_16x16x32_bf16 v[66:69], v[188:191], v[220:223], 0
	v_mfma_f32_16x16x32_bf16 v[74:77], v[180:183], v[220:223], 0
	v_mfma_f32_16x16x32_bf16 v[70:73], v[172:175], v[220:223], 0
	v_mfma_f32_16x16x32_bf16 v[78:81], v[164:167], v[220:223], 0
	v_mfma_f32_16x16x32_bf16 v[122:125], v[168:171], v[200:203], v[122:125]
	v_mfma_f32_16x16x32_bf16 v[118:121], v[176:179], v[200:203], v[118:121]
	v_mfma_f32_16x16x32_bf16 v[126:129], v[184:187], v[200:203], v[126:129]
	v_mfma_f32_16x16x32_bf16 v[114:117], v[192:195], v[200:203], v[114:117]
	v_mfma_f32_16x16x32_bf16 v[98:101], v[192:195], v[208:211], v[98:101]
	v_mfma_f32_16x16x32_bf16 v[106:109], v[184:187], v[208:211], v[106:109]
	v_mfma_f32_16x16x32_bf16 v[102:105], v[176:179], v[208:211], v[102:105]
	v_mfma_f32_16x16x32_bf16 v[110:113], v[168:171], v[208:211], v[110:113]
	v_mfma_f32_16x16x32_bf16 v[94:97], v[168:171], v[216:219], v[94:97]
	v_mfma_f32_16x16x32_bf16 v[86:89], v[176:179], v[216:219], v[86:89]
	v_mfma_f32_16x16x32_bf16 v[90:93], v[184:187], v[216:219], v[90:93]
	v_mfma_f32_16x16x32_bf16 v[82:85], v[192:195], v[216:219], v[82:85]
	v_mfma_f32_16x16x32_bf16 v[66:69], v[192:195], v[224:227], v[66:69]
	v_mfma_f32_16x16x32_bf16 v[74:77], v[184:187], v[224:227], v[74:77]
	v_mfma_f32_16x16x32_bf16 v[70:73], v[176:179], v[224:227], v[70:73]
	v_mfma_f32_16x16x32_bf16 v[78:81], v[168:171], v[224:227], v[78:81]
	s_barrier
	s_setprio 0
	s_add_u32 s98, s96, 0x40000
	s_addc_u32 s99, s97, 0
	s_add_i32 s5, s74, s23
	s_mov_b32 m0, s5
	ds_read_b128 v[196:199], v160 offset:16384
	global_load_lds_dwordx4 v132, s[96:97]
	s_add_i32 m0, s5, 0x2000
	s_add_i32 s5, s75, s23
	global_load_lds_dwordx4 v136, s[96:97]
	s_mov_b32 m0, s5
	ds_read_b128 v[200:203], v160 offset:17408
	global_load_lds_dwordx4 v132, s[98:99]
	s_add_i32 m0, s5, 0x2000
	ds_read_b128 v[204:207], v160 offset:18432
	global_load_lds_dwordx4 v136, s[98:99]
	s_mov_b32 m0, s47
	ds_read_b128 v[208:211], v160 offset:19456
	global_load_lds_dwordx4 v130, s[94:95]
	s_mov_b32 m0, s56
	ds_read_b128 v[212:215], v160 offset:20480
	global_load_lds_dwordx4 v134, s[94:95]
	ds_read_b128 v[216:219], v160 offset:21504
	ds_read_b128 v[220:223], v160 offset:22528
	ds_read_b128 v[224:227], v160 offset:23552
	s_waitcnt vmcnt(8)
	s_waitcnt lgkmcnt(0)
	s_setprio 1
	s_barrier
	v_mfma_f32_16x16x32_bf16 v[62:65], v[164:167], v[196:199], 0
	v_mfma_f32_16x16x32_bf16 v[54:57], v[172:175], v[196:199], 0
	v_mfma_f32_16x16x32_bf16 v[58:61], v[180:183], v[196:199], 0
	v_mfma_f32_16x16x32_bf16 v[50:53], v[188:191], v[196:199], 0
	v_mfma_f32_16x16x32_bf16 v[34:37], v[188:191], v[204:207], 0
	v_mfma_f32_16x16x32_bf16 v[42:45], v[180:183], v[204:207], 0
	v_mfma_f32_16x16x32_bf16 v[38:41], v[172:175], v[204:207], 0
	v_mfma_f32_16x16x32_bf16 v[46:49], v[164:167], v[204:207], 0
	v_mfma_f32_16x16x32_bf16 v[30:33], v[164:167], v[212:215], 0
	v_mfma_f32_16x16x32_bf16 v[22:25], v[172:175], v[212:215], 0
	v_mfma_f32_16x16x32_bf16 v[26:29], v[180:183], v[212:215], 0
	v_mfma_f32_16x16x32_bf16 v[18:21], v[188:191], v[212:215], 0
	v_mfma_f32_16x16x32_bf16 v[2:5], v[188:191], v[220:223], 0
	v_mfma_f32_16x16x32_bf16 v[10:13], v[180:183], v[220:223], 0
	v_mfma_f32_16x16x32_bf16 v[6:9], v[172:175], v[220:223], 0
	v_mfma_f32_16x16x32_bf16 v[14:17], v[164:167], v[220:223], 0
	v_mfma_f32_16x16x32_bf16 v[62:65], v[168:171], v[200:203], v[62:65]
	v_mfma_f32_16x16x32_bf16 v[54:57], v[176:179], v[200:203], v[54:57]
	v_mfma_f32_16x16x32_bf16 v[58:61], v[184:187], v[200:203], v[58:61]
	v_mfma_f32_16x16x32_bf16 v[50:53], v[192:195], v[200:203], v[50:53]
	v_mfma_f32_16x16x32_bf16 v[34:37], v[192:195], v[208:211], v[34:37]
	v_mfma_f32_16x16x32_bf16 v[42:45], v[184:187], v[208:211], v[42:45]
	v_mfma_f32_16x16x32_bf16 v[38:41], v[176:179], v[208:211], v[38:41]
	v_mfma_f32_16x16x32_bf16 v[46:49], v[168:171], v[208:211], v[46:49]
	v_mfma_f32_16x16x32_bf16 v[30:33], v[168:171], v[216:219], v[30:33]
	v_mfma_f32_16x16x32_bf16 v[22:25], v[176:179], v[216:219], v[22:25]
	v_mfma_f32_16x16x32_bf16 v[26:29], v[184:187], v[216:219], v[26:29]
	v_mfma_f32_16x16x32_bf16 v[18:21], v[192:195], v[216:219], v[18:21]
	v_mfma_f32_16x16x32_bf16 v[2:5], v[192:195], v[224:227], v[2:5]
	v_mfma_f32_16x16x32_bf16 v[10:13], v[184:187], v[224:227], v[10:13]
	v_mfma_f32_16x16x32_bf16 v[6:9], v[176:179], v[224:227], v[6:9]
	v_mfma_f32_16x16x32_bf16 v[14:17], v[168:171], v[224:227], v[14:17]
	s_barrier
	s_setprio 0
	s_add_u32 s98, s94, 0x40000
	s_addc_u32 s99, s95, 0
	s_add_i32 s5, 0, 0x18000
	s_add_i32 s45, 0, 0x1c000
	s_mov_b32 m0, s57
	ds_read_b128 v[164:167], v232
	global_load_lds_dwordx4 v130, s[98:99]
	s_mov_b32 m0, s58
	ds_read_b128 v[168:171], v232 offset:1024
	global_load_lds_dwordx4 v134, s[98:99]
	ds_read_b128 v[172:175], v232 offset:2048
	ds_read_b128 v[176:179], v232 offset:3072
	ds_read_b128 v[180:183], v233
	ds_read_b128 v[184:187], v233 offset:1024
	ds_read_b128 v[188:191], v233 offset:2048
	ds_read_b128 v[192:195], v233 offset:3072
	ds_read_b128 v[196:199], v160 offset:32768
	ds_read_b128 v[200:203], v160 offset:33792
	ds_read_b128 v[204:207], v160 offset:34816
	ds_read_b128 v[208:211], v160 offset:35840
	ds_read_b128 v[212:215], v160 offset:36864
	ds_read_b128 v[216:219], v160 offset:37888
	ds_read_b128 v[220:223], v160 offset:38912
	ds_read_b128 v[224:227], v160 offset:39936
	s_waitcnt vmcnt(8)
	s_waitcnt lgkmcnt(0)
	s_setprio 1
	s_barrier
	v_mfma_f32_16x16x32_bf16 v[122:125], v[164:167], v[196:199], v[122:125]
	v_mfma_f32_16x16x32_bf16 v[118:121], v[172:175], v[196:199], v[118:121]
	v_mfma_f32_16x16x32_bf16 v[126:129], v[180:183], v[196:199], v[126:129]
	v_mfma_f32_16x16x32_bf16 v[114:117], v[188:191], v[196:199], v[114:117]
	v_mfma_f32_16x16x32_bf16 v[98:101], v[188:191], v[204:207], v[98:101]
	v_mfma_f32_16x16x32_bf16 v[106:109], v[180:183], v[204:207], v[106:109]
	v_mfma_f32_16x16x32_bf16 v[102:105], v[172:175], v[204:207], v[102:105]
	v_mfma_f32_16x16x32_bf16 v[110:113], v[164:167], v[204:207], v[110:113]
	v_mfma_f32_16x16x32_bf16 v[94:97], v[164:167], v[212:215], v[94:97]
	v_mfma_f32_16x16x32_bf16 v[86:89], v[172:175], v[212:215], v[86:89]
	v_mfma_f32_16x16x32_bf16 v[90:93], v[180:183], v[212:215], v[90:93]
	v_mfma_f32_16x16x32_bf16 v[82:85], v[188:191], v[212:215], v[82:85]
	v_mfma_f32_16x16x32_bf16 v[66:69], v[188:191], v[220:223], v[66:69]
	v_mfma_f32_16x16x32_bf16 v[74:77], v[180:183], v[220:223], v[74:77]
	v_mfma_f32_16x16x32_bf16 v[70:73], v[172:175], v[220:223], v[70:73]
	v_mfma_f32_16x16x32_bf16 v[78:81], v[164:167], v[220:223], v[78:81]
	v_mfma_f32_16x16x32_bf16 v[122:125], v[168:171], v[200:203], v[122:125]
	v_mfma_f32_16x16x32_bf16 v[118:121], v[176:179], v[200:203], v[118:121]
	v_mfma_f32_16x16x32_bf16 v[126:129], v[184:187], v[200:203], v[126:129]
	v_mfma_f32_16x16x32_bf16 v[114:117], v[192:195], v[200:203], v[114:117]
	v_mfma_f32_16x16x32_bf16 v[98:101], v[192:195], v[208:211], v[98:101]
	v_mfma_f32_16x16x32_bf16 v[106:109], v[184:187], v[208:211], v[106:109]
	v_mfma_f32_16x16x32_bf16 v[102:105], v[176:179], v[208:211], v[102:105]
	v_mfma_f32_16x16x32_bf16 v[110:113], v[168:171], v[208:211], v[110:113]
	v_mfma_f32_16x16x32_bf16 v[94:97], v[168:171], v[216:219], v[94:97]
	v_mfma_f32_16x16x32_bf16 v[86:89], v[176:179], v[216:219], v[86:89]
	v_mfma_f32_16x16x32_bf16 v[90:93], v[184:187], v[216:219], v[90:93]
	v_mfma_f32_16x16x32_bf16 v[82:85], v[192:195], v[216:219], v[82:85]
	v_mfma_f32_16x16x32_bf16 v[66:69], v[192:195], v[224:227], v[66:69]
	v_mfma_f32_16x16x32_bf16 v[74:77], v[184:187], v[224:227], v[74:77]
	v_mfma_f32_16x16x32_bf16 v[70:73], v[176:179], v[224:227], v[70:73]
	v_mfma_f32_16x16x32_bf16 v[78:81], v[168:171], v[224:227], v[78:81]
	s_barrier
	s_setprio 0
	s_add_u32 s96, s96, 0x80
	s_addc_u32 s97, s97, 0
	s_add_u32 s98, s96, 0x40000
	s_addc_u32 s99, s97, 0
	s_add_u32 s94, s94, 0x80
	s_addc_u32 s95, s95, 0
	s_add_i32 s5, s5, s23
	s_mov_b32 m0, s5
	ds_read_b128 v[196:199], v160 offset:49152
	global_load_lds_dwordx4 v132, s[96:97]
	s_add_i32 m0, s5, 0x2000
	s_add_i32 s5, s45, s23
	global_load_lds_dwordx4 v136, s[96:97]
	s_mov_b32 m0, s5
	ds_read_b128 v[200:203], v160 offset:50176
	global_load_lds_dwordx4 v132, s[98:99]
	s_add_i32 m0, s5, 0x2000
	ds_read_b128 v[204:207], v160 offset:51200
	global_load_lds_dwordx4 v136, s[98:99]
	s_mov_b32 m0, s64
	ds_read_b128 v[208:211], v160 offset:52224
	global_load_lds_dwordx4 v130, s[94:95]
	s_mov_b32 m0, s65
	ds_read_b128 v[212:215], v160 offset:53248
	global_load_lds_dwordx4 v134, s[94:95]
	ds_read_b128 v[216:219], v160 offset:54272
	ds_read_b128 v[220:223], v160 offset:55296
	ds_read_b128 v[224:227], v160 offset:56320
	s_waitcnt vmcnt(8)
	s_waitcnt lgkmcnt(0)
	s_setprio 1
	s_barrier
	v_mfma_f32_16x16x32_bf16 v[62:65], v[164:167], v[196:199], v[62:65]
	v_mfma_f32_16x16x32_bf16 v[54:57], v[172:175], v[196:199], v[54:57]
	v_mfma_f32_16x16x32_bf16 v[58:61], v[180:183], v[196:199], v[58:61]
	v_mfma_f32_16x16x32_bf16 v[50:53], v[188:191], v[196:199], v[50:53]
	v_mfma_f32_16x16x32_bf16 v[34:37], v[188:191], v[204:207], v[34:37]
	v_mfma_f32_16x16x32_bf16 v[42:45], v[180:183], v[204:207], v[42:45]
	v_mfma_f32_16x16x32_bf16 v[38:41], v[172:175], v[204:207], v[38:41]
	v_mfma_f32_16x16x32_bf16 v[46:49], v[164:167], v[204:207], v[46:49]
	v_mfma_f32_16x16x32_bf16 v[30:33], v[164:167], v[212:215], v[30:33]
	v_mfma_f32_16x16x32_bf16 v[22:25], v[172:175], v[212:215], v[22:25]
	v_mfma_f32_16x16x32_bf16 v[26:29], v[180:183], v[212:215], v[26:29]
	v_mfma_f32_16x16x32_bf16 v[18:21], v[188:191], v[212:215], v[18:21]
	v_mfma_f32_16x16x32_bf16 v[2:5], v[188:191], v[220:223], v[2:5]
	v_mfma_f32_16x16x32_bf16 v[10:13], v[180:183], v[220:223], v[10:13]
	v_mfma_f32_16x16x32_bf16 v[6:9], v[172:175], v[220:223], v[6:9]
	v_mfma_f32_16x16x32_bf16 v[14:17], v[164:167], v[220:223], v[14:17]
	v_mfma_f32_16x16x32_bf16 v[62:65], v[168:171], v[200:203], v[62:65]
	v_mfma_f32_16x16x32_bf16 v[54:57], v[176:179], v[200:203], v[54:57]
	v_mfma_f32_16x16x32_bf16 v[58:61], v[184:187], v[200:203], v[58:61]
	v_mfma_f32_16x16x32_bf16 v[50:53], v[192:195], v[200:203], v[50:53]
	v_mfma_f32_16x16x32_bf16 v[34:37], v[192:195], v[208:211], v[34:37]
	v_mfma_f32_16x16x32_bf16 v[42:45], v[184:187], v[208:211], v[42:45]
	v_mfma_f32_16x16x32_bf16 v[38:41], v[176:179], v[208:211], v[38:41]
	v_mfma_f32_16x16x32_bf16 v[46:49], v[168:171], v[208:211], v[46:49]
	v_mfma_f32_16x16x32_bf16 v[30:33], v[168:171], v[216:219], v[30:33]
	v_mfma_f32_16x16x32_bf16 v[22:25], v[176:179], v[216:219], v[22:25]
	v_mfma_f32_16x16x32_bf16 v[26:29], v[184:187], v[216:219], v[26:29]
	v_mfma_f32_16x16x32_bf16 v[18:21], v[192:195], v[216:219], v[18:21]
	v_mfma_f32_16x16x32_bf16 v[2:5], v[192:195], v[224:227], v[2:5]
	v_mfma_f32_16x16x32_bf16 v[10:13], v[184:187], v[224:227], v[10:13]
	v_mfma_f32_16x16x32_bf16 v[6:9], v[176:179], v[224:227], v[6:9]
	v_mfma_f32_16x16x32_bf16 v[14:17], v[168:171], v[224:227], v[14:17]
	s_barrier
	s_setprio 0
	s_mov_b32 s5, s29
	s_add_u32 s88, s88, 0x100
	s_addc_u32 s89, s89, 0
	s_add_u32 s86, s86, 0x100
	s_addc_u32 s87, s87, 0
	s_cmp_ge_i32 s29, s101
	s_cbranch_scc1 .Lmy_kexit_9
.LBB0_1763:
	s_add_u32 s98, s86, 0xfffc0080
	s_addc_u32 s99, s87, -1
	s_cmp_eq_u32 s5, s100
	s_cselect_b64 s[94:95], s[90:91], s[98:99]
	s_cselect_b64 s[96:97], s[92:93], s[88:89]
	s_add_i32 s29, s5, 2
	s_add_i32 m0, s47, 0xc000
	ds_read_b128 v[164:167], v230
	global_load_lds_dwordx4 v144, s[86:87]
	s_add_i32 m0, s47, 0xe000
	ds_read_b128 v[168:171], v230 offset:1024
	global_load_lds_dwordx4 v142, s[86:87]
	ds_read_b128 v[172:175], v230 offset:2048
	ds_read_b128 v[176:179], v230 offset:3072
	ds_read_b128 v[180:183], v231
	ds_read_b128 v[184:187], v231 offset:1024
	ds_read_b128 v[188:191], v231 offset:2048
	ds_read_b128 v[192:195], v231 offset:3072
	ds_read_b128 v[196:199], v160
	ds_read_b128 v[200:203], v160 offset:1024
	ds_read_b128 v[204:207], v160 offset:2048
	ds_read_b128 v[208:211], v160 offset:3072
	ds_read_b128 v[212:215], v160 offset:4096
	ds_read_b128 v[216:219], v160 offset:5120
	ds_read_b128 v[220:223], v160 offset:6144
	ds_read_b128 v[224:227], v160 offset:7168
	s_waitcnt vmcnt(8)
	s_waitcnt lgkmcnt(0)
	s_setprio 1
	s_barrier
	v_mfma_f32_16x16x32_bf16 v[122:125], v[164:167], v[196:199], v[122:125]
	v_mfma_f32_16x16x32_bf16 v[118:121], v[172:175], v[196:199], v[118:121]
	v_mfma_f32_16x16x32_bf16 v[126:129], v[180:183], v[196:199], v[126:129]
	v_mfma_f32_16x16x32_bf16 v[114:117], v[188:191], v[196:199], v[114:117]
	v_mfma_f32_16x16x32_bf16 v[98:101], v[188:191], v[204:207], v[98:101]
	v_mfma_f32_16x16x32_bf16 v[106:109], v[180:183], v[204:207], v[106:109]
	v_mfma_f32_16x16x32_bf16 v[102:105], v[172:175], v[204:207], v[102:105]
	v_mfma_f32_16x16x32_bf16 v[110:113], v[164:167], v[204:207], v[110:113]
	v_mfma_f32_16x16x32_bf16 v[94:97], v[164:167], v[212:215], v[94:97]
	v_mfma_f32_16x16x32_bf16 v[86:89], v[172:175], v[212:215], v[86:89]
	v_mfma_f32_16x16x32_bf16 v[90:93], v[180:183], v[212:215], v[90:93]
	v_mfma_f32_16x16x32_bf16 v[82:85], v[188:191], v[212:215], v[82:85]
	v_mfma_f32_16x16x32_bf16 v[66:69], v[188:191], v[220:223], v[66:69]
	v_mfma_f32_16x16x32_bf16 v[74:77], v[180:183], v[220:223], v[74:77]
	v_mfma_f32_16x16x32_bf16 v[70:73], v[172:175], v[220:223], v[70:73]
	v_mfma_f32_16x16x32_bf16 v[78:81], v[164:167], v[220:223], v[78:81]
	v_mfma_f32_16x16x32_bf16 v[122:125], v[168:171], v[200:203], v[122:125]
	v_mfma_f32_16x16x32_bf16 v[118:121], v[176:179], v[200:203], v[118:121]
	v_mfma_f32_16x16x32_bf16 v[126:129], v[184:187], v[200:203], v[126:129]
	v_mfma_f32_16x16x32_bf16 v[114:117], v[192:195], v[200:203], v[114:117]
	v_mfma_f32_16x16x32_bf16 v[98:101], v[192:195], v[208:211], v[98:101]
	v_mfma_f32_16x16x32_bf16 v[106:109], v[184:187], v[208:211], v[106:109]
	v_mfma_f32_16x16x32_bf16 v[102:105], v[176:179], v[208:211], v[102:105]
	v_mfma_f32_16x16x32_bf16 v[110:113], v[168:171], v[208:211], v[110:113]
	v_mfma_f32_16x16x32_bf16 v[94:97], v[168:171], v[216:219], v[94:97]
	v_mfma_f32_16x16x32_bf16 v[86:89], v[176:179], v[216:219], v[86:89]
	v_mfma_f32_16x16x32_bf16 v[90:93], v[184:187], v[216:219], v[90:93]
	v_mfma_f32_16x16x32_bf16 v[82:85], v[192:195], v[216:219], v[82:85]
	v_mfma_f32_16x16x32_bf16 v[66:69], v[192:195], v[224:227], v[66:69]
	v_mfma_f32_16x16x32_bf16 v[74:77], v[184:187], v[224:227], v[74:77]
	v_mfma_f32_16x16x32_bf16 v[70:73], v[176:179], v[224:227], v[70:73]
	v_mfma_f32_16x16x32_bf16 v[78:81], v[168:171], v[224:227], v[78:81]
	s_barrier
	s_setprio 0
	s_add_u32 s98, s96, 0x40000
	s_addc_u32 s99, s97, 0
	s_add_i32 s5, s74, s23
	s_mov_b32 m0, s5
	ds_read_b128 v[196:199], v160 offset:16384
	global_load_lds_dwordx4 v132, s[96:97]
	s_add_i32 m0, s5, 0x2000
	s_add_i32 s5, s75, s23
	global_load_lds_dwordx4 v136, s[96:97]
	s_mov_b32 m0, s5
	ds_read_b128 v[200:203], v160 offset:17408
	global_load_lds_dwordx4 v132, s[98:99]
	s_add_i32 m0, s5, 0x2000
	ds_read_b128 v[204:207], v160 offset:18432
	global_load_lds_dwordx4 v136, s[98:99]
	s_mov_b32 m0, s47
	ds_read_b128 v[208:211], v160 offset:19456
	global_load_lds_dwordx4 v130, s[94:95]
	s_mov_b32 m0, s56
	ds_read_b128 v[212:215], v160 offset:20480
	global_load_lds_dwordx4 v134, s[94:95]
	ds_read_b128 v[216:219], v160 offset:21504
	ds_read_b128 v[220:223], v160 offset:22528
	ds_read_b128 v[224:227], v160 offset:23552
	s_waitcnt vmcnt(8)
	s_waitcnt lgkmcnt(0)
	s_setprio 1
	s_barrier
	v_mfma_f32_16x16x32_bf16 v[62:65], v[164:167], v[196:199], v[62:65]
	v_mfma_f32_16x16x32_bf16 v[54:57], v[172:175], v[196:199], v[54:57]
	v_mfma_f32_16x16x32_bf16 v[58:61], v[180:183], v[196:199], v[58:61]
	v_mfma_f32_16x16x32_bf16 v[50:53], v[188:191], v[196:199], v[50:53]
	v_mfma_f32_16x16x32_bf16 v[34:37], v[188:191], v[204:207], v[34:37]
	v_mfma_f32_16x16x32_bf16 v[42:45], v[180:183], v[204:207], v[42:45]
	v_mfma_f32_16x16x32_bf16 v[38:41], v[172:175], v[204:207], v[38:41]
	v_mfma_f32_16x16x32_bf16 v[46:49], v[164:167], v[204:207], v[46:49]
	v_mfma_f32_16x16x32_bf16 v[30:33], v[164:167], v[212:215], v[30:33]
	v_mfma_f32_16x16x32_bf16 v[22:25], v[172:175], v[212:215], v[22:25]
	v_mfma_f32_16x16x32_bf16 v[26:29], v[180:183], v[212:215], v[26:29]
	v_mfma_f32_16x16x32_bf16 v[18:21], v[188:191], v[212:215], v[18:21]
	v_mfma_f32_16x16x32_bf16 v[2:5], v[188:191], v[220:223], v[2:5]
	v_mfma_f32_16x16x32_bf16 v[10:13], v[180:183], v[220:223], v[10:13]
	v_mfma_f32_16x16x32_bf16 v[6:9], v[172:175], v[220:223], v[6:9]
	v_mfma_f32_16x16x32_bf16 v[14:17], v[164:167], v[220:223], v[14:17]
	v_mfma_f32_16x16x32_bf16 v[62:65], v[168:171], v[200:203], v[62:65]
	v_mfma_f32_16x16x32_bf16 v[54:57], v[176:179], v[200:203], v[54:57]
	v_mfma_f32_16x16x32_bf16 v[58:61], v[184:187], v[200:203], v[58:61]
	v_mfma_f32_16x16x32_bf16 v[50:53], v[192:195], v[200:203], v[50:53]
	v_mfma_f32_16x16x32_bf16 v[34:37], v[192:195], v[208:211], v[34:37]
	v_mfma_f32_16x16x32_bf16 v[42:45], v[184:187], v[208:211], v[42:45]
	v_mfma_f32_16x16x32_bf16 v[38:41], v[176:179], v[208:211], v[38:41]
	v_mfma_f32_16x16x32_bf16 v[46:49], v[168:171], v[208:211], v[46:49]
	v_mfma_f32_16x16x32_bf16 v[30:33], v[168:171], v[216:219], v[30:33]
	v_mfma_f32_16x16x32_bf16 v[22:25], v[176:179], v[216:219], v[22:25]
	v_mfma_f32_16x16x32_bf16 v[26:29], v[184:187], v[216:219], v[26:29]
	v_mfma_f32_16x16x32_bf16 v[18:21], v[192:195], v[216:219], v[18:21]
	v_mfma_f32_16x16x32_bf16 v[2:5], v[192:195], v[224:227], v[2:5]
	v_mfma_f32_16x16x32_bf16 v[10:13], v[184:187], v[224:227], v[10:13]
	v_mfma_f32_16x16x32_bf16 v[6:9], v[176:179], v[224:227], v[6:9]
	v_mfma_f32_16x16x32_bf16 v[14:17], v[168:171], v[224:227], v[14:17]
	s_barrier
	s_setprio 0
	s_add_u32 s98, s94, 0x40000
	s_addc_u32 s99, s95, 0
	s_add_i32 s5, 0, 0x18000
	s_add_i32 s45, 0, 0x1c000
	s_mov_b32 m0, s57
	ds_read_b128 v[164:167], v232
	global_load_lds_dwordx4 v130, s[98:99]
	s_mov_b32 m0, s58
	ds_read_b128 v[168:171], v232 offset:1024
	global_load_lds_dwordx4 v134, s[98:99]
	ds_read_b128 v[172:175], v232 offset:2048
	ds_read_b128 v[176:179], v232 offset:3072
	ds_read_b128 v[180:183], v233
	ds_read_b128 v[184:187], v233 offset:1024
	ds_read_b128 v[188:191], v233 offset:2048
	ds_read_b128 v[192:195], v233 offset:3072
	ds_read_b128 v[196:199], v160 offset:32768
	ds_read_b128 v[200:203], v160 offset:33792
	ds_read_b128 v[204:207], v160 offset:34816
	ds_read_b128 v[208:211], v160 offset:35840
	ds_read_b128 v[212:215], v160 offset:36864
	ds_read_b128 v[216:219], v160 offset:37888
	ds_read_b128 v[220:223], v160 offset:38912
	ds_read_b128 v[224:227], v160 offset:39936
	s_waitcnt vmcnt(8)
	s_waitcnt lgkmcnt(0)
	s_setprio 1
	s_barrier
	v_mfma_f32_16x16x32_bf16 v[122:125], v[164:167], v[196:199], v[122:125]
	v_mfma_f32_16x16x32_bf16 v[118:121], v[172:175], v[196:199], v[118:121]
	v_mfma_f32_16x16x32_bf16 v[126:129], v[180:183], v[196:199], v[126:129]
	v_mfma_f32_16x16x32_bf16 v[114:117], v[188:191], v[196:199], v[114:117]
	v_mfma_f32_16x16x32_bf16 v[98:101], v[188:191], v[204:207], v[98:101]
	v_mfma_f32_16x16x32_bf16 v[106:109], v[180:183], v[204:207], v[106:109]
	v_mfma_f32_16x16x32_bf16 v[102:105], v[172:175], v[204:207], v[102:105]
	v_mfma_f32_16x16x32_bf16 v[110:113], v[164:167], v[204:207], v[110:113]
	v_mfma_f32_16x16x32_bf16 v[94:97], v[164:167], v[212:215], v[94:97]
	v_mfma_f32_16x16x32_bf16 v[86:89], v[172:175], v[212:215], v[86:89]
	v_mfma_f32_16x16x32_bf16 v[90:93], v[180:183], v[212:215], v[90:93]
	v_mfma_f32_16x16x32_bf16 v[82:85], v[188:191], v[212:215], v[82:85]
	v_mfma_f32_16x16x32_bf16 v[66:69], v[188:191], v[220:223], v[66:69]
	v_mfma_f32_16x16x32_bf16 v[74:77], v[180:183], v[220:223], v[74:77]
	v_mfma_f32_16x16x32_bf16 v[70:73], v[172:175], v[220:223], v[70:73]
	v_mfma_f32_16x16x32_bf16 v[78:81], v[164:167], v[220:223], v[78:81]
	v_mfma_f32_16x16x32_bf16 v[122:125], v[168:171], v[200:203], v[122:125]
	v_mfma_f32_16x16x32_bf16 v[118:121], v[176:179], v[200:203], v[118:121]
	v_mfma_f32_16x16x32_bf16 v[126:129], v[184:187], v[200:203], v[126:129]
	v_mfma_f32_16x16x32_bf16 v[114:117], v[192:195], v[200:203], v[114:117]
	v_mfma_f32_16x16x32_bf16 v[98:101], v[192:195], v[208:211], v[98:101]
	v_mfma_f32_16x16x32_bf16 v[106:109], v[184:187], v[208:211], v[106:109]
	v_mfma_f32_16x16x32_bf16 v[102:105], v[176:179], v[208:211], v[102:105]
	v_mfma_f32_16x16x32_bf16 v[110:113], v[168:171], v[208:211], v[110:113]
	v_mfma_f32_16x16x32_bf16 v[94:97], v[168:171], v[216:219], v[94:97]
	v_mfma_f32_16x16x32_bf16 v[86:89], v[176:179], v[216:219], v[86:89]
	v_mfma_f32_16x16x32_bf16 v[90:93], v[184:187], v[216:219], v[90:93]
	v_mfma_f32_16x16x32_bf16 v[82:85], v[192:195], v[216:219], v[82:85]
	v_mfma_f32_16x16x32_bf16 v[66:69], v[192:195], v[224:227], v[66:69]
	v_mfma_f32_16x16x32_bf16 v[74:77], v[184:187], v[224:227], v[74:77]
	v_mfma_f32_16x16x32_bf16 v[70:73], v[176:179], v[224:227], v[70:73]
	v_mfma_f32_16x16x32_bf16 v[78:81], v[168:171], v[224:227], v[78:81]
	s_barrier
	s_setprio 0
	s_add_u32 s96, s96, 0x80
	s_addc_u32 s97, s97, 0
	s_add_u32 s98, s96, 0x40000
	s_addc_u32 s99, s97, 0
	s_add_u32 s94, s94, 0x80
	s_addc_u32 s95, s95, 0
	s_add_i32 s5, s5, s23
	s_mov_b32 m0, s5
	ds_read_b128 v[196:199], v160 offset:49152
	global_load_lds_dwordx4 v132, s[96:97]
	s_add_i32 m0, s5, 0x2000
	s_add_i32 s5, s45, s23
	global_load_lds_dwordx4 v136, s[96:97]
	s_mov_b32 m0, s5
	ds_read_b128 v[200:203], v160 offset:50176
	global_load_lds_dwordx4 v132, s[98:99]
	s_add_i32 m0, s5, 0x2000
	ds_read_b128 v[204:207], v160 offset:51200
	global_load_lds_dwordx4 v136, s[98:99]
	s_mov_b32 m0, s64
	ds_read_b128 v[208:211], v160 offset:52224
	global_load_lds_dwordx4 v130, s[94:95]
	s_mov_b32 m0, s65
	ds_read_b128 v[212:215], v160 offset:53248
	global_load_lds_dwordx4 v134, s[94:95]
	ds_read_b128 v[216:219], v160 offset:54272
	ds_read_b128 v[220:223], v160 offset:55296
	ds_read_b128 v[224:227], v160 offset:56320
	s_waitcnt vmcnt(8)
	s_waitcnt lgkmcnt(0)
	s_setprio 1
	s_barrier
	v_mfma_f32_16x16x32_bf16 v[62:65], v[164:167], v[196:199], v[62:65]
	v_mfma_f32_16x16x32_bf16 v[54:57], v[172:175], v[196:199], v[54:57]
	v_mfma_f32_16x16x32_bf16 v[58:61], v[180:183], v[196:199], v[58:61]
	v_mfma_f32_16x16x32_bf16 v[50:53], v[188:191], v[196:199], v[50:53]
	v_mfma_f32_16x16x32_bf16 v[34:37], v[188:191], v[204:207], v[34:37]
	v_mfma_f32_16x16x32_bf16 v[42:45], v[180:183], v[204:207], v[42:45]
	v_mfma_f32_16x16x32_bf16 v[38:41], v[172:175], v[204:207], v[38:41]
	v_mfma_f32_16x16x32_bf16 v[46:49], v[164:167], v[204:207], v[46:49]
	v_mfma_f32_16x16x32_bf16 v[30:33], v[164:167], v[212:215], v[30:33]
	v_mfma_f32_16x16x32_bf16 v[22:25], v[172:175], v[212:215], v[22:25]
	v_mfma_f32_16x16x32_bf16 v[26:29], v[180:183], v[212:215], v[26:29]
	v_mfma_f32_16x16x32_bf16 v[18:21], v[188:191], v[212:215], v[18:21]
	v_mfma_f32_16x16x32_bf16 v[2:5], v[188:191], v[220:223], v[2:5]
	v_mfma_f32_16x16x32_bf16 v[10:13], v[180:183], v[220:223], v[10:13]
	v_mfma_f32_16x16x32_bf16 v[6:9], v[172:175], v[220:223], v[6:9]
	v_mfma_f32_16x16x32_bf16 v[14:17], v[164:167], v[220:223], v[14:17]
	v_mfma_f32_16x16x32_bf16 v[62:65], v[168:171], v[200:203], v[62:65]
	v_mfma_f32_16x16x32_bf16 v[54:57], v[176:179], v[200:203], v[54:57]
	v_mfma_f32_16x16x32_bf16 v[58:61], v[184:187], v[200:203], v[58:61]
	v_mfma_f32_16x16x32_bf16 v[50:53], v[192:195], v[200:203], v[50:53]
	v_mfma_f32_16x16x32_bf16 v[34:37], v[192:195], v[208:211], v[34:37]
	v_mfma_f32_16x16x32_bf16 v[42:45], v[184:187], v[208:211], v[42:45]
	v_mfma_f32_16x16x32_bf16 v[38:41], v[176:179], v[208:211], v[38:41]
	v_mfma_f32_16x16x32_bf16 v[46:49], v[168:171], v[208:211], v[46:49]
	v_mfma_f32_16x16x32_bf16 v[30:33], v[168:171], v[216:219], v[30:33]
	v_mfma_f32_16x16x32_bf16 v[22:25], v[176:179], v[216:219], v[22:25]
	v_mfma_f32_16x16x32_bf16 v[26:29], v[184:187], v[216:219], v[26:29]
	v_mfma_f32_16x16x32_bf16 v[18:21], v[192:195], v[216:219], v[18:21]
	v_mfma_f32_16x16x32_bf16 v[2:5], v[192:195], v[224:227], v[2:5]
	v_mfma_f32_16x16x32_bf16 v[10:13], v[184:187], v[224:227], v[10:13]
	v_mfma_f32_16x16x32_bf16 v[6:9], v[176:179], v[224:227], v[6:9]
	v_mfma_f32_16x16x32_bf16 v[14:17], v[168:171], v[224:227], v[14:17]
	s_barrier
	s_setprio 0
	s_mov_b32 s5, s29
	s_add_u32 s88, s88, 0x100
	s_addc_u32 s89, s89, 0
	s_add_u32 s86, s86, 0x100
	s_addc_u32 s87, s87, 0
	s_cmp_ge_i32 s29, s101
	s_cbranch_scc0 .LBB0_1763

.Lmy_nb_10:
	s_nop 0
	v_readfirstlane_b32 s86, v152
	v_readfirstlane_b32 s87, v153
	v_readfirstlane_b32 s88, v150
	v_readfirstlane_b32 s89, v151
	v_readfirstlane_b32 s90, v146
	v_readfirstlane_b32 s91, v147
	v_readfirstlane_b32 s92, v148
	v_readfirstlane_b32 s93, v149
	v_readfirstlane_b32 s100, v154
	v_readfirstlane_b32 s101, v138
	v_add_u32_e32 v230, s72, v141
	v_add_u32_e32 v231, s73, v141
	v_add_u32_e32 v232, 0x18000, v141
	v_add_u32_e32 v233, 0x1c000, v141
	s_add_u32 s98, s86, 0xfffc0080
	s_addc_u32 s99, s87, -1
	s_cmp_eq_u32 s5, s100
	s_cselect_b64 s[94:95], s[90:91], s[98:99]
	s_cselect_b64 s[96:97], s[92:93], s[88:89]
	s_add_i32 s45, s5, 2
	s_mov_b32 m0, s74
	ds_read_b128 v[164:167], v230
	global_load_lds_dwordx4 v144, s[86:87]
	s_mov_b32 m0, s75
	ds_read_b128 v[168:171], v230 offset:1024
	global_load_lds_dwordx4 v142, s[86:87]
	ds_read_b128 v[172:175], v230 offset:2048
	ds_read_b128 v[176:179], v230 offset:3072
	ds_read_b128 v[180:183], v231
	ds_read_b128 v[184:187], v231 offset:1024
	ds_read_b128 v[188:191], v231 offset:2048
	ds_read_b128 v[192:195], v231 offset:3072
	ds_read_b128 v[196:199], v160
	ds_read_b128 v[200:203], v160 offset:1024
	ds_read_b128 v[204:207], v160 offset:2048
	ds_read_b128 v[208:211], v160 offset:3072
	ds_read_b128 v[212:215], v160 offset:4096
	ds_read_b128 v[216:219], v160 offset:5120
	ds_read_b128 v[220:223], v160 offset:6144
	ds_read_b128 v[224:227], v160 offset:7168
	s_waitcnt vmcnt(8)
	s_waitcnt lgkmcnt(0)
	s_setprio 1
	s_barrier
	v_mfma_f32_16x16x32_bf16 v[122:125], v[164:167], v[196:199], 0
	v_mfma_f32_16x16x32_bf16 v[118:121], v[172:175], v[196:199], 0
	v_mfma_f32_16x16x32_bf16 v[126:129], v[180:183], v[196:199], 0
	v_mfma_f32_16x16x32_bf16 v[114:117], v[188:191], v[196:199], 0
	v_mfma_f32_16x16x32_bf16 v[98:101], v[188:191], v[204:207], 0
	v_mfma_f32_16x16x32_bf16 v[106:109], v[180:183], v[204:207], 0
	v_mfma_f32_16x16x32_bf16 v[102:105], v[172:175], v[204:207], 0
	v_mfma_f32_16x16x32_bf16 v[110:113], v[164:167], v[204:207], 0
	v_mfma_f32_16x16x32_bf16 v[94:97], v[164:167], v[212:215], 0
	v_mfma_f32_16x16x32_bf16 v[86:89], v[172:175], v[212:215], 0
	v_mfma_f32_16x16x32_bf16 v[90:93], v[180:183], v[212:215], 0
	v_mfma_f32_16x16x32_bf16 v[82:85], v[188:191], v[212:215], 0
	v_mfma_f32_16x16x32_bf16 v[66:69], v[188:191], v[220:223], 0
	v_mfma_f32_16x16x32_bf16 v[74:77], v[180:183], v[220:223], 0
	v_mfma_f32_16x16x32_bf16 v[70:73], v[172:175], v[220:223], 0
	v_mfma_f32_16x16x32_bf16 v[78:81], v[164:167], v[220:223], 0
	v_mfma_f32_16x16x32_bf16 v[122:125], v[168:171], v[200:203], v[122:125]
	v_mfma_f32_16x16x32_bf16 v[118:121], v[176:179], v[200:203], v[118:121]
	v_mfma_f32_16x16x32_bf16 v[126:129], v[184:187], v[200:203], v[126:129]
	v_mfma_f32_16x16x32_bf16 v[114:117], v[192:195], v[200:203], v[114:117]
	v_mfma_f32_16x16x32_bf16 v[98:101], v[192:195], v[208:211], v[98:101]
	v_mfma_f32_16x16x32_bf16 v[106:109], v[184:187], v[208:211], v[106:109]
	v_mfma_f32_16x16x32_bf16 v[102:105], v[176:179], v[208:211], v[102:105]
	v_mfma_f32_16x16x32_bf16 v[110:113], v[168:171], v[208:211], v[110:113]
	v_mfma_f32_16x16x32_bf16 v[94:97], v[168:171], v[216:219], v[94:97]
	v_mfma_f32_16x16x32_bf16 v[86:89], v[176:179], v[216:219], v[86:89]
	v_mfma_f32_16x16x32_bf16 v[90:93], v[184:187], v[216:219], v[90:93]
	v_mfma_f32_16x16x32_bf16 v[82:85], v[192:195], v[216:219], v[82:85]
	v_mfma_f32_16x16x32_bf16 v[66:69], v[192:195], v[224:227], v[66:69]
	v_mfma_f32_16x16x32_bf16 v[74:77], v[184:187], v[224:227], v[74:77]
	v_mfma_f32_16x16x32_bf16 v[70:73], v[176:179], v[224:227], v[70:73]
	v_mfma_f32_16x16x32_bf16 v[78:81], v[168:171], v[224:227], v[78:81]
	s_barrier
	s_setprio 0
	s_add_u32 s98, s96, 0x40000
	s_addc_u32 s99, s97, 0
	s_mov_b32 m0, s76
	ds_read_b128 v[196:199], v160 offset:16384
	global_load_lds_dwordx4 v132, s[96:97]
	s_mov_b32 m0, s77
	s_add_i32 s5, s73, s25
	global_load_lds_dwordx4 v136, s[96:97]
	s_mov_b32 m0, s5
	ds_read_b128 v[200:203], v160 offset:17408
	global_load_lds_dwordx4 v132, s[98:99]
	s_add_i32 m0, s5, 0x2000
	ds_read_b128 v[204:207], v160 offset:18432
	global_load_lds_dwordx4 v136, s[98:99]
	s_mov_b32 m0, s49
	ds_read_b128 v[208:211], v160 offset:19456
	global_load_lds_dwordx4 v130, s[94:95]
	s_mov_b32 m0, s58
	ds_read_b128 v[212:215], v160 offset:20480
	global_load_lds_dwordx4 v134, s[94:95]
	ds_read_b128 v[216:219], v160 offset:21504
	ds_read_b128 v[220:223], v160 offset:22528
	ds_read_b128 v[224:227], v160 offset:23552
	s_waitcnt vmcnt(8)
	s_waitcnt lgkmcnt(0)
	s_setprio 1
	s_barrier
	v_mfma_f32_16x16x32_bf16 v[62:65], v[164:167], v[196:199], 0
	v_mfma_f32_16x16x32_bf16 v[54:57], v[172:175], v[196:199], 0
	v_mfma_f32_16x16x32_bf16 v[58:61], v[180:183], v[196:199], 0
	v_mfma_f32_16x16x32_bf16 v[50:53], v[188:191], v[196:199], 0
	v_mfma_f32_16x16x32_bf16 v[34:37], v[188:191], v[204:207], 0
	v_mfma_f32_16x16x32_bf16 v[42:45], v[180:183], v[204:207], 0
	v_mfma_f32_16x16x32_bf16 v[38:41], v[172:175], v[204:207], 0
	v_mfma_f32_16x16x32_bf16 v[46:49], v[164:167], v[204:207], 0
	v_mfma_f32_16x16x32_bf16 v[30:33], v[164:167], v[212:215], 0
	v_mfma_f32_16x16x32_bf16 v[22:25], v[172:175], v[212:215], 0
	v_mfma_f32_16x16x32_bf16 v[26:29], v[180:183], v[212:215], 0
	v_mfma_f32_16x16x32_bf16 v[18:21], v[188:191], v[212:215], 0
	v_mfma_f32_16x16x32_bf16 v[2:5], v[188:191], v[220:223], 0
	v_mfma_f32_16x16x32_bf16 v[10:13], v[180:183], v[220:223], 0
	v_mfma_f32_16x16x32_bf16 v[6:9], v[172:175], v[220:223], 0
	v_mfma_f32_16x16x32_bf16 v[14:17], v[164:167], v[220:223], 0
	v_mfma_f32_16x16x32_bf16 v[62:65], v[168:171], v[200:203], v[62:65]
	v_mfma_f32_16x16x32_bf16 v[54:57], v[176:179], v[200:203], v[54:57]
	v_mfma_f32_16x16x32_bf16 v[58:61], v[184:187], v[200:203], v[58:61]
	v_mfma_f32_16x16x32_bf16 v[50:53], v[192:195], v[200:203], v[50:53]
	v_mfma_f32_16x16x32_bf16 v[34:37], v[192:195], v[208:211], v[34:37]
	v_mfma_f32_16x16x32_bf16 v[42:45], v[184:187], v[208:211], v[42:45]
	v_mfma_f32_16x16x32_bf16 v[38:41], v[176:179], v[208:211], v[38:41]
	v_mfma_f32_16x16x32_bf16 v[46:49], v[168:171], v[208:211], v[46:49]
	v_mfma_f32_16x16x32_bf16 v[30:33], v[168:171], v[216:219], v[30:33]
	v_mfma_f32_16x16x32_bf16 v[22:25], v[176:179], v[216:219], v[22:25]
	v_mfma_f32_16x16x32_bf16 v[26:29], v[184:187], v[216:219], v[26:29]
	v_mfma_f32_16x16x32_bf16 v[18:21], v[192:195], v[216:219], v[18:21]
	v_mfma_f32_16x16x32_bf16 v[2:5], v[192:195], v[224:227], v[2:5]
	v_mfma_f32_16x16x32_bf16 v[10:13], v[184:187], v[224:227], v[10:13]
	v_mfma_f32_16x16x32_bf16 v[6:9], v[176:179], v[224:227], v[6:9]
	v_mfma_f32_16x16x32_bf16 v[14:17], v[168:171], v[224:227], v[14:17]
	s_barrier
	s_setprio 0
	s_add_u32 s98, s94, 0x40000
	s_addc_u32 s99, s95, 0
	s_add_i32 s5, 0, 0x18000
	s_add_i32 s47, 0, 0x1c000
	s_mov_b32 m0, s59
	ds_read_b128 v[164:167], v232
	global_load_lds_dwordx4 v130, s[98:99]
	s_mov_b32 m0, s60
	ds_read_b128 v[168:171], v232 offset:1024
	global_load_lds_dwordx4 v134, s[98:99]
	ds_read_b128 v[172:175], v232 offset:2048
	ds_read_b128 v[176:179], v232 offset:3072
	ds_read_b128 v[180:183], v233
	ds_read_b128 v[184:187], v233 offset:1024
	ds_read_b128 v[188:191], v233 offset:2048
	ds_read_b128 v[192:195], v233 offset:3072
	ds_read_b128 v[196:199], v160 offset:32768
	ds_read_b128 v[200:203], v160 offset:33792
	ds_read_b128 v[204:207], v160 offset:34816
	ds_read_b128 v[208:211], v160 offset:35840
	ds_read_b128 v[212:215], v160 offset:36864
	ds_read_b128 v[216:219], v160 offset:37888
	ds_read_b128 v[220:223], v160 offset:38912
	ds_read_b128 v[224:227], v160 offset:39936
	s_waitcnt vmcnt(8)
	s_waitcnt lgkmcnt(0)
	s_setprio 1
	s_barrier
	v_mfma_f32_16x16x32_bf16 v[122:125], v[164:167], v[196:199], v[122:125]
	v_mfma_f32_16x16x32_bf16 v[118:121], v[172:175], v[196:199], v[118:121]
	v_mfma_f32_16x16x32_bf16 v[126:129], v[180:183], v[196:199], v[126:129]
	v_mfma_f32_16x16x32_bf16 v[114:117], v[188:191], v[196:199], v[114:117]
	v_mfma_f32_16x16x32_bf16 v[98:101], v[188:191], v[204:207], v[98:101]
	v_mfma_f32_16x16x32_bf16 v[106:109], v[180:183], v[204:207], v[106:109]
	v_mfma_f32_16x16x32_bf16 v[102:105], v[172:175], v[204:207], v[102:105]
	v_mfma_f32_16x16x32_bf16 v[110:113], v[164:167], v[204:207], v[110:113]
	v_mfma_f32_16x16x32_bf16 v[94:97], v[164:167], v[212:215], v[94:97]
	v_mfma_f32_16x16x32_bf16 v[86:89], v[172:175], v[212:215], v[86:89]
	v_mfma_f32_16x16x32_bf16 v[90:93], v[180:183], v[212:215], v[90:93]
	v_mfma_f32_16x16x32_bf16 v[82:85], v[188:191], v[212:215], v[82:85]
	v_mfma_f32_16x16x32_bf16 v[66:69], v[188:191], v[220:223], v[66:69]
	v_mfma_f32_16x16x32_bf16 v[74:77], v[180:183], v[220:223], v[74:77]
	v_mfma_f32_16x16x32_bf16 v[70:73], v[172:175], v[220:223], v[70:73]
	v_mfma_f32_16x16x32_bf16 v[78:81], v[164:167], v[220:223], v[78:81]
	v_mfma_f32_16x16x32_bf16 v[122:125], v[168:171], v[200:203], v[122:125]
	v_mfma_f32_16x16x32_bf16 v[118:121], v[176:179], v[200:203], v[118:121]
	v_mfma_f32_16x16x32_bf16 v[126:129], v[184:187], v[200:203], v[126:129]
	v_mfma_f32_16x16x32_bf16 v[114:117], v[192:195], v[200:203], v[114:117]
	v_mfma_f32_16x16x32_bf16 v[98:101], v[192:195], v[208:211], v[98:101]
	v_mfma_f32_16x16x32_bf16 v[106:109], v[184:187], v[208:211], v[106:109]
	v_mfma_f32_16x16x32_bf16 v[102:105], v[176:179], v[208:211], v[102:105]
	v_mfma_f32_16x16x32_bf16 v[110:113], v[168:171], v[208:211], v[110:113]
	v_mfma_f32_16x16x32_bf16 v[94:97], v[168:171], v[216:219], v[94:97]
	v_mfma_f32_16x16x32_bf16 v[86:89], v[176:179], v[216:219], v[86:89]
	v_mfma_f32_16x16x32_bf16 v[90:93], v[184:187], v[216:219], v[90:93]
	v_mfma_f32_16x16x32_bf16 v[82:85], v[192:195], v[216:219], v[82:85]
	v_mfma_f32_16x16x32_bf16 v[66:69], v[192:195], v[224:227], v[66:69]
	v_mfma_f32_16x16x32_bf16 v[74:77], v[184:187], v[224:227], v[74:77]
	v_mfma_f32_16x16x32_bf16 v[70:73], v[176:179], v[224:227], v[70:73]
	v_mfma_f32_16x16x32_bf16 v[78:81], v[168:171], v[224:227], v[78:81]
	s_barrier
	s_setprio 0
	s_add_u32 s96, s96, 0x80
	s_addc_u32 s97, s97, 0
	s_add_u32 s98, s96, 0x40000
	s_addc_u32 s99, s97, 0
	s_add_u32 s94, s94, 0x80
	s_addc_u32 s95, s95, 0
	s_add_i32 s5, s5, s25
	s_mov_b32 m0, s5
	ds_read_b128 v[196:199], v160 offset:49152
	global_load_lds_dwordx4 v132, s[96:97]
	s_add_i32 m0, s5, 0x2000
	s_add_i32 s5, s47, s25
	global_load_lds_dwordx4 v136, s[96:97]
	s_mov_b32 m0, s5
	ds_read_b128 v[200:203], v160 offset:50176
	global_load_lds_dwordx4 v132, s[98:99]
	s_add_i32 m0, s5, 0x2000
	ds_read_b128 v[204:207], v160 offset:51200
	global_load_lds_dwordx4 v136, s[98:99]
	s_mov_b32 m0, s61
	ds_read_b128 v[208:211], v160 offset:52224
	global_load_lds_dwordx4 v130, s[94:95]
	s_mov_b32 m0, s62
	ds_read_b128 v[212:215], v160 offset:53248
	global_load_lds_dwordx4 v134, s[94:95]
	ds_read_b128 v[216:219], v160 offset:54272
	ds_read_b128 v[220:223], v160 offset:55296
	ds_read_b128 v[224:227], v160 offset:56320
	s_waitcnt vmcnt(8)
	s_waitcnt lgkmcnt(0)
	s_setprio 1
	s_barrier
	v_mfma_f32_16x16x32_bf16 v[62:65], v[164:167], v[196:199], v[62:65]
	v_mfma_f32_16x16x32_bf16 v[54:57], v[172:175], v[196:199], v[54:57]
	v_mfma_f32_16x16x32_bf16 v[58:61], v[180:183], v[196:199], v[58:61]
	v_mfma_f32_16x16x32_bf16 v[50:53], v[188:191], v[196:199], v[50:53]
	v_mfma_f32_16x16x32_bf16 v[34:37], v[188:191], v[204:207], v[34:37]
	v_mfma_f32_16x16x32_bf16 v[42:45], v[180:183], v[204:207], v[42:45]
	v_mfma_f32_16x16x32_bf16 v[38:41], v[172:175], v[204:207], v[38:41]
	v_mfma_f32_16x16x32_bf16 v[46:49], v[164:167], v[204:207], v[46:49]
	v_mfma_f32_16x16x32_bf16 v[30:33], v[164:167], v[212:215], v[30:33]
	v_mfma_f32_16x16x32_bf16 v[22:25], v[172:175], v[212:215], v[22:25]
	v_mfma_f32_16x16x32_bf16 v[26:29], v[180:183], v[212:215], v[26:29]
	v_mfma_f32_16x16x32_bf16 v[18:21], v[188:191], v[212:215], v[18:21]
	v_mfma_f32_16x16x32_bf16 v[2:5], v[188:191], v[220:223], v[2:5]
	v_mfma_f32_16x16x32_bf16 v[10:13], v[180:183], v[220:223], v[10:13]
	v_mfma_f32_16x16x32_bf16 v[6:9], v[172:175], v[220:223], v[6:9]
	v_mfma_f32_16x16x32_bf16 v[14:17], v[164:167], v[220:223], v[14:17]
	v_mfma_f32_16x16x32_bf16 v[62:65], v[168:171], v[200:203], v[62:65]
	v_mfma_f32_16x16x32_bf16 v[54:57], v[176:179], v[200:203], v[54:57]
	v_mfma_f32_16x16x32_bf16 v[58:61], v[184:187], v[200:203], v[58:61]
	v_mfma_f32_16x16x32_bf16 v[50:53], v[192:195], v[200:203], v[50:53]
	v_mfma_f32_16x16x32_bf16 v[34:37], v[192:195], v[208:211], v[34:37]
	v_mfma_f32_16x16x32_bf16 v[42:45], v[184:187], v[208:211], v[42:45]
	v_mfma_f32_16x16x32_bf16 v[38:41], v[176:179], v[208:211], v[38:41]
	v_mfma_f32_16x16x32_bf16 v[46:49], v[168:171], v[208:211], v[46:49]
	v_mfma_f32_16x16x32_bf16 v[30:33], v[168:171], v[216:219], v[30:33]
	v_mfma_f32_16x16x32_bf16 v[22:25], v[176:179], v[216:219], v[22:25]
	v_mfma_f32_16x16x32_bf16 v[26:29], v[184:187], v[216:219], v[26:29]
	v_mfma_f32_16x16x32_bf16 v[18:21], v[192:195], v[216:219], v[18:21]
	v_mfma_f32_16x16x32_bf16 v[2:5], v[192:195], v[224:227], v[2:5]
	v_mfma_f32_16x16x32_bf16 v[10:13], v[184:187], v[224:227], v[10:13]
	v_mfma_f32_16x16x32_bf16 v[6:9], v[176:179], v[224:227], v[6:9]
	v_mfma_f32_16x16x32_bf16 v[14:17], v[168:171], v[224:227], v[14:17]
	s_barrier
	s_setprio 0
	s_mov_b32 s5, s45
	s_add_u32 s88, s88, 0x100
	s_addc_u32 s89, s89, 0
	s_add_u32 s86, s86, 0x100
	s_addc_u32 s87, s87, 0
	s_cmp_ge_i32 s45, s101
	s_cbranch_scc1 .Lmy_kexit_10
.LBB0_1944:
	s_add_u32 s98, s86, 0xfffc0080
	s_addc_u32 s99, s87, -1
	s_cmp_eq_u32 s5, s100
	s_cselect_b64 s[94:95], s[90:91], s[98:99]
	s_cselect_b64 s[96:97], s[92:93], s[88:89]
	s_add_i32 s45, s5, 2
	s_mov_b32 m0, s74
	ds_read_b128 v[164:167], v230
	global_load_lds_dwordx4 v144, s[86:87]
	s_mov_b32 m0, s75
	ds_read_b128 v[168:171], v230 offset:1024
	global_load_lds_dwordx4 v142, s[86:87]
	ds_read_b128 v[172:175], v230 offset:2048
	ds_read_b128 v[176:179], v230 offset:3072
	ds_read_b128 v[180:183], v231
	ds_read_b128 v[184:187], v231 offset:1024
	ds_read_b128 v[188:191], v231 offset:2048
	ds_read_b128 v[192:195], v231 offset:3072
	ds_read_b128 v[196:199], v160
	ds_read_b128 v[200:203], v160 offset:1024
	ds_read_b128 v[204:207], v160 offset:2048
	ds_read_b128 v[208:211], v160 offset:3072
	ds_read_b128 v[212:215], v160 offset:4096
	ds_read_b128 v[216:219], v160 offset:5120
	ds_read_b128 v[220:223], v160 offset:6144
	ds_read_b128 v[224:227], v160 offset:7168
	s_waitcnt vmcnt(8)
	s_waitcnt lgkmcnt(0)
	s_setprio 1
	s_barrier
	v_mfma_f32_16x16x32_bf16 v[122:125], v[164:167], v[196:199], v[122:125]
	v_mfma_f32_16x16x32_bf16 v[118:121], v[172:175], v[196:199], v[118:121]
	v_mfma_f32_16x16x32_bf16 v[126:129], v[180:183], v[196:199], v[126:129]
	v_mfma_f32_16x16x32_bf16 v[114:117], v[188:191], v[196:199], v[114:117]
	v_mfma_f32_16x16x32_bf16 v[98:101], v[188:191], v[204:207], v[98:101]
	v_mfma_f32_16x16x32_bf16 v[106:109], v[180:183], v[204:207], v[106:109]
	v_mfma_f32_16x16x32_bf16 v[102:105], v[172:175], v[204:207], v[102:105]
	v_mfma_f32_16x16x32_bf16 v[110:113], v[164:167], v[204:207], v[110:113]
	v_mfma_f32_16x16x32_bf16 v[94:97], v[164:167], v[212:215], v[94:97]
	v_mfma_f32_16x16x32_bf16 v[86:89], v[172:175], v[212:215], v[86:89]
	v_mfma_f32_16x16x32_bf16 v[90:93], v[180:183], v[212:215], v[90:93]
	v_mfma_f32_16x16x32_bf16 v[82:85], v[188:191], v[212:215], v[82:85]
	v_mfma_f32_16x16x32_bf16 v[66:69], v[188:191], v[220:223], v[66:69]
	v_mfma_f32_16x16x32_bf16 v[74:77], v[180:183], v[220:223], v[74:77]
	v_mfma_f32_16x16x32_bf16 v[70:73], v[172:175], v[220:223], v[70:73]
	v_mfma_f32_16x16x32_bf16 v[78:81], v[164:167], v[220:223], v[78:81]
	v_mfma_f32_16x16x32_bf16 v[122:125], v[168:171], v[200:203], v[122:125]
	v_mfma_f32_16x16x32_bf16 v[118:121], v[176:179], v[200:203], v[118:121]
	v_mfma_f32_16x16x32_bf16 v[126:129], v[184:187], v[200:203], v[126:129]
	v_mfma_f32_16x16x32_bf16 v[114:117], v[192:195], v[200:203], v[114:117]
	v_mfma_f32_16x16x32_bf16 v[98:101], v[192:195], v[208:211], v[98:101]
	v_mfma_f32_16x16x32_bf16 v[106:109], v[184:187], v[208:211], v[106:109]
	v_mfma_f32_16x16x32_bf16 v[102:105], v[176:179], v[208:211], v[102:105]
	v_mfma_f32_16x16x32_bf16 v[110:113], v[168:171], v[208:211], v[110:113]
	v_mfma_f32_16x16x32_bf16 v[94:97], v[168:171], v[216:219], v[94:97]
	v_mfma_f32_16x16x32_bf16 v[86:89], v[176:179], v[216:219], v[86:89]
	v_mfma_f32_16x16x32_bf16 v[90:93], v[184:187], v[216:219], v[90:93]
	v_mfma_f32_16x16x32_bf16 v[82:85], v[192:195], v[216:219], v[82:85]
	v_mfma_f32_16x16x32_bf16 v[66:69], v[192:195], v[224:227], v[66:69]
	v_mfma_f32_16x16x32_bf16 v[74:77], v[184:187], v[224:227], v[74:77]
	v_mfma_f32_16x16x32_bf16 v[70:73], v[176:179], v[224:227], v[70:73]
	v_mfma_f32_16x16x32_bf16 v[78:81], v[168:171], v[224:227], v[78:81]
	s_barrier
	s_setprio 0
	s_add_u32 s98, s96, 0x40000
	s_addc_u32 s99, s97, 0
	s_mov_b32 m0, s76
	ds_read_b128 v[196:199], v160 offset:16384
	global_load_lds_dwordx4 v132, s[96:97]
	s_mov_b32 m0, s77
	s_add_i32 s5, s73, s25
	global_load_lds_dwordx4 v136, s[96:97]
	s_mov_b32 m0, s5
	ds_read_b128 v[200:203], v160 offset:17408
	global_load_lds_dwordx4 v132, s[98:99]
	s_add_i32 m0, s5, 0x2000
	ds_read_b128 v[204:207], v160 offset:18432
	global_load_lds_dwordx4 v136, s[98:99]
	s_mov_b32 m0, s49
	ds_read_b128 v[208:211], v160 offset:19456
	global_load_lds_dwordx4 v130, s[94:95]
	s_mov_b32 m0, s58
	ds_read_b128 v[212:215], v160 offset:20480
	global_load_lds_dwordx4 v134, s[94:95]
	ds_read_b128 v[216:219], v160 offset:21504
	ds_read_b128 v[220:223], v160 offset:22528
	ds_read_b128 v[224:227], v160 offset:23552
	s_waitcnt vmcnt(8)
	s_waitcnt lgkmcnt(0)
	s_setprio 1
	s_barrier
	v_mfma_f32_16x16x32_bf16 v[62:65], v[164:167], v[196:199], v[62:65]
	v_mfma_f32_16x16x32_bf16 v[54:57], v[172:175], v[196:199], v[54:57]
	v_mfma_f32_16x16x32_bf16 v[58:61], v[180:183], v[196:199], v[58:61]
	v_mfma_f32_16x16x32_bf16 v[50:53], v[188:191], v[196:199], v[50:53]
	v_mfma_f32_16x16x32_bf16 v[34:37], v[188:191], v[204:207], v[34:37]
	v_mfma_f32_16x16x32_bf16 v[42:45], v[180:183], v[204:207], v[42:45]
	v_mfma_f32_16x16x32_bf16 v[38:41], v[172:175], v[204:207], v[38:41]
	v_mfma_f32_16x16x32_bf16 v[46:49], v[164:167], v[204:207], v[46:49]
	v_mfma_f32_16x16x32_bf16 v[30:33], v[164:167], v[212:215], v[30:33]
	v_mfma_f32_16x16x32_bf16 v[22:25], v[172:175], v[212:215], v[22:25]
	v_mfma_f32_16x16x32_bf16 v[26:29], v[180:183], v[212:215], v[26:29]
	v_mfma_f32_16x16x32_bf16 v[18:21], v[188:191], v[212:215], v[18:21]
	v_mfma_f32_16x16x32_bf16 v[2:5], v[188:191], v[220:223], v[2:5]
	v_mfma_f32_16x16x32_bf16 v[10:13], v[180:183], v[220:223], v[10:13]
	v_mfma_f32_16x16x32_bf16 v[6:9], v[172:175], v[220:223], v[6:9]
	v_mfma_f32_16x16x32_bf16 v[14:17], v[164:167], v[220:223], v[14:17]
	v_mfma_f32_16x16x32_bf16 v[62:65], v[168:171], v[200:203], v[62:65]
	v_mfma_f32_16x16x32_bf16 v[54:57], v[176:179], v[200:203], v[54:57]
	v_mfma_f32_16x16x32_bf16 v[58:61], v[184:187], v[200:203], v[58:61]
	v_mfma_f32_16x16x32_bf16 v[50:53], v[192:195], v[200:203], v[50:53]
	v_mfma_f32_16x16x32_bf16 v[34:37], v[192:195], v[208:211], v[34:37]
	v_mfma_f32_16x16x32_bf16 v[42:45], v[184:187], v[208:211], v[42:45]
	v_mfma_f32_16x16x32_bf16 v[38:41], v[176:179], v[208:211], v[38:41]
	v_mfma_f32_16x16x32_bf16 v[46:49], v[168:171], v[208:211], v[46:49]
	v_mfma_f32_16x16x32_bf16 v[30:33], v[168:171], v[216:219], v[30:33]
	v_mfma_f32_16x16x32_bf16 v[22:25], v[176:179], v[216:219], v[22:25]
	v_mfma_f32_16x16x32_bf16 v[26:29], v[184:187], v[216:219], v[26:29]
	v_mfma_f32_16x16x32_bf16 v[18:21], v[192:195], v[216:219], v[18:21]
	v_mfma_f32_16x16x32_bf16 v[2:5], v[192:195], v[224:227], v[2:5]
	v_mfma_f32_16x16x32_bf16 v[10:13], v[184:187], v[224:227], v[10:13]
	v_mfma_f32_16x16x32_bf16 v[6:9], v[176:179], v[224:227], v[6:9]
	v_mfma_f32_16x16x32_bf16 v[14:17], v[168:171], v[224:227], v[14:17]
	s_barrier
	s_setprio 0
	s_add_u32 s98, s94, 0x40000
	s_addc_u32 s99, s95, 0
	s_add_i32 s5, 0, 0x18000
	s_add_i32 s47, 0, 0x1c000
	s_mov_b32 m0, s59
	ds_read_b128 v[164:167], v232
	global_load_lds_dwordx4 v130, s[98:99]
	s_mov_b32 m0, s60
	ds_read_b128 v[168:171], v232 offset:1024
	global_load_lds_dwordx4 v134, s[98:99]
	ds_read_b128 v[172:175], v232 offset:2048
	ds_read_b128 v[176:179], v232 offset:3072
	ds_read_b128 v[180:183], v233
	ds_read_b128 v[184:187], v233 offset:1024
	ds_read_b128 v[188:191], v233 offset:2048
	ds_read_b128 v[192:195], v233 offset:3072
	ds_read_b128 v[196:199], v160 offset:32768
	ds_read_b128 v[200:203], v160 offset:33792
	ds_read_b128 v[204:207], v160 offset:34816
	ds_read_b128 v[208:211], v160 offset:35840
	ds_read_b128 v[212:215], v160 offset:36864
	ds_read_b128 v[216:219], v160 offset:37888
	ds_read_b128 v[220:223], v160 offset:38912
	ds_read_b128 v[224:227], v160 offset:39936
	s_waitcnt vmcnt(8)
	s_waitcnt lgkmcnt(0)
	s_setprio 1
	s_barrier
	v_mfma_f32_16x16x32_bf16 v[122:125], v[164:167], v[196:199], v[122:125]
	v_mfma_f32_16x16x32_bf16 v[118:121], v[172:175], v[196:199], v[118:121]
	v_mfma_f32_16x16x32_bf16 v[126:129], v[180:183], v[196:199], v[126:129]
	v_mfma_f32_16x16x32_bf16 v[114:117], v[188:191], v[196:199], v[114:117]
	v_mfma_f32_16x16x32_bf16 v[98:101], v[188:191], v[204:207], v[98:101]
	v_mfma_f32_16x16x32_bf16 v[106:109], v[180:183], v[204:207], v[106:109]
	v_mfma_f32_16x16x32_bf16 v[102:105], v[172:175], v[204:207], v[102:105]
	v_mfma_f32_16x16x32_bf16 v[110:113], v[164:167], v[204:207], v[110:113]
	v_mfma_f32_16x16x32_bf16 v[94:97], v[164:167], v[212:215], v[94:97]
	v_mfma_f32_16x16x32_bf16 v[86:89], v[172:175], v[212:215], v[86:89]
	v_mfma_f32_16x16x32_bf16 v[90:93], v[180:183], v[212:215], v[90:93]
	v_mfma_f32_16x16x32_bf16 v[82:85], v[188:191], v[212:215], v[82:85]
	v_mfma_f32_16x16x32_bf16 v[66:69], v[188:191], v[220:223], v[66:69]
	v_mfma_f32_16x16x32_bf16 v[74:77], v[180:183], v[220:223], v[74:77]
	v_mfma_f32_16x16x32_bf16 v[70:73], v[172:175], v[220:223], v[70:73]
	v_mfma_f32_16x16x32_bf16 v[78:81], v[164:167], v[220:223], v[78:81]
	v_mfma_f32_16x16x32_bf16 v[122:125], v[168:171], v[200:203], v[122:125]
	v_mfma_f32_16x16x32_bf16 v[118:121], v[176:179], v[200:203], v[118:121]
	v_mfma_f32_16x16x32_bf16 v[126:129], v[184:187], v[200:203], v[126:129]
	v_mfma_f32_16x16x32_bf16 v[114:117], v[192:195], v[200:203], v[114:117]
	v_mfma_f32_16x16x32_bf16 v[98:101], v[192:195], v[208:211], v[98:101]
	v_mfma_f32_16x16x32_bf16 v[106:109], v[184:187], v[208:211], v[106:109]
	v_mfma_f32_16x16x32_bf16 v[102:105], v[176:179], v[208:211], v[102:105]
	v_mfma_f32_16x16x32_bf16 v[110:113], v[168:171], v[208:211], v[110:113]
	v_mfma_f32_16x16x32_bf16 v[94:97], v[168:171], v[216:219], v[94:97]
	v_mfma_f32_16x16x32_bf16 v[86:89], v[176:179], v[216:219], v[86:89]
	v_mfma_f32_16x16x32_bf16 v[90:93], v[184:187], v[216:219], v[90:93]
	v_mfma_f32_16x16x32_bf16 v[82:85], v[192:195], v[216:219], v[82:85]
	v_mfma_f32_16x16x32_bf16 v[66:69], v[192:195], v[224:227], v[66:69]
	v_mfma_f32_16x16x32_bf16 v[74:77], v[184:187], v[224:227], v[74:77]
	v_mfma_f32_16x16x32_bf16 v[70:73], v[176:179], v[224:227], v[70:73]
	v_mfma_f32_16x16x32_bf16 v[78:81], v[168:171], v[224:227], v[78:81]
	s_barrier
	s_setprio 0
	s_add_u32 s96, s96, 0x80
	s_addc_u32 s97, s97, 0
	s_add_u32 s98, s96, 0x40000
	s_addc_u32 s99, s97, 0
	s_add_u32 s94, s94, 0x80
	s_addc_u32 s95, s95, 0
	s_add_i32 s5, s5, s25
	s_mov_b32 m0, s5
	ds_read_b128 v[196:199], v160 offset:49152
	global_load_lds_dwordx4 v132, s[96:97]
	s_add_i32 m0, s5, 0x2000
	s_add_i32 s5, s47, s25
	global_load_lds_dwordx4 v136, s[96:97]
	s_mov_b32 m0, s5
	ds_read_b128 v[200:203], v160 offset:50176
	global_load_lds_dwordx4 v132, s[98:99]
	s_add_i32 m0, s5, 0x2000
	ds_read_b128 v[204:207], v160 offset:51200
	global_load_lds_dwordx4 v136, s[98:99]
	s_mov_b32 m0, s61
	ds_read_b128 v[208:211], v160 offset:52224
	global_load_lds_dwordx4 v130, s[94:95]
	s_mov_b32 m0, s62
	ds_read_b128 v[212:215], v160 offset:53248
	global_load_lds_dwordx4 v134, s[94:95]
	ds_read_b128 v[216:219], v160 offset:54272
	ds_read_b128 v[220:223], v160 offset:55296
	ds_read_b128 v[224:227], v160 offset:56320
	s_waitcnt vmcnt(8)
	s_waitcnt lgkmcnt(0)
	s_setprio 1
	s_barrier
	v_mfma_f32_16x16x32_bf16 v[62:65], v[164:167], v[196:199], v[62:65]
	v_mfma_f32_16x16x32_bf16 v[54:57], v[172:175], v[196:199], v[54:57]
	v_mfma_f32_16x16x32_bf16 v[58:61], v[180:183], v[196:199], v[58:61]
	v_mfma_f32_16x16x32_bf16 v[50:53], v[188:191], v[196:199], v[50:53]
	v_mfma_f32_16x16x32_bf16 v[34:37], v[188:191], v[204:207], v[34:37]
	v_mfma_f32_16x16x32_bf16 v[42:45], v[180:183], v[204:207], v[42:45]
	v_mfma_f32_16x16x32_bf16 v[38:41], v[172:175], v[204:207], v[38:41]
	v_mfma_f32_16x16x32_bf16 v[46:49], v[164:167], v[204:207], v[46:49]
	v_mfma_f32_16x16x32_bf16 v[30:33], v[164:167], v[212:215], v[30:33]
	v_mfma_f32_16x16x32_bf16 v[22:25], v[172:175], v[212:215], v[22:25]
	v_mfma_f32_16x16x32_bf16 v[26:29], v[180:183], v[212:215], v[26:29]
	v_mfma_f32_16x16x32_bf16 v[18:21], v[188:191], v[212:215], v[18:21]
	v_mfma_f32_16x16x32_bf16 v[2:5], v[188:191], v[220:223], v[2:5]
	v_mfma_f32_16x16x32_bf16 v[10:13], v[180:183], v[220:223], v[10:13]
	v_mfma_f32_16x16x32_bf16 v[6:9], v[172:175], v[220:223], v[6:9]
	v_mfma_f32_16x16x32_bf16 v[14:17], v[164:167], v[220:223], v[14:17]
	v_mfma_f32_16x16x32_bf16 v[62:65], v[168:171], v[200:203], v[62:65]
	v_mfma_f32_16x16x32_bf16 v[54:57], v[176:179], v[200:203], v[54:57]
	v_mfma_f32_16x16x32_bf16 v[58:61], v[184:187], v[200:203], v[58:61]
	v_mfma_f32_16x16x32_bf16 v[50:53], v[192:195], v[200:203], v[50:53]
	v_mfma_f32_16x16x32_bf16 v[34:37], v[192:195], v[208:211], v[34:37]
	v_mfma_f32_16x16x32_bf16 v[42:45], v[184:187], v[208:211], v[42:45]
	v_mfma_f32_16x16x32_bf16 v[38:41], v[176:179], v[208:211], v[38:41]
	v_mfma_f32_16x16x32_bf16 v[46:49], v[168:171], v[208:211], v[46:49]
	v_mfma_f32_16x16x32_bf16 v[30:33], v[168:171], v[216:219], v[30:33]
	v_mfma_f32_16x16x32_bf16 v[22:25], v[176:179], v[216:219], v[22:25]
	v_mfma_f32_16x16x32_bf16 v[26:29], v[184:187], v[216:219], v[26:29]
	v_mfma_f32_16x16x32_bf16 v[18:21], v[192:195], v[216:219], v[18:21]
	v_mfma_f32_16x16x32_bf16 v[2:5], v[192:195], v[224:227], v[2:5]
	v_mfma_f32_16x16x32_bf16 v[10:13], v[184:187], v[224:227], v[10:13]
	v_mfma_f32_16x16x32_bf16 v[6:9], v[176:179], v[224:227], v[6:9]
	v_mfma_f32_16x16x32_bf16 v[14:17], v[168:171], v[224:227], v[14:17]
	s_barrier
	s_setprio 0
	s_mov_b32 s5, s45
	s_add_u32 s88, s88, 0x100
	s_addc_u32 s89, s89, 0
	s_add_u32 s86, s86, 0x100
	s_addc_u32 s87, s87, 0
	s_cmp_ge_i32 s45, s101
	s_cbranch_scc0 .LBB0_1944

.Lmy_nb_11:
	s_nop 0
	v_readfirstlane_b32 s86, v150
	v_readfirstlane_b32 s87, v151
	v_readfirstlane_b32 s88, v152
	v_readfirstlane_b32 s89, v153
	v_readfirstlane_b32 s90, v146
	v_readfirstlane_b32 s91, v147
	v_readfirstlane_b32 s92, v148
	v_readfirstlane_b32 s93, v149
	v_readfirstlane_b32 s100, v138
	v_readfirstlane_b32 s101, v156
	v_add_u32_e32 v230, s65, v141
	v_add_u32_e32 v231, s66, v141
	v_add_u32_e32 v232, 0x18000, v141
	v_add_u32_e32 v233, 0x1c000, v141
	s_add_u32 s98, s86, 0x100
	s_addc_u32 s99, s87, 0
	s_cmp_eq_u32 s4, s100
	s_cselect_b64 s[94:95], s[90:91], s[98:99]
	s_cselect_b64 s[96:97], s[92:93], s[88:89]
	s_add_i32 s5, s4, 2
	s_add_i32 m0, s44, 0xc000
	ds_read_b128 v[164:167], v230
	global_load_lds_dwordx4 v144, s[86:87]
	s_add_i32 m0, s44, 0xe000
	ds_read_b128 v[168:171], v230 offset:1024
	global_load_lds_dwordx4 v142, s[86:87]
	ds_read_b128 v[172:175], v230 offset:2048
	ds_read_b128 v[176:179], v230 offset:3072
	ds_read_b128 v[180:183], v231
	ds_read_b128 v[184:187], v231 offset:1024
	ds_read_b128 v[188:191], v231 offset:2048
	ds_read_b128 v[192:195], v231 offset:3072
	ds_read_b128 v[196:199], v160
	ds_read_b128 v[200:203], v160 offset:1024
	ds_read_b128 v[204:207], v160 offset:2048
	ds_read_b128 v[208:211], v160 offset:3072
	ds_read_b128 v[212:215], v160 offset:4096
	ds_read_b128 v[216:219], v160 offset:5120
	ds_read_b128 v[220:223], v160 offset:6144
	ds_read_b128 v[224:227], v160 offset:7168
	s_waitcnt vmcnt(8)
	s_waitcnt lgkmcnt(0)
	s_setprio 1
	s_barrier
	v_mfma_f32_16x16x32_bf16 v[122:125], v[164:167], v[196:199], 0
	v_mfma_f32_16x16x32_bf16 v[118:121], v[172:175], v[196:199], 0
	v_mfma_f32_16x16x32_bf16 v[126:129], v[180:183], v[196:199], 0
	v_mfma_f32_16x16x32_bf16 v[114:117], v[188:191], v[196:199], 0
	v_mfma_f32_16x16x32_bf16 v[98:101], v[188:191], v[204:207], 0
	v_mfma_f32_16x16x32_bf16 v[106:109], v[180:183], v[204:207], 0
	v_mfma_f32_16x16x32_bf16 v[102:105], v[172:175], v[204:207], 0
	v_mfma_f32_16x16x32_bf16 v[110:113], v[164:167], v[204:207], 0
	v_mfma_f32_16x16x32_bf16 v[94:97], v[164:167], v[212:215], 0
	v_mfma_f32_16x16x32_bf16 v[86:89], v[172:175], v[212:215], 0
	v_mfma_f32_16x16x32_bf16 v[90:93], v[180:183], v[212:215], 0
	v_mfma_f32_16x16x32_bf16 v[82:85], v[188:191], v[212:215], 0
	v_mfma_f32_16x16x32_bf16 v[66:69], v[188:191], v[220:223], 0
	v_mfma_f32_16x16x32_bf16 v[74:77], v[180:183], v[220:223], 0
	v_mfma_f32_16x16x32_bf16 v[70:73], v[172:175], v[220:223], 0
	v_mfma_f32_16x16x32_bf16 v[78:81], v[164:167], v[220:223], 0
	v_mfma_f32_16x16x32_bf16 v[122:125], v[168:171], v[200:203], v[122:125]
	v_mfma_f32_16x16x32_bf16 v[118:121], v[176:179], v[200:203], v[118:121]
	v_mfma_f32_16x16x32_bf16 v[126:129], v[184:187], v[200:203], v[126:129]
	v_mfma_f32_16x16x32_bf16 v[114:117], v[192:195], v[200:203], v[114:117]
	v_mfma_f32_16x16x32_bf16 v[98:101], v[192:195], v[208:211], v[98:101]
	v_mfma_f32_16x16x32_bf16 v[106:109], v[184:187], v[208:211], v[106:109]
	v_mfma_f32_16x16x32_bf16 v[102:105], v[176:179], v[208:211], v[102:105]
	v_mfma_f32_16x16x32_bf16 v[110:113], v[168:171], v[208:211], v[110:113]
	v_mfma_f32_16x16x32_bf16 v[94:97], v[168:171], v[216:219], v[94:97]
	v_mfma_f32_16x16x32_bf16 v[86:89], v[176:179], v[216:219], v[86:89]
	v_mfma_f32_16x16x32_bf16 v[90:93], v[184:187], v[216:219], v[90:93]
	v_mfma_f32_16x16x32_bf16 v[82:85], v[192:195], v[216:219], v[82:85]
	v_mfma_f32_16x16x32_bf16 v[66:69], v[192:195], v[224:227], v[66:69]
	v_mfma_f32_16x16x32_bf16 v[74:77], v[184:187], v[224:227], v[74:77]
	v_mfma_f32_16x16x32_bf16 v[70:73], v[176:179], v[224:227], v[70:73]
	v_mfma_f32_16x16x32_bf16 v[78:81], v[168:171], v[224:227], v[78:81]
	s_barrier
	s_setprio 0
	s_add_u32 s98, s96, 0xb0000
	s_addc_u32 s99, s97, 0
	s_add_i32 s4, s65, s21
	s_mov_b32 m0, s4
	ds_read_b128 v[196:199], v160 offset:16384
	global_load_lds_dwordx4 v132, s[96:97]
	s_add_i32 m0, s4, 0x2000
	s_add_i32 s4, s66, s21
	global_load_lds_dwordx4 v136, s[96:97]
	s_mov_b32 m0, s4
	ds_read_b128 v[200:203], v160 offset:17408
	global_load_lds_dwordx4 v132, s[98:99]
	s_add_i32 m0, s4, 0x2000
	ds_read_b128 v[204:207], v160 offset:18432
	global_load_lds_dwordx4 v136, s[98:99]
	s_mov_b32 m0, s44
	ds_read_b128 v[208:211], v160 offset:19456
	global_load_lds_dwordx4 v130, s[94:95]
	s_mov_b32 m0, s45
	ds_read_b128 v[212:215], v160 offset:20480
	global_load_lds_dwordx4 v134, s[94:95]
	ds_read_b128 v[216:219], v160 offset:21504
	ds_read_b128 v[220:223], v160 offset:22528
	ds_read_b128 v[224:227], v160 offset:23552
	s_waitcnt vmcnt(8)
	s_waitcnt lgkmcnt(0)
	s_setprio 1
	s_barrier
	v_mfma_f32_16x16x32_bf16 v[62:65], v[164:167], v[196:199], 0
	v_mfma_f32_16x16x32_bf16 v[54:57], v[172:175], v[196:199], 0
	v_mfma_f32_16x16x32_bf16 v[58:61], v[180:183], v[196:199], 0
	v_mfma_f32_16x16x32_bf16 v[50:53], v[188:191], v[196:199], 0
	v_mfma_f32_16x16x32_bf16 v[34:37], v[188:191], v[204:207], 0
	v_mfma_f32_16x16x32_bf16 v[42:45], v[180:183], v[204:207], 0
	v_mfma_f32_16x16x32_bf16 v[38:41], v[172:175], v[204:207], 0
	v_mfma_f32_16x16x32_bf16 v[46:49], v[164:167], v[204:207], 0
	v_mfma_f32_16x16x32_bf16 v[30:33], v[164:167], v[212:215], 0
	v_mfma_f32_16x16x32_bf16 v[22:25], v[172:175], v[212:215], 0
	v_mfma_f32_16x16x32_bf16 v[26:29], v[180:183], v[212:215], 0
	v_mfma_f32_16x16x32_bf16 v[18:21], v[188:191], v[212:215], 0
	v_mfma_f32_16x16x32_bf16 v[2:5], v[188:191], v[220:223], 0
	v_mfma_f32_16x16x32_bf16 v[10:13], v[180:183], v[220:223], 0
	v_mfma_f32_16x16x32_bf16 v[6:9], v[172:175], v[220:223], 0
	v_mfma_f32_16x16x32_bf16 v[14:17], v[164:167], v[220:223], 0
	v_mfma_f32_16x16x32_bf16 v[62:65], v[168:171], v[200:203], v[62:65]
	v_mfma_f32_16x16x32_bf16 v[54:57], v[176:179], v[200:203], v[54:57]
	v_mfma_f32_16x16x32_bf16 v[58:61], v[184:187], v[200:203], v[58:61]
	v_mfma_f32_16x16x32_bf16 v[50:53], v[192:195], v[200:203], v[50:53]
	v_mfma_f32_16x16x32_bf16 v[34:37], v[192:195], v[208:211], v[34:37]
	v_mfma_f32_16x16x32_bf16 v[42:45], v[184:187], v[208:211], v[42:45]
	v_mfma_f32_16x16x32_bf16 v[38:41], v[176:179], v[208:211], v[38:41]
	v_mfma_f32_16x16x32_bf16 v[46:49], v[168:171], v[208:211], v[46:49]
	v_mfma_f32_16x16x32_bf16 v[30:33], v[168:171], v[216:219], v[30:33]
	v_mfma_f32_16x16x32_bf16 v[22:25], v[176:179], v[216:219], v[22:25]
	v_mfma_f32_16x16x32_bf16 v[26:29], v[184:187], v[216:219], v[26:29]
	v_mfma_f32_16x16x32_bf16 v[18:21], v[192:195], v[216:219], v[18:21]
	v_mfma_f32_16x16x32_bf16 v[2:5], v[192:195], v[224:227], v[2:5]
	v_mfma_f32_16x16x32_bf16 v[10:13], v[184:187], v[224:227], v[10:13]
	v_mfma_f32_16x16x32_bf16 v[6:9], v[176:179], v[224:227], v[6:9]
	v_mfma_f32_16x16x32_bf16 v[14:17], v[168:171], v[224:227], v[14:17]
	s_barrier
	s_setprio 0
	s_add_u32 s98, s94, 0xb0000
	s_addc_u32 s99, s95, 0
	s_add_i32 s4, 0, 0x18000
	s_add_i32 s25, 0, 0x1c000
	s_mov_b32 m0, s46
	ds_read_b128 v[164:167], v232
	global_load_lds_dwordx4 v130, s[98:99]
	s_mov_b32 m0, s47
	ds_read_b128 v[168:171], v232 offset:1024
	global_load_lds_dwordx4 v134, s[98:99]
	ds_read_b128 v[172:175], v232 offset:2048
	ds_read_b128 v[176:179], v232 offset:3072
	ds_read_b128 v[180:183], v233
	ds_read_b128 v[184:187], v233 offset:1024
	ds_read_b128 v[188:191], v233 offset:2048
	ds_read_b128 v[192:195], v233 offset:3072
	ds_read_b128 v[196:199], v160 offset:32768
	ds_read_b128 v[200:203], v160 offset:33792
	ds_read_b128 v[204:207], v160 offset:34816
	ds_read_b128 v[208:211], v160 offset:35840
	ds_read_b128 v[212:215], v160 offset:36864
	ds_read_b128 v[216:219], v160 offset:37888
	ds_read_b128 v[220:223], v160 offset:38912
	ds_read_b128 v[224:227], v160 offset:39936
	s_waitcnt vmcnt(8)
	s_waitcnt lgkmcnt(0)
	s_setprio 1
	s_barrier
	v_mfma_f32_16x16x32_bf16 v[122:125], v[164:167], v[196:199], v[122:125]
	v_mfma_f32_16x16x32_bf16 v[118:121], v[172:175], v[196:199], v[118:121]
	v_mfma_f32_16x16x32_bf16 v[126:129], v[180:183], v[196:199], v[126:129]
	v_mfma_f32_16x16x32_bf16 v[114:117], v[188:191], v[196:199], v[114:117]
	v_mfma_f32_16x16x32_bf16 v[98:101], v[188:191], v[204:207], v[98:101]
	v_mfma_f32_16x16x32_bf16 v[106:109], v[180:183], v[204:207], v[106:109]
	v_mfma_f32_16x16x32_bf16 v[102:105], v[172:175], v[204:207], v[102:105]
	v_mfma_f32_16x16x32_bf16 v[110:113], v[164:167], v[204:207], v[110:113]
	v_mfma_f32_16x16x32_bf16 v[94:97], v[164:167], v[212:215], v[94:97]
	v_mfma_f32_16x16x32_bf16 v[86:89], v[172:175], v[212:215], v[86:89]
	v_mfma_f32_16x16x32_bf16 v[90:93], v[180:183], v[212:215], v[90:93]
	v_mfma_f32_16x16x32_bf16 v[82:85], v[188:191], v[212:215], v[82:85]
	v_mfma_f32_16x16x32_bf16 v[66:69], v[188:191], v[220:223], v[66:69]
	v_mfma_f32_16x16x32_bf16 v[74:77], v[180:183], v[220:223], v[74:77]
	v_mfma_f32_16x16x32_bf16 v[70:73], v[172:175], v[220:223], v[70:73]
	v_mfma_f32_16x16x32_bf16 v[78:81], v[164:167], v[220:223], v[78:81]
	v_mfma_f32_16x16x32_bf16 v[122:125], v[168:171], v[200:203], v[122:125]
	v_mfma_f32_16x16x32_bf16 v[118:121], v[176:179], v[200:203], v[118:121]
	v_mfma_f32_16x16x32_bf16 v[126:129], v[184:187], v[200:203], v[126:129]
	v_mfma_f32_16x16x32_bf16 v[114:117], v[192:195], v[200:203], v[114:117]
	v_mfma_f32_16x16x32_bf16 v[98:101], v[192:195], v[208:211], v[98:101]
	v_mfma_f32_16x16x32_bf16 v[106:109], v[184:187], v[208:211], v[106:109]
	v_mfma_f32_16x16x32_bf16 v[102:105], v[176:179], v[208:211], v[102:105]
	v_mfma_f32_16x16x32_bf16 v[110:113], v[168:171], v[208:211], v[110:113]
	v_mfma_f32_16x16x32_bf16 v[94:97], v[168:171], v[216:219], v[94:97]
	v_mfma_f32_16x16x32_bf16 v[86:89], v[176:179], v[216:219], v[86:89]
	v_mfma_f32_16x16x32_bf16 v[90:93], v[184:187], v[216:219], v[90:93]
	v_mfma_f32_16x16x32_bf16 v[82:85], v[192:195], v[216:219], v[82:85]
	v_mfma_f32_16x16x32_bf16 v[66:69], v[192:195], v[224:227], v[66:69]
	v_mfma_f32_16x16x32_bf16 v[74:77], v[184:187], v[224:227], v[74:77]
	v_mfma_f32_16x16x32_bf16 v[70:73], v[176:179], v[224:227], v[70:73]
	v_mfma_f32_16x16x32_bf16 v[78:81], v[168:171], v[224:227], v[78:81]
	s_barrier
	s_setprio 0
	s_add_u32 s96, s96, 0x80
	s_addc_u32 s97, s97, 0
	s_add_u32 s98, s96, 0xb0000
	s_addc_u32 s99, s97, 0
	s_add_u32 s94, s94, 0x80
	s_addc_u32 s95, s95, 0
	s_add_i32 s4, s4, s21
	s_mov_b32 m0, s4
	ds_read_b128 v[196:199], v160 offset:49152
	global_load_lds_dwordx4 v132, s[96:97]
	s_add_i32 m0, s4, 0x2000
	s_add_i32 s4, s25, s21
	global_load_lds_dwordx4 v136, s[96:97]
	s_mov_b32 m0, s4
	ds_read_b128 v[200:203], v160 offset:50176
	global_load_lds_dwordx4 v132, s[98:99]
	s_add_i32 m0, s4, 0x2000
	ds_read_b128 v[204:207], v160 offset:51200
	global_load_lds_dwordx4 v136, s[98:99]
	s_mov_b32 m0, s57
	ds_read_b128 v[208:211], v160 offset:52224
	global_load_lds_dwordx4 v130, s[94:95]
	s_mov_b32 m0, s58
	ds_read_b128 v[212:215], v160 offset:53248
	global_load_lds_dwordx4 v134, s[94:95]
	ds_read_b128 v[216:219], v160 offset:54272
	ds_read_b128 v[220:223], v160 offset:55296
	ds_read_b128 v[224:227], v160 offset:56320
	s_waitcnt vmcnt(8)
	s_waitcnt lgkmcnt(0)
	s_setprio 1
	s_barrier
	v_mfma_f32_16x16x32_bf16 v[62:65], v[164:167], v[196:199], v[62:65]
	v_mfma_f32_16x16x32_bf16 v[54:57], v[172:175], v[196:199], v[54:57]
	v_mfma_f32_16x16x32_bf16 v[58:61], v[180:183], v[196:199], v[58:61]
	v_mfma_f32_16x16x32_bf16 v[50:53], v[188:191], v[196:199], v[50:53]
	v_mfma_f32_16x16x32_bf16 v[34:37], v[188:191], v[204:207], v[34:37]
	v_mfma_f32_16x16x32_bf16 v[42:45], v[180:183], v[204:207], v[42:45]
	v_mfma_f32_16x16x32_bf16 v[38:41], v[172:175], v[204:207], v[38:41]
	v_mfma_f32_16x16x32_bf16 v[46:49], v[164:167], v[204:207], v[46:49]
	v_mfma_f32_16x16x32_bf16 v[30:33], v[164:167], v[212:215], v[30:33]
	v_mfma_f32_16x16x32_bf16 v[22:25], v[172:175], v[212:215], v[22:25]
	v_mfma_f32_16x16x32_bf16 v[26:29], v[180:183], v[212:215], v[26:29]
	v_mfma_f32_16x16x32_bf16 v[18:21], v[188:191], v[212:215], v[18:21]
	v_mfma_f32_16x16x32_bf16 v[2:5], v[188:191], v[220:223], v[2:5]
	v_mfma_f32_16x16x32_bf16 v[10:13], v[180:183], v[220:223], v[10:13]
	v_mfma_f32_16x16x32_bf16 v[6:9], v[172:175], v[220:223], v[6:9]
	v_mfma_f32_16x16x32_bf16 v[14:17], v[164:167], v[220:223], v[14:17]
	v_mfma_f32_16x16x32_bf16 v[62:65], v[168:171], v[200:203], v[62:65]
	v_mfma_f32_16x16x32_bf16 v[54:57], v[176:179], v[200:203], v[54:57]
	v_mfma_f32_16x16x32_bf16 v[58:61], v[184:187], v[200:203], v[58:61]
	v_mfma_f32_16x16x32_bf16 v[50:53], v[192:195], v[200:203], v[50:53]
	v_mfma_f32_16x16x32_bf16 v[34:37], v[192:195], v[208:211], v[34:37]
	v_mfma_f32_16x16x32_bf16 v[42:45], v[184:187], v[208:211], v[42:45]
	v_mfma_f32_16x16x32_bf16 v[38:41], v[176:179], v[208:211], v[38:41]
	v_mfma_f32_16x16x32_bf16 v[46:49], v[168:171], v[208:211], v[46:49]
	v_mfma_f32_16x16x32_bf16 v[30:33], v[168:171], v[216:219], v[30:33]
	v_mfma_f32_16x16x32_bf16 v[22:25], v[176:179], v[216:219], v[22:25]
	v_mfma_f32_16x16x32_bf16 v[26:29], v[184:187], v[216:219], v[26:29]
	v_mfma_f32_16x16x32_bf16 v[18:21], v[192:195], v[216:219], v[18:21]
	v_mfma_f32_16x16x32_bf16 v[2:5], v[192:195], v[224:227], v[2:5]
	v_mfma_f32_16x16x32_bf16 v[10:13], v[184:187], v[224:227], v[10:13]
	v_mfma_f32_16x16x32_bf16 v[6:9], v[176:179], v[224:227], v[6:9]
	v_mfma_f32_16x16x32_bf16 v[14:17], v[168:171], v[224:227], v[14:17]
	s_barrier
	s_setprio 0
	s_mov_b32 s4, s5
	s_add_u32 s88, s88, 0x100
	s_addc_u32 s89, s89, 0
	s_add_u32 s86, s86, 0x100
	s_addc_u32 s87, s87, 0
	s_cmp_ge_i32 s5, s101
	s_cbranch_scc1 .Lmy_kexit_11
.LBB0_2075:
	s_add_u32 s98, s86, 0x100
	s_addc_u32 s99, s87, 0
	s_cmp_eq_u32 s4, s100
	s_cselect_b64 s[94:95], s[90:91], s[98:99]
	s_cselect_b64 s[96:97], s[92:93], s[88:89]
	s_add_i32 s5, s4, 2
	s_add_i32 m0, s44, 0xc000
	ds_read_b128 v[164:167], v230
	global_load_lds_dwordx4 v144, s[86:87]
	s_add_i32 m0, s44, 0xe000
	ds_read_b128 v[168:171], v230 offset:1024
	global_load_lds_dwordx4 v142, s[86:87]
	ds_read_b128 v[172:175], v230 offset:2048
	ds_read_b128 v[176:179], v230 offset:3072
	ds_read_b128 v[180:183], v231
	ds_read_b128 v[184:187], v231 offset:1024
	ds_read_b128 v[188:191], v231 offset:2048
	ds_read_b128 v[192:195], v231 offset:3072
	ds_read_b128 v[196:199], v160
	ds_read_b128 v[200:203], v160 offset:1024
	ds_read_b128 v[204:207], v160 offset:2048
	ds_read_b128 v[208:211], v160 offset:3072
	ds_read_b128 v[212:215], v160 offset:4096
	ds_read_b128 v[216:219], v160 offset:5120
	ds_read_b128 v[220:223], v160 offset:6144
	ds_read_b128 v[224:227], v160 offset:7168
	s_waitcnt vmcnt(8)
	s_waitcnt lgkmcnt(0)
	s_setprio 1
	s_barrier
	v_mfma_f32_16x16x32_bf16 v[122:125], v[164:167], v[196:199], v[122:125]
	v_mfma_f32_16x16x32_bf16 v[118:121], v[172:175], v[196:199], v[118:121]
	v_mfma_f32_16x16x32_bf16 v[126:129], v[180:183], v[196:199], v[126:129]
	v_mfma_f32_16x16x32_bf16 v[114:117], v[188:191], v[196:199], v[114:117]
	v_mfma_f32_16x16x32_bf16 v[98:101], v[188:191], v[204:207], v[98:101]
	v_mfma_f32_16x16x32_bf16 v[106:109], v[180:183], v[204:207], v[106:109]
	v_mfma_f32_16x16x32_bf16 v[102:105], v[172:175], v[204:207], v[102:105]
	v_mfma_f32_16x16x32_bf16 v[110:113], v[164:167], v[204:207], v[110:113]
	v_mfma_f32_16x16x32_bf16 v[94:97], v[164:167], v[212:215], v[94:97]
	v_mfma_f32_16x16x32_bf16 v[86:89], v[172:175], v[212:215], v[86:89]
	v_mfma_f32_16x16x32_bf16 v[90:93], v[180:183], v[212:215], v[90:93]
	v_mfma_f32_16x16x32_bf16 v[82:85], v[188:191], v[212:215], v[82:85]
	v_mfma_f32_16x16x32_bf16 v[66:69], v[188:191], v[220:223], v[66:69]
	v_mfma_f32_16x16x32_bf16 v[74:77], v[180:183], v[220:223], v[74:77]
	v_mfma_f32_16x16x32_bf16 v[70:73], v[172:175], v[220:223], v[70:73]
	v_mfma_f32_16x16x32_bf16 v[78:81], v[164:167], v[220:223], v[78:81]
	v_mfma_f32_16x16x32_bf16 v[122:125], v[168:171], v[200:203], v[122:125]
	v_mfma_f32_16x16x32_bf16 v[118:121], v[176:179], v[200:203], v[118:121]
	v_mfma_f32_16x16x32_bf16 v[126:129], v[184:187], v[200:203], v[126:129]
	v_mfma_f32_16x16x32_bf16 v[114:117], v[192:195], v[200:203], v[114:117]
	v_mfma_f32_16x16x32_bf16 v[98:101], v[192:195], v[208:211], v[98:101]
	v_mfma_f32_16x16x32_bf16 v[106:109], v[184:187], v[208:211], v[106:109]
	v_mfma_f32_16x16x32_bf16 v[102:105], v[176:179], v[208:211], v[102:105]
	v_mfma_f32_16x16x32_bf16 v[110:113], v[168:171], v[208:211], v[110:113]
	v_mfma_f32_16x16x32_bf16 v[94:97], v[168:171], v[216:219], v[94:97]
	v_mfma_f32_16x16x32_bf16 v[86:89], v[176:179], v[216:219], v[86:89]
	v_mfma_f32_16x16x32_bf16 v[90:93], v[184:187], v[216:219], v[90:93]
	v_mfma_f32_16x16x32_bf16 v[82:85], v[192:195], v[216:219], v[82:85]
	v_mfma_f32_16x16x32_bf16 v[66:69], v[192:195], v[224:227], v[66:69]
	v_mfma_f32_16x16x32_bf16 v[74:77], v[184:187], v[224:227], v[74:77]
	v_mfma_f32_16x16x32_bf16 v[70:73], v[176:179], v[224:227], v[70:73]
	v_mfma_f32_16x16x32_bf16 v[78:81], v[168:171], v[224:227], v[78:81]
	s_barrier
	s_setprio 0
	s_add_u32 s98, s96, 0xb0000
	s_addc_u32 s99, s97, 0
	s_add_i32 s4, s65, s21
	s_mov_b32 m0, s4
	ds_read_b128 v[196:199], v160 offset:16384
	global_load_lds_dwordx4 v132, s[96:97]
	s_add_i32 m0, s4, 0x2000
	s_add_i32 s4, s66, s21
	global_load_lds_dwordx4 v136, s[96:97]
	s_mov_b32 m0, s4
	ds_read_b128 v[200:203], v160 offset:17408
	global_load_lds_dwordx4 v132, s[98:99]
	s_add_i32 m0, s4, 0x2000
	ds_read_b128 v[204:207], v160 offset:18432
	global_load_lds_dwordx4 v136, s[98:99]
	s_mov_b32 m0, s44
	ds_read_b128 v[208:211], v160 offset:19456
	global_load_lds_dwordx4 v130, s[94:95]
	s_mov_b32 m0, s45
	ds_read_b128 v[212:215], v160 offset:20480
	global_load_lds_dwordx4 v134, s[94:95]
	ds_read_b128 v[216:219], v160 offset:21504
	ds_read_b128 v[220:223], v160 offset:22528
	ds_read_b128 v[224:227], v160 offset:23552
	s_waitcnt vmcnt(8)
	s_waitcnt lgkmcnt(0)
	s_setprio 1
	s_barrier
	v_mfma_f32_16x16x32_bf16 v[62:65], v[164:167], v[196:199], v[62:65]
	v_mfma_f32_16x16x32_bf16 v[54:57], v[172:175], v[196:199], v[54:57]
	v_mfma_f32_16x16x32_bf16 v[58:61], v[180:183], v[196:199], v[58:61]
	v_mfma_f32_16x16x32_bf16 v[50:53], v[188:191], v[196:199], v[50:53]
	v_mfma_f32_16x16x32_bf16 v[34:37], v[188:191], v[204:207], v[34:37]
	v_mfma_f32_16x16x32_bf16 v[42:45], v[180:183], v[204:207], v[42:45]
	v_mfma_f32_16x16x32_bf16 v[38:41], v[172:175], v[204:207], v[38:41]
	v_mfma_f32_16x16x32_bf16 v[46:49], v[164:167], v[204:207], v[46:49]
	v_mfma_f32_16x16x32_bf16 v[30:33], v[164:167], v[212:215], v[30:33]
	v_mfma_f32_16x16x32_bf16 v[22:25], v[172:175], v[212:215], v[22:25]
	v_mfma_f32_16x16x32_bf16 v[26:29], v[180:183], v[212:215], v[26:29]
	v_mfma_f32_16x16x32_bf16 v[18:21], v[188:191], v[212:215], v[18:21]
	v_mfma_f32_16x16x32_bf16 v[2:5], v[188:191], v[220:223], v[2:5]
	v_mfma_f32_16x16x32_bf16 v[10:13], v[180:183], v[220:223], v[10:13]
	v_mfma_f32_16x16x32_bf16 v[6:9], v[172:175], v[220:223], v[6:9]
	v_mfma_f32_16x16x32_bf16 v[14:17], v[164:167], v[220:223], v[14:17]
	v_mfma_f32_16x16x32_bf16 v[62:65], v[168:171], v[200:203], v[62:65]
	v_mfma_f32_16x16x32_bf16 v[54:57], v[176:179], v[200:203], v[54:57]
	v_mfma_f32_16x16x32_bf16 v[58:61], v[184:187], v[200:203], v[58:61]
	v_mfma_f32_16x16x32_bf16 v[50:53], v[192:195], v[200:203], v[50:53]
	v_mfma_f32_16x16x32_bf16 v[34:37], v[192:195], v[208:211], v[34:37]
	v_mfma_f32_16x16x32_bf16 v[42:45], v[184:187], v[208:211], v[42:45]
	v_mfma_f32_16x16x32_bf16 v[38:41], v[176:179], v[208:211], v[38:41]
	v_mfma_f32_16x16x32_bf16 v[46:49], v[168:171], v[208:211], v[46:49]
	v_mfma_f32_16x16x32_bf16 v[30:33], v[168:171], v[216:219], v[30:33]
	v_mfma_f32_16x16x32_bf16 v[22:25], v[176:179], v[216:219], v[22:25]
	v_mfma_f32_16x16x32_bf16 v[26:29], v[184:187], v[216:219], v[26:29]
	v_mfma_f32_16x16x32_bf16 v[18:21], v[192:195], v[216:219], v[18:21]
	v_mfma_f32_16x16x32_bf16 v[2:5], v[192:195], v[224:227], v[2:5]
	v_mfma_f32_16x16x32_bf16 v[10:13], v[184:187], v[224:227], v[10:13]
	v_mfma_f32_16x16x32_bf16 v[6:9], v[176:179], v[224:227], v[6:9]
	v_mfma_f32_16x16x32_bf16 v[14:17], v[168:171], v[224:227], v[14:17]
	s_barrier
	s_setprio 0
	s_add_u32 s98, s94, 0xb0000
	s_addc_u32 s99, s95, 0
	s_add_i32 s4, 0, 0x18000
	s_add_i32 s25, 0, 0x1c000
	s_mov_b32 m0, s46
	ds_read_b128 v[164:167], v232
	global_load_lds_dwordx4 v130, s[98:99]
	s_mov_b32 m0, s47
	ds_read_b128 v[168:171], v232 offset:1024
	global_load_lds_dwordx4 v134, s[98:99]
	ds_read_b128 v[172:175], v232 offset:2048
	ds_read_b128 v[176:179], v232 offset:3072
	ds_read_b128 v[180:183], v233
	ds_read_b128 v[184:187], v233 offset:1024
	ds_read_b128 v[188:191], v233 offset:2048
	ds_read_b128 v[192:195], v233 offset:3072
	ds_read_b128 v[196:199], v160 offset:32768
	ds_read_b128 v[200:203], v160 offset:33792
	ds_read_b128 v[204:207], v160 offset:34816
	ds_read_b128 v[208:211], v160 offset:35840
	ds_read_b128 v[212:215], v160 offset:36864
	ds_read_b128 v[216:219], v160 offset:37888
	ds_read_b128 v[220:223], v160 offset:38912
	ds_read_b128 v[224:227], v160 offset:39936
	s_waitcnt vmcnt(8)
	s_waitcnt lgkmcnt(0)
	s_setprio 1
	s_barrier
	v_mfma_f32_16x16x32_bf16 v[122:125], v[164:167], v[196:199], v[122:125]
	v_mfma_f32_16x16x32_bf16 v[118:121], v[172:175], v[196:199], v[118:121]
	v_mfma_f32_16x16x32_bf16 v[126:129], v[180:183], v[196:199], v[126:129]
	v_mfma_f32_16x16x32_bf16 v[114:117], v[188:191], v[196:199], v[114:117]
	v_mfma_f32_16x16x32_bf16 v[98:101], v[188:191], v[204:207], v[98:101]
	v_mfma_f32_16x16x32_bf16 v[106:109], v[180:183], v[204:207], v[106:109]
	v_mfma_f32_16x16x32_bf16 v[102:105], v[172:175], v[204:207], v[102:105]
	v_mfma_f32_16x16x32_bf16 v[110:113], v[164:167], v[204:207], v[110:113]
	v_mfma_f32_16x16x32_bf16 v[94:97], v[164:167], v[212:215], v[94:97]
	v_mfma_f32_16x16x32_bf16 v[86:89], v[172:175], v[212:215], v[86:89]
	v_mfma_f32_16x16x32_bf16 v[90:93], v[180:183], v[212:215], v[90:93]
	v_mfma_f32_16x16x32_bf16 v[82:85], v[188:191], v[212:215], v[82:85]
	v_mfma_f32_16x16x32_bf16 v[66:69], v[188:191], v[220:223], v[66:69]
	v_mfma_f32_16x16x32_bf16 v[74:77], v[180:183], v[220:223], v[74:77]
	v_mfma_f32_16x16x32_bf16 v[70:73], v[172:175], v[220:223], v[70:73]
	v_mfma_f32_16x16x32_bf16 v[78:81], v[164:167], v[220:223], v[78:81]
	v_mfma_f32_16x16x32_bf16 v[122:125], v[168:171], v[200:203], v[122:125]
	v_mfma_f32_16x16x32_bf16 v[118:121], v[176:179], v[200:203], v[118:121]
	v_mfma_f32_16x16x32_bf16 v[126:129], v[184:187], v[200:203], v[126:129]
	v_mfma_f32_16x16x32_bf16 v[114:117], v[192:195], v[200:203], v[114:117]
	v_mfma_f32_16x16x32_bf16 v[98:101], v[192:195], v[208:211], v[98:101]
	v_mfma_f32_16x16x32_bf16 v[106:109], v[184:187], v[208:211], v[106:109]
	v_mfma_f32_16x16x32_bf16 v[102:105], v[176:179], v[208:211], v[102:105]
	v_mfma_f32_16x16x32_bf16 v[110:113], v[168:171], v[208:211], v[110:113]
	v_mfma_f32_16x16x32_bf16 v[94:97], v[168:171], v[216:219], v[94:97]
	v_mfma_f32_16x16x32_bf16 v[86:89], v[176:179], v[216:219], v[86:89]
	v_mfma_f32_16x16x32_bf16 v[90:93], v[184:187], v[216:219], v[90:93]
	v_mfma_f32_16x16x32_bf16 v[82:85], v[192:195], v[216:219], v[82:85]
	v_mfma_f32_16x16x32_bf16 v[66:69], v[192:195], v[224:227], v[66:69]
	v_mfma_f32_16x16x32_bf16 v[74:77], v[184:187], v[224:227], v[74:77]
	v_mfma_f32_16x16x32_bf16 v[70:73], v[176:179], v[224:227], v[70:73]
	v_mfma_f32_16x16x32_bf16 v[78:81], v[168:171], v[224:227], v[78:81]
	s_barrier
	s_setprio 0
	s_add_u32 s96, s96, 0x80
	s_addc_u32 s97, s97, 0
	s_add_u32 s98, s96, 0xb0000
	s_addc_u32 s99, s97, 0
	s_add_u32 s94, s94, 0x80
	s_addc_u32 s95, s95, 0
	s_add_i32 s4, s4, s21
	s_mov_b32 m0, s4
	ds_read_b128 v[196:199], v160 offset:49152
	global_load_lds_dwordx4 v132, s[96:97]
	s_add_i32 m0, s4, 0x2000
	s_add_i32 s4, s25, s21
	global_load_lds_dwordx4 v136, s[96:97]
	s_mov_b32 m0, s4
	ds_read_b128 v[200:203], v160 offset:50176
	global_load_lds_dwordx4 v132, s[98:99]
	s_add_i32 m0, s4, 0x2000
	ds_read_b128 v[204:207], v160 offset:51200
	global_load_lds_dwordx4 v136, s[98:99]
	s_mov_b32 m0, s57
	ds_read_b128 v[208:211], v160 offset:52224
	global_load_lds_dwordx4 v130, s[94:95]
	s_mov_b32 m0, s58
	ds_read_b128 v[212:215], v160 offset:53248
	global_load_lds_dwordx4 v134, s[94:95]
	ds_read_b128 v[216:219], v160 offset:54272
	ds_read_b128 v[220:223], v160 offset:55296
	ds_read_b128 v[224:227], v160 offset:56320
	s_waitcnt vmcnt(8)
	s_waitcnt lgkmcnt(0)
	s_setprio 1
	s_barrier
	v_mfma_f32_16x16x32_bf16 v[62:65], v[164:167], v[196:199], v[62:65]
	v_mfma_f32_16x16x32_bf16 v[54:57], v[172:175], v[196:199], v[54:57]
	v_mfma_f32_16x16x32_bf16 v[58:61], v[180:183], v[196:199], v[58:61]
	v_mfma_f32_16x16x32_bf16 v[50:53], v[188:191], v[196:199], v[50:53]
	v_mfma_f32_16x16x32_bf16 v[34:37], v[188:191], v[204:207], v[34:37]
	v_mfma_f32_16x16x32_bf16 v[42:45], v[180:183], v[204:207], v[42:45]
	v_mfma_f32_16x16x32_bf16 v[38:41], v[172:175], v[204:207], v[38:41]
	v_mfma_f32_16x16x32_bf16 v[46:49], v[164:167], v[204:207], v[46:49]
	v_mfma_f32_16x16x32_bf16 v[30:33], v[164:167], v[212:215], v[30:33]
	v_mfma_f32_16x16x32_bf16 v[22:25], v[172:175], v[212:215], v[22:25]
	v_mfma_f32_16x16x32_bf16 v[26:29], v[180:183], v[212:215], v[26:29]
	v_mfma_f32_16x16x32_bf16 v[18:21], v[188:191], v[212:215], v[18:21]
	v_mfma_f32_16x16x32_bf16 v[2:5], v[188:191], v[220:223], v[2:5]
	v_mfma_f32_16x16x32_bf16 v[10:13], v[180:183], v[220:223], v[10:13]
	v_mfma_f32_16x16x32_bf16 v[6:9], v[172:175], v[220:223], v[6:9]
	v_mfma_f32_16x16x32_bf16 v[14:17], v[164:167], v[220:223], v[14:17]
	v_mfma_f32_16x16x32_bf16 v[62:65], v[168:171], v[200:203], v[62:65]
	v_mfma_f32_16x16x32_bf16 v[54:57], v[176:179], v[200:203], v[54:57]
	v_mfma_f32_16x16x32_bf16 v[58:61], v[184:187], v[200:203], v[58:61]
	v_mfma_f32_16x16x32_bf16 v[50:53], v[192:195], v[200:203], v[50:53]
	v_mfma_f32_16x16x32_bf16 v[34:37], v[192:195], v[208:211], v[34:37]
	v_mfma_f32_16x16x32_bf16 v[42:45], v[184:187], v[208:211], v[42:45]
	v_mfma_f32_16x16x32_bf16 v[38:41], v[176:179], v[208:211], v[38:41]
	v_mfma_f32_16x16x32_bf16 v[46:49], v[168:171], v[208:211], v[46:49]
	v_mfma_f32_16x16x32_bf16 v[30:33], v[168:171], v[216:219], v[30:33]
	v_mfma_f32_16x16x32_bf16 v[22:25], v[176:179], v[216:219], v[22:25]
	v_mfma_f32_16x16x32_bf16 v[26:29], v[184:187], v[216:219], v[26:29]
	v_mfma_f32_16x16x32_bf16 v[18:21], v[192:195], v[216:219], v[18:21]
	v_mfma_f32_16x16x32_bf16 v[2:5], v[192:195], v[224:227], v[2:5]
	v_mfma_f32_16x16x32_bf16 v[10:13], v[184:187], v[224:227], v[10:13]
	v_mfma_f32_16x16x32_bf16 v[6:9], v[176:179], v[224:227], v[6:9]
	v_mfma_f32_16x16x32_bf16 v[14:17], v[168:171], v[224:227], v[14:17]
	s_barrier
	s_setprio 0
	s_mov_b32 s4, s5
	s_add_u32 s88, s88, 0x100
	s_addc_u32 s89, s89, 0
	s_add_u32 s86, s86, 0x100
	s_addc_u32 s87, s87, 0
	s_cmp_ge_i32 s5, s101
	s_cbranch_scc0 .LBB0_2075
